# GEMM K-loops: removed the mid-segment s_setprio 0/1 flip and the redundant lgkmcnt(0) after each compute-segment barrier
# baseline (speedup 1.0000x reference)
.Lpk354_peel:
	ds_read_b128 v[166:169], v139
	ds_read_b128 v[170:173], v139 offset:1024
	ds_read_b128 v[178:181], v139 offset:2048
	ds_read_b128 v[182:185], v139 offset:3072
	ds_read_b128 v[186:189], v164
	ds_read_b128 v[190:193], v164 offset:1024
	ds_read_b128 v[194:197], v164 offset:2048
	ds_read_b128 v[198:201], v164 offset:3072
	s_add_u32 s2, s26, 0xfffc0080
	s_addc_u32 s3, s27, -1
	s_cmp_eq_u32 s52, 12
	s_cselect_b32 s3, s11, s3
	s_cselect_b32 s2, s13, s2
	s_cselect_b32 s29, s44, s47
	s_cselect_b32 s28, s45, s46
	v_lshl_add_u64 v[148:149], s[26:27], 0, v[142:143]
	s_add_i32 m0, s34, 0xc000
	ds_read_b128 v[202:205], v165
	ds_read_b128 v[206:209], v165 offset:1024
	ds_read_b128 v[210:213], v165 offset:2048
	ds_read_b128 v[214:217], v165 offset:3072
	ds_read_b128 v[218:221], v165 offset:4096
	ds_read_b128 v[222:225], v165 offset:5120
	ds_read_b128 v[226:229], v165 offset:6144
	ds_read_b128 v[230:233], v165 offset:7168
	global_load_lds_dwordx4 v[148:149], off
	v_lshl_add_u64 v[148:149], s[26:27], 0, v[144:145]
	s_add_i32 m0, s34, 0xe000
	s_nop 0
	global_load_lds_dwordx4 v[148:149], off
	s_waitcnt vmcnt(8)
	s_waitcnt lgkmcnt(0)
	s_barrier
	s_setprio 1
	v_mfma_f32_16x16x32_bf16 v[126:129], v[166:169], v[202:205], 0
	v_mfma_f32_16x16x32_bf16 v[122:125], v[178:181], v[202:205], 0
	v_mfma_f32_16x16x32_bf16 v[110:113], v[166:169], v[210:213], 0
	v_mfma_f32_16x16x32_bf16 v[106:109], v[178:181], v[210:213], 0
	v_mfma_f32_16x16x32_bf16 v[94:97], v[166:169], v[218:221], 0
	v_mfma_f32_16x16x32_bf16 v[90:93], v[178:181], v[218:221], 0
	v_mfma_f32_16x16x32_bf16 v[78:81], v[166:169], v[226:229], 0
	v_mfma_f32_16x16x32_bf16 v[74:77], v[178:181], v[226:229], 0
	v_mfma_f32_16x16x32_bf16 v[126:129], v[170:173], v[206:209], v[126:129]
	v_mfma_f32_16x16x32_bf16 v[122:125], v[182:185], v[206:209], v[122:125]
	v_mfma_f32_16x16x32_bf16 v[110:113], v[170:173], v[214:217], v[110:113]
	v_mfma_f32_16x16x32_bf16 v[106:109], v[182:185], v[214:217], v[106:109]
	v_mfma_f32_16x16x32_bf16 v[94:97], v[170:173], v[222:225], v[94:97]
	v_mfma_f32_16x16x32_bf16 v[90:93], v[182:185], v[222:225], v[90:93]
	v_mfma_f32_16x16x32_bf16 v[78:81], v[170:173], v[230:233], v[78:81]
	v_mfma_f32_16x16x32_bf16 v[74:77], v[182:185], v[230:233], v[74:77]
	v_mfma_f32_16x16x32_bf16 v[118:121], v[186:189], v[202:205], 0
	v_mfma_f32_16x16x32_bf16 v[114:117], v[194:197], v[202:205], 0
	v_mfma_f32_16x16x32_bf16 v[102:105], v[186:189], v[210:213], 0
	v_mfma_f32_16x16x32_bf16 v[98:101], v[194:197], v[210:213], 0
	v_mfma_f32_16x16x32_bf16 v[86:89], v[186:189], v[218:221], 0
	v_mfma_f32_16x16x32_bf16 v[82:85], v[194:197], v[218:221], 0
	v_mfma_f32_16x16x32_bf16 v[70:73], v[186:189], v[226:229], 0
	v_mfma_f32_16x16x32_bf16 v[66:69], v[194:197], v[226:229], 0
	v_mfma_f32_16x16x32_bf16 v[118:121], v[190:193], v[206:209], v[118:121]
	v_mfma_f32_16x16x32_bf16 v[114:117], v[198:201], v[206:209], v[114:117]
	v_mfma_f32_16x16x32_bf16 v[102:105], v[190:193], v[214:217], v[102:105]
	v_mfma_f32_16x16x32_bf16 v[98:101], v[198:201], v[214:217], v[98:101]
	v_mfma_f32_16x16x32_bf16 v[86:89], v[190:193], v[222:225], v[86:89]
	v_mfma_f32_16x16x32_bf16 v[82:85], v[198:201], v[222:225], v[82:85]
	v_mfma_f32_16x16x32_bf16 v[70:73], v[190:193], v[230:233], v[70:73]
	v_mfma_f32_16x16x32_bf16 v[66:69], v[198:201], v[230:233], v[66:69]
	s_setprio 0
	s_barrier
	s_add_i32 s53, s41, s30
	v_lshl_add_u64 v[148:149], s[28:29], 0, v[132:133]
	s_mov_b32 m0, s53
	ds_read_b128 v[202:205], v165 offset:16384
	ds_read_b128 v[206:209], v165 offset:17408
	ds_read_b128 v[210:213], v165 offset:18432
	ds_read_b128 v[214:217], v165 offset:19456
	ds_read_b128 v[218:221], v165 offset:20480
	ds_read_b128 v[222:225], v165 offset:21504
	ds_read_b128 v[226:229], v165 offset:22528
	ds_read_b128 v[230:233], v165 offset:23552
	global_load_lds_dwordx4 v[148:149], off
	s_add_i32 m0, s53, 0x2000
	s_add_u32 s54, s28, 0x40000
	v_lshl_add_u64 v[174:175], s[28:29], 0, v[136:137]
	s_addc_u32 s55, s29, 0
	s_add_i32 s53, s42, s30
	global_load_lds_dwordx4 v[174:175], off
	v_lshl_add_u64 v[234:235], s[54:55], 0, v[132:133]
	s_mov_b32 m0, s53
	v_lshl_add_u64 v[236:237], s[2:3], 0, v[134:135]
	global_load_lds_dwordx4 v[234:235], off
	v_lshl_add_u64 v[234:235], s[54:55], 0, v[136:137]
	s_add_i32 m0, s53, 0x2000
	s_nop 0
	global_load_lds_dwordx4 v[234:235], off
	v_lshl_add_u64 v[234:235], s[2:3], 0, v[130:131]
	s_mov_b32 m0, s34
	s_nop 0
	global_load_lds_dwordx4 v[234:235], off
	s_mov_b32 m0, s25
	s_nop 0
	global_load_lds_dwordx4 v[236:237], off
	s_waitcnt vmcnt(8)
	s_waitcnt lgkmcnt(0)
	s_barrier
	s_setprio 1
	v_mfma_f32_16x16x32_bf16 v[62:65], v[166:169], v[202:205], 0
	v_mfma_f32_16x16x32_bf16 v[58:61], v[178:181], v[202:205], 0
	v_mfma_f32_16x16x32_bf16 v[46:49], v[166:169], v[210:213], 0
	v_mfma_f32_16x16x32_bf16 v[42:45], v[178:181], v[210:213], 0
	v_mfma_f32_16x16x32_bf16 v[30:33], v[166:169], v[218:221], 0
	v_mfma_f32_16x16x32_bf16 v[26:29], v[178:181], v[218:221], 0
	v_mfma_f32_16x16x32_bf16 v[14:17], v[166:169], v[226:229], 0
	v_mfma_f32_16x16x32_bf16 v[10:13], v[178:181], v[226:229], 0
	v_mfma_f32_16x16x32_bf16 v[62:65], v[170:173], v[206:209], v[62:65]
	v_mfma_f32_16x16x32_bf16 v[58:61], v[182:185], v[206:209], v[58:61]
	v_mfma_f32_16x16x32_bf16 v[46:49], v[170:173], v[214:217], v[46:49]
	v_mfma_f32_16x16x32_bf16 v[42:45], v[182:185], v[214:217], v[42:45]
	v_mfma_f32_16x16x32_bf16 v[30:33], v[170:173], v[222:225], v[30:33]
	v_mfma_f32_16x16x32_bf16 v[26:29], v[182:185], v[222:225], v[26:29]
	v_mfma_f32_16x16x32_bf16 v[14:17], v[170:173], v[230:233], v[14:17]
	v_mfma_f32_16x16x32_bf16 v[10:13], v[182:185], v[230:233], v[10:13]
	v_mfma_f32_16x16x32_bf16 v[54:57], v[186:189], v[202:205], 0
	v_mfma_f32_16x16x32_bf16 v[50:53], v[194:197], v[202:205], 0
	v_mfma_f32_16x16x32_bf16 v[38:41], v[186:189], v[210:213], 0
	v_mfma_f32_16x16x32_bf16 v[34:37], v[194:197], v[210:213], 0
	v_mfma_f32_16x16x32_bf16 v[22:25], v[186:189], v[218:221], 0
	v_mfma_f32_16x16x32_bf16 v[18:21], v[194:197], v[218:221], 0
	v_mfma_f32_16x16x32_bf16 v[6:9], v[186:189], v[226:229], 0
	v_mfma_f32_16x16x32_bf16 v[2:5], v[194:197], v[226:229], 0
	v_mfma_f32_16x16x32_bf16 v[54:57], v[190:193], v[206:209], v[54:57]
	v_mfma_f32_16x16x32_bf16 v[50:53], v[198:201], v[206:209], v[50:53]
	v_mfma_f32_16x16x32_bf16 v[38:41], v[190:193], v[214:217], v[38:41]
	v_mfma_f32_16x16x32_bf16 v[34:37], v[198:201], v[214:217], v[34:37]
	v_mfma_f32_16x16x32_bf16 v[22:25], v[190:193], v[222:225], v[22:25]
	v_mfma_f32_16x16x32_bf16 v[18:21], v[198:201], v[222:225], v[18:21]
	v_mfma_f32_16x16x32_bf16 v[6:9], v[190:193], v[230:233], v[6:9]
	v_mfma_f32_16x16x32_bf16 v[2:5], v[198:201], v[230:233], v[2:5]
	s_setprio 0
	s_barrier
	s_add_i32 s53, 0, 0x18000
	v_add_u32_e32 v176, s53, v163
	s_add_i32 s54, 0, 0x1c000
	ds_read_b128 v[166:169], v176
	ds_read_b128 v[170:173], v176 offset:1024
	ds_read_b128 v[178:181], v176 offset:2048
	ds_read_b128 v[182:185], v176 offset:3072
	v_add_u32_e32 v176, s54, v163
	ds_read_b128 v[186:189], v176
	ds_read_b128 v[190:193], v176 offset:1024
	ds_read_b128 v[194:197], v176 offset:2048
	ds_read_b128 v[198:201], v176 offset:3072
	s_add_u32 s2, s2, 0x40000
	s_addc_u32 s3, s3, 0
	s_mov_b32 m0, s35
	v_lshl_add_u64 v[238:239], s[2:3], 0, v[130:131]
	ds_read_b128 v[202:205], v165 offset:32768
	ds_read_b128 v[206:209], v165 offset:33792
	ds_read_b128 v[210:213], v165 offset:34816
	ds_read_b128 v[214:217], v165 offset:35840
	ds_read_b128 v[218:221], v165 offset:36864
	ds_read_b128 v[222:225], v165 offset:37888
	ds_read_b128 v[226:229], v165 offset:38912
	ds_read_b128 v[230:233], v165 offset:39936
	global_load_lds_dwordx4 v[238:239], off
	v_lshl_add_u64 v[238:239], s[2:3], 0, v[134:135]
	s_mov_b32 m0, s36
	s_nop 0
	global_load_lds_dwordx4 v[238:239], off
	s_waitcnt vmcnt(8)
	s_waitcnt lgkmcnt(0)
	s_barrier
	s_setprio 1
	v_mfma_f32_16x16x32_bf16 v[126:129], v[166:169], v[202:205], v[126:129]
	v_mfma_f32_16x16x32_bf16 v[122:125], v[178:181], v[202:205], v[122:125]
	v_mfma_f32_16x16x32_bf16 v[110:113], v[166:169], v[210:213], v[110:113]
	v_mfma_f32_16x16x32_bf16 v[106:109], v[178:181], v[210:213], v[106:109]
	v_mfma_f32_16x16x32_bf16 v[94:97], v[166:169], v[218:221], v[94:97]
	v_mfma_f32_16x16x32_bf16 v[90:93], v[178:181], v[218:221], v[90:93]
	v_mfma_f32_16x16x32_bf16 v[78:81], v[166:169], v[226:229], v[78:81]
	v_mfma_f32_16x16x32_bf16 v[74:77], v[178:181], v[226:229], v[74:77]
	v_mfma_f32_16x16x32_bf16 v[126:129], v[170:173], v[206:209], v[126:129]
	v_mfma_f32_16x16x32_bf16 v[122:125], v[182:185], v[206:209], v[122:125]
	v_mfma_f32_16x16x32_bf16 v[110:113], v[170:173], v[214:217], v[110:113]
	v_mfma_f32_16x16x32_bf16 v[106:109], v[182:185], v[214:217], v[106:109]
	v_mfma_f32_16x16x32_bf16 v[94:97], v[170:173], v[222:225], v[94:97]
	v_mfma_f32_16x16x32_bf16 v[90:93], v[182:185], v[222:225], v[90:93]
	v_mfma_f32_16x16x32_bf16 v[78:81], v[170:173], v[230:233], v[78:81]
	v_mfma_f32_16x16x32_bf16 v[74:77], v[182:185], v[230:233], v[74:77]
	v_mfma_f32_16x16x32_bf16 v[118:121], v[186:189], v[202:205], v[118:121]
	v_mfma_f32_16x16x32_bf16 v[114:117], v[194:197], v[202:205], v[114:117]
	v_mfma_f32_16x16x32_bf16 v[102:105], v[186:189], v[210:213], v[102:105]
	v_mfma_f32_16x16x32_bf16 v[98:101], v[194:197], v[210:213], v[98:101]
	v_mfma_f32_16x16x32_bf16 v[86:89], v[186:189], v[218:221], v[86:89]
	v_mfma_f32_16x16x32_bf16 v[82:85], v[194:197], v[218:221], v[82:85]
	v_mfma_f32_16x16x32_bf16 v[70:73], v[186:189], v[226:229], v[70:73]
	v_mfma_f32_16x16x32_bf16 v[66:69], v[194:197], v[226:229], v[66:69]
	v_mfma_f32_16x16x32_bf16 v[118:121], v[190:193], v[206:209], v[118:121]
	v_mfma_f32_16x16x32_bf16 v[114:117], v[198:201], v[206:209], v[114:117]
	v_mfma_f32_16x16x32_bf16 v[102:105], v[190:193], v[214:217], v[102:105]
	v_mfma_f32_16x16x32_bf16 v[98:101], v[198:201], v[214:217], v[98:101]
	v_mfma_f32_16x16x32_bf16 v[86:89], v[190:193], v[222:225], v[86:89]
	v_mfma_f32_16x16x32_bf16 v[82:85], v[198:201], v[222:225], v[82:85]
	v_mfma_f32_16x16x32_bf16 v[70:73], v[190:193], v[230:233], v[70:73]
	v_mfma_f32_16x16x32_bf16 v[66:69], v[198:201], v[230:233], v[66:69]
	s_setprio 0
	s_barrier
	s_add_i32 s2, s53, s30
	v_lshl_add_u64 v[148:149], v[148:149], 0, s[6:7]
	s_mov_b32 m0, s2
	ds_read_b128 v[202:205], v165 offset:49152
	ds_read_b128 v[206:209], v165 offset:50176
	ds_read_b128 v[210:213], v165 offset:51200
	ds_read_b128 v[214:217], v165 offset:52224
	ds_read_b128 v[218:221], v165 offset:53248
	ds_read_b128 v[222:225], v165 offset:54272
	ds_read_b128 v[226:229], v165 offset:55296
	ds_read_b128 v[230:233], v165 offset:56320
	global_load_lds_dwordx4 v[148:149], off
	s_add_i32 m0, s2, 0x2000
	s_add_u32 s2, s28, 0x40080
	v_lshl_add_u64 v[148:149], v[174:175], 0, s[6:7]
	s_addc_u32 s3, s29, 0
	s_add_i32 s28, s54, s30
	global_load_lds_dwordx4 v[148:149], off
	v_lshl_add_u64 v[148:149], s[2:3], 0, v[132:133]
	s_mov_b32 m0, s28
	s_nop 0
	global_load_lds_dwordx4 v[148:149], off
	v_lshl_add_u64 v[148:149], s[2:3], 0, v[136:137]
	s_add_i32 m0, s28, 0x2000
	s_nop 0
	global_load_lds_dwordx4 v[148:149], off
	v_lshl_add_u64 v[148:149], v[234:235], 0, s[6:7]
	s_mov_b32 m0, s38
	s_nop 0
	global_load_lds_dwordx4 v[148:149], off
	v_lshl_add_u64 v[148:149], v[236:237], 0, s[6:7]
	s_mov_b32 m0, s39
	s_nop 0
	global_load_lds_dwordx4 v[148:149], off
	s_waitcnt vmcnt(8)
	s_waitcnt lgkmcnt(0)
	s_barrier
	s_setprio 1
	v_mfma_f32_16x16x32_bf16 v[62:65], v[166:169], v[202:205], v[62:65]
	v_mfma_f32_16x16x32_bf16 v[58:61], v[178:181], v[202:205], v[58:61]
	v_mfma_f32_16x16x32_bf16 v[46:49], v[166:169], v[210:213], v[46:49]
	v_mfma_f32_16x16x32_bf16 v[42:45], v[178:181], v[210:213], v[42:45]
	v_mfma_f32_16x16x32_bf16 v[30:33], v[166:169], v[218:221], v[30:33]
	v_mfma_f32_16x16x32_bf16 v[26:29], v[178:181], v[218:221], v[26:29]
	v_mfma_f32_16x16x32_bf16 v[14:17], v[166:169], v[226:229], v[14:17]
	v_mfma_f32_16x16x32_bf16 v[10:13], v[178:181], v[226:229], v[10:13]
	v_mfma_f32_16x16x32_bf16 v[62:65], v[170:173], v[206:209], v[62:65]
	v_mfma_f32_16x16x32_bf16 v[58:61], v[182:185], v[206:209], v[58:61]
	v_mfma_f32_16x16x32_bf16 v[46:49], v[170:173], v[214:217], v[46:49]
	v_mfma_f32_16x16x32_bf16 v[42:45], v[182:185], v[214:217], v[42:45]
	v_mfma_f32_16x16x32_bf16 v[30:33], v[170:173], v[222:225], v[30:33]
	v_mfma_f32_16x16x32_bf16 v[26:29], v[182:185], v[222:225], v[26:29]
	v_mfma_f32_16x16x32_bf16 v[14:17], v[170:173], v[230:233], v[14:17]
	v_mfma_f32_16x16x32_bf16 v[10:13], v[182:185], v[230:233], v[10:13]
	v_mfma_f32_16x16x32_bf16 v[54:57], v[186:189], v[202:205], v[54:57]
	v_mfma_f32_16x16x32_bf16 v[50:53], v[194:197], v[202:205], v[50:53]
	v_mfma_f32_16x16x32_bf16 v[38:41], v[186:189], v[210:213], v[38:41]
	v_mfma_f32_16x16x32_bf16 v[34:37], v[194:197], v[210:213], v[34:37]
	v_mfma_f32_16x16x32_bf16 v[22:25], v[186:189], v[218:221], v[22:25]
	v_mfma_f32_16x16x32_bf16 v[18:21], v[194:197], v[218:221], v[18:21]
	v_mfma_f32_16x16x32_bf16 v[6:9], v[186:189], v[226:229], v[6:9]
	v_mfma_f32_16x16x32_bf16 v[2:5], v[194:197], v[226:229], v[2:5]
	v_mfma_f32_16x16x32_bf16 v[54:57], v[190:193], v[206:209], v[54:57]
	v_mfma_f32_16x16x32_bf16 v[50:53], v[198:201], v[206:209], v[50:53]
	v_mfma_f32_16x16x32_bf16 v[38:41], v[190:193], v[214:217], v[38:41]
	v_mfma_f32_16x16x32_bf16 v[34:37], v[198:201], v[214:217], v[34:37]
	v_mfma_f32_16x16x32_bf16 v[22:25], v[190:193], v[222:225], v[22:25]
	v_mfma_f32_16x16x32_bf16 v[18:21], v[198:201], v[222:225], v[18:21]
	v_mfma_f32_16x16x32_bf16 v[6:9], v[190:193], v[230:233], v[6:9]
	v_mfma_f32_16x16x32_bf16 v[2:5], v[198:201], v[230:233], v[2:5]
	s_setprio 0
	s_barrier
	s_add_i32 s52, s52, 2
	s_add_u32 s26, s26, 0x100
	s_addc_u32 s27, s27, 0
	s_add_u32 s46, s46, 0x100
	s_addc_u32 s47, s47, 0
	s_cmp_gt_u32 s52, 13
	s_cbranch_scc0 .LBB0_354
	s_branch .Lpk354_exit
.LBB0_354:
	ds_read_b128 v[166:169], v139
	ds_read_b128 v[170:173], v139 offset:1024
	ds_read_b128 v[178:181], v139 offset:2048
	ds_read_b128 v[182:185], v139 offset:3072
	ds_read_b128 v[186:189], v164
	ds_read_b128 v[190:193], v164 offset:1024
	ds_read_b128 v[194:197], v164 offset:2048
	ds_read_b128 v[198:201], v164 offset:3072
	s_add_u32 s2, s26, 0xfffc0080
	s_addc_u32 s3, s27, -1
	s_cmp_eq_u32 s52, 12
	s_cselect_b32 s3, s11, s3
	s_cselect_b32 s2, s13, s2
	s_cselect_b32 s29, s44, s47
	s_cselect_b32 s28, s45, s46
	v_lshl_add_u64 v[148:149], s[26:27], 0, v[142:143]
	s_add_i32 m0, s34, 0xc000
	ds_read_b128 v[202:205], v165
	ds_read_b128 v[206:209], v165 offset:1024
	ds_read_b128 v[210:213], v165 offset:2048
	ds_read_b128 v[214:217], v165 offset:3072
	ds_read_b128 v[218:221], v165 offset:4096
	ds_read_b128 v[222:225], v165 offset:5120
	ds_read_b128 v[226:229], v165 offset:6144
	ds_read_b128 v[230:233], v165 offset:7168
	global_load_lds_dwordx4 v[148:149], off
	v_lshl_add_u64 v[148:149], s[26:27], 0, v[144:145]
	s_add_i32 m0, s34, 0xe000
	s_nop 0
	global_load_lds_dwordx4 v[148:149], off
	s_waitcnt vmcnt(8)
	s_waitcnt lgkmcnt(0)
	s_barrier
	s_setprio 1
	v_mfma_f32_16x16x32_bf16 v[126:129], v[166:169], v[202:205], v[126:129]
	v_mfma_f32_16x16x32_bf16 v[122:125], v[178:181], v[202:205], v[122:125]
	v_mfma_f32_16x16x32_bf16 v[110:113], v[166:169], v[210:213], v[110:113]
	v_mfma_f32_16x16x32_bf16 v[106:109], v[178:181], v[210:213], v[106:109]
	v_mfma_f32_16x16x32_bf16 v[94:97], v[166:169], v[218:221], v[94:97]
	v_mfma_f32_16x16x32_bf16 v[90:93], v[178:181], v[218:221], v[90:93]
	v_mfma_f32_16x16x32_bf16 v[78:81], v[166:169], v[226:229], v[78:81]
	v_mfma_f32_16x16x32_bf16 v[74:77], v[178:181], v[226:229], v[74:77]
	v_mfma_f32_16x16x32_bf16 v[126:129], v[170:173], v[206:209], v[126:129]
	v_mfma_f32_16x16x32_bf16 v[122:125], v[182:185], v[206:209], v[122:125]
	v_mfma_f32_16x16x32_bf16 v[110:113], v[170:173], v[214:217], v[110:113]
	v_mfma_f32_16x16x32_bf16 v[106:109], v[182:185], v[214:217], v[106:109]
	v_mfma_f32_16x16x32_bf16 v[94:97], v[170:173], v[222:225], v[94:97]
	v_mfma_f32_16x16x32_bf16 v[90:93], v[182:185], v[222:225], v[90:93]
	v_mfma_f32_16x16x32_bf16 v[78:81], v[170:173], v[230:233], v[78:81]
	v_mfma_f32_16x16x32_bf16 v[74:77], v[182:185], v[230:233], v[74:77]
	v_mfma_f32_16x16x32_bf16 v[118:121], v[186:189], v[202:205], v[118:121]
	v_mfma_f32_16x16x32_bf16 v[114:117], v[194:197], v[202:205], v[114:117]
	v_mfma_f32_16x16x32_bf16 v[102:105], v[186:189], v[210:213], v[102:105]
	v_mfma_f32_16x16x32_bf16 v[98:101], v[194:197], v[210:213], v[98:101]
	v_mfma_f32_16x16x32_bf16 v[86:89], v[186:189], v[218:221], v[86:89]
	v_mfma_f32_16x16x32_bf16 v[82:85], v[194:197], v[218:221], v[82:85]
	v_mfma_f32_16x16x32_bf16 v[70:73], v[186:189], v[226:229], v[70:73]
	v_mfma_f32_16x16x32_bf16 v[66:69], v[194:197], v[226:229], v[66:69]
	v_mfma_f32_16x16x32_bf16 v[118:121], v[190:193], v[206:209], v[118:121]
	v_mfma_f32_16x16x32_bf16 v[114:117], v[198:201], v[206:209], v[114:117]
	v_mfma_f32_16x16x32_bf16 v[102:105], v[190:193], v[214:217], v[102:105]
	v_mfma_f32_16x16x32_bf16 v[98:101], v[198:201], v[214:217], v[98:101]
	v_mfma_f32_16x16x32_bf16 v[86:89], v[190:193], v[222:225], v[86:89]
	v_mfma_f32_16x16x32_bf16 v[82:85], v[198:201], v[222:225], v[82:85]
	v_mfma_f32_16x16x32_bf16 v[70:73], v[190:193], v[230:233], v[70:73]
	v_mfma_f32_16x16x32_bf16 v[66:69], v[198:201], v[230:233], v[66:69]
	s_setprio 0
	s_barrier
	s_add_i32 s53, s41, s30
	v_lshl_add_u64 v[148:149], s[28:29], 0, v[132:133]
	s_mov_b32 m0, s53
	ds_read_b128 v[202:205], v165 offset:16384
	ds_read_b128 v[206:209], v165 offset:17408
	ds_read_b128 v[210:213], v165 offset:18432
	ds_read_b128 v[214:217], v165 offset:19456
	ds_read_b128 v[218:221], v165 offset:20480
	ds_read_b128 v[222:225], v165 offset:21504
	ds_read_b128 v[226:229], v165 offset:22528
	ds_read_b128 v[230:233], v165 offset:23552
	global_load_lds_dwordx4 v[148:149], off
	s_add_i32 m0, s53, 0x2000
	s_add_u32 s54, s28, 0x40000
	v_lshl_add_u64 v[174:175], s[28:29], 0, v[136:137]
	s_addc_u32 s55, s29, 0
	s_add_i32 s53, s42, s30
	global_load_lds_dwordx4 v[174:175], off
	v_lshl_add_u64 v[234:235], s[54:55], 0, v[132:133]
	s_mov_b32 m0, s53
	v_lshl_add_u64 v[236:237], s[2:3], 0, v[134:135]
	global_load_lds_dwordx4 v[234:235], off
	v_lshl_add_u64 v[234:235], s[54:55], 0, v[136:137]
	s_add_i32 m0, s53, 0x2000
	s_nop 0
	global_load_lds_dwordx4 v[234:235], off
	v_lshl_add_u64 v[234:235], s[2:3], 0, v[130:131]
	s_mov_b32 m0, s34
	s_nop 0
	global_load_lds_dwordx4 v[234:235], off
	s_mov_b32 m0, s25
	s_nop 0
	global_load_lds_dwordx4 v[236:237], off
	s_waitcnt vmcnt(8)
	s_waitcnt lgkmcnt(0)
	s_barrier
	s_setprio 1
	v_mfma_f32_16x16x32_bf16 v[62:65], v[166:169], v[202:205], v[62:65]
	v_mfma_f32_16x16x32_bf16 v[58:61], v[178:181], v[202:205], v[58:61]
	v_mfma_f32_16x16x32_bf16 v[46:49], v[166:169], v[210:213], v[46:49]
	v_mfma_f32_16x16x32_bf16 v[42:45], v[178:181], v[210:213], v[42:45]
	v_mfma_f32_16x16x32_bf16 v[30:33], v[166:169], v[218:221], v[30:33]
	v_mfma_f32_16x16x32_bf16 v[26:29], v[178:181], v[218:221], v[26:29]
	v_mfma_f32_16x16x32_bf16 v[14:17], v[166:169], v[226:229], v[14:17]
	v_mfma_f32_16x16x32_bf16 v[10:13], v[178:181], v[226:229], v[10:13]
	v_mfma_f32_16x16x32_bf16 v[62:65], v[170:173], v[206:209], v[62:65]
	v_mfma_f32_16x16x32_bf16 v[58:61], v[182:185], v[206:209], v[58:61]
	v_mfma_f32_16x16x32_bf16 v[46:49], v[170:173], v[214:217], v[46:49]
	v_mfma_f32_16x16x32_bf16 v[42:45], v[182:185], v[214:217], v[42:45]
	v_mfma_f32_16x16x32_bf16 v[30:33], v[170:173], v[222:225], v[30:33]
	v_mfma_f32_16x16x32_bf16 v[26:29], v[182:185], v[222:225], v[26:29]
	v_mfma_f32_16x16x32_bf16 v[14:17], v[170:173], v[230:233], v[14:17]
	v_mfma_f32_16x16x32_bf16 v[10:13], v[182:185], v[230:233], v[10:13]
	v_mfma_f32_16x16x32_bf16 v[54:57], v[186:189], v[202:205], v[54:57]
	v_mfma_f32_16x16x32_bf16 v[50:53], v[194:197], v[202:205], v[50:53]
	v_mfma_f32_16x16x32_bf16 v[38:41], v[186:189], v[210:213], v[38:41]
	v_mfma_f32_16x16x32_bf16 v[34:37], v[194:197], v[210:213], v[34:37]
	v_mfma_f32_16x16x32_bf16 v[22:25], v[186:189], v[218:221], v[22:25]
	v_mfma_f32_16x16x32_bf16 v[18:21], v[194:197], v[218:221], v[18:21]
	v_mfma_f32_16x16x32_bf16 v[6:9], v[186:189], v[226:229], v[6:9]
	v_mfma_f32_16x16x32_bf16 v[2:5], v[194:197], v[226:229], v[2:5]
	v_mfma_f32_16x16x32_bf16 v[54:57], v[190:193], v[206:209], v[54:57]
	v_mfma_f32_16x16x32_bf16 v[50:53], v[198:201], v[206:209], v[50:53]
	v_mfma_f32_16x16x32_bf16 v[38:41], v[190:193], v[214:217], v[38:41]
	v_mfma_f32_16x16x32_bf16 v[34:37], v[198:201], v[214:217], v[34:37]
	v_mfma_f32_16x16x32_bf16 v[22:25], v[190:193], v[222:225], v[22:25]
	v_mfma_f32_16x16x32_bf16 v[18:21], v[198:201], v[222:225], v[18:21]
	v_mfma_f32_16x16x32_bf16 v[6:9], v[190:193], v[230:233], v[6:9]
	v_mfma_f32_16x16x32_bf16 v[2:5], v[198:201], v[230:233], v[2:5]
	s_setprio 0
	s_barrier
	s_add_i32 s53, 0, 0x18000
	v_add_u32_e32 v176, s53, v163
	s_add_i32 s54, 0, 0x1c000
	ds_read_b128 v[166:169], v176
	ds_read_b128 v[170:173], v176 offset:1024
	ds_read_b128 v[178:181], v176 offset:2048
	ds_read_b128 v[182:185], v176 offset:3072
	v_add_u32_e32 v176, s54, v163
	ds_read_b128 v[186:189], v176
	ds_read_b128 v[190:193], v176 offset:1024
	ds_read_b128 v[194:197], v176 offset:2048
	ds_read_b128 v[198:201], v176 offset:3072
	s_add_u32 s2, s2, 0x40000
	s_addc_u32 s3, s3, 0
	s_mov_b32 m0, s35
	v_lshl_add_u64 v[238:239], s[2:3], 0, v[130:131]
	ds_read_b128 v[202:205], v165 offset:32768
	ds_read_b128 v[206:209], v165 offset:33792
	ds_read_b128 v[210:213], v165 offset:34816
	ds_read_b128 v[214:217], v165 offset:35840
	ds_read_b128 v[218:221], v165 offset:36864
	ds_read_b128 v[222:225], v165 offset:37888
	ds_read_b128 v[226:229], v165 offset:38912
	ds_read_b128 v[230:233], v165 offset:39936
	global_load_lds_dwordx4 v[238:239], off
	v_lshl_add_u64 v[238:239], s[2:3], 0, v[134:135]
	s_mov_b32 m0, s36
	s_nop 0
	global_load_lds_dwordx4 v[238:239], off
	s_waitcnt vmcnt(8)
	s_waitcnt lgkmcnt(0)
	s_barrier
	s_setprio 1
	v_mfma_f32_16x16x32_bf16 v[126:129], v[166:169], v[202:205], v[126:129]
	v_mfma_f32_16x16x32_bf16 v[122:125], v[178:181], v[202:205], v[122:125]
	v_mfma_f32_16x16x32_bf16 v[110:113], v[166:169], v[210:213], v[110:113]
	v_mfma_f32_16x16x32_bf16 v[106:109], v[178:181], v[210:213], v[106:109]
	v_mfma_f32_16x16x32_bf16 v[94:97], v[166:169], v[218:221], v[94:97]
	v_mfma_f32_16x16x32_bf16 v[90:93], v[178:181], v[218:221], v[90:93]
	v_mfma_f32_16x16x32_bf16 v[78:81], v[166:169], v[226:229], v[78:81]
	v_mfma_f32_16x16x32_bf16 v[74:77], v[178:181], v[226:229], v[74:77]
	v_mfma_f32_16x16x32_bf16 v[126:129], v[170:173], v[206:209], v[126:129]
	v_mfma_f32_16x16x32_bf16 v[122:125], v[182:185], v[206:209], v[122:125]
	v_mfma_f32_16x16x32_bf16 v[110:113], v[170:173], v[214:217], v[110:113]
	v_mfma_f32_16x16x32_bf16 v[106:109], v[182:185], v[214:217], v[106:109]
	v_mfma_f32_16x16x32_bf16 v[94:97], v[170:173], v[222:225], v[94:97]
	v_mfma_f32_16x16x32_bf16 v[90:93], v[182:185], v[222:225], v[90:93]
	v_mfma_f32_16x16x32_bf16 v[78:81], v[170:173], v[230:233], v[78:81]
	v_mfma_f32_16x16x32_bf16 v[74:77], v[182:185], v[230:233], v[74:77]
	v_mfma_f32_16x16x32_bf16 v[118:121], v[186:189], v[202:205], v[118:121]
	v_mfma_f32_16x16x32_bf16 v[114:117], v[194:197], v[202:205], v[114:117]
	v_mfma_f32_16x16x32_bf16 v[102:105], v[186:189], v[210:213], v[102:105]
	v_mfma_f32_16x16x32_bf16 v[98:101], v[194:197], v[210:213], v[98:101]
	v_mfma_f32_16x16x32_bf16 v[86:89], v[186:189], v[218:221], v[86:89]
	v_mfma_f32_16x16x32_bf16 v[82:85], v[194:197], v[218:221], v[82:85]
	v_mfma_f32_16x16x32_bf16 v[70:73], v[186:189], v[226:229], v[70:73]
	v_mfma_f32_16x16x32_bf16 v[66:69], v[194:197], v[226:229], v[66:69]
	v_mfma_f32_16x16x32_bf16 v[118:121], v[190:193], v[206:209], v[118:121]
	v_mfma_f32_16x16x32_bf16 v[114:117], v[198:201], v[206:209], v[114:117]
	v_mfma_f32_16x16x32_bf16 v[102:105], v[190:193], v[214:217], v[102:105]
	v_mfma_f32_16x16x32_bf16 v[98:101], v[198:201], v[214:217], v[98:101]
	v_mfma_f32_16x16x32_bf16 v[86:89], v[190:193], v[222:225], v[86:89]
	v_mfma_f32_16x16x32_bf16 v[82:85], v[198:201], v[222:225], v[82:85]
	v_mfma_f32_16x16x32_bf16 v[70:73], v[190:193], v[230:233], v[70:73]
	v_mfma_f32_16x16x32_bf16 v[66:69], v[198:201], v[230:233], v[66:69]
	s_setprio 0
	s_barrier
	s_add_i32 s2, s53, s30
	v_lshl_add_u64 v[148:149], v[148:149], 0, s[6:7]
	s_mov_b32 m0, s2
	ds_read_b128 v[202:205], v165 offset:49152
	ds_read_b128 v[206:209], v165 offset:50176
	ds_read_b128 v[210:213], v165 offset:51200
	ds_read_b128 v[214:217], v165 offset:52224
	ds_read_b128 v[218:221], v165 offset:53248
	ds_read_b128 v[222:225], v165 offset:54272
	ds_read_b128 v[226:229], v165 offset:55296
	ds_read_b128 v[230:233], v165 offset:56320
	global_load_lds_dwordx4 v[148:149], off
	s_add_i32 m0, s2, 0x2000
	s_add_u32 s2, s28, 0x40080
	v_lshl_add_u64 v[148:149], v[174:175], 0, s[6:7]
	s_addc_u32 s3, s29, 0
	s_add_i32 s28, s54, s30
	global_load_lds_dwordx4 v[148:149], off
	v_lshl_add_u64 v[148:149], s[2:3], 0, v[132:133]
	s_mov_b32 m0, s28
	s_nop 0
	global_load_lds_dwordx4 v[148:149], off
	v_lshl_add_u64 v[148:149], s[2:3], 0, v[136:137]
	s_add_i32 m0, s28, 0x2000
	s_nop 0
	global_load_lds_dwordx4 v[148:149], off
	v_lshl_add_u64 v[148:149], v[234:235], 0, s[6:7]
	s_mov_b32 m0, s38
	s_nop 0
	global_load_lds_dwordx4 v[148:149], off
	v_lshl_add_u64 v[148:149], v[236:237], 0, s[6:7]
	s_mov_b32 m0, s39
	s_nop 0
	global_load_lds_dwordx4 v[148:149], off
	s_waitcnt vmcnt(8)
	s_waitcnt lgkmcnt(0)
	s_barrier
	s_setprio 1
	v_mfma_f32_16x16x32_bf16 v[62:65], v[166:169], v[202:205], v[62:65]
	v_mfma_f32_16x16x32_bf16 v[58:61], v[178:181], v[202:205], v[58:61]
	v_mfma_f32_16x16x32_bf16 v[46:49], v[166:169], v[210:213], v[46:49]
	v_mfma_f32_16x16x32_bf16 v[42:45], v[178:181], v[210:213], v[42:45]
	v_mfma_f32_16x16x32_bf16 v[30:33], v[166:169], v[218:221], v[30:33]
	v_mfma_f32_16x16x32_bf16 v[26:29], v[178:181], v[218:221], v[26:29]
	v_mfma_f32_16x16x32_bf16 v[14:17], v[166:169], v[226:229], v[14:17]
	v_mfma_f32_16x16x32_bf16 v[10:13], v[178:181], v[226:229], v[10:13]
	v_mfma_f32_16x16x32_bf16 v[62:65], v[170:173], v[206:209], v[62:65]
	v_mfma_f32_16x16x32_bf16 v[58:61], v[182:185], v[206:209], v[58:61]
	v_mfma_f32_16x16x32_bf16 v[46:49], v[170:173], v[214:217], v[46:49]
	v_mfma_f32_16x16x32_bf16 v[42:45], v[182:185], v[214:217], v[42:45]
	v_mfma_f32_16x16x32_bf16 v[30:33], v[170:173], v[222:225], v[30:33]
	v_mfma_f32_16x16x32_bf16 v[26:29], v[182:185], v[222:225], v[26:29]
	v_mfma_f32_16x16x32_bf16 v[14:17], v[170:173], v[230:233], v[14:17]
	v_mfma_f32_16x16x32_bf16 v[10:13], v[182:185], v[230:233], v[10:13]
	v_mfma_f32_16x16x32_bf16 v[54:57], v[186:189], v[202:205], v[54:57]
	v_mfma_f32_16x16x32_bf16 v[50:53], v[194:197], v[202:205], v[50:53]
	v_mfma_f32_16x16x32_bf16 v[38:41], v[186:189], v[210:213], v[38:41]
	v_mfma_f32_16x16x32_bf16 v[34:37], v[194:197], v[210:213], v[34:37]
	v_mfma_f32_16x16x32_bf16 v[22:25], v[186:189], v[218:221], v[22:25]
	v_mfma_f32_16x16x32_bf16 v[18:21], v[194:197], v[218:221], v[18:21]
	v_mfma_f32_16x16x32_bf16 v[6:9], v[186:189], v[226:229], v[6:9]
	v_mfma_f32_16x16x32_bf16 v[2:5], v[194:197], v[226:229], v[2:5]
	v_mfma_f32_16x16x32_bf16 v[54:57], v[190:193], v[206:209], v[54:57]
	v_mfma_f32_16x16x32_bf16 v[50:53], v[198:201], v[206:209], v[50:53]
	v_mfma_f32_16x16x32_bf16 v[38:41], v[190:193], v[214:217], v[38:41]
	v_mfma_f32_16x16x32_bf16 v[34:37], v[198:201], v[214:217], v[34:37]
	v_mfma_f32_16x16x32_bf16 v[22:25], v[190:193], v[222:225], v[22:25]
	v_mfma_f32_16x16x32_bf16 v[18:21], v[198:201], v[222:225], v[18:21]
	v_mfma_f32_16x16x32_bf16 v[6:9], v[190:193], v[230:233], v[6:9]
	v_mfma_f32_16x16x32_bf16 v[2:5], v[198:201], v[230:233], v[2:5]
	s_setprio 0
	s_barrier
	s_add_i32 s52, s52, 2
	s_add_u32 s26, s26, 0x100
	s_addc_u32 s27, s27, 0
	s_add_u32 s46, s46, 0x100
	s_addc_u32 s47, s47, 0
	s_cmp_gt_u32 s52, 13
	s_cbranch_scc0 .LBB0_354

.LBB0_437:
	ds_read_b128 v[160:163], v133
	ds_read_b128 v[164:167], v133 offset:1024
	ds_read_b128 v[168:171], v133 offset:2048
	ds_read_b128 v[172:175], v133 offset:3072
	ds_read_b128 v[178:181], v135
	ds_read_b128 v[182:185], v135 offset:1024
	ds_read_b128 v[186:189], v135 offset:2048
	ds_read_b128 v[190:193], v135 offset:3072
	s_cmp_lg_u32 s8, 0x160000
	s_cselect_b32 s13, s8, 0
	s_cselect_b32 s12, s9, 0
	s_add_u32 s2, s6, s13
	s_addc_u32 s3, s7, s12
	s_add_u32 s14, s0, s13
	s_addc_u32 s15, s1, s12
	s_add_u32 s12, s2, 0x8000
	s_addc_u32 s13, s3, 0
	v_lshl_add_u64 v[226:227], v[148:149], 0, s[8:9]
	s_mov_b32 m0, s27
	v_lshl_add_u64 v[226:227], v[226:227], 0, s[10:11]
	ds_read_b128 v[194:197], v137
	ds_read_b128 v[198:201], v137 offset:1024
	ds_read_b128 v[202:205], v137 offset:2048
	ds_read_b128 v[206:209], v137 offset:3072
	ds_read_b128 v[210:213], v137 offset:4096
	ds_read_b128 v[214:217], v137 offset:5120
	ds_read_b128 v[218:221], v137 offset:6144
	ds_read_b128 v[222:225], v137 offset:7168
	global_load_lds_dwordx4 v[226:227], off
	v_lshl_add_u64 v[226:227], v[150:151], 0, s[8:9]
	v_lshl_add_u64 v[226:227], v[226:227], 0, s[10:11]
	s_mov_b32 m0, s28
	s_nop 0
	global_load_lds_dwordx4 v[226:227], off
	s_waitcnt vmcnt(8)
	s_waitcnt lgkmcnt(0)
	s_barrier
	s_setprio 1
	v_mfma_f32_16x16x32_bf16 v[126:129], v[160:163], v[194:197], v[126:129]
	v_mfma_f32_16x16x32_bf16 v[122:125], v[168:171], v[194:197], v[122:125]
	v_mfma_f32_16x16x32_bf16 v[114:117], v[160:163], v[202:205], v[114:117]
	v_mfma_f32_16x16x32_bf16 v[106:109], v[168:171], v[202:205], v[106:109]
	v_mfma_f32_16x16x32_bf16 v[98:101], v[160:163], v[210:213], v[98:101]
	v_mfma_f32_16x16x32_bf16 v[90:93], v[168:171], v[210:213], v[90:93]
	v_mfma_f32_16x16x32_bf16 v[82:85], v[160:163], v[218:221], v[82:85]
	v_mfma_f32_16x16x32_bf16 v[74:77], v[168:171], v[218:221], v[74:77]
	v_mfma_f32_16x16x32_bf16 v[126:129], v[164:167], v[198:201], v[126:129]
	v_mfma_f32_16x16x32_bf16 v[122:125], v[172:175], v[198:201], v[122:125]
	v_mfma_f32_16x16x32_bf16 v[114:117], v[164:167], v[206:209], v[114:117]
	v_mfma_f32_16x16x32_bf16 v[106:109], v[172:175], v[206:209], v[106:109]
	v_mfma_f32_16x16x32_bf16 v[98:101], v[164:167], v[214:217], v[98:101]
	v_mfma_f32_16x16x32_bf16 v[90:93], v[172:175], v[214:217], v[90:93]
	v_mfma_f32_16x16x32_bf16 v[82:85], v[164:167], v[222:225], v[82:85]
	v_mfma_f32_16x16x32_bf16 v[74:77], v[172:175], v[222:225], v[74:77]
	v_mfma_f32_16x16x32_bf16 v[118:121], v[178:181], v[194:197], v[118:121]
	v_mfma_f32_16x16x32_bf16 v[110:113], v[186:189], v[194:197], v[110:113]
	v_mfma_f32_16x16x32_bf16 v[102:105], v[178:181], v[202:205], v[102:105]
	v_mfma_f32_16x16x32_bf16 v[94:97], v[186:189], v[202:205], v[94:97]
	v_mfma_f32_16x16x32_bf16 v[86:89], v[178:181], v[210:213], v[86:89]
	v_mfma_f32_16x16x32_bf16 v[78:81], v[186:189], v[210:213], v[78:81]
	v_mfma_f32_16x16x32_bf16 v[70:73], v[178:181], v[218:221], v[70:73]
	v_mfma_f32_16x16x32_bf16 v[66:69], v[186:189], v[218:221], v[66:69]
	v_mfma_f32_16x16x32_bf16 v[118:121], v[182:185], v[198:201], v[118:121]
	v_mfma_f32_16x16x32_bf16 v[110:113], v[190:193], v[198:201], v[110:113]
	v_mfma_f32_16x16x32_bf16 v[102:105], v[182:185], v[206:209], v[102:105]
	v_mfma_f32_16x16x32_bf16 v[94:97], v[190:193], v[206:209], v[94:97]
	v_mfma_f32_16x16x32_bf16 v[86:89], v[182:185], v[214:217], v[86:89]
	v_mfma_f32_16x16x32_bf16 v[78:81], v[190:193], v[214:217], v[78:81]
	v_mfma_f32_16x16x32_bf16 v[70:73], v[182:185], v[222:225], v[70:73]
	v_mfma_f32_16x16x32_bf16 v[66:69], v[190:193], v[222:225], v[66:69]
	s_setprio 0
	s_barrier
	s_mov_b32 m0, s29
	v_lshl_add_u64 v[226:227], s[14:15], 0, v[142:143]
	s_add_u32 s40, s14, 0x4000
	ds_read_b128 v[194:197], v137 offset:16384
	ds_read_b128 v[198:201], v137 offset:17408
	ds_read_b128 v[202:205], v137 offset:18432
	ds_read_b128 v[206:209], v137 offset:19456
	ds_read_b128 v[210:213], v137 offset:20480
	ds_read_b128 v[214:217], v137 offset:21504
	ds_read_b128 v[218:221], v137 offset:22528
	ds_read_b128 v[222:225], v137 offset:23552
	global_load_lds_dwordx4 v[226:227], off
	v_lshl_add_u64 v[226:227], s[14:15], 0, v[146:147]
	s_mov_b32 m0, s30
	s_addc_u32 s41, s15, 0
	global_load_lds_dwordx4 v[226:227], off
	v_lshl_add_u64 v[226:227], s[40:41], 0, v[142:143]
	s_mov_b32 m0, s31
	s_nop 0
	global_load_lds_dwordx4 v[226:227], off
	v_lshl_add_u64 v[226:227], s[40:41], 0, v[146:147]
	s_mov_b32 m0, s34
	s_nop 0
	global_load_lds_dwordx4 v[226:227], off
	v_lshl_add_u64 v[226:227], s[2:3], 0, v[140:141]
	s_mov_b32 m0, s19
	s_nop 0
	global_load_lds_dwordx4 v[226:227], off
	v_lshl_add_u64 v[226:227], s[2:3], 0, v[144:145]
	s_mov_b32 m0, s20
	s_nop 0
	global_load_lds_dwordx4 v[226:227], off
	s_waitcnt vmcnt(8)
	s_waitcnt lgkmcnt(0)
	s_barrier
	s_setprio 1
	v_mfma_f32_16x16x32_bf16 v[62:65], v[160:163], v[194:197], v[62:65]
	v_mfma_f32_16x16x32_bf16 v[58:61], v[168:171], v[194:197], v[58:61]
	v_mfma_f32_16x16x32_bf16 v[50:53], v[160:163], v[202:205], v[50:53]
	v_mfma_f32_16x16x32_bf16 v[42:45], v[168:171], v[202:205], v[42:45]
	v_mfma_f32_16x16x32_bf16 v[34:37], v[160:163], v[210:213], v[34:37]
	v_mfma_f32_16x16x32_bf16 v[26:29], v[168:171], v[210:213], v[26:29]
	v_mfma_f32_16x16x32_bf16 v[18:21], v[160:163], v[218:221], v[18:21]
	v_mfma_f32_16x16x32_bf16 v[10:13], v[168:171], v[218:221], v[10:13]
	v_mfma_f32_16x16x32_bf16 v[62:65], v[164:167], v[198:201], v[62:65]
	v_mfma_f32_16x16x32_bf16 v[58:61], v[172:175], v[198:201], v[58:61]
	v_mfma_f32_16x16x32_bf16 v[50:53], v[164:167], v[206:209], v[50:53]
	v_mfma_f32_16x16x32_bf16 v[42:45], v[172:175], v[206:209], v[42:45]
	v_mfma_f32_16x16x32_bf16 v[34:37], v[164:167], v[214:217], v[34:37]
	v_mfma_f32_16x16x32_bf16 v[26:29], v[172:175], v[214:217], v[26:29]
	v_mfma_f32_16x16x32_bf16 v[18:21], v[164:167], v[222:225], v[18:21]
	v_mfma_f32_16x16x32_bf16 v[10:13], v[172:175], v[222:225], v[10:13]
	v_mfma_f32_16x16x32_bf16 v[54:57], v[178:181], v[194:197], v[54:57]
	v_mfma_f32_16x16x32_bf16 v[46:49], v[186:189], v[194:197], v[46:49]
	v_mfma_f32_16x16x32_bf16 v[38:41], v[178:181], v[202:205], v[38:41]
	v_mfma_f32_16x16x32_bf16 v[30:33], v[186:189], v[202:205], v[30:33]
	v_mfma_f32_16x16x32_bf16 v[22:25], v[178:181], v[210:213], v[22:25]
	v_mfma_f32_16x16x32_bf16 v[14:17], v[186:189], v[210:213], v[14:17]
	v_mfma_f32_16x16x32_bf16 v[6:9], v[178:181], v[218:221], v[6:9]
	v_mfma_f32_16x16x32_bf16 v[2:5], v[186:189], v[218:221], v[2:5]
	v_mfma_f32_16x16x32_bf16 v[54:57], v[182:185], v[198:201], v[54:57]
	v_mfma_f32_16x16x32_bf16 v[46:49], v[190:193], v[198:201], v[46:49]
	v_mfma_f32_16x16x32_bf16 v[38:41], v[182:185], v[206:209], v[38:41]
	v_mfma_f32_16x16x32_bf16 v[30:33], v[190:193], v[206:209], v[30:33]
	v_mfma_f32_16x16x32_bf16 v[22:25], v[182:185], v[214:217], v[22:25]
	v_mfma_f32_16x16x32_bf16 v[14:17], v[190:193], v[214:217], v[14:17]
	v_mfma_f32_16x16x32_bf16 v[6:9], v[182:185], v[222:225], v[6:9]
	v_mfma_f32_16x16x32_bf16 v[2:5], v[190:193], v[222:225], v[2:5]
	s_setprio 0
	s_barrier
	ds_read_b128 v[160:163], v139
	ds_read_b128 v[164:167], v139 offset:1024
	ds_read_b128 v[168:171], v139 offset:2048
	ds_read_b128 v[172:175], v139 offset:3072
	ds_read_b128 v[178:181], v159
	ds_read_b128 v[182:185], v159 offset:1024
	ds_read_b128 v[186:189], v159 offset:2048
	ds_read_b128 v[190:193], v159 offset:3072
	s_add_u32 s2, s2, 0x4000
	s_addc_u32 s3, s3, 0
	s_mov_b32 m0, s21
	v_lshl_add_u64 v[226:227], s[2:3], 0, v[140:141]
	ds_read_b128 v[194:197], v137 offset:32768
	ds_read_b128 v[198:201], v137 offset:33792
	ds_read_b128 v[202:205], v137 offset:34816
	ds_read_b128 v[206:209], v137 offset:35840
	ds_read_b128 v[210:213], v137 offset:36864
	ds_read_b128 v[214:217], v137 offset:37888
	ds_read_b128 v[218:221], v137 offset:38912
	ds_read_b128 v[222:225], v137 offset:39936
	global_load_lds_dwordx4 v[226:227], off
	v_lshl_add_u64 v[226:227], s[2:3], 0, v[144:145]
	s_mov_b32 m0, s22
	s_nop 0
	global_load_lds_dwordx4 v[226:227], off
	s_waitcnt vmcnt(8)
	s_waitcnt lgkmcnt(0)
	s_barrier
	s_setprio 1
	v_mfma_f32_16x16x32_bf16 v[126:129], v[160:163], v[194:197], v[126:129]
	v_mfma_f32_16x16x32_bf16 v[122:125], v[168:171], v[194:197], v[122:125]
	v_mfma_f32_16x16x32_bf16 v[114:117], v[160:163], v[202:205], v[114:117]
	v_mfma_f32_16x16x32_bf16 v[106:109], v[168:171], v[202:205], v[106:109]
	v_mfma_f32_16x16x32_bf16 v[98:101], v[160:163], v[210:213], v[98:101]
	v_mfma_f32_16x16x32_bf16 v[90:93], v[168:171], v[210:213], v[90:93]
	v_mfma_f32_16x16x32_bf16 v[82:85], v[160:163], v[218:221], v[82:85]
	v_mfma_f32_16x16x32_bf16 v[74:77], v[168:171], v[218:221], v[74:77]
	v_mfma_f32_16x16x32_bf16 v[126:129], v[164:167], v[198:201], v[126:129]
	v_mfma_f32_16x16x32_bf16 v[122:125], v[172:175], v[198:201], v[122:125]
	v_mfma_f32_16x16x32_bf16 v[114:117], v[164:167], v[206:209], v[114:117]
	v_mfma_f32_16x16x32_bf16 v[106:109], v[172:175], v[206:209], v[106:109]
	v_mfma_f32_16x16x32_bf16 v[98:101], v[164:167], v[214:217], v[98:101]
	v_mfma_f32_16x16x32_bf16 v[90:93], v[172:175], v[214:217], v[90:93]
	v_mfma_f32_16x16x32_bf16 v[82:85], v[164:167], v[222:225], v[82:85]
	v_mfma_f32_16x16x32_bf16 v[74:77], v[172:175], v[222:225], v[74:77]
	v_mfma_f32_16x16x32_bf16 v[118:121], v[178:181], v[194:197], v[118:121]
	v_mfma_f32_16x16x32_bf16 v[110:113], v[186:189], v[194:197], v[110:113]
	v_mfma_f32_16x16x32_bf16 v[102:105], v[178:181], v[202:205], v[102:105]
	v_mfma_f32_16x16x32_bf16 v[94:97], v[186:189], v[202:205], v[94:97]
	v_mfma_f32_16x16x32_bf16 v[86:89], v[178:181], v[210:213], v[86:89]
	v_mfma_f32_16x16x32_bf16 v[78:81], v[186:189], v[210:213], v[78:81]
	v_mfma_f32_16x16x32_bf16 v[70:73], v[178:181], v[218:221], v[70:73]
	v_mfma_f32_16x16x32_bf16 v[66:69], v[186:189], v[218:221], v[66:69]
	v_mfma_f32_16x16x32_bf16 v[118:121], v[182:185], v[198:201], v[118:121]
	v_mfma_f32_16x16x32_bf16 v[110:113], v[190:193], v[198:201], v[110:113]
	v_mfma_f32_16x16x32_bf16 v[102:105], v[182:185], v[206:209], v[102:105]
	v_mfma_f32_16x16x32_bf16 v[94:97], v[190:193], v[206:209], v[94:97]
	v_mfma_f32_16x16x32_bf16 v[86:89], v[182:185], v[214:217], v[86:89]
	v_mfma_f32_16x16x32_bf16 v[78:81], v[190:193], v[214:217], v[78:81]
	v_mfma_f32_16x16x32_bf16 v[70:73], v[182:185], v[222:225], v[70:73]
	v_mfma_f32_16x16x32_bf16 v[66:69], v[190:193], v[222:225], v[66:69]
	s_setprio 0
	s_barrier
	s_add_u32 s2, s14, 0x8000
	s_addc_u32 s3, s15, 0
	s_mov_b32 m0, s35
	v_lshl_add_u64 v[226:227], s[2:3], 0, v[142:143]
	ds_read_b128 v[194:197], v137 offset:49152
	ds_read_b128 v[198:201], v137 offset:50176
	ds_read_b128 v[202:205], v137 offset:51200
	ds_read_b128 v[206:209], v137 offset:52224
	ds_read_b128 v[210:213], v137 offset:53248
	ds_read_b128 v[214:217], v137 offset:54272
	ds_read_b128 v[218:221], v137 offset:55296
	ds_read_b128 v[222:225], v137 offset:56320
	global_load_lds_dwordx4 v[226:227], off
	v_lshl_add_u64 v[226:227], s[2:3], 0, v[146:147]
	s_add_u32 s2, s14, 0xc000
	s_mov_b32 m0, s36
	s_addc_u32 s3, s15, 0
	global_load_lds_dwordx4 v[226:227], off
	v_lshl_add_u64 v[226:227], s[2:3], 0, v[142:143]
	s_mov_b32 m0, s37
	s_nop 0
	global_load_lds_dwordx4 v[226:227], off
	v_lshl_add_u64 v[226:227], s[2:3], 0, v[146:147]
	s_mov_b32 m0, s38
	s_nop 0
	global_load_lds_dwordx4 v[226:227], off
	v_lshl_add_u64 v[226:227], s[12:13], 0, v[140:141]
	s_mov_b32 m0, s24
	s_nop 0
	global_load_lds_dwordx4 v[226:227], off
	v_lshl_add_u64 v[226:227], s[12:13], 0, v[144:145]
	s_mov_b32 m0, s25
	s_nop 0
	global_load_lds_dwordx4 v[226:227], off
	s_waitcnt vmcnt(8)
	s_waitcnt lgkmcnt(0)
	s_barrier
	s_setprio 1
	v_mfma_f32_16x16x32_bf16 v[62:65], v[160:163], v[194:197], v[62:65]
	v_mfma_f32_16x16x32_bf16 v[58:61], v[168:171], v[194:197], v[58:61]
	v_mfma_f32_16x16x32_bf16 v[50:53], v[160:163], v[202:205], v[50:53]
	v_mfma_f32_16x16x32_bf16 v[42:45], v[168:171], v[202:205], v[42:45]
	v_mfma_f32_16x16x32_bf16 v[34:37], v[160:163], v[210:213], v[34:37]
	v_mfma_f32_16x16x32_bf16 v[26:29], v[168:171], v[210:213], v[26:29]
	v_mfma_f32_16x16x32_bf16 v[18:21], v[160:163], v[218:221], v[18:21]
	v_mfma_f32_16x16x32_bf16 v[10:13], v[168:171], v[218:221], v[10:13]
	v_mfma_f32_16x16x32_bf16 v[62:65], v[164:167], v[198:201], v[62:65]
	v_mfma_f32_16x16x32_bf16 v[58:61], v[172:175], v[198:201], v[58:61]
	v_mfma_f32_16x16x32_bf16 v[50:53], v[164:167], v[206:209], v[50:53]
	v_mfma_f32_16x16x32_bf16 v[42:45], v[172:175], v[206:209], v[42:45]
	v_mfma_f32_16x16x32_bf16 v[34:37], v[164:167], v[214:217], v[34:37]
	v_mfma_f32_16x16x32_bf16 v[26:29], v[172:175], v[214:217], v[26:29]
	v_mfma_f32_16x16x32_bf16 v[18:21], v[164:167], v[222:225], v[18:21]
	v_mfma_f32_16x16x32_bf16 v[10:13], v[172:175], v[222:225], v[10:13]
	v_mfma_f32_16x16x32_bf16 v[54:57], v[178:181], v[194:197], v[54:57]
	v_mfma_f32_16x16x32_bf16 v[46:49], v[186:189], v[194:197], v[46:49]
	v_mfma_f32_16x16x32_bf16 v[38:41], v[178:181], v[202:205], v[38:41]
	v_mfma_f32_16x16x32_bf16 v[30:33], v[186:189], v[202:205], v[30:33]
	v_mfma_f32_16x16x32_bf16 v[22:25], v[178:181], v[210:213], v[22:25]
	v_mfma_f32_16x16x32_bf16 v[14:17], v[186:189], v[210:213], v[14:17]
	v_mfma_f32_16x16x32_bf16 v[6:9], v[178:181], v[218:221], v[6:9]
	v_mfma_f32_16x16x32_bf16 v[2:5], v[186:189], v[218:221], v[2:5]
	v_mfma_f32_16x16x32_bf16 v[54:57], v[182:185], v[198:201], v[54:57]
	v_mfma_f32_16x16x32_bf16 v[46:49], v[190:193], v[198:201], v[46:49]
	v_mfma_f32_16x16x32_bf16 v[38:41], v[182:185], v[206:209], v[38:41]
	v_mfma_f32_16x16x32_bf16 v[30:33], v[190:193], v[206:209], v[30:33]
	v_mfma_f32_16x16x32_bf16 v[22:25], v[182:185], v[214:217], v[22:25]
	v_mfma_f32_16x16x32_bf16 v[14:17], v[190:193], v[214:217], v[14:17]
	v_mfma_f32_16x16x32_bf16 v[6:9], v[182:185], v[222:225], v[6:9]
	v_mfma_f32_16x16x32_bf16 v[2:5], v[190:193], v[222:225], v[2:5]
	s_setprio 0
	s_barrier
	s_add_i32 s26, s26, 2
	s_add_u32 s8, s8, 0x10000
	s_addc_u32 s9, s9, 0
	s_cmp_gt_u32 s26, 41
	s_cbranch_scc0 .LBB0_437
	s_cmpk_lt_u32 s16, 0x100
	s_cbranch_scc0 .LBB0_440
	s_barrier

.Lpk451_peel:
	ds_read_b128 v[152:155], v149
	ds_read_b128 v[156:159], v149 offset:1024
	ds_read_b128 v[160:163], v149 offset:2048
	ds_read_b128 v[164:167], v149 offset:3072
	ds_read_b128 v[168:171], v150
	ds_read_b128 v[172:175], v150 offset:1024
	ds_read_b128 v[178:181], v150 offset:2048
	ds_read_b128 v[182:185], v150 offset:3072
	s_add_u32 s2, s28, 0xfffc0080
	s_addc_u32 s3, s29, -1
	s_cmp_eq_u32 s52, 12
	s_cselect_b32 s3, s11, s3
	s_cselect_b32 s2, s13, s2
	s_cselect_b32 s31, s44, s47
	s_cselect_b32 s30, s45, s46
	v_lshl_add_u64 v[146:147], s[28:29], 0, v[140:141]
	s_add_i32 m0, s25, 0xc000
	ds_read_b128 v[186:189], v151
	ds_read_b128 v[190:193], v151 offset:1024
	ds_read_b128 v[194:197], v151 offset:2048
	ds_read_b128 v[198:201], v151 offset:3072
	ds_read_b128 v[202:205], v151 offset:4096
	ds_read_b128 v[206:209], v151 offset:5120
	ds_read_b128 v[210:213], v151 offset:6144
	ds_read_b128 v[214:217], v151 offset:7168
	global_load_lds_dwordx4 v[146:147], off
	v_lshl_add_u64 v[146:147], s[28:29], 0, v[142:143]
	s_add_i32 m0, s25, 0xe000
	s_nop 0
	global_load_lds_dwordx4 v[146:147], off
	s_waitcnt vmcnt(8)
	s_waitcnt lgkmcnt(0)
	s_barrier
	s_setprio 1
	v_mfma_f32_16x16x32_bf16 v[126:129], v[152:155], v[186:189], 0
	v_mfma_f32_16x16x32_bf16 v[122:125], v[160:163], v[186:189], 0
	v_mfma_f32_16x16x32_bf16 v[110:113], v[152:155], v[194:197], 0
	v_mfma_f32_16x16x32_bf16 v[106:109], v[160:163], v[194:197], 0
	v_mfma_f32_16x16x32_bf16 v[94:97], v[152:155], v[202:205], 0
	v_mfma_f32_16x16x32_bf16 v[90:93], v[160:163], v[202:205], 0
	v_mfma_f32_16x16x32_bf16 v[78:81], v[152:155], v[210:213], 0
	v_mfma_f32_16x16x32_bf16 v[74:77], v[160:163], v[210:213], 0
	v_mfma_f32_16x16x32_bf16 v[126:129], v[156:159], v[190:193], v[126:129]
	v_mfma_f32_16x16x32_bf16 v[122:125], v[164:167], v[190:193], v[122:125]
	v_mfma_f32_16x16x32_bf16 v[110:113], v[156:159], v[198:201], v[110:113]
	v_mfma_f32_16x16x32_bf16 v[106:109], v[164:167], v[198:201], v[106:109]
	v_mfma_f32_16x16x32_bf16 v[94:97], v[156:159], v[206:209], v[94:97]
	v_mfma_f32_16x16x32_bf16 v[90:93], v[164:167], v[206:209], v[90:93]
	v_mfma_f32_16x16x32_bf16 v[78:81], v[156:159], v[214:217], v[78:81]
	v_mfma_f32_16x16x32_bf16 v[74:77], v[164:167], v[214:217], v[74:77]
	v_mfma_f32_16x16x32_bf16 v[118:121], v[168:171], v[186:189], 0
	v_mfma_f32_16x16x32_bf16 v[114:117], v[178:181], v[186:189], 0
	v_mfma_f32_16x16x32_bf16 v[102:105], v[168:171], v[194:197], 0
	v_mfma_f32_16x16x32_bf16 v[98:101], v[178:181], v[194:197], 0
	v_mfma_f32_16x16x32_bf16 v[86:89], v[168:171], v[202:205], 0
	v_mfma_f32_16x16x32_bf16 v[82:85], v[178:181], v[202:205], 0
	v_mfma_f32_16x16x32_bf16 v[70:73], v[168:171], v[210:213], 0
	v_mfma_f32_16x16x32_bf16 v[66:69], v[178:181], v[210:213], 0
	v_mfma_f32_16x16x32_bf16 v[118:121], v[172:175], v[190:193], v[118:121]
	v_mfma_f32_16x16x32_bf16 v[114:117], v[182:185], v[190:193], v[114:117]
	v_mfma_f32_16x16x32_bf16 v[102:105], v[172:175], v[198:201], v[102:105]
	v_mfma_f32_16x16x32_bf16 v[98:101], v[182:185], v[198:201], v[98:101]
	v_mfma_f32_16x16x32_bf16 v[86:89], v[172:175], v[206:209], v[86:89]
	v_mfma_f32_16x16x32_bf16 v[82:85], v[182:185], v[206:209], v[82:85]
	v_mfma_f32_16x16x32_bf16 v[70:73], v[172:175], v[214:217], v[70:73]
	v_mfma_f32_16x16x32_bf16 v[66:69], v[182:185], v[214:217], v[66:69]
	s_setprio 0
	s_barrier
	s_add_i32 s53, s42, s34
	v_lshl_add_u64 v[146:147], s[30:31], 0, v[132:133]
	s_mov_b32 m0, s53
	ds_read_b128 v[186:189], v151 offset:16384
	ds_read_b128 v[190:193], v151 offset:17408
	ds_read_b128 v[194:197], v151 offset:18432
	ds_read_b128 v[198:201], v151 offset:19456
	ds_read_b128 v[202:205], v151 offset:20480
	ds_read_b128 v[206:209], v151 offset:21504
	ds_read_b128 v[210:213], v151 offset:22528
	ds_read_b128 v[214:217], v151 offset:23552
	global_load_lds_dwordx4 v[146:147], off
	s_add_i32 m0, s53, 0x2000
	s_add_u32 s54, s30, 0x40000
	v_lshl_add_u64 v[218:219], s[30:31], 0, v[136:137]
	s_addc_u32 s55, s31, 0
	s_add_i32 s53, s43, s34
	global_load_lds_dwordx4 v[218:219], off
	v_lshl_add_u64 v[220:221], s[54:55], 0, v[132:133]
	s_mov_b32 m0, s53
	v_lshl_add_u64 v[222:223], s[2:3], 0, v[134:135]
	global_load_lds_dwordx4 v[220:221], off
	v_lshl_add_u64 v[220:221], s[54:55], 0, v[136:137]
	s_add_i32 m0, s53, 0x2000
	s_nop 0
	global_load_lds_dwordx4 v[220:221], off
	v_lshl_add_u64 v[220:221], s[2:3], 0, v[130:131]
	s_mov_b32 m0, s25
	s_nop 0
	global_load_lds_dwordx4 v[220:221], off
	s_mov_b32 m0, s27
	s_nop 0
	global_load_lds_dwordx4 v[222:223], off
	s_waitcnt vmcnt(8)
	s_waitcnt lgkmcnt(0)
	s_barrier
	s_setprio 1
	v_mfma_f32_16x16x32_bf16 v[62:65], v[152:155], v[186:189], 0
	v_mfma_f32_16x16x32_bf16 v[58:61], v[160:163], v[186:189], 0
	v_mfma_f32_16x16x32_bf16 v[46:49], v[152:155], v[194:197], 0
	v_mfma_f32_16x16x32_bf16 v[42:45], v[160:163], v[194:197], 0
	v_mfma_f32_16x16x32_bf16 v[30:33], v[152:155], v[202:205], 0
	v_mfma_f32_16x16x32_bf16 v[26:29], v[160:163], v[202:205], 0
	v_mfma_f32_16x16x32_bf16 v[14:17], v[152:155], v[210:213], 0
	v_mfma_f32_16x16x32_bf16 v[10:13], v[160:163], v[210:213], 0
	v_mfma_f32_16x16x32_bf16 v[62:65], v[156:159], v[190:193], v[62:65]
	v_mfma_f32_16x16x32_bf16 v[58:61], v[164:167], v[190:193], v[58:61]
	v_mfma_f32_16x16x32_bf16 v[46:49], v[156:159], v[198:201], v[46:49]
	v_mfma_f32_16x16x32_bf16 v[42:45], v[164:167], v[198:201], v[42:45]
	v_mfma_f32_16x16x32_bf16 v[30:33], v[156:159], v[206:209], v[30:33]
	v_mfma_f32_16x16x32_bf16 v[26:29], v[164:167], v[206:209], v[26:29]
	v_mfma_f32_16x16x32_bf16 v[14:17], v[156:159], v[214:217], v[14:17]
	v_mfma_f32_16x16x32_bf16 v[10:13], v[164:167], v[214:217], v[10:13]
	v_mfma_f32_16x16x32_bf16 v[54:57], v[168:171], v[186:189], 0
	v_mfma_f32_16x16x32_bf16 v[50:53], v[178:181], v[186:189], 0
	v_mfma_f32_16x16x32_bf16 v[38:41], v[168:171], v[194:197], 0
	v_mfma_f32_16x16x32_bf16 v[34:37], v[178:181], v[194:197], 0
	v_mfma_f32_16x16x32_bf16 v[22:25], v[168:171], v[202:205], 0
	v_mfma_f32_16x16x32_bf16 v[18:21], v[178:181], v[202:205], 0
	v_mfma_f32_16x16x32_bf16 v[6:9], v[168:171], v[210:213], 0
	v_mfma_f32_16x16x32_bf16 v[2:5], v[178:181], v[210:213], 0
	v_mfma_f32_16x16x32_bf16 v[54:57], v[172:175], v[190:193], v[54:57]
	v_mfma_f32_16x16x32_bf16 v[50:53], v[182:185], v[190:193], v[50:53]
	v_mfma_f32_16x16x32_bf16 v[38:41], v[172:175], v[198:201], v[38:41]
	v_mfma_f32_16x16x32_bf16 v[34:37], v[182:185], v[198:201], v[34:37]
	v_mfma_f32_16x16x32_bf16 v[22:25], v[172:175], v[206:209], v[22:25]
	v_mfma_f32_16x16x32_bf16 v[18:21], v[182:185], v[206:209], v[18:21]
	v_mfma_f32_16x16x32_bf16 v[6:9], v[172:175], v[214:217], v[6:9]
	v_mfma_f32_16x16x32_bf16 v[2:5], v[182:185], v[214:217], v[2:5]
	s_setprio 0
	s_barrier
	s_add_i32 s53, 0, 0x18000
	s_add_i32 s54, 0, 0x1c000
	v_add_u32_e32 v164, s53, v148
	v_add_u32_e32 v176, s54, v148
	ds_read_b128 v[152:155], v164
	ds_read_b128 v[156:159], v164 offset:1024
	ds_read_b128 v[160:163], v164 offset:2048
	ds_read_b128 v[164:167], v164 offset:3072
	ds_read_b128 v[168:171], v176
	ds_read_b128 v[172:175], v176 offset:1024
	ds_read_b128 v[178:181], v176 offset:2048
	ds_read_b128 v[182:185], v176 offset:3072
	s_add_u32 s2, s2, 0x40000
	s_addc_u32 s3, s3, 0
	s_mov_b32 m0, s36
	v_lshl_add_u64 v[224:225], s[2:3], 0, v[130:131]
	ds_read_b128 v[186:189], v151 offset:32768
	ds_read_b128 v[190:193], v151 offset:33792
	ds_read_b128 v[194:197], v151 offset:34816
	ds_read_b128 v[198:201], v151 offset:35840
	ds_read_b128 v[202:205], v151 offset:36864
	ds_read_b128 v[206:209], v151 offset:37888
	ds_read_b128 v[210:213], v151 offset:38912
	ds_read_b128 v[214:217], v151 offset:39936
	global_load_lds_dwordx4 v[224:225], off
	v_lshl_add_u64 v[224:225], s[2:3], 0, v[134:135]
	s_mov_b32 m0, s37
	s_nop 0
	global_load_lds_dwordx4 v[224:225], off
	s_waitcnt vmcnt(8)
	s_waitcnt lgkmcnt(0)
	s_barrier
	s_setprio 1
	v_mfma_f32_16x16x32_bf16 v[126:129], v[152:155], v[186:189], v[126:129]
	v_mfma_f32_16x16x32_bf16 v[122:125], v[160:163], v[186:189], v[122:125]
	v_mfma_f32_16x16x32_bf16 v[110:113], v[152:155], v[194:197], v[110:113]
	v_mfma_f32_16x16x32_bf16 v[106:109], v[160:163], v[194:197], v[106:109]
	v_mfma_f32_16x16x32_bf16 v[94:97], v[152:155], v[202:205], v[94:97]
	v_mfma_f32_16x16x32_bf16 v[90:93], v[160:163], v[202:205], v[90:93]
	v_mfma_f32_16x16x32_bf16 v[78:81], v[152:155], v[210:213], v[78:81]
	v_mfma_f32_16x16x32_bf16 v[74:77], v[160:163], v[210:213], v[74:77]
	v_mfma_f32_16x16x32_bf16 v[126:129], v[156:159], v[190:193], v[126:129]
	v_mfma_f32_16x16x32_bf16 v[122:125], v[164:167], v[190:193], v[122:125]
	v_mfma_f32_16x16x32_bf16 v[110:113], v[156:159], v[198:201], v[110:113]
	v_mfma_f32_16x16x32_bf16 v[106:109], v[164:167], v[198:201], v[106:109]
	v_mfma_f32_16x16x32_bf16 v[94:97], v[156:159], v[206:209], v[94:97]
	v_mfma_f32_16x16x32_bf16 v[90:93], v[164:167], v[206:209], v[90:93]
	v_mfma_f32_16x16x32_bf16 v[78:81], v[156:159], v[214:217], v[78:81]
	v_mfma_f32_16x16x32_bf16 v[74:77], v[164:167], v[214:217], v[74:77]
	v_mfma_f32_16x16x32_bf16 v[118:121], v[168:171], v[186:189], v[118:121]
	v_mfma_f32_16x16x32_bf16 v[114:117], v[178:181], v[186:189], v[114:117]
	v_mfma_f32_16x16x32_bf16 v[102:105], v[168:171], v[194:197], v[102:105]
	v_mfma_f32_16x16x32_bf16 v[98:101], v[178:181], v[194:197], v[98:101]
	v_mfma_f32_16x16x32_bf16 v[86:89], v[168:171], v[202:205], v[86:89]
	v_mfma_f32_16x16x32_bf16 v[82:85], v[178:181], v[202:205], v[82:85]
	v_mfma_f32_16x16x32_bf16 v[70:73], v[168:171], v[210:213], v[70:73]
	v_mfma_f32_16x16x32_bf16 v[66:69], v[178:181], v[210:213], v[66:69]
	v_mfma_f32_16x16x32_bf16 v[118:121], v[172:175], v[190:193], v[118:121]
	v_mfma_f32_16x16x32_bf16 v[114:117], v[182:185], v[190:193], v[114:117]
	v_mfma_f32_16x16x32_bf16 v[102:105], v[172:175], v[198:201], v[102:105]
	v_mfma_f32_16x16x32_bf16 v[98:101], v[182:185], v[198:201], v[98:101]
	v_mfma_f32_16x16x32_bf16 v[86:89], v[172:175], v[206:209], v[86:89]
	v_mfma_f32_16x16x32_bf16 v[82:85], v[182:185], v[206:209], v[82:85]
	v_mfma_f32_16x16x32_bf16 v[70:73], v[172:175], v[214:217], v[70:73]
	v_mfma_f32_16x16x32_bf16 v[66:69], v[182:185], v[214:217], v[66:69]
	s_setprio 0
	s_barrier
	s_add_i32 s2, s53, s34
	v_lshl_add_u64 v[146:147], v[146:147], 0, s[6:7]
	s_mov_b32 m0, s2
	ds_read_b128 v[186:189], v151 offset:49152
	ds_read_b128 v[190:193], v151 offset:50176
	ds_read_b128 v[194:197], v151 offset:51200
	ds_read_b128 v[198:201], v151 offset:52224
	ds_read_b128 v[202:205], v151 offset:53248
	ds_read_b128 v[206:209], v151 offset:54272
	ds_read_b128 v[210:213], v151 offset:55296
	ds_read_b128 v[214:217], v151 offset:56320
	global_load_lds_dwordx4 v[146:147], off
	s_add_i32 m0, s2, 0x2000
	s_add_u32 s2, s30, 0x40080
	v_lshl_add_u64 v[146:147], v[218:219], 0, s[6:7]
	s_addc_u32 s3, s31, 0
	s_add_i32 s30, s54, s34
	global_load_lds_dwordx4 v[146:147], off
	v_lshl_add_u64 v[146:147], s[2:3], 0, v[132:133]
	s_mov_b32 m0, s30
	s_nop 0
	global_load_lds_dwordx4 v[146:147], off
	v_lshl_add_u64 v[146:147], s[2:3], 0, v[136:137]
	s_add_i32 m0, s30, 0x2000
	s_nop 0
	global_load_lds_dwordx4 v[146:147], off
	v_lshl_add_u64 v[146:147], v[220:221], 0, s[6:7]
	s_mov_b32 m0, s39
	s_nop 0
	global_load_lds_dwordx4 v[146:147], off
	v_lshl_add_u64 v[146:147], v[222:223], 0, s[6:7]
	s_mov_b32 m0, s40
	s_nop 0
	global_load_lds_dwordx4 v[146:147], off
	s_waitcnt vmcnt(8)
	s_waitcnt lgkmcnt(0)
	s_barrier
	s_setprio 1
	v_mfma_f32_16x16x32_bf16 v[62:65], v[152:155], v[186:189], v[62:65]
	v_mfma_f32_16x16x32_bf16 v[58:61], v[160:163], v[186:189], v[58:61]
	v_mfma_f32_16x16x32_bf16 v[46:49], v[152:155], v[194:197], v[46:49]
	v_mfma_f32_16x16x32_bf16 v[42:45], v[160:163], v[194:197], v[42:45]
	v_mfma_f32_16x16x32_bf16 v[30:33], v[152:155], v[202:205], v[30:33]
	v_mfma_f32_16x16x32_bf16 v[26:29], v[160:163], v[202:205], v[26:29]
	v_mfma_f32_16x16x32_bf16 v[14:17], v[152:155], v[210:213], v[14:17]
	v_mfma_f32_16x16x32_bf16 v[10:13], v[160:163], v[210:213], v[10:13]
	v_mfma_f32_16x16x32_bf16 v[62:65], v[156:159], v[190:193], v[62:65]
	v_mfma_f32_16x16x32_bf16 v[58:61], v[164:167], v[190:193], v[58:61]
	v_mfma_f32_16x16x32_bf16 v[46:49], v[156:159], v[198:201], v[46:49]
	v_mfma_f32_16x16x32_bf16 v[42:45], v[164:167], v[198:201], v[42:45]
	v_mfma_f32_16x16x32_bf16 v[30:33], v[156:159], v[206:209], v[30:33]
	v_mfma_f32_16x16x32_bf16 v[26:29], v[164:167], v[206:209], v[26:29]
	v_mfma_f32_16x16x32_bf16 v[14:17], v[156:159], v[214:217], v[14:17]
	v_mfma_f32_16x16x32_bf16 v[10:13], v[164:167], v[214:217], v[10:13]
	v_mfma_f32_16x16x32_bf16 v[54:57], v[168:171], v[186:189], v[54:57]
	v_mfma_f32_16x16x32_bf16 v[50:53], v[178:181], v[186:189], v[50:53]
	v_mfma_f32_16x16x32_bf16 v[38:41], v[168:171], v[194:197], v[38:41]
	v_mfma_f32_16x16x32_bf16 v[34:37], v[178:181], v[194:197], v[34:37]
	v_mfma_f32_16x16x32_bf16 v[22:25], v[168:171], v[202:205], v[22:25]
	v_mfma_f32_16x16x32_bf16 v[18:21], v[178:181], v[202:205], v[18:21]
	v_mfma_f32_16x16x32_bf16 v[6:9], v[168:171], v[210:213], v[6:9]
	v_mfma_f32_16x16x32_bf16 v[2:5], v[178:181], v[210:213], v[2:5]
	v_mfma_f32_16x16x32_bf16 v[54:57], v[172:175], v[190:193], v[54:57]
	v_mfma_f32_16x16x32_bf16 v[50:53], v[182:185], v[190:193], v[50:53]
	v_mfma_f32_16x16x32_bf16 v[38:41], v[172:175], v[198:201], v[38:41]
	v_mfma_f32_16x16x32_bf16 v[34:37], v[182:185], v[198:201], v[34:37]
	v_mfma_f32_16x16x32_bf16 v[22:25], v[172:175], v[206:209], v[22:25]
	v_mfma_f32_16x16x32_bf16 v[18:21], v[182:185], v[206:209], v[18:21]
	v_mfma_f32_16x16x32_bf16 v[6:9], v[172:175], v[214:217], v[6:9]
	v_mfma_f32_16x16x32_bf16 v[2:5], v[182:185], v[214:217], v[2:5]
	s_setprio 0
	s_barrier
	s_add_i32 s52, s52, 2
	s_add_u32 s28, s28, 0x100
	s_addc_u32 s29, s29, 0
	s_add_u32 s46, s46, 0x100
	s_addc_u32 s47, s47, 0
	s_cmp_gt_u32 s52, 13
	s_cbranch_scc0 .LBB0_451
	s_branch .Lpk451_exit
.LBB0_451:
	ds_read_b128 v[152:155], v149
	ds_read_b128 v[156:159], v149 offset:1024
	ds_read_b128 v[160:163], v149 offset:2048
	ds_read_b128 v[164:167], v149 offset:3072
	ds_read_b128 v[168:171], v150
	ds_read_b128 v[172:175], v150 offset:1024
	ds_read_b128 v[178:181], v150 offset:2048
	ds_read_b128 v[182:185], v150 offset:3072
	s_add_u32 s2, s28, 0xfffc0080
	s_addc_u32 s3, s29, -1
	s_cmp_eq_u32 s52, 12
	s_cselect_b32 s3, s11, s3
	s_cselect_b32 s2, s13, s2
	s_cselect_b32 s31, s44, s47
	s_cselect_b32 s30, s45, s46
	v_lshl_add_u64 v[146:147], s[28:29], 0, v[140:141]
	s_add_i32 m0, s25, 0xc000
	ds_read_b128 v[186:189], v151
	ds_read_b128 v[190:193], v151 offset:1024
	ds_read_b128 v[194:197], v151 offset:2048
	ds_read_b128 v[198:201], v151 offset:3072
	ds_read_b128 v[202:205], v151 offset:4096
	ds_read_b128 v[206:209], v151 offset:5120
	ds_read_b128 v[210:213], v151 offset:6144
	ds_read_b128 v[214:217], v151 offset:7168
	global_load_lds_dwordx4 v[146:147], off
	v_lshl_add_u64 v[146:147], s[28:29], 0, v[142:143]
	s_add_i32 m0, s25, 0xe000
	s_nop 0
	global_load_lds_dwordx4 v[146:147], off
	s_waitcnt vmcnt(8)
	s_waitcnt lgkmcnt(0)
	s_barrier
	s_setprio 1
	v_mfma_f32_16x16x32_bf16 v[126:129], v[152:155], v[186:189], v[126:129]
	v_mfma_f32_16x16x32_bf16 v[122:125], v[160:163], v[186:189], v[122:125]
	v_mfma_f32_16x16x32_bf16 v[110:113], v[152:155], v[194:197], v[110:113]
	v_mfma_f32_16x16x32_bf16 v[106:109], v[160:163], v[194:197], v[106:109]
	v_mfma_f32_16x16x32_bf16 v[94:97], v[152:155], v[202:205], v[94:97]
	v_mfma_f32_16x16x32_bf16 v[90:93], v[160:163], v[202:205], v[90:93]
	v_mfma_f32_16x16x32_bf16 v[78:81], v[152:155], v[210:213], v[78:81]
	v_mfma_f32_16x16x32_bf16 v[74:77], v[160:163], v[210:213], v[74:77]
	v_mfma_f32_16x16x32_bf16 v[126:129], v[156:159], v[190:193], v[126:129]
	v_mfma_f32_16x16x32_bf16 v[122:125], v[164:167], v[190:193], v[122:125]
	v_mfma_f32_16x16x32_bf16 v[110:113], v[156:159], v[198:201], v[110:113]
	v_mfma_f32_16x16x32_bf16 v[106:109], v[164:167], v[198:201], v[106:109]
	v_mfma_f32_16x16x32_bf16 v[94:97], v[156:159], v[206:209], v[94:97]
	v_mfma_f32_16x16x32_bf16 v[90:93], v[164:167], v[206:209], v[90:93]
	v_mfma_f32_16x16x32_bf16 v[78:81], v[156:159], v[214:217], v[78:81]
	v_mfma_f32_16x16x32_bf16 v[74:77], v[164:167], v[214:217], v[74:77]
	v_mfma_f32_16x16x32_bf16 v[118:121], v[168:171], v[186:189], v[118:121]
	v_mfma_f32_16x16x32_bf16 v[114:117], v[178:181], v[186:189], v[114:117]
	v_mfma_f32_16x16x32_bf16 v[102:105], v[168:171], v[194:197], v[102:105]
	v_mfma_f32_16x16x32_bf16 v[98:101], v[178:181], v[194:197], v[98:101]
	v_mfma_f32_16x16x32_bf16 v[86:89], v[168:171], v[202:205], v[86:89]
	v_mfma_f32_16x16x32_bf16 v[82:85], v[178:181], v[202:205], v[82:85]
	v_mfma_f32_16x16x32_bf16 v[70:73], v[168:171], v[210:213], v[70:73]
	v_mfma_f32_16x16x32_bf16 v[66:69], v[178:181], v[210:213], v[66:69]
	v_mfma_f32_16x16x32_bf16 v[118:121], v[172:175], v[190:193], v[118:121]
	v_mfma_f32_16x16x32_bf16 v[114:117], v[182:185], v[190:193], v[114:117]
	v_mfma_f32_16x16x32_bf16 v[102:105], v[172:175], v[198:201], v[102:105]
	v_mfma_f32_16x16x32_bf16 v[98:101], v[182:185], v[198:201], v[98:101]
	v_mfma_f32_16x16x32_bf16 v[86:89], v[172:175], v[206:209], v[86:89]
	v_mfma_f32_16x16x32_bf16 v[82:85], v[182:185], v[206:209], v[82:85]
	v_mfma_f32_16x16x32_bf16 v[70:73], v[172:175], v[214:217], v[70:73]
	v_mfma_f32_16x16x32_bf16 v[66:69], v[182:185], v[214:217], v[66:69]
	s_setprio 0
	s_barrier
	s_add_i32 s53, s42, s34
	v_lshl_add_u64 v[146:147], s[30:31], 0, v[132:133]
	s_mov_b32 m0, s53
	ds_read_b128 v[186:189], v151 offset:16384
	ds_read_b128 v[190:193], v151 offset:17408
	ds_read_b128 v[194:197], v151 offset:18432
	ds_read_b128 v[198:201], v151 offset:19456
	ds_read_b128 v[202:205], v151 offset:20480
	ds_read_b128 v[206:209], v151 offset:21504
	ds_read_b128 v[210:213], v151 offset:22528
	ds_read_b128 v[214:217], v151 offset:23552
	global_load_lds_dwordx4 v[146:147], off
	s_add_i32 m0, s53, 0x2000
	s_add_u32 s54, s30, 0x40000
	v_lshl_add_u64 v[218:219], s[30:31], 0, v[136:137]
	s_addc_u32 s55, s31, 0
	s_add_i32 s53, s43, s34
	global_load_lds_dwordx4 v[218:219], off
	v_lshl_add_u64 v[220:221], s[54:55], 0, v[132:133]
	s_mov_b32 m0, s53
	v_lshl_add_u64 v[222:223], s[2:3], 0, v[134:135]
	global_load_lds_dwordx4 v[220:221], off
	v_lshl_add_u64 v[220:221], s[54:55], 0, v[136:137]
	s_add_i32 m0, s53, 0x2000
	s_nop 0
	global_load_lds_dwordx4 v[220:221], off
	v_lshl_add_u64 v[220:221], s[2:3], 0, v[130:131]
	s_mov_b32 m0, s25
	s_nop 0
	global_load_lds_dwordx4 v[220:221], off
	s_mov_b32 m0, s27
	s_nop 0
	global_load_lds_dwordx4 v[222:223], off
	s_waitcnt vmcnt(8)
	s_waitcnt lgkmcnt(0)
	s_barrier
	s_setprio 1
	v_mfma_f32_16x16x32_bf16 v[62:65], v[152:155], v[186:189], v[62:65]
	v_mfma_f32_16x16x32_bf16 v[58:61], v[160:163], v[186:189], v[58:61]
	v_mfma_f32_16x16x32_bf16 v[46:49], v[152:155], v[194:197], v[46:49]
	v_mfma_f32_16x16x32_bf16 v[42:45], v[160:163], v[194:197], v[42:45]
	v_mfma_f32_16x16x32_bf16 v[30:33], v[152:155], v[202:205], v[30:33]
	v_mfma_f32_16x16x32_bf16 v[26:29], v[160:163], v[202:205], v[26:29]
	v_mfma_f32_16x16x32_bf16 v[14:17], v[152:155], v[210:213], v[14:17]
	v_mfma_f32_16x16x32_bf16 v[10:13], v[160:163], v[210:213], v[10:13]
	v_mfma_f32_16x16x32_bf16 v[62:65], v[156:159], v[190:193], v[62:65]
	v_mfma_f32_16x16x32_bf16 v[58:61], v[164:167], v[190:193], v[58:61]
	v_mfma_f32_16x16x32_bf16 v[46:49], v[156:159], v[198:201], v[46:49]
	v_mfma_f32_16x16x32_bf16 v[42:45], v[164:167], v[198:201], v[42:45]
	v_mfma_f32_16x16x32_bf16 v[30:33], v[156:159], v[206:209], v[30:33]
	v_mfma_f32_16x16x32_bf16 v[26:29], v[164:167], v[206:209], v[26:29]
	v_mfma_f32_16x16x32_bf16 v[14:17], v[156:159], v[214:217], v[14:17]
	v_mfma_f32_16x16x32_bf16 v[10:13], v[164:167], v[214:217], v[10:13]
	v_mfma_f32_16x16x32_bf16 v[54:57], v[168:171], v[186:189], v[54:57]
	v_mfma_f32_16x16x32_bf16 v[50:53], v[178:181], v[186:189], v[50:53]
	v_mfma_f32_16x16x32_bf16 v[38:41], v[168:171], v[194:197], v[38:41]
	v_mfma_f32_16x16x32_bf16 v[34:37], v[178:181], v[194:197], v[34:37]
	v_mfma_f32_16x16x32_bf16 v[22:25], v[168:171], v[202:205], v[22:25]
	v_mfma_f32_16x16x32_bf16 v[18:21], v[178:181], v[202:205], v[18:21]
	v_mfma_f32_16x16x32_bf16 v[6:9], v[168:171], v[210:213], v[6:9]
	v_mfma_f32_16x16x32_bf16 v[2:5], v[178:181], v[210:213], v[2:5]
	v_mfma_f32_16x16x32_bf16 v[54:57], v[172:175], v[190:193], v[54:57]
	v_mfma_f32_16x16x32_bf16 v[50:53], v[182:185], v[190:193], v[50:53]
	v_mfma_f32_16x16x32_bf16 v[38:41], v[172:175], v[198:201], v[38:41]
	v_mfma_f32_16x16x32_bf16 v[34:37], v[182:185], v[198:201], v[34:37]
	v_mfma_f32_16x16x32_bf16 v[22:25], v[172:175], v[206:209], v[22:25]
	v_mfma_f32_16x16x32_bf16 v[18:21], v[182:185], v[206:209], v[18:21]
	v_mfma_f32_16x16x32_bf16 v[6:9], v[172:175], v[214:217], v[6:9]
	v_mfma_f32_16x16x32_bf16 v[2:5], v[182:185], v[214:217], v[2:5]
	s_setprio 0
	s_barrier
	s_add_i32 s53, 0, 0x18000
	s_add_i32 s54, 0, 0x1c000
	v_add_u32_e32 v164, s53, v148
	v_add_u32_e32 v176, s54, v148
	ds_read_b128 v[152:155], v164
	ds_read_b128 v[156:159], v164 offset:1024
	ds_read_b128 v[160:163], v164 offset:2048
	ds_read_b128 v[164:167], v164 offset:3072
	ds_read_b128 v[168:171], v176
	ds_read_b128 v[172:175], v176 offset:1024
	ds_read_b128 v[178:181], v176 offset:2048
	ds_read_b128 v[182:185], v176 offset:3072
	s_add_u32 s2, s2, 0x40000
	s_addc_u32 s3, s3, 0
	s_mov_b32 m0, s36
	v_lshl_add_u64 v[224:225], s[2:3], 0, v[130:131]
	ds_read_b128 v[186:189], v151 offset:32768
	ds_read_b128 v[190:193], v151 offset:33792
	ds_read_b128 v[194:197], v151 offset:34816
	ds_read_b128 v[198:201], v151 offset:35840
	ds_read_b128 v[202:205], v151 offset:36864
	ds_read_b128 v[206:209], v151 offset:37888
	ds_read_b128 v[210:213], v151 offset:38912
	ds_read_b128 v[214:217], v151 offset:39936
	global_load_lds_dwordx4 v[224:225], off
	v_lshl_add_u64 v[224:225], s[2:3], 0, v[134:135]
	s_mov_b32 m0, s37
	s_nop 0
	global_load_lds_dwordx4 v[224:225], off
	s_waitcnt vmcnt(8)
	s_waitcnt lgkmcnt(0)
	s_barrier
	s_setprio 1
	v_mfma_f32_16x16x32_bf16 v[126:129], v[152:155], v[186:189], v[126:129]
	v_mfma_f32_16x16x32_bf16 v[122:125], v[160:163], v[186:189], v[122:125]
	v_mfma_f32_16x16x32_bf16 v[110:113], v[152:155], v[194:197], v[110:113]
	v_mfma_f32_16x16x32_bf16 v[106:109], v[160:163], v[194:197], v[106:109]
	v_mfma_f32_16x16x32_bf16 v[94:97], v[152:155], v[202:205], v[94:97]
	v_mfma_f32_16x16x32_bf16 v[90:93], v[160:163], v[202:205], v[90:93]
	v_mfma_f32_16x16x32_bf16 v[78:81], v[152:155], v[210:213], v[78:81]
	v_mfma_f32_16x16x32_bf16 v[74:77], v[160:163], v[210:213], v[74:77]
	v_mfma_f32_16x16x32_bf16 v[126:129], v[156:159], v[190:193], v[126:129]
	v_mfma_f32_16x16x32_bf16 v[122:125], v[164:167], v[190:193], v[122:125]
	v_mfma_f32_16x16x32_bf16 v[110:113], v[156:159], v[198:201], v[110:113]
	v_mfma_f32_16x16x32_bf16 v[106:109], v[164:167], v[198:201], v[106:109]
	v_mfma_f32_16x16x32_bf16 v[94:97], v[156:159], v[206:209], v[94:97]
	v_mfma_f32_16x16x32_bf16 v[90:93], v[164:167], v[206:209], v[90:93]
	v_mfma_f32_16x16x32_bf16 v[78:81], v[156:159], v[214:217], v[78:81]
	v_mfma_f32_16x16x32_bf16 v[74:77], v[164:167], v[214:217], v[74:77]
	v_mfma_f32_16x16x32_bf16 v[118:121], v[168:171], v[186:189], v[118:121]
	v_mfma_f32_16x16x32_bf16 v[114:117], v[178:181], v[186:189], v[114:117]
	v_mfma_f32_16x16x32_bf16 v[102:105], v[168:171], v[194:197], v[102:105]
	v_mfma_f32_16x16x32_bf16 v[98:101], v[178:181], v[194:197], v[98:101]
	v_mfma_f32_16x16x32_bf16 v[86:89], v[168:171], v[202:205], v[86:89]
	v_mfma_f32_16x16x32_bf16 v[82:85], v[178:181], v[202:205], v[82:85]
	v_mfma_f32_16x16x32_bf16 v[70:73], v[168:171], v[210:213], v[70:73]
	v_mfma_f32_16x16x32_bf16 v[66:69], v[178:181], v[210:213], v[66:69]
	v_mfma_f32_16x16x32_bf16 v[118:121], v[172:175], v[190:193], v[118:121]
	v_mfma_f32_16x16x32_bf16 v[114:117], v[182:185], v[190:193], v[114:117]
	v_mfma_f32_16x16x32_bf16 v[102:105], v[172:175], v[198:201], v[102:105]
	v_mfma_f32_16x16x32_bf16 v[98:101], v[182:185], v[198:201], v[98:101]
	v_mfma_f32_16x16x32_bf16 v[86:89], v[172:175], v[206:209], v[86:89]
	v_mfma_f32_16x16x32_bf16 v[82:85], v[182:185], v[206:209], v[82:85]
	v_mfma_f32_16x16x32_bf16 v[70:73], v[172:175], v[214:217], v[70:73]
	v_mfma_f32_16x16x32_bf16 v[66:69], v[182:185], v[214:217], v[66:69]
	s_setprio 0
	s_barrier
	s_add_i32 s2, s53, s34
	v_lshl_add_u64 v[146:147], v[146:147], 0, s[6:7]
	s_mov_b32 m0, s2
	ds_read_b128 v[186:189], v151 offset:49152
	ds_read_b128 v[190:193], v151 offset:50176
	ds_read_b128 v[194:197], v151 offset:51200
	ds_read_b128 v[198:201], v151 offset:52224
	ds_read_b128 v[202:205], v151 offset:53248
	ds_read_b128 v[206:209], v151 offset:54272
	ds_read_b128 v[210:213], v151 offset:55296
	ds_read_b128 v[214:217], v151 offset:56320
	global_load_lds_dwordx4 v[146:147], off
	s_add_i32 m0, s2, 0x2000
	s_add_u32 s2, s30, 0x40080
	v_lshl_add_u64 v[146:147], v[218:219], 0, s[6:7]
	s_addc_u32 s3, s31, 0
	s_add_i32 s30, s54, s34
	global_load_lds_dwordx4 v[146:147], off
	v_lshl_add_u64 v[146:147], s[2:3], 0, v[132:133]
	s_mov_b32 m0, s30
	s_nop 0
	global_load_lds_dwordx4 v[146:147], off
	v_lshl_add_u64 v[146:147], s[2:3], 0, v[136:137]
	s_add_i32 m0, s30, 0x2000
	s_nop 0
	global_load_lds_dwordx4 v[146:147], off
	v_lshl_add_u64 v[146:147], v[220:221], 0, s[6:7]
	s_mov_b32 m0, s39
	s_nop 0
	global_load_lds_dwordx4 v[146:147], off
	v_lshl_add_u64 v[146:147], v[222:223], 0, s[6:7]
	s_mov_b32 m0, s40
	s_nop 0
	global_load_lds_dwordx4 v[146:147], off
	s_waitcnt vmcnt(8)
	s_waitcnt lgkmcnt(0)
	s_barrier
	s_setprio 1
	v_mfma_f32_16x16x32_bf16 v[62:65], v[152:155], v[186:189], v[62:65]
	v_mfma_f32_16x16x32_bf16 v[58:61], v[160:163], v[186:189], v[58:61]
	v_mfma_f32_16x16x32_bf16 v[46:49], v[152:155], v[194:197], v[46:49]
	v_mfma_f32_16x16x32_bf16 v[42:45], v[160:163], v[194:197], v[42:45]
	v_mfma_f32_16x16x32_bf16 v[30:33], v[152:155], v[202:205], v[30:33]
	v_mfma_f32_16x16x32_bf16 v[26:29], v[160:163], v[202:205], v[26:29]
	v_mfma_f32_16x16x32_bf16 v[14:17], v[152:155], v[210:213], v[14:17]
	v_mfma_f32_16x16x32_bf16 v[10:13], v[160:163], v[210:213], v[10:13]
	v_mfma_f32_16x16x32_bf16 v[62:65], v[156:159], v[190:193], v[62:65]
	v_mfma_f32_16x16x32_bf16 v[58:61], v[164:167], v[190:193], v[58:61]
	v_mfma_f32_16x16x32_bf16 v[46:49], v[156:159], v[198:201], v[46:49]
	v_mfma_f32_16x16x32_bf16 v[42:45], v[164:167], v[198:201], v[42:45]
	v_mfma_f32_16x16x32_bf16 v[30:33], v[156:159], v[206:209], v[30:33]
	v_mfma_f32_16x16x32_bf16 v[26:29], v[164:167], v[206:209], v[26:29]
	v_mfma_f32_16x16x32_bf16 v[14:17], v[156:159], v[214:217], v[14:17]
	v_mfma_f32_16x16x32_bf16 v[10:13], v[164:167], v[214:217], v[10:13]
	v_mfma_f32_16x16x32_bf16 v[54:57], v[168:171], v[186:189], v[54:57]
	v_mfma_f32_16x16x32_bf16 v[50:53], v[178:181], v[186:189], v[50:53]
	v_mfma_f32_16x16x32_bf16 v[38:41], v[168:171], v[194:197], v[38:41]
	v_mfma_f32_16x16x32_bf16 v[34:37], v[178:181], v[194:197], v[34:37]
	v_mfma_f32_16x16x32_bf16 v[22:25], v[168:171], v[202:205], v[22:25]
	v_mfma_f32_16x16x32_bf16 v[18:21], v[178:181], v[202:205], v[18:21]
	v_mfma_f32_16x16x32_bf16 v[6:9], v[168:171], v[210:213], v[6:9]
	v_mfma_f32_16x16x32_bf16 v[2:5], v[178:181], v[210:213], v[2:5]
	v_mfma_f32_16x16x32_bf16 v[54:57], v[172:175], v[190:193], v[54:57]
	v_mfma_f32_16x16x32_bf16 v[50:53], v[182:185], v[190:193], v[50:53]
	v_mfma_f32_16x16x32_bf16 v[38:41], v[172:175], v[198:201], v[38:41]
	v_mfma_f32_16x16x32_bf16 v[34:37], v[182:185], v[198:201], v[34:37]
	v_mfma_f32_16x16x32_bf16 v[22:25], v[172:175], v[206:209], v[22:25]
	v_mfma_f32_16x16x32_bf16 v[18:21], v[182:185], v[206:209], v[18:21]
	v_mfma_f32_16x16x32_bf16 v[6:9], v[172:175], v[214:217], v[6:9]
	v_mfma_f32_16x16x32_bf16 v[2:5], v[182:185], v[214:217], v[2:5]
	s_setprio 0
	s_barrier
	s_add_i32 s52, s52, 2
	s_add_u32 s28, s28, 0x100
	s_addc_u32 s29, s29, 0
	s_add_u32 s46, s46, 0x100
	s_addc_u32 s47, s47, 0
	s_cmp_gt_u32 s52, 13
	s_cbranch_scc0 .LBB0_451

.Lpk495_peel:
	ds_read_b128 v[152:155], v149
	ds_read_b128 v[156:159], v149 offset:1024
	ds_read_b128 v[160:163], v149 offset:2048
	ds_read_b128 v[164:167], v149 offset:3072
	ds_read_b128 v[168:171], v150
	ds_read_b128 v[172:175], v150 offset:1024
	ds_read_b128 v[178:181], v150 offset:2048
	ds_read_b128 v[182:185], v150 offset:3072
	s_add_u32 s2, s18, 0x4000
	s_addc_u32 s3, s19, 0
	s_cmp_eq_u32 s50, 40
	s_cselect_b32 s2, s45, s2
	s_cselect_b32 s3, s44, s3
	s_cselect_b32 s23, s46, s49
	s_cselect_b32 s22, s47, s48
	s_add_u32 s20, s2, 0x8000
	s_addc_u32 s21, s3, 0
	v_lshl_add_u64 v[144:145], s[18:19], 0, v[138:139]
	s_add_i32 m0, s29, 0xc000
	ds_read_b128 v[186:189], v151
	ds_read_b128 v[190:193], v151 offset:1024
	ds_read_b128 v[194:197], v151 offset:2048
	ds_read_b128 v[198:201], v151 offset:3072
	ds_read_b128 v[202:205], v151 offset:4096
	ds_read_b128 v[206:209], v151 offset:5120
	ds_read_b128 v[210:213], v151 offset:6144
	ds_read_b128 v[214:217], v151 offset:7168
	global_load_lds_dwordx4 v[144:145], off
	v_lshl_add_u64 v[144:145], s[18:19], 0, v[140:141]
	s_add_i32 m0, s29, 0xe000
	s_nop 0
	global_load_lds_dwordx4 v[144:145], off
	s_waitcnt vmcnt(8)
	s_waitcnt lgkmcnt(0)
	s_barrier
	s_setprio 1
	v_mfma_f32_16x16x32_bf16 v[126:129], v[152:155], v[186:189], 0
	v_mfma_f32_16x16x32_bf16 v[122:125], v[160:163], v[186:189], 0
	v_mfma_f32_16x16x32_bf16 v[114:117], v[152:155], v[194:197], 0
	v_mfma_f32_16x16x32_bf16 v[106:109], v[160:163], v[194:197], 0
	v_mfma_f32_16x16x32_bf16 v[98:101], v[152:155], v[202:205], 0
	v_mfma_f32_16x16x32_bf16 v[90:93], v[160:163], v[202:205], 0
	v_mfma_f32_16x16x32_bf16 v[82:85], v[152:155], v[210:213], 0
	v_mfma_f32_16x16x32_bf16 v[74:77], v[160:163], v[210:213], 0
	v_mfma_f32_16x16x32_bf16 v[126:129], v[156:159], v[190:193], v[126:129]
	v_mfma_f32_16x16x32_bf16 v[122:125], v[164:167], v[190:193], v[122:125]
	v_mfma_f32_16x16x32_bf16 v[114:117], v[156:159], v[198:201], v[114:117]
	v_mfma_f32_16x16x32_bf16 v[106:109], v[164:167], v[198:201], v[106:109]
	v_mfma_f32_16x16x32_bf16 v[98:101], v[156:159], v[206:209], v[98:101]
	v_mfma_f32_16x16x32_bf16 v[90:93], v[164:167], v[206:209], v[90:93]
	v_mfma_f32_16x16x32_bf16 v[82:85], v[156:159], v[214:217], v[82:85]
	v_mfma_f32_16x16x32_bf16 v[74:77], v[164:167], v[214:217], v[74:77]
	v_mfma_f32_16x16x32_bf16 v[118:121], v[168:171], v[186:189], 0
	v_mfma_f32_16x16x32_bf16 v[110:113], v[178:181], v[186:189], 0
	v_mfma_f32_16x16x32_bf16 v[102:105], v[168:171], v[194:197], 0
	v_mfma_f32_16x16x32_bf16 v[94:97], v[178:181], v[194:197], 0
	v_mfma_f32_16x16x32_bf16 v[86:89], v[168:171], v[202:205], 0
	v_mfma_f32_16x16x32_bf16 v[78:81], v[178:181], v[202:205], 0
	v_mfma_f32_16x16x32_bf16 v[70:73], v[168:171], v[210:213], 0
	v_mfma_f32_16x16x32_bf16 v[66:69], v[178:181], v[210:213], 0
	v_mfma_f32_16x16x32_bf16 v[118:121], v[172:175], v[190:193], v[118:121]
	v_mfma_f32_16x16x32_bf16 v[110:113], v[182:185], v[190:193], v[110:113]
	v_mfma_f32_16x16x32_bf16 v[102:105], v[172:175], v[198:201], v[102:105]
	v_mfma_f32_16x16x32_bf16 v[94:97], v[182:185], v[198:201], v[94:97]
	v_mfma_f32_16x16x32_bf16 v[86:89], v[172:175], v[206:209], v[86:89]
	v_mfma_f32_16x16x32_bf16 v[78:81], v[182:185], v[206:209], v[78:81]
	v_mfma_f32_16x16x32_bf16 v[70:73], v[172:175], v[214:217], v[70:73]
	v_mfma_f32_16x16x32_bf16 v[66:69], v[182:185], v[214:217], v[66:69]
	s_setprio 0
	s_barrier
	s_add_i32 s51, s38, s28
	v_lshl_add_u64 v[144:145], s[22:23], 0, v[132:133]
	s_mov_b32 m0, s51
	ds_read_b128 v[186:189], v151 offset:16384
	ds_read_b128 v[190:193], v151 offset:17408
	ds_read_b128 v[194:197], v151 offset:18432
	ds_read_b128 v[198:201], v151 offset:19456
	ds_read_b128 v[202:205], v151 offset:20480
	ds_read_b128 v[206:209], v151 offset:21504
	ds_read_b128 v[210:213], v151 offset:22528
	ds_read_b128 v[214:217], v151 offset:23552
	global_load_lds_dwordx4 v[144:145], off
	s_add_i32 m0, s51, 0x2000
	s_add_u32 s52, s22, 0x4000
	v_lshl_add_u64 v[144:145], s[22:23], 0, v[136:137]
	s_addc_u32 s53, s23, 0
	s_add_i32 s51, s39, s28
	global_load_lds_dwordx4 v[144:145], off
	v_lshl_add_u64 v[144:145], s[52:53], 0, v[132:133]
	s_mov_b32 m0, s51
	s_nop 0
	global_load_lds_dwordx4 v[144:145], off
	v_lshl_add_u64 v[144:145], s[52:53], 0, v[136:137]
	s_add_i32 m0, s51, 0x2000
	s_nop 0
	global_load_lds_dwordx4 v[144:145], off
	v_lshl_add_u64 v[144:145], s[2:3], 0, v[130:131]
	s_mov_b32 m0, s29
	s_nop 0
	global_load_lds_dwordx4 v[144:145], off
	v_lshl_add_u64 v[144:145], s[2:3], 0, v[134:135]
	s_mov_b32 m0, s30
	s_nop 0
	global_load_lds_dwordx4 v[144:145], off
	s_waitcnt vmcnt(8)
	s_waitcnt lgkmcnt(0)
	s_barrier
	s_setprio 1
	v_mfma_f32_16x16x32_bf16 v[62:65], v[152:155], v[186:189], 0
	v_mfma_f32_16x16x32_bf16 v[58:61], v[160:163], v[186:189], 0
	v_mfma_f32_16x16x32_bf16 v[50:53], v[152:155], v[194:197], 0
	v_mfma_f32_16x16x32_bf16 v[42:45], v[160:163], v[194:197], 0
	v_mfma_f32_16x16x32_bf16 v[34:37], v[152:155], v[202:205], 0
	v_mfma_f32_16x16x32_bf16 v[26:29], v[160:163], v[202:205], 0
	v_mfma_f32_16x16x32_bf16 v[18:21], v[152:155], v[210:213], 0
	v_mfma_f32_16x16x32_bf16 v[10:13], v[160:163], v[210:213], 0
	v_mfma_f32_16x16x32_bf16 v[62:65], v[156:159], v[190:193], v[62:65]
	v_mfma_f32_16x16x32_bf16 v[58:61], v[164:167], v[190:193], v[58:61]
	v_mfma_f32_16x16x32_bf16 v[50:53], v[156:159], v[198:201], v[50:53]
	v_mfma_f32_16x16x32_bf16 v[42:45], v[164:167], v[198:201], v[42:45]
	v_mfma_f32_16x16x32_bf16 v[34:37], v[156:159], v[206:209], v[34:37]
	v_mfma_f32_16x16x32_bf16 v[26:29], v[164:167], v[206:209], v[26:29]
	v_mfma_f32_16x16x32_bf16 v[18:21], v[156:159], v[214:217], v[18:21]
	v_mfma_f32_16x16x32_bf16 v[10:13], v[164:167], v[214:217], v[10:13]
	v_mfma_f32_16x16x32_bf16 v[54:57], v[168:171], v[186:189], 0
	v_mfma_f32_16x16x32_bf16 v[46:49], v[178:181], v[186:189], 0
	v_mfma_f32_16x16x32_bf16 v[38:41], v[168:171], v[194:197], 0
	v_mfma_f32_16x16x32_bf16 v[30:33], v[178:181], v[194:197], 0
	v_mfma_f32_16x16x32_bf16 v[22:25], v[168:171], v[202:205], 0
	v_mfma_f32_16x16x32_bf16 v[14:17], v[178:181], v[202:205], 0
	v_mfma_f32_16x16x32_bf16 v[6:9], v[168:171], v[210:213], 0
	v_mfma_f32_16x16x32_bf16 v[2:5], v[178:181], v[210:213], 0
	v_mfma_f32_16x16x32_bf16 v[54:57], v[172:175], v[190:193], v[54:57]
	v_mfma_f32_16x16x32_bf16 v[46:49], v[182:185], v[190:193], v[46:49]
	v_mfma_f32_16x16x32_bf16 v[38:41], v[172:175], v[198:201], v[38:41]
	v_mfma_f32_16x16x32_bf16 v[30:33], v[182:185], v[198:201], v[30:33]
	v_mfma_f32_16x16x32_bf16 v[22:25], v[172:175], v[206:209], v[22:25]
	v_mfma_f32_16x16x32_bf16 v[14:17], v[182:185], v[206:209], v[14:17]
	v_mfma_f32_16x16x32_bf16 v[6:9], v[172:175], v[214:217], v[6:9]
	v_mfma_f32_16x16x32_bf16 v[2:5], v[182:185], v[214:217], v[2:5]
	s_setprio 0
	s_barrier
	s_add_i32 s51, 0, 0x18000
	v_add_u32_e32 v144, s51, v147
	s_add_i32 s52, 0, 0x1c000
	ds_read_b128 v[152:155], v144
	ds_read_b128 v[156:159], v144 offset:1024
	ds_read_b128 v[160:163], v144 offset:2048
	ds_read_b128 v[164:167], v144 offset:3072
	v_add_u32_e32 v144, s52, v147
	ds_read_b128 v[168:171], v144
	ds_read_b128 v[172:175], v144 offset:1024
	ds_read_b128 v[178:181], v144 offset:2048
	ds_read_b128 v[182:185], v144 offset:3072
	s_add_u32 s2, s2, 0x4000
	s_addc_u32 s3, s3, 0
	s_mov_b32 m0, s31
	v_lshl_add_u64 v[144:145], s[2:3], 0, v[130:131]
	ds_read_b128 v[186:189], v151 offset:32768
	ds_read_b128 v[190:193], v151 offset:33792
	ds_read_b128 v[194:197], v151 offset:34816
	ds_read_b128 v[198:201], v151 offset:35840
	ds_read_b128 v[202:205], v151 offset:36864
	ds_read_b128 v[206:209], v151 offset:37888
	ds_read_b128 v[210:213], v151 offset:38912
	ds_read_b128 v[214:217], v151 offset:39936
	global_load_lds_dwordx4 v[144:145], off
	v_lshl_add_u64 v[144:145], s[2:3], 0, v[134:135]
	s_mov_b32 m0, s34
	s_nop 0
	global_load_lds_dwordx4 v[144:145], off
	s_waitcnt vmcnt(8)
	s_waitcnt lgkmcnt(0)
	s_barrier
	s_setprio 1
	v_mfma_f32_16x16x32_bf16 v[126:129], v[152:155], v[186:189], v[126:129]
	v_mfma_f32_16x16x32_bf16 v[122:125], v[160:163], v[186:189], v[122:125]
	v_mfma_f32_16x16x32_bf16 v[114:117], v[152:155], v[194:197], v[114:117]
	v_mfma_f32_16x16x32_bf16 v[106:109], v[160:163], v[194:197], v[106:109]
	v_mfma_f32_16x16x32_bf16 v[98:101], v[152:155], v[202:205], v[98:101]
	v_mfma_f32_16x16x32_bf16 v[90:93], v[160:163], v[202:205], v[90:93]
	v_mfma_f32_16x16x32_bf16 v[82:85], v[152:155], v[210:213], v[82:85]
	v_mfma_f32_16x16x32_bf16 v[74:77], v[160:163], v[210:213], v[74:77]
	v_mfma_f32_16x16x32_bf16 v[126:129], v[156:159], v[190:193], v[126:129]
	v_mfma_f32_16x16x32_bf16 v[122:125], v[164:167], v[190:193], v[122:125]
	v_mfma_f32_16x16x32_bf16 v[114:117], v[156:159], v[198:201], v[114:117]
	v_mfma_f32_16x16x32_bf16 v[106:109], v[164:167], v[198:201], v[106:109]
	v_mfma_f32_16x16x32_bf16 v[98:101], v[156:159], v[206:209], v[98:101]
	v_mfma_f32_16x16x32_bf16 v[90:93], v[164:167], v[206:209], v[90:93]
	v_mfma_f32_16x16x32_bf16 v[82:85], v[156:159], v[214:217], v[82:85]
	v_mfma_f32_16x16x32_bf16 v[74:77], v[164:167], v[214:217], v[74:77]
	v_mfma_f32_16x16x32_bf16 v[118:121], v[168:171], v[186:189], v[118:121]
	v_mfma_f32_16x16x32_bf16 v[110:113], v[178:181], v[186:189], v[110:113]
	v_mfma_f32_16x16x32_bf16 v[102:105], v[168:171], v[194:197], v[102:105]
	v_mfma_f32_16x16x32_bf16 v[94:97], v[178:181], v[194:197], v[94:97]
	v_mfma_f32_16x16x32_bf16 v[86:89], v[168:171], v[202:205], v[86:89]
	v_mfma_f32_16x16x32_bf16 v[78:81], v[178:181], v[202:205], v[78:81]
	v_mfma_f32_16x16x32_bf16 v[70:73], v[168:171], v[210:213], v[70:73]
	v_mfma_f32_16x16x32_bf16 v[66:69], v[178:181], v[210:213], v[66:69]
	v_mfma_f32_16x16x32_bf16 v[118:121], v[172:175], v[190:193], v[118:121]
	v_mfma_f32_16x16x32_bf16 v[110:113], v[182:185], v[190:193], v[110:113]
	v_mfma_f32_16x16x32_bf16 v[102:105], v[172:175], v[198:201], v[102:105]
	v_mfma_f32_16x16x32_bf16 v[94:97], v[182:185], v[198:201], v[94:97]
	v_mfma_f32_16x16x32_bf16 v[86:89], v[172:175], v[206:209], v[86:89]
	v_mfma_f32_16x16x32_bf16 v[78:81], v[182:185], v[206:209], v[78:81]
	v_mfma_f32_16x16x32_bf16 v[70:73], v[172:175], v[214:217], v[70:73]
	v_mfma_f32_16x16x32_bf16 v[66:69], v[182:185], v[214:217], v[66:69]
	s_setprio 0
	s_barrier
	s_add_u32 s2, s22, 0x8000
	s_addc_u32 s3, s23, 0
	s_add_i32 s51, s51, s28
	v_lshl_add_u64 v[144:145], s[2:3], 0, v[132:133]
	s_mov_b32 m0, s51
	ds_read_b128 v[186:189], v151 offset:49152
	ds_read_b128 v[190:193], v151 offset:50176
	ds_read_b128 v[194:197], v151 offset:51200
	ds_read_b128 v[198:201], v151 offset:52224
	ds_read_b128 v[202:205], v151 offset:53248
	ds_read_b128 v[206:209], v151 offset:54272
	ds_read_b128 v[210:213], v151 offset:55296
	ds_read_b128 v[214:217], v151 offset:56320
	global_load_lds_dwordx4 v[144:145], off
	s_add_i32 m0, s51, 0x2000
	v_lshl_add_u64 v[144:145], s[2:3], 0, v[136:137]
	s_add_u32 s2, s22, 0xc000
	s_addc_u32 s3, s23, 0
	s_add_i32 s22, s52, s28
	global_load_lds_dwordx4 v[144:145], off
	v_lshl_add_u64 v[144:145], s[2:3], 0, v[132:133]
	s_mov_b32 m0, s22
	s_nop 0
	global_load_lds_dwordx4 v[144:145], off
	v_lshl_add_u64 v[144:145], s[2:3], 0, v[136:137]
	s_add_i32 m0, s22, 0x2000
	s_nop 0
	global_load_lds_dwordx4 v[144:145], off
	v_lshl_add_u64 v[144:145], s[20:21], 0, v[130:131]
	s_mov_b32 m0, s36
	s_nop 0
	global_load_lds_dwordx4 v[144:145], off
	v_lshl_add_u64 v[144:145], s[20:21], 0, v[134:135]
	s_mov_b32 m0, s37
	s_nop 0
	global_load_lds_dwordx4 v[144:145], off
	s_waitcnt vmcnt(8)
	s_waitcnt lgkmcnt(0)
	s_barrier
	s_setprio 1
	v_mfma_f32_16x16x32_bf16 v[62:65], v[152:155], v[186:189], v[62:65]
	v_mfma_f32_16x16x32_bf16 v[58:61], v[160:163], v[186:189], v[58:61]
	v_mfma_f32_16x16x32_bf16 v[50:53], v[152:155], v[194:197], v[50:53]
	v_mfma_f32_16x16x32_bf16 v[42:45], v[160:163], v[194:197], v[42:45]
	v_mfma_f32_16x16x32_bf16 v[34:37], v[152:155], v[202:205], v[34:37]
	v_mfma_f32_16x16x32_bf16 v[26:29], v[160:163], v[202:205], v[26:29]
	v_mfma_f32_16x16x32_bf16 v[18:21], v[152:155], v[210:213], v[18:21]
	v_mfma_f32_16x16x32_bf16 v[10:13], v[160:163], v[210:213], v[10:13]
	v_mfma_f32_16x16x32_bf16 v[62:65], v[156:159], v[190:193], v[62:65]
	v_mfma_f32_16x16x32_bf16 v[58:61], v[164:167], v[190:193], v[58:61]
	v_mfma_f32_16x16x32_bf16 v[50:53], v[156:159], v[198:201], v[50:53]
	v_mfma_f32_16x16x32_bf16 v[42:45], v[164:167], v[198:201], v[42:45]
	v_mfma_f32_16x16x32_bf16 v[34:37], v[156:159], v[206:209], v[34:37]
	v_mfma_f32_16x16x32_bf16 v[26:29], v[164:167], v[206:209], v[26:29]
	v_mfma_f32_16x16x32_bf16 v[18:21], v[156:159], v[214:217], v[18:21]
	v_mfma_f32_16x16x32_bf16 v[10:13], v[164:167], v[214:217], v[10:13]
	v_mfma_f32_16x16x32_bf16 v[54:57], v[168:171], v[186:189], v[54:57]
	v_mfma_f32_16x16x32_bf16 v[46:49], v[178:181], v[186:189], v[46:49]
	v_mfma_f32_16x16x32_bf16 v[38:41], v[168:171], v[194:197], v[38:41]
	v_mfma_f32_16x16x32_bf16 v[30:33], v[178:181], v[194:197], v[30:33]
	v_mfma_f32_16x16x32_bf16 v[22:25], v[168:171], v[202:205], v[22:25]
	v_mfma_f32_16x16x32_bf16 v[14:17], v[178:181], v[202:205], v[14:17]
	v_mfma_f32_16x16x32_bf16 v[6:9], v[168:171], v[210:213], v[6:9]
	v_mfma_f32_16x16x32_bf16 v[2:5], v[178:181], v[210:213], v[2:5]
	v_mfma_f32_16x16x32_bf16 v[54:57], v[172:175], v[190:193], v[54:57]
	v_mfma_f32_16x16x32_bf16 v[46:49], v[182:185], v[190:193], v[46:49]
	v_mfma_f32_16x16x32_bf16 v[38:41], v[172:175], v[198:201], v[38:41]
	v_mfma_f32_16x16x32_bf16 v[30:33], v[182:185], v[198:201], v[30:33]
	v_mfma_f32_16x16x32_bf16 v[22:25], v[172:175], v[206:209], v[22:25]
	v_mfma_f32_16x16x32_bf16 v[14:17], v[182:185], v[206:209], v[14:17]
	v_mfma_f32_16x16x32_bf16 v[6:9], v[172:175], v[214:217], v[6:9]
	v_mfma_f32_16x16x32_bf16 v[2:5], v[182:185], v[214:217], v[2:5]
	s_setprio 0
	s_barrier
	s_add_i32 s50, s50, 2
	s_add_u32 s18, s18, 0x10000
	s_addc_u32 s19, s19, 0
	s_add_u32 s48, s48, 0x10000
	s_addc_u32 s49, s49, 0
	s_cmp_gt_u32 s50, 41
	s_cbranch_scc0 .LBB0_495
	s_branch .Lpk495_exit
.LBB0_495:
	ds_read_b128 v[152:155], v149
	ds_read_b128 v[156:159], v149 offset:1024
	ds_read_b128 v[160:163], v149 offset:2048
	ds_read_b128 v[164:167], v149 offset:3072
	ds_read_b128 v[168:171], v150
	ds_read_b128 v[172:175], v150 offset:1024
	ds_read_b128 v[178:181], v150 offset:2048
	ds_read_b128 v[182:185], v150 offset:3072
	s_add_u32 s2, s18, 0x4000
	s_addc_u32 s3, s19, 0
	s_cmp_eq_u32 s50, 40
	s_cselect_b32 s2, s45, s2
	s_cselect_b32 s3, s44, s3
	s_cselect_b32 s23, s46, s49
	s_cselect_b32 s22, s47, s48
	s_add_u32 s20, s2, 0x8000
	s_addc_u32 s21, s3, 0
	v_lshl_add_u64 v[144:145], s[18:19], 0, v[138:139]
	s_add_i32 m0, s29, 0xc000
	ds_read_b128 v[186:189], v151
	ds_read_b128 v[190:193], v151 offset:1024
	ds_read_b128 v[194:197], v151 offset:2048
	ds_read_b128 v[198:201], v151 offset:3072
	ds_read_b128 v[202:205], v151 offset:4096
	ds_read_b128 v[206:209], v151 offset:5120
	ds_read_b128 v[210:213], v151 offset:6144
	ds_read_b128 v[214:217], v151 offset:7168
	global_load_lds_dwordx4 v[144:145], off
	v_lshl_add_u64 v[144:145], s[18:19], 0, v[140:141]
	s_add_i32 m0, s29, 0xe000
	s_nop 0
	global_load_lds_dwordx4 v[144:145], off
	s_waitcnt vmcnt(8)
	s_waitcnt lgkmcnt(0)
	s_barrier
	s_setprio 1
	v_mfma_f32_16x16x32_bf16 v[126:129], v[152:155], v[186:189], v[126:129]
	v_mfma_f32_16x16x32_bf16 v[122:125], v[160:163], v[186:189], v[122:125]
	v_mfma_f32_16x16x32_bf16 v[114:117], v[152:155], v[194:197], v[114:117]
	v_mfma_f32_16x16x32_bf16 v[106:109], v[160:163], v[194:197], v[106:109]
	v_mfma_f32_16x16x32_bf16 v[98:101], v[152:155], v[202:205], v[98:101]
	v_mfma_f32_16x16x32_bf16 v[90:93], v[160:163], v[202:205], v[90:93]
	v_mfma_f32_16x16x32_bf16 v[82:85], v[152:155], v[210:213], v[82:85]
	v_mfma_f32_16x16x32_bf16 v[74:77], v[160:163], v[210:213], v[74:77]
	v_mfma_f32_16x16x32_bf16 v[126:129], v[156:159], v[190:193], v[126:129]
	v_mfma_f32_16x16x32_bf16 v[122:125], v[164:167], v[190:193], v[122:125]
	v_mfma_f32_16x16x32_bf16 v[114:117], v[156:159], v[198:201], v[114:117]
	v_mfma_f32_16x16x32_bf16 v[106:109], v[164:167], v[198:201], v[106:109]
	v_mfma_f32_16x16x32_bf16 v[98:101], v[156:159], v[206:209], v[98:101]
	v_mfma_f32_16x16x32_bf16 v[90:93], v[164:167], v[206:209], v[90:93]
	v_mfma_f32_16x16x32_bf16 v[82:85], v[156:159], v[214:217], v[82:85]
	v_mfma_f32_16x16x32_bf16 v[74:77], v[164:167], v[214:217], v[74:77]
	v_mfma_f32_16x16x32_bf16 v[118:121], v[168:171], v[186:189], v[118:121]
	v_mfma_f32_16x16x32_bf16 v[110:113], v[178:181], v[186:189], v[110:113]
	v_mfma_f32_16x16x32_bf16 v[102:105], v[168:171], v[194:197], v[102:105]
	v_mfma_f32_16x16x32_bf16 v[94:97], v[178:181], v[194:197], v[94:97]
	v_mfma_f32_16x16x32_bf16 v[86:89], v[168:171], v[202:205], v[86:89]
	v_mfma_f32_16x16x32_bf16 v[78:81], v[178:181], v[202:205], v[78:81]
	v_mfma_f32_16x16x32_bf16 v[70:73], v[168:171], v[210:213], v[70:73]
	v_mfma_f32_16x16x32_bf16 v[66:69], v[178:181], v[210:213], v[66:69]
	v_mfma_f32_16x16x32_bf16 v[118:121], v[172:175], v[190:193], v[118:121]
	v_mfma_f32_16x16x32_bf16 v[110:113], v[182:185], v[190:193], v[110:113]
	v_mfma_f32_16x16x32_bf16 v[102:105], v[172:175], v[198:201], v[102:105]
	v_mfma_f32_16x16x32_bf16 v[94:97], v[182:185], v[198:201], v[94:97]
	v_mfma_f32_16x16x32_bf16 v[86:89], v[172:175], v[206:209], v[86:89]
	v_mfma_f32_16x16x32_bf16 v[78:81], v[182:185], v[206:209], v[78:81]
	v_mfma_f32_16x16x32_bf16 v[70:73], v[172:175], v[214:217], v[70:73]
	v_mfma_f32_16x16x32_bf16 v[66:69], v[182:185], v[214:217], v[66:69]
	s_setprio 0
	s_barrier
	s_add_i32 s51, s38, s28
	v_lshl_add_u64 v[144:145], s[22:23], 0, v[132:133]
	s_mov_b32 m0, s51
	ds_read_b128 v[186:189], v151 offset:16384
	ds_read_b128 v[190:193], v151 offset:17408
	ds_read_b128 v[194:197], v151 offset:18432
	ds_read_b128 v[198:201], v151 offset:19456
	ds_read_b128 v[202:205], v151 offset:20480
	ds_read_b128 v[206:209], v151 offset:21504
	ds_read_b128 v[210:213], v151 offset:22528
	ds_read_b128 v[214:217], v151 offset:23552
	global_load_lds_dwordx4 v[144:145], off
	s_add_i32 m0, s51, 0x2000
	s_add_u32 s52, s22, 0x4000
	v_lshl_add_u64 v[144:145], s[22:23], 0, v[136:137]
	s_addc_u32 s53, s23, 0
	s_add_i32 s51, s39, s28
	global_load_lds_dwordx4 v[144:145], off
	v_lshl_add_u64 v[144:145], s[52:53], 0, v[132:133]
	s_mov_b32 m0, s51
	s_nop 0
	global_load_lds_dwordx4 v[144:145], off
	v_lshl_add_u64 v[144:145], s[52:53], 0, v[136:137]
	s_add_i32 m0, s51, 0x2000
	s_nop 0
	global_load_lds_dwordx4 v[144:145], off
	v_lshl_add_u64 v[144:145], s[2:3], 0, v[130:131]
	s_mov_b32 m0, s29
	s_nop 0
	global_load_lds_dwordx4 v[144:145], off
	v_lshl_add_u64 v[144:145], s[2:3], 0, v[134:135]
	s_mov_b32 m0, s30
	s_nop 0
	global_load_lds_dwordx4 v[144:145], off
	s_waitcnt vmcnt(8)
	s_waitcnt lgkmcnt(0)
	s_barrier
	s_setprio 1
	v_mfma_f32_16x16x32_bf16 v[62:65], v[152:155], v[186:189], v[62:65]
	v_mfma_f32_16x16x32_bf16 v[58:61], v[160:163], v[186:189], v[58:61]
	v_mfma_f32_16x16x32_bf16 v[50:53], v[152:155], v[194:197], v[50:53]
	v_mfma_f32_16x16x32_bf16 v[42:45], v[160:163], v[194:197], v[42:45]
	v_mfma_f32_16x16x32_bf16 v[34:37], v[152:155], v[202:205], v[34:37]
	v_mfma_f32_16x16x32_bf16 v[26:29], v[160:163], v[202:205], v[26:29]
	v_mfma_f32_16x16x32_bf16 v[18:21], v[152:155], v[210:213], v[18:21]
	v_mfma_f32_16x16x32_bf16 v[10:13], v[160:163], v[210:213], v[10:13]
	v_mfma_f32_16x16x32_bf16 v[62:65], v[156:159], v[190:193], v[62:65]
	v_mfma_f32_16x16x32_bf16 v[58:61], v[164:167], v[190:193], v[58:61]
	v_mfma_f32_16x16x32_bf16 v[50:53], v[156:159], v[198:201], v[50:53]
	v_mfma_f32_16x16x32_bf16 v[42:45], v[164:167], v[198:201], v[42:45]
	v_mfma_f32_16x16x32_bf16 v[34:37], v[156:159], v[206:209], v[34:37]
	v_mfma_f32_16x16x32_bf16 v[26:29], v[164:167], v[206:209], v[26:29]
	v_mfma_f32_16x16x32_bf16 v[18:21], v[156:159], v[214:217], v[18:21]
	v_mfma_f32_16x16x32_bf16 v[10:13], v[164:167], v[214:217], v[10:13]
	v_mfma_f32_16x16x32_bf16 v[54:57], v[168:171], v[186:189], v[54:57]
	v_mfma_f32_16x16x32_bf16 v[46:49], v[178:181], v[186:189], v[46:49]
	v_mfma_f32_16x16x32_bf16 v[38:41], v[168:171], v[194:197], v[38:41]
	v_mfma_f32_16x16x32_bf16 v[30:33], v[178:181], v[194:197], v[30:33]
	v_mfma_f32_16x16x32_bf16 v[22:25], v[168:171], v[202:205], v[22:25]
	v_mfma_f32_16x16x32_bf16 v[14:17], v[178:181], v[202:205], v[14:17]
	v_mfma_f32_16x16x32_bf16 v[6:9], v[168:171], v[210:213], v[6:9]
	v_mfma_f32_16x16x32_bf16 v[2:5], v[178:181], v[210:213], v[2:5]
	v_mfma_f32_16x16x32_bf16 v[54:57], v[172:175], v[190:193], v[54:57]
	v_mfma_f32_16x16x32_bf16 v[46:49], v[182:185], v[190:193], v[46:49]
	v_mfma_f32_16x16x32_bf16 v[38:41], v[172:175], v[198:201], v[38:41]
	v_mfma_f32_16x16x32_bf16 v[30:33], v[182:185], v[198:201], v[30:33]
	v_mfma_f32_16x16x32_bf16 v[22:25], v[172:175], v[206:209], v[22:25]
	v_mfma_f32_16x16x32_bf16 v[14:17], v[182:185], v[206:209], v[14:17]
	v_mfma_f32_16x16x32_bf16 v[6:9], v[172:175], v[214:217], v[6:9]
	v_mfma_f32_16x16x32_bf16 v[2:5], v[182:185], v[214:217], v[2:5]
	s_setprio 0
	s_barrier
	s_add_i32 s51, 0, 0x18000
	v_add_u32_e32 v144, s51, v147
	s_add_i32 s52, 0, 0x1c000
	ds_read_b128 v[152:155], v144
	ds_read_b128 v[156:159], v144 offset:1024
	ds_read_b128 v[160:163], v144 offset:2048
	ds_read_b128 v[164:167], v144 offset:3072
	v_add_u32_e32 v144, s52, v147
	ds_read_b128 v[168:171], v144
	ds_read_b128 v[172:175], v144 offset:1024
	ds_read_b128 v[178:181], v144 offset:2048
	ds_read_b128 v[182:185], v144 offset:3072
	s_add_u32 s2, s2, 0x4000
	s_addc_u32 s3, s3, 0
	s_mov_b32 m0, s31
	v_lshl_add_u64 v[144:145], s[2:3], 0, v[130:131]
	ds_read_b128 v[186:189], v151 offset:32768
	ds_read_b128 v[190:193], v151 offset:33792
	ds_read_b128 v[194:197], v151 offset:34816
	ds_read_b128 v[198:201], v151 offset:35840
	ds_read_b128 v[202:205], v151 offset:36864
	ds_read_b128 v[206:209], v151 offset:37888
	ds_read_b128 v[210:213], v151 offset:38912
	ds_read_b128 v[214:217], v151 offset:39936
	global_load_lds_dwordx4 v[144:145], off
	v_lshl_add_u64 v[144:145], s[2:3], 0, v[134:135]
	s_mov_b32 m0, s34
	s_nop 0
	global_load_lds_dwordx4 v[144:145], off
	s_waitcnt vmcnt(8)
	s_waitcnt lgkmcnt(0)
	s_barrier
	s_setprio 1
	v_mfma_f32_16x16x32_bf16 v[126:129], v[152:155], v[186:189], v[126:129]
	v_mfma_f32_16x16x32_bf16 v[122:125], v[160:163], v[186:189], v[122:125]
	v_mfma_f32_16x16x32_bf16 v[114:117], v[152:155], v[194:197], v[114:117]
	v_mfma_f32_16x16x32_bf16 v[106:109], v[160:163], v[194:197], v[106:109]
	v_mfma_f32_16x16x32_bf16 v[98:101], v[152:155], v[202:205], v[98:101]
	v_mfma_f32_16x16x32_bf16 v[90:93], v[160:163], v[202:205], v[90:93]
	v_mfma_f32_16x16x32_bf16 v[82:85], v[152:155], v[210:213], v[82:85]
	v_mfma_f32_16x16x32_bf16 v[74:77], v[160:163], v[210:213], v[74:77]
	v_mfma_f32_16x16x32_bf16 v[126:129], v[156:159], v[190:193], v[126:129]
	v_mfma_f32_16x16x32_bf16 v[122:125], v[164:167], v[190:193], v[122:125]
	v_mfma_f32_16x16x32_bf16 v[114:117], v[156:159], v[198:201], v[114:117]
	v_mfma_f32_16x16x32_bf16 v[106:109], v[164:167], v[198:201], v[106:109]
	v_mfma_f32_16x16x32_bf16 v[98:101], v[156:159], v[206:209], v[98:101]
	v_mfma_f32_16x16x32_bf16 v[90:93], v[164:167], v[206:209], v[90:93]
	v_mfma_f32_16x16x32_bf16 v[82:85], v[156:159], v[214:217], v[82:85]
	v_mfma_f32_16x16x32_bf16 v[74:77], v[164:167], v[214:217], v[74:77]
	v_mfma_f32_16x16x32_bf16 v[118:121], v[168:171], v[186:189], v[118:121]
	v_mfma_f32_16x16x32_bf16 v[110:113], v[178:181], v[186:189], v[110:113]
	v_mfma_f32_16x16x32_bf16 v[102:105], v[168:171], v[194:197], v[102:105]
	v_mfma_f32_16x16x32_bf16 v[94:97], v[178:181], v[194:197], v[94:97]
	v_mfma_f32_16x16x32_bf16 v[86:89], v[168:171], v[202:205], v[86:89]
	v_mfma_f32_16x16x32_bf16 v[78:81], v[178:181], v[202:205], v[78:81]
	v_mfma_f32_16x16x32_bf16 v[70:73], v[168:171], v[210:213], v[70:73]
	v_mfma_f32_16x16x32_bf16 v[66:69], v[178:181], v[210:213], v[66:69]
	v_mfma_f32_16x16x32_bf16 v[118:121], v[172:175], v[190:193], v[118:121]
	v_mfma_f32_16x16x32_bf16 v[110:113], v[182:185], v[190:193], v[110:113]
	v_mfma_f32_16x16x32_bf16 v[102:105], v[172:175], v[198:201], v[102:105]
	v_mfma_f32_16x16x32_bf16 v[94:97], v[182:185], v[198:201], v[94:97]
	v_mfma_f32_16x16x32_bf16 v[86:89], v[172:175], v[206:209], v[86:89]
	v_mfma_f32_16x16x32_bf16 v[78:81], v[182:185], v[206:209], v[78:81]
	v_mfma_f32_16x16x32_bf16 v[70:73], v[172:175], v[214:217], v[70:73]
	v_mfma_f32_16x16x32_bf16 v[66:69], v[182:185], v[214:217], v[66:69]
	s_setprio 0
	s_barrier
	s_add_u32 s2, s22, 0x8000
	s_addc_u32 s3, s23, 0
	s_add_i32 s51, s51, s28
	v_lshl_add_u64 v[144:145], s[2:3], 0, v[132:133]
	s_mov_b32 m0, s51
	ds_read_b128 v[186:189], v151 offset:49152
	ds_read_b128 v[190:193], v151 offset:50176
	ds_read_b128 v[194:197], v151 offset:51200
	ds_read_b128 v[198:201], v151 offset:52224
	ds_read_b128 v[202:205], v151 offset:53248
	ds_read_b128 v[206:209], v151 offset:54272
	ds_read_b128 v[210:213], v151 offset:55296
	ds_read_b128 v[214:217], v151 offset:56320
	global_load_lds_dwordx4 v[144:145], off
	s_add_i32 m0, s51, 0x2000
	v_lshl_add_u64 v[144:145], s[2:3], 0, v[136:137]
	s_add_u32 s2, s22, 0xc000
	s_addc_u32 s3, s23, 0
	s_add_i32 s22, s52, s28
	global_load_lds_dwordx4 v[144:145], off
	v_lshl_add_u64 v[144:145], s[2:3], 0, v[132:133]
	s_mov_b32 m0, s22
	s_nop 0
	global_load_lds_dwordx4 v[144:145], off
	v_lshl_add_u64 v[144:145], s[2:3], 0, v[136:137]
	s_add_i32 m0, s22, 0x2000
	s_nop 0
	global_load_lds_dwordx4 v[144:145], off
	v_lshl_add_u64 v[144:145], s[20:21], 0, v[130:131]
	s_mov_b32 m0, s36
	s_nop 0
	global_load_lds_dwordx4 v[144:145], off
	v_lshl_add_u64 v[144:145], s[20:21], 0, v[134:135]
	s_mov_b32 m0, s37
	s_nop 0
	global_load_lds_dwordx4 v[144:145], off
	s_waitcnt vmcnt(8)
	s_waitcnt lgkmcnt(0)
	s_barrier
	s_setprio 1
	v_mfma_f32_16x16x32_bf16 v[62:65], v[152:155], v[186:189], v[62:65]
	v_mfma_f32_16x16x32_bf16 v[58:61], v[160:163], v[186:189], v[58:61]
	v_mfma_f32_16x16x32_bf16 v[50:53], v[152:155], v[194:197], v[50:53]
	v_mfma_f32_16x16x32_bf16 v[42:45], v[160:163], v[194:197], v[42:45]
	v_mfma_f32_16x16x32_bf16 v[34:37], v[152:155], v[202:205], v[34:37]
	v_mfma_f32_16x16x32_bf16 v[26:29], v[160:163], v[202:205], v[26:29]
	v_mfma_f32_16x16x32_bf16 v[18:21], v[152:155], v[210:213], v[18:21]
	v_mfma_f32_16x16x32_bf16 v[10:13], v[160:163], v[210:213], v[10:13]
	v_mfma_f32_16x16x32_bf16 v[62:65], v[156:159], v[190:193], v[62:65]
	v_mfma_f32_16x16x32_bf16 v[58:61], v[164:167], v[190:193], v[58:61]
	v_mfma_f32_16x16x32_bf16 v[50:53], v[156:159], v[198:201], v[50:53]
	v_mfma_f32_16x16x32_bf16 v[42:45], v[164:167], v[198:201], v[42:45]
	v_mfma_f32_16x16x32_bf16 v[34:37], v[156:159], v[206:209], v[34:37]
	v_mfma_f32_16x16x32_bf16 v[26:29], v[164:167], v[206:209], v[26:29]
	v_mfma_f32_16x16x32_bf16 v[18:21], v[156:159], v[214:217], v[18:21]
	v_mfma_f32_16x16x32_bf16 v[10:13], v[164:167], v[214:217], v[10:13]
	v_mfma_f32_16x16x32_bf16 v[54:57], v[168:171], v[186:189], v[54:57]
	v_mfma_f32_16x16x32_bf16 v[46:49], v[178:181], v[186:189], v[46:49]
	v_mfma_f32_16x16x32_bf16 v[38:41], v[168:171], v[194:197], v[38:41]
	v_mfma_f32_16x16x32_bf16 v[30:33], v[178:181], v[194:197], v[30:33]
	v_mfma_f32_16x16x32_bf16 v[22:25], v[168:171], v[202:205], v[22:25]
	v_mfma_f32_16x16x32_bf16 v[14:17], v[178:181], v[202:205], v[14:17]
	v_mfma_f32_16x16x32_bf16 v[6:9], v[168:171], v[210:213], v[6:9]
	v_mfma_f32_16x16x32_bf16 v[2:5], v[178:181], v[210:213], v[2:5]
	v_mfma_f32_16x16x32_bf16 v[54:57], v[172:175], v[190:193], v[54:57]
	v_mfma_f32_16x16x32_bf16 v[46:49], v[182:185], v[190:193], v[46:49]
	v_mfma_f32_16x16x32_bf16 v[38:41], v[172:175], v[198:201], v[38:41]
	v_mfma_f32_16x16x32_bf16 v[30:33], v[182:185], v[198:201], v[30:33]
	v_mfma_f32_16x16x32_bf16 v[22:25], v[172:175], v[206:209], v[22:25]
	v_mfma_f32_16x16x32_bf16 v[14:17], v[182:185], v[206:209], v[14:17]
	v_mfma_f32_16x16x32_bf16 v[6:9], v[172:175], v[214:217], v[6:9]
	v_mfma_f32_16x16x32_bf16 v[2:5], v[182:185], v[214:217], v[2:5]
	s_setprio 0
	s_barrier
	s_add_i32 s50, s50, 2
	s_add_u32 s18, s18, 0x10000
	s_addc_u32 s19, s19, 0
	s_add_u32 s48, s48, 0x10000
	s_addc_u32 s49, s49, 0
	s_cmp_gt_u32 s50, 41
	s_cbranch_scc0 .LBB0_495

.Lpk555_peel:
	ds_read_b128 v[154:157], v151
	ds_read_b128 v[158:161], v151 offset:1024
	ds_read_b128 v[162:165], v151 offset:2048
	ds_read_b128 v[166:169], v151 offset:3072
	ds_read_b128 v[170:173], v152
	ds_read_b128 v[178:181], v152 offset:1024
	ds_read_b128 v[182:185], v152 offset:2048
	ds_read_b128 v[186:189], v152 offset:3072
	s_add_u32 s2, s26, 0xfffc0080
	s_addc_u32 s3, s27, -1
	s_cmp_eq_u32 s52, 12
	s_cselect_b32 s3, s11, s3
	s_cselect_b32 s2, s13, s2
	s_cselect_b32 s29, s48, s51
	s_cselect_b32 s28, s49, s50
	v_lshl_add_u64 v[144:145], s[26:27], 0, v[138:139]
	s_add_i32 m0, s37, 0xc000
	ds_read_b128 v[190:193], v153
	ds_read_b128 v[194:197], v153 offset:1024
	ds_read_b128 v[198:201], v153 offset:2048
	ds_read_b128 v[202:205], v153 offset:3072
	ds_read_b128 v[206:209], v153 offset:4096
	ds_read_b128 v[210:213], v153 offset:5120
	ds_read_b128 v[214:217], v153 offset:6144
	ds_read_b128 v[218:221], v153 offset:7168
	global_load_lds_dwordx4 v[144:145], off
	v_lshl_add_u64 v[144:145], s[26:27], 0, v[140:141]
	s_add_i32 m0, s37, 0xe000
	s_nop 0
	global_load_lds_dwordx4 v[144:145], off
	s_waitcnt vmcnt(8)
	s_waitcnt lgkmcnt(0)
	s_barrier
	s_setprio 1
	v_mfma_f32_16x16x32_bf16 v[126:129], v[154:157], v[190:193], 0
	v_mfma_f32_16x16x32_bf16 v[122:125], v[162:165], v[190:193], 0
	v_mfma_f32_16x16x32_bf16 v[114:117], v[154:157], v[198:201], 0
	v_mfma_f32_16x16x32_bf16 v[106:109], v[162:165], v[198:201], 0
	v_mfma_f32_16x16x32_bf16 v[98:101], v[154:157], v[206:209], 0
	v_mfma_f32_16x16x32_bf16 v[90:93], v[162:165], v[206:209], 0
	v_mfma_f32_16x16x32_bf16 v[82:85], v[154:157], v[214:217], 0
	v_mfma_f32_16x16x32_bf16 v[74:77], v[162:165], v[214:217], 0
	v_mfma_f32_16x16x32_bf16 v[126:129], v[158:161], v[194:197], v[126:129]
	v_mfma_f32_16x16x32_bf16 v[122:125], v[166:169], v[194:197], v[122:125]
	v_mfma_f32_16x16x32_bf16 v[114:117], v[158:161], v[202:205], v[114:117]
	v_mfma_f32_16x16x32_bf16 v[106:109], v[166:169], v[202:205], v[106:109]
	v_mfma_f32_16x16x32_bf16 v[98:101], v[158:161], v[210:213], v[98:101]
	v_mfma_f32_16x16x32_bf16 v[90:93], v[166:169], v[210:213], v[90:93]
	v_mfma_f32_16x16x32_bf16 v[82:85], v[158:161], v[218:221], v[82:85]
	v_mfma_f32_16x16x32_bf16 v[74:77], v[166:169], v[218:221], v[74:77]
	v_mfma_f32_16x16x32_bf16 v[118:121], v[170:173], v[190:193], 0
	v_mfma_f32_16x16x32_bf16 v[110:113], v[182:185], v[190:193], 0
	v_mfma_f32_16x16x32_bf16 v[102:105], v[170:173], v[198:201], 0
	v_mfma_f32_16x16x32_bf16 v[94:97], v[182:185], v[198:201], 0
	v_mfma_f32_16x16x32_bf16 v[86:89], v[170:173], v[206:209], 0
	v_mfma_f32_16x16x32_bf16 v[78:81], v[182:185], v[206:209], 0
	v_mfma_f32_16x16x32_bf16 v[70:73], v[170:173], v[214:217], 0
	v_mfma_f32_16x16x32_bf16 v[66:69], v[182:185], v[214:217], 0
	v_mfma_f32_16x16x32_bf16 v[118:121], v[178:181], v[194:197], v[118:121]
	v_mfma_f32_16x16x32_bf16 v[110:113], v[186:189], v[194:197], v[110:113]
	v_mfma_f32_16x16x32_bf16 v[102:105], v[178:181], v[202:205], v[102:105]
	v_mfma_f32_16x16x32_bf16 v[94:97], v[186:189], v[202:205], v[94:97]
	v_mfma_f32_16x16x32_bf16 v[86:89], v[178:181], v[210:213], v[86:89]
	v_mfma_f32_16x16x32_bf16 v[78:81], v[186:189], v[210:213], v[78:81]
	v_mfma_f32_16x16x32_bf16 v[70:73], v[178:181], v[218:221], v[70:73]
	v_mfma_f32_16x16x32_bf16 v[66:69], v[186:189], v[218:221], v[66:69]
	s_setprio 0
	s_barrier
	s_add_i32 s53, s44, s34
	v_lshl_add_u64 v[144:145], s[28:29], 0, v[134:135]
	s_mov_b32 m0, s53
	ds_read_b128 v[190:193], v153 offset:16384
	ds_read_b128 v[194:197], v153 offset:17408
	ds_read_b128 v[198:201], v153 offset:18432
	ds_read_b128 v[202:205], v153 offset:19456
	ds_read_b128 v[206:209], v153 offset:20480
	ds_read_b128 v[210:213], v153 offset:21504
	ds_read_b128 v[214:217], v153 offset:22528
	ds_read_b128 v[218:221], v153 offset:23552
	global_load_lds_dwordx4 v[144:145], off
	s_add_i32 m0, s53, 0x2000
	s_add_u32 s54, s28, 0x40000
	v_lshl_add_u64 v[174:175], s[28:29], 0, v[130:131]
	s_addc_u32 s55, s29, 0
	s_add_i32 s53, s45, s34
	global_load_lds_dwordx4 v[174:175], off
	v_lshl_add_u64 v[222:223], s[54:55], 0, v[134:135]
	s_mov_b32 m0, s53
	v_lshl_add_u64 v[224:225], s[2:3], 0, v[132:133]
	global_load_lds_dwordx4 v[222:223], off
	v_lshl_add_u64 v[222:223], s[54:55], 0, v[130:131]
	s_add_i32 m0, s53, 0x2000
	s_nop 0
	global_load_lds_dwordx4 v[222:223], off
	v_lshl_add_u64 v[222:223], s[2:3], 0, v[136:137]
	s_mov_b32 m0, s37
	s_nop 0
	global_load_lds_dwordx4 v[222:223], off
	s_mov_b32 m0, s25
	s_nop 0
	global_load_lds_dwordx4 v[224:225], off
	s_waitcnt vmcnt(8)
	s_waitcnt lgkmcnt(0)
	s_barrier
	s_setprio 1
	v_mfma_f32_16x16x32_bf16 v[62:65], v[154:157], v[190:193], 0
	v_mfma_f32_16x16x32_bf16 v[58:61], v[162:165], v[190:193], 0
	v_mfma_f32_16x16x32_bf16 v[50:53], v[154:157], v[198:201], 0
	v_mfma_f32_16x16x32_bf16 v[42:45], v[162:165], v[198:201], 0
	v_mfma_f32_16x16x32_bf16 v[34:37], v[154:157], v[206:209], 0
	v_mfma_f32_16x16x32_bf16 v[26:29], v[162:165], v[206:209], 0
	v_mfma_f32_16x16x32_bf16 v[18:21], v[154:157], v[214:217], 0
	v_mfma_f32_16x16x32_bf16 v[10:13], v[162:165], v[214:217], 0
	v_mfma_f32_16x16x32_bf16 v[62:65], v[158:161], v[194:197], v[62:65]
	v_mfma_f32_16x16x32_bf16 v[58:61], v[166:169], v[194:197], v[58:61]
	v_mfma_f32_16x16x32_bf16 v[50:53], v[158:161], v[202:205], v[50:53]
	v_mfma_f32_16x16x32_bf16 v[42:45], v[166:169], v[202:205], v[42:45]
	v_mfma_f32_16x16x32_bf16 v[34:37], v[158:161], v[210:213], v[34:37]
	v_mfma_f32_16x16x32_bf16 v[26:29], v[166:169], v[210:213], v[26:29]
	v_mfma_f32_16x16x32_bf16 v[18:21], v[158:161], v[218:221], v[18:21]
	v_mfma_f32_16x16x32_bf16 v[10:13], v[166:169], v[218:221], v[10:13]
	v_mfma_f32_16x16x32_bf16 v[54:57], v[170:173], v[190:193], 0
	v_mfma_f32_16x16x32_bf16 v[46:49], v[182:185], v[190:193], 0
	v_mfma_f32_16x16x32_bf16 v[38:41], v[170:173], v[198:201], 0
	v_mfma_f32_16x16x32_bf16 v[30:33], v[182:185], v[198:201], 0
	v_mfma_f32_16x16x32_bf16 v[22:25], v[170:173], v[206:209], 0
	v_mfma_f32_16x16x32_bf16 v[14:17], v[182:185], v[206:209], 0
	v_mfma_f32_16x16x32_bf16 v[6:9], v[170:173], v[214:217], 0
	v_mfma_f32_16x16x32_bf16 v[2:5], v[182:185], v[214:217], 0
	v_mfma_f32_16x16x32_bf16 v[54:57], v[178:181], v[194:197], v[54:57]
	v_mfma_f32_16x16x32_bf16 v[46:49], v[186:189], v[194:197], v[46:49]
	v_mfma_f32_16x16x32_bf16 v[38:41], v[178:181], v[202:205], v[38:41]
	v_mfma_f32_16x16x32_bf16 v[30:33], v[186:189], v[202:205], v[30:33]
	v_mfma_f32_16x16x32_bf16 v[22:25], v[178:181], v[210:213], v[22:25]
	v_mfma_f32_16x16x32_bf16 v[14:17], v[186:189], v[210:213], v[14:17]
	v_mfma_f32_16x16x32_bf16 v[6:9], v[178:181], v[218:221], v[6:9]
	v_mfma_f32_16x16x32_bf16 v[2:5], v[186:189], v[218:221], v[2:5]
	s_setprio 0
	s_barrier
	s_add_i32 s53, 0, 0x18000
	s_add_i32 s54, 0, 0x1c000
	v_add_u32_e32 v166, s53, v149
	v_add_u32_e32 v176, s54, v149
	ds_read_b128 v[154:157], v166
	ds_read_b128 v[158:161], v166 offset:1024
	ds_read_b128 v[162:165], v166 offset:2048
	ds_read_b128 v[166:169], v166 offset:3072
	ds_read_b128 v[170:173], v176
	ds_read_b128 v[178:181], v176 offset:1024
	ds_read_b128 v[182:185], v176 offset:2048
	ds_read_b128 v[186:189], v176 offset:3072
	s_add_u32 s2, s2, 0x40000
	s_addc_u32 s3, s3, 0
	s_mov_b32 m0, s38
	v_lshl_add_u64 v[226:227], s[2:3], 0, v[136:137]
	ds_read_b128 v[190:193], v153 offset:32768
	ds_read_b128 v[194:197], v153 offset:33792
	ds_read_b128 v[198:201], v153 offset:34816
	ds_read_b128 v[202:205], v153 offset:35840
	ds_read_b128 v[206:209], v153 offset:36864
	ds_read_b128 v[210:213], v153 offset:37888
	ds_read_b128 v[214:217], v153 offset:38912
	ds_read_b128 v[218:221], v153 offset:39936
	global_load_lds_dwordx4 v[226:227], off
	v_lshl_add_u64 v[226:227], s[2:3], 0, v[132:133]
	s_mov_b32 m0, s39
	s_nop 0
	global_load_lds_dwordx4 v[226:227], off
	s_waitcnt vmcnt(8)
	s_waitcnt lgkmcnt(0)
	s_barrier
	s_setprio 1
	v_mfma_f32_16x16x32_bf16 v[126:129], v[154:157], v[190:193], v[126:129]
	v_mfma_f32_16x16x32_bf16 v[122:125], v[162:165], v[190:193], v[122:125]
	v_mfma_f32_16x16x32_bf16 v[114:117], v[154:157], v[198:201], v[114:117]
	v_mfma_f32_16x16x32_bf16 v[106:109], v[162:165], v[198:201], v[106:109]
	v_mfma_f32_16x16x32_bf16 v[98:101], v[154:157], v[206:209], v[98:101]
	v_mfma_f32_16x16x32_bf16 v[90:93], v[162:165], v[206:209], v[90:93]
	v_mfma_f32_16x16x32_bf16 v[82:85], v[154:157], v[214:217], v[82:85]
	v_mfma_f32_16x16x32_bf16 v[74:77], v[162:165], v[214:217], v[74:77]
	v_mfma_f32_16x16x32_bf16 v[126:129], v[158:161], v[194:197], v[126:129]
	v_mfma_f32_16x16x32_bf16 v[122:125], v[166:169], v[194:197], v[122:125]
	v_mfma_f32_16x16x32_bf16 v[114:117], v[158:161], v[202:205], v[114:117]
	v_mfma_f32_16x16x32_bf16 v[106:109], v[166:169], v[202:205], v[106:109]
	v_mfma_f32_16x16x32_bf16 v[98:101], v[158:161], v[210:213], v[98:101]
	v_mfma_f32_16x16x32_bf16 v[90:93], v[166:169], v[210:213], v[90:93]
	v_mfma_f32_16x16x32_bf16 v[82:85], v[158:161], v[218:221], v[82:85]
	v_mfma_f32_16x16x32_bf16 v[74:77], v[166:169], v[218:221], v[74:77]
	v_mfma_f32_16x16x32_bf16 v[118:121], v[170:173], v[190:193], v[118:121]
	v_mfma_f32_16x16x32_bf16 v[110:113], v[182:185], v[190:193], v[110:113]
	v_mfma_f32_16x16x32_bf16 v[102:105], v[170:173], v[198:201], v[102:105]
	v_mfma_f32_16x16x32_bf16 v[94:97], v[182:185], v[198:201], v[94:97]
	v_mfma_f32_16x16x32_bf16 v[86:89], v[170:173], v[206:209], v[86:89]
	v_mfma_f32_16x16x32_bf16 v[78:81], v[182:185], v[206:209], v[78:81]
	v_mfma_f32_16x16x32_bf16 v[70:73], v[170:173], v[214:217], v[70:73]
	v_mfma_f32_16x16x32_bf16 v[66:69], v[182:185], v[214:217], v[66:69]
	v_mfma_f32_16x16x32_bf16 v[118:121], v[178:181], v[194:197], v[118:121]
	v_mfma_f32_16x16x32_bf16 v[110:113], v[186:189], v[194:197], v[110:113]
	v_mfma_f32_16x16x32_bf16 v[102:105], v[178:181], v[202:205], v[102:105]
	v_mfma_f32_16x16x32_bf16 v[94:97], v[186:189], v[202:205], v[94:97]
	v_mfma_f32_16x16x32_bf16 v[86:89], v[178:181], v[210:213], v[86:89]
	v_mfma_f32_16x16x32_bf16 v[78:81], v[186:189], v[210:213], v[78:81]
	v_mfma_f32_16x16x32_bf16 v[70:73], v[178:181], v[218:221], v[70:73]
	v_mfma_f32_16x16x32_bf16 v[66:69], v[186:189], v[218:221], v[66:69]
	s_setprio 0
	s_barrier
	s_add_i32 s2, s53, s34
	v_lshl_add_u64 v[144:145], v[144:145], 0, s[6:7]
	s_mov_b32 m0, s2
	ds_read_b128 v[190:193], v153 offset:49152
	ds_read_b128 v[194:197], v153 offset:50176
	ds_read_b128 v[198:201], v153 offset:51200
	ds_read_b128 v[202:205], v153 offset:52224
	ds_read_b128 v[206:209], v153 offset:53248
	ds_read_b128 v[210:213], v153 offset:54272
	ds_read_b128 v[214:217], v153 offset:55296
	ds_read_b128 v[218:221], v153 offset:56320
	global_load_lds_dwordx4 v[144:145], off
	s_add_i32 m0, s2, 0x2000
	s_add_u32 s2, s28, 0x40080
	v_lshl_add_u64 v[144:145], v[174:175], 0, s[6:7]
	s_addc_u32 s3, s29, 0
	s_add_i32 s28, s54, s34
	global_load_lds_dwordx4 v[144:145], off
	v_lshl_add_u64 v[144:145], s[2:3], 0, v[134:135]
	s_mov_b32 m0, s28
	s_nop 0
	global_load_lds_dwordx4 v[144:145], off
	v_lshl_add_u64 v[144:145], s[2:3], 0, v[130:131]
	s_add_i32 m0, s28, 0x2000
	s_nop 0
	global_load_lds_dwordx4 v[144:145], off
	v_lshl_add_u64 v[144:145], v[222:223], 0, s[6:7]
	s_mov_b32 m0, s41
	s_nop 0
	global_load_lds_dwordx4 v[144:145], off
	v_lshl_add_u64 v[144:145], v[224:225], 0, s[6:7]
	s_mov_b32 m0, s42
	s_nop 0
	global_load_lds_dwordx4 v[144:145], off
	s_waitcnt vmcnt(8)
	s_waitcnt lgkmcnt(0)
	s_barrier
	s_setprio 1
	v_mfma_f32_16x16x32_bf16 v[62:65], v[154:157], v[190:193], v[62:65]
	v_mfma_f32_16x16x32_bf16 v[58:61], v[162:165], v[190:193], v[58:61]
	v_mfma_f32_16x16x32_bf16 v[50:53], v[154:157], v[198:201], v[50:53]
	v_mfma_f32_16x16x32_bf16 v[42:45], v[162:165], v[198:201], v[42:45]
	v_mfma_f32_16x16x32_bf16 v[34:37], v[154:157], v[206:209], v[34:37]
	v_mfma_f32_16x16x32_bf16 v[26:29], v[162:165], v[206:209], v[26:29]
	v_mfma_f32_16x16x32_bf16 v[18:21], v[154:157], v[214:217], v[18:21]
	v_mfma_f32_16x16x32_bf16 v[10:13], v[162:165], v[214:217], v[10:13]
	v_mfma_f32_16x16x32_bf16 v[62:65], v[158:161], v[194:197], v[62:65]
	v_mfma_f32_16x16x32_bf16 v[58:61], v[166:169], v[194:197], v[58:61]
	v_mfma_f32_16x16x32_bf16 v[50:53], v[158:161], v[202:205], v[50:53]
	v_mfma_f32_16x16x32_bf16 v[42:45], v[166:169], v[202:205], v[42:45]
	v_mfma_f32_16x16x32_bf16 v[34:37], v[158:161], v[210:213], v[34:37]
	v_mfma_f32_16x16x32_bf16 v[26:29], v[166:169], v[210:213], v[26:29]
	v_mfma_f32_16x16x32_bf16 v[18:21], v[158:161], v[218:221], v[18:21]
	v_mfma_f32_16x16x32_bf16 v[10:13], v[166:169], v[218:221], v[10:13]
	v_mfma_f32_16x16x32_bf16 v[54:57], v[170:173], v[190:193], v[54:57]
	v_mfma_f32_16x16x32_bf16 v[46:49], v[182:185], v[190:193], v[46:49]
	v_mfma_f32_16x16x32_bf16 v[38:41], v[170:173], v[198:201], v[38:41]
	v_mfma_f32_16x16x32_bf16 v[30:33], v[182:185], v[198:201], v[30:33]
	v_mfma_f32_16x16x32_bf16 v[22:25], v[170:173], v[206:209], v[22:25]
	v_mfma_f32_16x16x32_bf16 v[14:17], v[182:185], v[206:209], v[14:17]
	v_mfma_f32_16x16x32_bf16 v[6:9], v[170:173], v[214:217], v[6:9]
	v_mfma_f32_16x16x32_bf16 v[2:5], v[182:185], v[214:217], v[2:5]
	v_mfma_f32_16x16x32_bf16 v[54:57], v[178:181], v[194:197], v[54:57]
	v_mfma_f32_16x16x32_bf16 v[46:49], v[186:189], v[194:197], v[46:49]
	v_mfma_f32_16x16x32_bf16 v[38:41], v[178:181], v[202:205], v[38:41]
	v_mfma_f32_16x16x32_bf16 v[30:33], v[186:189], v[202:205], v[30:33]
	v_mfma_f32_16x16x32_bf16 v[22:25], v[178:181], v[210:213], v[22:25]
	v_mfma_f32_16x16x32_bf16 v[14:17], v[186:189], v[210:213], v[14:17]
	v_mfma_f32_16x16x32_bf16 v[6:9], v[178:181], v[218:221], v[6:9]
	v_mfma_f32_16x16x32_bf16 v[2:5], v[186:189], v[218:221], v[2:5]
	s_setprio 0
	s_barrier
	s_add_i32 s52, s52, 2
	s_add_u32 s26, s26, 0x100
	s_addc_u32 s27, s27, 0
	s_add_u32 s50, s50, 0x100
	s_addc_u32 s51, s51, 0
	s_cmp_gt_u32 s52, 13
	s_cbranch_scc0 .LBB0_555
	s_branch .Lpk555_exit
.LBB0_555:
	ds_read_b128 v[154:157], v151
	ds_read_b128 v[158:161], v151 offset:1024
	ds_read_b128 v[162:165], v151 offset:2048
	ds_read_b128 v[166:169], v151 offset:3072
	ds_read_b128 v[170:173], v152
	ds_read_b128 v[178:181], v152 offset:1024
	ds_read_b128 v[182:185], v152 offset:2048
	ds_read_b128 v[186:189], v152 offset:3072
	s_add_u32 s2, s26, 0xfffc0080
	s_addc_u32 s3, s27, -1
	s_cmp_eq_u32 s52, 12
	s_cselect_b32 s3, s11, s3
	s_cselect_b32 s2, s13, s2
	s_cselect_b32 s29, s48, s51
	s_cselect_b32 s28, s49, s50
	v_lshl_add_u64 v[144:145], s[26:27], 0, v[138:139]
	s_add_i32 m0, s37, 0xc000
	ds_read_b128 v[190:193], v153
	ds_read_b128 v[194:197], v153 offset:1024
	ds_read_b128 v[198:201], v153 offset:2048
	ds_read_b128 v[202:205], v153 offset:3072
	ds_read_b128 v[206:209], v153 offset:4096
	ds_read_b128 v[210:213], v153 offset:5120
	ds_read_b128 v[214:217], v153 offset:6144
	ds_read_b128 v[218:221], v153 offset:7168
	global_load_lds_dwordx4 v[144:145], off
	v_lshl_add_u64 v[144:145], s[26:27], 0, v[140:141]
	s_add_i32 m0, s37, 0xe000
	s_nop 0
	global_load_lds_dwordx4 v[144:145], off
	s_waitcnt vmcnt(8)
	s_waitcnt lgkmcnt(0)
	s_barrier
	s_setprio 1
	v_mfma_f32_16x16x32_bf16 v[126:129], v[154:157], v[190:193], v[126:129]
	v_mfma_f32_16x16x32_bf16 v[122:125], v[162:165], v[190:193], v[122:125]
	v_mfma_f32_16x16x32_bf16 v[114:117], v[154:157], v[198:201], v[114:117]
	v_mfma_f32_16x16x32_bf16 v[106:109], v[162:165], v[198:201], v[106:109]
	v_mfma_f32_16x16x32_bf16 v[98:101], v[154:157], v[206:209], v[98:101]
	v_mfma_f32_16x16x32_bf16 v[90:93], v[162:165], v[206:209], v[90:93]
	v_mfma_f32_16x16x32_bf16 v[82:85], v[154:157], v[214:217], v[82:85]
	v_mfma_f32_16x16x32_bf16 v[74:77], v[162:165], v[214:217], v[74:77]
	v_mfma_f32_16x16x32_bf16 v[126:129], v[158:161], v[194:197], v[126:129]
	v_mfma_f32_16x16x32_bf16 v[122:125], v[166:169], v[194:197], v[122:125]
	v_mfma_f32_16x16x32_bf16 v[114:117], v[158:161], v[202:205], v[114:117]
	v_mfma_f32_16x16x32_bf16 v[106:109], v[166:169], v[202:205], v[106:109]
	v_mfma_f32_16x16x32_bf16 v[98:101], v[158:161], v[210:213], v[98:101]
	v_mfma_f32_16x16x32_bf16 v[90:93], v[166:169], v[210:213], v[90:93]
	v_mfma_f32_16x16x32_bf16 v[82:85], v[158:161], v[218:221], v[82:85]
	v_mfma_f32_16x16x32_bf16 v[74:77], v[166:169], v[218:221], v[74:77]
	v_mfma_f32_16x16x32_bf16 v[118:121], v[170:173], v[190:193], v[118:121]
	v_mfma_f32_16x16x32_bf16 v[110:113], v[182:185], v[190:193], v[110:113]
	v_mfma_f32_16x16x32_bf16 v[102:105], v[170:173], v[198:201], v[102:105]
	v_mfma_f32_16x16x32_bf16 v[94:97], v[182:185], v[198:201], v[94:97]
	v_mfma_f32_16x16x32_bf16 v[86:89], v[170:173], v[206:209], v[86:89]
	v_mfma_f32_16x16x32_bf16 v[78:81], v[182:185], v[206:209], v[78:81]
	v_mfma_f32_16x16x32_bf16 v[70:73], v[170:173], v[214:217], v[70:73]
	v_mfma_f32_16x16x32_bf16 v[66:69], v[182:185], v[214:217], v[66:69]
	v_mfma_f32_16x16x32_bf16 v[118:121], v[178:181], v[194:197], v[118:121]
	v_mfma_f32_16x16x32_bf16 v[110:113], v[186:189], v[194:197], v[110:113]
	v_mfma_f32_16x16x32_bf16 v[102:105], v[178:181], v[202:205], v[102:105]
	v_mfma_f32_16x16x32_bf16 v[94:97], v[186:189], v[202:205], v[94:97]
	v_mfma_f32_16x16x32_bf16 v[86:89], v[178:181], v[210:213], v[86:89]
	v_mfma_f32_16x16x32_bf16 v[78:81], v[186:189], v[210:213], v[78:81]
	v_mfma_f32_16x16x32_bf16 v[70:73], v[178:181], v[218:221], v[70:73]
	v_mfma_f32_16x16x32_bf16 v[66:69], v[186:189], v[218:221], v[66:69]
	s_setprio 0
	s_barrier
	s_add_i32 s53, s44, s34
	v_lshl_add_u64 v[144:145], s[28:29], 0, v[134:135]
	s_mov_b32 m0, s53
	ds_read_b128 v[190:193], v153 offset:16384
	ds_read_b128 v[194:197], v153 offset:17408
	ds_read_b128 v[198:201], v153 offset:18432
	ds_read_b128 v[202:205], v153 offset:19456
	ds_read_b128 v[206:209], v153 offset:20480
	ds_read_b128 v[210:213], v153 offset:21504
	ds_read_b128 v[214:217], v153 offset:22528
	ds_read_b128 v[218:221], v153 offset:23552
	global_load_lds_dwordx4 v[144:145], off
	s_add_i32 m0, s53, 0x2000
	s_add_u32 s54, s28, 0x40000
	v_lshl_add_u64 v[174:175], s[28:29], 0, v[130:131]
	s_addc_u32 s55, s29, 0
	s_add_i32 s53, s45, s34
	global_load_lds_dwordx4 v[174:175], off
	v_lshl_add_u64 v[222:223], s[54:55], 0, v[134:135]
	s_mov_b32 m0, s53
	v_lshl_add_u64 v[224:225], s[2:3], 0, v[132:133]
	global_load_lds_dwordx4 v[222:223], off
	v_lshl_add_u64 v[222:223], s[54:55], 0, v[130:131]
	s_add_i32 m0, s53, 0x2000
	s_nop 0
	global_load_lds_dwordx4 v[222:223], off
	v_lshl_add_u64 v[222:223], s[2:3], 0, v[136:137]
	s_mov_b32 m0, s37
	s_nop 0
	global_load_lds_dwordx4 v[222:223], off
	s_mov_b32 m0, s25
	s_nop 0
	global_load_lds_dwordx4 v[224:225], off
	s_waitcnt vmcnt(8)
	s_waitcnt lgkmcnt(0)
	s_barrier
	s_setprio 1
	v_mfma_f32_16x16x32_bf16 v[62:65], v[154:157], v[190:193], v[62:65]
	v_mfma_f32_16x16x32_bf16 v[58:61], v[162:165], v[190:193], v[58:61]
	v_mfma_f32_16x16x32_bf16 v[50:53], v[154:157], v[198:201], v[50:53]
	v_mfma_f32_16x16x32_bf16 v[42:45], v[162:165], v[198:201], v[42:45]
	v_mfma_f32_16x16x32_bf16 v[34:37], v[154:157], v[206:209], v[34:37]
	v_mfma_f32_16x16x32_bf16 v[26:29], v[162:165], v[206:209], v[26:29]
	v_mfma_f32_16x16x32_bf16 v[18:21], v[154:157], v[214:217], v[18:21]
	v_mfma_f32_16x16x32_bf16 v[10:13], v[162:165], v[214:217], v[10:13]
	v_mfma_f32_16x16x32_bf16 v[62:65], v[158:161], v[194:197], v[62:65]
	v_mfma_f32_16x16x32_bf16 v[58:61], v[166:169], v[194:197], v[58:61]
	v_mfma_f32_16x16x32_bf16 v[50:53], v[158:161], v[202:205], v[50:53]
	v_mfma_f32_16x16x32_bf16 v[42:45], v[166:169], v[202:205], v[42:45]
	v_mfma_f32_16x16x32_bf16 v[34:37], v[158:161], v[210:213], v[34:37]
	v_mfma_f32_16x16x32_bf16 v[26:29], v[166:169], v[210:213], v[26:29]
	v_mfma_f32_16x16x32_bf16 v[18:21], v[158:161], v[218:221], v[18:21]
	v_mfma_f32_16x16x32_bf16 v[10:13], v[166:169], v[218:221], v[10:13]
	v_mfma_f32_16x16x32_bf16 v[54:57], v[170:173], v[190:193], v[54:57]
	v_mfma_f32_16x16x32_bf16 v[46:49], v[182:185], v[190:193], v[46:49]
	v_mfma_f32_16x16x32_bf16 v[38:41], v[170:173], v[198:201], v[38:41]
	v_mfma_f32_16x16x32_bf16 v[30:33], v[182:185], v[198:201], v[30:33]
	v_mfma_f32_16x16x32_bf16 v[22:25], v[170:173], v[206:209], v[22:25]
	v_mfma_f32_16x16x32_bf16 v[14:17], v[182:185], v[206:209], v[14:17]
	v_mfma_f32_16x16x32_bf16 v[6:9], v[170:173], v[214:217], v[6:9]
	v_mfma_f32_16x16x32_bf16 v[2:5], v[182:185], v[214:217], v[2:5]
	v_mfma_f32_16x16x32_bf16 v[54:57], v[178:181], v[194:197], v[54:57]
	v_mfma_f32_16x16x32_bf16 v[46:49], v[186:189], v[194:197], v[46:49]
	v_mfma_f32_16x16x32_bf16 v[38:41], v[178:181], v[202:205], v[38:41]
	v_mfma_f32_16x16x32_bf16 v[30:33], v[186:189], v[202:205], v[30:33]
	v_mfma_f32_16x16x32_bf16 v[22:25], v[178:181], v[210:213], v[22:25]
	v_mfma_f32_16x16x32_bf16 v[14:17], v[186:189], v[210:213], v[14:17]
	v_mfma_f32_16x16x32_bf16 v[6:9], v[178:181], v[218:221], v[6:9]
	v_mfma_f32_16x16x32_bf16 v[2:5], v[186:189], v[218:221], v[2:5]
	s_setprio 0
	s_barrier
	s_add_i32 s53, 0, 0x18000
	s_add_i32 s54, 0, 0x1c000
	v_add_u32_e32 v166, s53, v149
	v_add_u32_e32 v176, s54, v149
	ds_read_b128 v[154:157], v166
	ds_read_b128 v[158:161], v166 offset:1024
	ds_read_b128 v[162:165], v166 offset:2048
	ds_read_b128 v[166:169], v166 offset:3072
	ds_read_b128 v[170:173], v176
	ds_read_b128 v[178:181], v176 offset:1024
	ds_read_b128 v[182:185], v176 offset:2048
	ds_read_b128 v[186:189], v176 offset:3072
	s_add_u32 s2, s2, 0x40000
	s_addc_u32 s3, s3, 0
	s_mov_b32 m0, s38
	v_lshl_add_u64 v[226:227], s[2:3], 0, v[136:137]
	ds_read_b128 v[190:193], v153 offset:32768
	ds_read_b128 v[194:197], v153 offset:33792
	ds_read_b128 v[198:201], v153 offset:34816
	ds_read_b128 v[202:205], v153 offset:35840
	ds_read_b128 v[206:209], v153 offset:36864
	ds_read_b128 v[210:213], v153 offset:37888
	ds_read_b128 v[214:217], v153 offset:38912
	ds_read_b128 v[218:221], v153 offset:39936
	global_load_lds_dwordx4 v[226:227], off
	v_lshl_add_u64 v[226:227], s[2:3], 0, v[132:133]
	s_mov_b32 m0, s39
	s_nop 0
	global_load_lds_dwordx4 v[226:227], off
	s_waitcnt vmcnt(8)
	s_waitcnt lgkmcnt(0)
	s_barrier
	s_setprio 1
	v_mfma_f32_16x16x32_bf16 v[126:129], v[154:157], v[190:193], v[126:129]
	v_mfma_f32_16x16x32_bf16 v[122:125], v[162:165], v[190:193], v[122:125]
	v_mfma_f32_16x16x32_bf16 v[114:117], v[154:157], v[198:201], v[114:117]
	v_mfma_f32_16x16x32_bf16 v[106:109], v[162:165], v[198:201], v[106:109]
	v_mfma_f32_16x16x32_bf16 v[98:101], v[154:157], v[206:209], v[98:101]
	v_mfma_f32_16x16x32_bf16 v[90:93], v[162:165], v[206:209], v[90:93]
	v_mfma_f32_16x16x32_bf16 v[82:85], v[154:157], v[214:217], v[82:85]
	v_mfma_f32_16x16x32_bf16 v[74:77], v[162:165], v[214:217], v[74:77]
	v_mfma_f32_16x16x32_bf16 v[126:129], v[158:161], v[194:197], v[126:129]
	v_mfma_f32_16x16x32_bf16 v[122:125], v[166:169], v[194:197], v[122:125]
	v_mfma_f32_16x16x32_bf16 v[114:117], v[158:161], v[202:205], v[114:117]
	v_mfma_f32_16x16x32_bf16 v[106:109], v[166:169], v[202:205], v[106:109]
	v_mfma_f32_16x16x32_bf16 v[98:101], v[158:161], v[210:213], v[98:101]
	v_mfma_f32_16x16x32_bf16 v[90:93], v[166:169], v[210:213], v[90:93]
	v_mfma_f32_16x16x32_bf16 v[82:85], v[158:161], v[218:221], v[82:85]
	v_mfma_f32_16x16x32_bf16 v[74:77], v[166:169], v[218:221], v[74:77]
	v_mfma_f32_16x16x32_bf16 v[118:121], v[170:173], v[190:193], v[118:121]
	v_mfma_f32_16x16x32_bf16 v[110:113], v[182:185], v[190:193], v[110:113]
	v_mfma_f32_16x16x32_bf16 v[102:105], v[170:173], v[198:201], v[102:105]
	v_mfma_f32_16x16x32_bf16 v[94:97], v[182:185], v[198:201], v[94:97]
	v_mfma_f32_16x16x32_bf16 v[86:89], v[170:173], v[206:209], v[86:89]
	v_mfma_f32_16x16x32_bf16 v[78:81], v[182:185], v[206:209], v[78:81]
	v_mfma_f32_16x16x32_bf16 v[70:73], v[170:173], v[214:217], v[70:73]
	v_mfma_f32_16x16x32_bf16 v[66:69], v[182:185], v[214:217], v[66:69]
	v_mfma_f32_16x16x32_bf16 v[118:121], v[178:181], v[194:197], v[118:121]
	v_mfma_f32_16x16x32_bf16 v[110:113], v[186:189], v[194:197], v[110:113]
	v_mfma_f32_16x16x32_bf16 v[102:105], v[178:181], v[202:205], v[102:105]
	v_mfma_f32_16x16x32_bf16 v[94:97], v[186:189], v[202:205], v[94:97]
	v_mfma_f32_16x16x32_bf16 v[86:89], v[178:181], v[210:213], v[86:89]
	v_mfma_f32_16x16x32_bf16 v[78:81], v[186:189], v[210:213], v[78:81]
	v_mfma_f32_16x16x32_bf16 v[70:73], v[178:181], v[218:221], v[70:73]
	v_mfma_f32_16x16x32_bf16 v[66:69], v[186:189], v[218:221], v[66:69]
	s_setprio 0
	s_barrier
	s_add_i32 s2, s53, s34
	v_lshl_add_u64 v[144:145], v[144:145], 0, s[6:7]
	s_mov_b32 m0, s2
	ds_read_b128 v[190:193], v153 offset:49152
	ds_read_b128 v[194:197], v153 offset:50176
	ds_read_b128 v[198:201], v153 offset:51200
	ds_read_b128 v[202:205], v153 offset:52224
	ds_read_b128 v[206:209], v153 offset:53248
	ds_read_b128 v[210:213], v153 offset:54272
	ds_read_b128 v[214:217], v153 offset:55296
	ds_read_b128 v[218:221], v153 offset:56320
	global_load_lds_dwordx4 v[144:145], off
	s_add_i32 m0, s2, 0x2000
	s_add_u32 s2, s28, 0x40080
	v_lshl_add_u64 v[144:145], v[174:175], 0, s[6:7]
	s_addc_u32 s3, s29, 0
	s_add_i32 s28, s54, s34
	global_load_lds_dwordx4 v[144:145], off
	v_lshl_add_u64 v[144:145], s[2:3], 0, v[134:135]
	s_mov_b32 m0, s28
	s_nop 0
	global_load_lds_dwordx4 v[144:145], off
	v_lshl_add_u64 v[144:145], s[2:3], 0, v[130:131]
	s_add_i32 m0, s28, 0x2000
	s_nop 0
	global_load_lds_dwordx4 v[144:145], off
	v_lshl_add_u64 v[144:145], v[222:223], 0, s[6:7]
	s_mov_b32 m0, s41
	s_nop 0
	global_load_lds_dwordx4 v[144:145], off
	v_lshl_add_u64 v[144:145], v[224:225], 0, s[6:7]
	s_mov_b32 m0, s42
	s_nop 0
	global_load_lds_dwordx4 v[144:145], off
	s_waitcnt vmcnt(8)
	s_waitcnt lgkmcnt(0)
	s_barrier
	s_setprio 1
	v_mfma_f32_16x16x32_bf16 v[62:65], v[154:157], v[190:193], v[62:65]
	v_mfma_f32_16x16x32_bf16 v[58:61], v[162:165], v[190:193], v[58:61]
	v_mfma_f32_16x16x32_bf16 v[50:53], v[154:157], v[198:201], v[50:53]
	v_mfma_f32_16x16x32_bf16 v[42:45], v[162:165], v[198:201], v[42:45]
	v_mfma_f32_16x16x32_bf16 v[34:37], v[154:157], v[206:209], v[34:37]
	v_mfma_f32_16x16x32_bf16 v[26:29], v[162:165], v[206:209], v[26:29]
	v_mfma_f32_16x16x32_bf16 v[18:21], v[154:157], v[214:217], v[18:21]
	v_mfma_f32_16x16x32_bf16 v[10:13], v[162:165], v[214:217], v[10:13]
	v_mfma_f32_16x16x32_bf16 v[62:65], v[158:161], v[194:197], v[62:65]
	v_mfma_f32_16x16x32_bf16 v[58:61], v[166:169], v[194:197], v[58:61]
	v_mfma_f32_16x16x32_bf16 v[50:53], v[158:161], v[202:205], v[50:53]
	v_mfma_f32_16x16x32_bf16 v[42:45], v[166:169], v[202:205], v[42:45]
	v_mfma_f32_16x16x32_bf16 v[34:37], v[158:161], v[210:213], v[34:37]
	v_mfma_f32_16x16x32_bf16 v[26:29], v[166:169], v[210:213], v[26:29]
	v_mfma_f32_16x16x32_bf16 v[18:21], v[158:161], v[218:221], v[18:21]
	v_mfma_f32_16x16x32_bf16 v[10:13], v[166:169], v[218:221], v[10:13]
	v_mfma_f32_16x16x32_bf16 v[54:57], v[170:173], v[190:193], v[54:57]
	v_mfma_f32_16x16x32_bf16 v[46:49], v[182:185], v[190:193], v[46:49]
	v_mfma_f32_16x16x32_bf16 v[38:41], v[170:173], v[198:201], v[38:41]
	v_mfma_f32_16x16x32_bf16 v[30:33], v[182:185], v[198:201], v[30:33]
	v_mfma_f32_16x16x32_bf16 v[22:25], v[170:173], v[206:209], v[22:25]
	v_mfma_f32_16x16x32_bf16 v[14:17], v[182:185], v[206:209], v[14:17]
	v_mfma_f32_16x16x32_bf16 v[6:9], v[170:173], v[214:217], v[6:9]
	v_mfma_f32_16x16x32_bf16 v[2:5], v[182:185], v[214:217], v[2:5]
	v_mfma_f32_16x16x32_bf16 v[54:57], v[178:181], v[194:197], v[54:57]
	v_mfma_f32_16x16x32_bf16 v[46:49], v[186:189], v[194:197], v[46:49]
	v_mfma_f32_16x16x32_bf16 v[38:41], v[178:181], v[202:205], v[38:41]
	v_mfma_f32_16x16x32_bf16 v[30:33], v[186:189], v[202:205], v[30:33]
	v_mfma_f32_16x16x32_bf16 v[22:25], v[178:181], v[210:213], v[22:25]
	v_mfma_f32_16x16x32_bf16 v[14:17], v[186:189], v[210:213], v[14:17]
	v_mfma_f32_16x16x32_bf16 v[6:9], v[178:181], v[218:221], v[6:9]
	v_mfma_f32_16x16x32_bf16 v[2:5], v[186:189], v[218:221], v[2:5]
	s_setprio 0
	s_barrier
	s_add_i32 s52, s52, 2
	s_add_u32 s26, s26, 0x100
	s_addc_u32 s27, s27, 0
	s_add_u32 s50, s50, 0x100
	s_addc_u32 s51, s51, 0
	s_cmp_gt_u32 s52, 13
	s_cbranch_scc0 .LBB0_555

.LBB0_646:
	ds_read_b128 v[152:155], v146
	ds_read_b128 v[156:159], v146 offset:1024
	ds_read_b128 v[160:163], v146 offset:2048
	ds_read_b128 v[164:167], v146 offset:3072
	ds_read_b128 v[168:171], v147
	ds_read_b128 v[172:175], v147 offset:1024
	ds_read_b128 v[178:181], v147 offset:2048
	ds_read_b128 v[182:185], v147 offset:3072
	s_add_u32 s2, s10, s12
	s_addc_u32 s3, s11, s13
	s_add_u32 s2, s2, 0x3400100
	s_addc_u32 s3, s3, 0
	s_add_u32 s14, s24, s12
	s_addc_u32 s15, s25, s13
	s_cmpk_eq_i32 s12, 0x700
	s_cselect_b32 s3, s7, s3
	s_cselect_b32 s2, s6, s2
	s_cselect_b32 s15, s5, s15
	s_cselect_b32 s14, s4, s14
	s_mov_b32 m0, s27
	v_lshl_add_u64 v[218:219], v[138:139], 0, s[12:13]
	ds_read_b128 v[186:189], v148
	ds_read_b128 v[190:193], v148 offset:1024
	ds_read_b128 v[194:197], v148 offset:2048
	ds_read_b128 v[198:201], v148 offset:3072
	ds_read_b128 v[202:205], v148 offset:4096
	ds_read_b128 v[206:209], v148 offset:5120
	ds_read_b128 v[210:213], v148 offset:6144
	ds_read_b128 v[214:217], v148 offset:7168
	global_load_lds_dwordx4 v[218:219], off
	v_lshl_add_u64 v[218:219], v[140:141], 0, s[12:13]
	s_mov_b32 m0, s28
	s_nop 0
	global_load_lds_dwordx4 v[218:219], off
	s_waitcnt vmcnt(8)
	s_waitcnt lgkmcnt(0)
	s_barrier
	s_setprio 1
	v_mfma_f32_16x16x32_bf16 v[126:129], v[152:155], v[186:189], v[126:129]
	v_mfma_f32_16x16x32_bf16 v[122:125], v[160:163], v[186:189], v[122:125]
	v_mfma_f32_16x16x32_bf16 v[114:117], v[152:155], v[194:197], v[114:117]
	v_mfma_f32_16x16x32_bf16 v[106:109], v[160:163], v[194:197], v[106:109]
	v_mfma_f32_16x16x32_bf16 v[98:101], v[152:155], v[202:205], v[98:101]
	v_mfma_f32_16x16x32_bf16 v[90:93], v[160:163], v[202:205], v[90:93]
	v_mfma_f32_16x16x32_bf16 v[82:85], v[152:155], v[210:213], v[82:85]
	v_mfma_f32_16x16x32_bf16 v[74:77], v[160:163], v[210:213], v[74:77]
	v_mfma_f32_16x16x32_bf16 v[126:129], v[156:159], v[190:193], v[126:129]
	v_mfma_f32_16x16x32_bf16 v[122:125], v[164:167], v[190:193], v[122:125]
	v_mfma_f32_16x16x32_bf16 v[114:117], v[156:159], v[198:201], v[114:117]
	v_mfma_f32_16x16x32_bf16 v[106:109], v[164:167], v[198:201], v[106:109]
	v_mfma_f32_16x16x32_bf16 v[98:101], v[156:159], v[206:209], v[98:101]
	v_mfma_f32_16x16x32_bf16 v[90:93], v[164:167], v[206:209], v[90:93]
	v_mfma_f32_16x16x32_bf16 v[82:85], v[156:159], v[214:217], v[82:85]
	v_mfma_f32_16x16x32_bf16 v[74:77], v[164:167], v[214:217], v[74:77]
	v_mfma_f32_16x16x32_bf16 v[118:121], v[168:171], v[186:189], v[118:121]
	v_mfma_f32_16x16x32_bf16 v[110:113], v[178:181], v[186:189], v[110:113]
	v_mfma_f32_16x16x32_bf16 v[102:105], v[168:171], v[194:197], v[102:105]
	v_mfma_f32_16x16x32_bf16 v[94:97], v[178:181], v[194:197], v[94:97]
	v_mfma_f32_16x16x32_bf16 v[86:89], v[168:171], v[202:205], v[86:89]
	v_mfma_f32_16x16x32_bf16 v[78:81], v[178:181], v[202:205], v[78:81]
	v_mfma_f32_16x16x32_bf16 v[70:73], v[168:171], v[210:213], v[70:73]
	v_mfma_f32_16x16x32_bf16 v[66:69], v[178:181], v[210:213], v[66:69]
	v_mfma_f32_16x16x32_bf16 v[118:121], v[172:175], v[190:193], v[118:121]
	v_mfma_f32_16x16x32_bf16 v[110:113], v[182:185], v[190:193], v[110:113]
	v_mfma_f32_16x16x32_bf16 v[102:105], v[172:175], v[198:201], v[102:105]
	v_mfma_f32_16x16x32_bf16 v[94:97], v[182:185], v[198:201], v[94:97]
	v_mfma_f32_16x16x32_bf16 v[86:89], v[172:175], v[206:209], v[86:89]
	v_mfma_f32_16x16x32_bf16 v[78:81], v[182:185], v[206:209], v[78:81]
	v_mfma_f32_16x16x32_bf16 v[70:73], v[172:175], v[214:217], v[70:73]
	v_mfma_f32_16x16x32_bf16 v[66:69], v[182:185], v[214:217], v[66:69]
	s_setprio 0
	s_barrier
	s_mov_b32 m0, s29
	v_lshl_add_u64 v[218:219], s[14:15], 0, v[134:135]
	s_add_u32 s40, s14, 0x40000
	ds_read_b128 v[186:189], v148 offset:16384
	ds_read_b128 v[190:193], v148 offset:17408
	ds_read_b128 v[194:197], v148 offset:18432
	ds_read_b128 v[198:201], v148 offset:19456
	ds_read_b128 v[202:205], v148 offset:20480
	ds_read_b128 v[206:209], v148 offset:21504
	ds_read_b128 v[210:213], v148 offset:22528
	ds_read_b128 v[214:217], v148 offset:23552
	global_load_lds_dwordx4 v[218:219], off
	v_lshl_add_u64 v[220:221], s[14:15], 0, v[130:131]
	s_mov_b32 m0, s30
	s_addc_u32 s41, s15, 0
	global_load_lds_dwordx4 v[220:221], off
	v_lshl_add_u64 v[222:223], s[40:41], 0, v[134:135]
	s_mov_b32 m0, s31
	v_lshl_add_u64 v[224:225], s[2:3], 0, v[132:133]
	global_load_lds_dwordx4 v[222:223], off
	v_lshl_add_u64 v[222:223], s[40:41], 0, v[130:131]
	s_mov_b32 m0, s34
	s_nop 0
	global_load_lds_dwordx4 v[222:223], off
	v_lshl_add_u64 v[222:223], s[2:3], 0, v[136:137]
	s_mov_b32 m0, s18
	s_nop 0
	global_load_lds_dwordx4 v[222:223], off
	s_mov_b32 m0, s1
	s_nop 0
	global_load_lds_dwordx4 v[224:225], off
	s_waitcnt vmcnt(8)
	s_waitcnt lgkmcnt(0)
	s_barrier
	s_setprio 1
	v_mfma_f32_16x16x32_bf16 v[62:65], v[152:155], v[186:189], v[62:65]
	v_mfma_f32_16x16x32_bf16 v[58:61], v[160:163], v[186:189], v[58:61]
	v_mfma_f32_16x16x32_bf16 v[50:53], v[152:155], v[194:197], v[50:53]
	v_mfma_f32_16x16x32_bf16 v[42:45], v[160:163], v[194:197], v[42:45]
	v_mfma_f32_16x16x32_bf16 v[34:37], v[152:155], v[202:205], v[34:37]
	v_mfma_f32_16x16x32_bf16 v[26:29], v[160:163], v[202:205], v[26:29]
	v_mfma_f32_16x16x32_bf16 v[18:21], v[152:155], v[210:213], v[18:21]
	v_mfma_f32_16x16x32_bf16 v[10:13], v[160:163], v[210:213], v[10:13]
	v_mfma_f32_16x16x32_bf16 v[62:65], v[156:159], v[190:193], v[62:65]
	v_mfma_f32_16x16x32_bf16 v[58:61], v[164:167], v[190:193], v[58:61]
	v_mfma_f32_16x16x32_bf16 v[50:53], v[156:159], v[198:201], v[50:53]
	v_mfma_f32_16x16x32_bf16 v[42:45], v[164:167], v[198:201], v[42:45]
	v_mfma_f32_16x16x32_bf16 v[34:37], v[156:159], v[206:209], v[34:37]
	v_mfma_f32_16x16x32_bf16 v[26:29], v[164:167], v[206:209], v[26:29]
	v_mfma_f32_16x16x32_bf16 v[18:21], v[156:159], v[214:217], v[18:21]
	v_mfma_f32_16x16x32_bf16 v[10:13], v[164:167], v[214:217], v[10:13]
	v_mfma_f32_16x16x32_bf16 v[54:57], v[168:171], v[186:189], v[54:57]
	v_mfma_f32_16x16x32_bf16 v[46:49], v[178:181], v[186:189], v[46:49]
	v_mfma_f32_16x16x32_bf16 v[38:41], v[168:171], v[194:197], v[38:41]
	v_mfma_f32_16x16x32_bf16 v[30:33], v[178:181], v[194:197], v[30:33]
	v_mfma_f32_16x16x32_bf16 v[22:25], v[168:171], v[202:205], v[22:25]
	v_mfma_f32_16x16x32_bf16 v[14:17], v[178:181], v[202:205], v[14:17]
	v_mfma_f32_16x16x32_bf16 v[6:9], v[168:171], v[210:213], v[6:9]
	v_mfma_f32_16x16x32_bf16 v[2:5], v[178:181], v[210:213], v[2:5]
	v_mfma_f32_16x16x32_bf16 v[54:57], v[172:175], v[190:193], v[54:57]
	v_mfma_f32_16x16x32_bf16 v[46:49], v[182:185], v[190:193], v[46:49]
	v_mfma_f32_16x16x32_bf16 v[38:41], v[172:175], v[198:201], v[38:41]
	v_mfma_f32_16x16x32_bf16 v[30:33], v[182:185], v[198:201], v[30:33]
	v_mfma_f32_16x16x32_bf16 v[22:25], v[172:175], v[206:209], v[22:25]
	v_mfma_f32_16x16x32_bf16 v[14:17], v[182:185], v[206:209], v[14:17]
	v_mfma_f32_16x16x32_bf16 v[6:9], v[172:175], v[214:217], v[6:9]
	v_mfma_f32_16x16x32_bf16 v[2:5], v[182:185], v[214:217], v[2:5]
	s_setprio 0
	s_barrier
	ds_read_b128 v[152:155], v149
	ds_read_b128 v[156:159], v149 offset:1024
	ds_read_b128 v[160:163], v149 offset:2048
	ds_read_b128 v[164:167], v149 offset:3072
	ds_read_b128 v[168:171], v150
	ds_read_b128 v[172:175], v150 offset:1024
	ds_read_b128 v[178:181], v150 offset:2048
	ds_read_b128 v[182:185], v150 offset:3072
	s_add_u32 s2, s2, 0x40000
	s_addc_u32 s3, s3, 0
	s_mov_b32 m0, s19
	v_lshl_add_u64 v[226:227], s[2:3], 0, v[136:137]
	ds_read_b128 v[186:189], v148 offset:32768
	ds_read_b128 v[190:193], v148 offset:33792
	ds_read_b128 v[194:197], v148 offset:34816
	ds_read_b128 v[198:201], v148 offset:35840
	ds_read_b128 v[202:205], v148 offset:36864
	ds_read_b128 v[206:209], v148 offset:37888
	ds_read_b128 v[210:213], v148 offset:38912
	ds_read_b128 v[214:217], v148 offset:39936
	global_load_lds_dwordx4 v[226:227], off
	v_lshl_add_u64 v[226:227], s[2:3], 0, v[132:133]
	s_mov_b32 m0, s20
	s_nop 0
	global_load_lds_dwordx4 v[226:227], off
	s_waitcnt vmcnt(8)
	s_waitcnt lgkmcnt(0)
	s_barrier
	s_setprio 1
	v_mfma_f32_16x16x32_bf16 v[126:129], v[152:155], v[186:189], v[126:129]
	v_mfma_f32_16x16x32_bf16 v[122:125], v[160:163], v[186:189], v[122:125]
	v_mfma_f32_16x16x32_bf16 v[114:117], v[152:155], v[194:197], v[114:117]
	v_mfma_f32_16x16x32_bf16 v[106:109], v[160:163], v[194:197], v[106:109]
	v_mfma_f32_16x16x32_bf16 v[98:101], v[152:155], v[202:205], v[98:101]
	v_mfma_f32_16x16x32_bf16 v[90:93], v[160:163], v[202:205], v[90:93]
	v_mfma_f32_16x16x32_bf16 v[82:85], v[152:155], v[210:213], v[82:85]
	v_mfma_f32_16x16x32_bf16 v[74:77], v[160:163], v[210:213], v[74:77]
	v_mfma_f32_16x16x32_bf16 v[126:129], v[156:159], v[190:193], v[126:129]
	v_mfma_f32_16x16x32_bf16 v[122:125], v[164:167], v[190:193], v[122:125]
	v_mfma_f32_16x16x32_bf16 v[114:117], v[156:159], v[198:201], v[114:117]
	v_mfma_f32_16x16x32_bf16 v[106:109], v[164:167], v[198:201], v[106:109]
	v_mfma_f32_16x16x32_bf16 v[98:101], v[156:159], v[206:209], v[98:101]
	v_mfma_f32_16x16x32_bf16 v[90:93], v[164:167], v[206:209], v[90:93]
	v_mfma_f32_16x16x32_bf16 v[82:85], v[156:159], v[214:217], v[82:85]
	v_mfma_f32_16x16x32_bf16 v[74:77], v[164:167], v[214:217], v[74:77]
	v_mfma_f32_16x16x32_bf16 v[118:121], v[168:171], v[186:189], v[118:121]
	v_mfma_f32_16x16x32_bf16 v[110:113], v[178:181], v[186:189], v[110:113]
	v_mfma_f32_16x16x32_bf16 v[102:105], v[168:171], v[194:197], v[102:105]
	v_mfma_f32_16x16x32_bf16 v[94:97], v[178:181], v[194:197], v[94:97]
	v_mfma_f32_16x16x32_bf16 v[86:89], v[168:171], v[202:205], v[86:89]
	v_mfma_f32_16x16x32_bf16 v[78:81], v[178:181], v[202:205], v[78:81]
	v_mfma_f32_16x16x32_bf16 v[70:73], v[168:171], v[210:213], v[70:73]
	v_mfma_f32_16x16x32_bf16 v[66:69], v[178:181], v[210:213], v[66:69]
	v_mfma_f32_16x16x32_bf16 v[118:121], v[172:175], v[190:193], v[118:121]
	v_mfma_f32_16x16x32_bf16 v[110:113], v[182:185], v[190:193], v[110:113]
	v_mfma_f32_16x16x32_bf16 v[102:105], v[172:175], v[198:201], v[102:105]
	v_mfma_f32_16x16x32_bf16 v[94:97], v[182:185], v[198:201], v[94:97]
	v_mfma_f32_16x16x32_bf16 v[86:89], v[172:175], v[206:209], v[86:89]
	v_mfma_f32_16x16x32_bf16 v[78:81], v[182:185], v[206:209], v[78:81]
	v_mfma_f32_16x16x32_bf16 v[70:73], v[172:175], v[214:217], v[70:73]
	v_mfma_f32_16x16x32_bf16 v[66:69], v[182:185], v[214:217], v[66:69]
	s_setprio 0
	s_barrier
	s_mov_b32 m0, s35
	v_lshl_add_u64 v[218:219], v[218:219], 0, s[8:9]
	s_add_u32 s2, s14, 0x40080
	ds_read_b128 v[186:189], v148 offset:49152
	ds_read_b128 v[190:193], v148 offset:50176
	ds_read_b128 v[194:197], v148 offset:51200
	ds_read_b128 v[198:201], v148 offset:52224
	ds_read_b128 v[202:205], v148 offset:53248
	ds_read_b128 v[206:209], v148 offset:54272
	ds_read_b128 v[210:213], v148 offset:55296
	ds_read_b128 v[214:217], v148 offset:56320
	global_load_lds_dwordx4 v[218:219], off
	v_lshl_add_u64 v[218:219], v[220:221], 0, s[8:9]
	s_mov_b32 m0, s36
	s_addc_u32 s3, s15, 0
	global_load_lds_dwordx4 v[218:219], off
	v_lshl_add_u64 v[218:219], s[2:3], 0, v[134:135]
	s_mov_b32 m0, s37
	s_nop 0
	global_load_lds_dwordx4 v[218:219], off
	v_lshl_add_u64 v[218:219], s[2:3], 0, v[130:131]
	s_mov_b32 m0, s38
	s_nop 0
	global_load_lds_dwordx4 v[218:219], off
	v_lshl_add_u64 v[218:219], v[222:223], 0, s[8:9]
	s_mov_b32 m0, s22
	s_nop 0
	global_load_lds_dwordx4 v[218:219], off
	v_lshl_add_u64 v[218:219], v[224:225], 0, s[8:9]
	s_mov_b32 m0, s23
	s_nop 0
	global_load_lds_dwordx4 v[218:219], off
	s_waitcnt vmcnt(8)
	s_waitcnt lgkmcnt(0)
	s_barrier
	s_setprio 1
	v_mfma_f32_16x16x32_bf16 v[62:65], v[152:155], v[186:189], v[62:65]
	v_mfma_f32_16x16x32_bf16 v[58:61], v[160:163], v[186:189], v[58:61]
	v_mfma_f32_16x16x32_bf16 v[50:53], v[152:155], v[194:197], v[50:53]
	v_mfma_f32_16x16x32_bf16 v[42:45], v[160:163], v[194:197], v[42:45]
	v_mfma_f32_16x16x32_bf16 v[34:37], v[152:155], v[202:205], v[34:37]
	v_mfma_f32_16x16x32_bf16 v[26:29], v[160:163], v[202:205], v[26:29]
	v_mfma_f32_16x16x32_bf16 v[18:21], v[152:155], v[210:213], v[18:21]
	v_mfma_f32_16x16x32_bf16 v[10:13], v[160:163], v[210:213], v[10:13]
	v_mfma_f32_16x16x32_bf16 v[62:65], v[156:159], v[190:193], v[62:65]
	v_mfma_f32_16x16x32_bf16 v[58:61], v[164:167], v[190:193], v[58:61]
	v_mfma_f32_16x16x32_bf16 v[50:53], v[156:159], v[198:201], v[50:53]
	v_mfma_f32_16x16x32_bf16 v[42:45], v[164:167], v[198:201], v[42:45]
	v_mfma_f32_16x16x32_bf16 v[34:37], v[156:159], v[206:209], v[34:37]
	v_mfma_f32_16x16x32_bf16 v[26:29], v[164:167], v[206:209], v[26:29]
	v_mfma_f32_16x16x32_bf16 v[18:21], v[156:159], v[214:217], v[18:21]
	v_mfma_f32_16x16x32_bf16 v[10:13], v[164:167], v[214:217], v[10:13]
	v_mfma_f32_16x16x32_bf16 v[54:57], v[168:171], v[186:189], v[54:57]
	v_mfma_f32_16x16x32_bf16 v[46:49], v[178:181], v[186:189], v[46:49]
	v_mfma_f32_16x16x32_bf16 v[38:41], v[168:171], v[194:197], v[38:41]
	v_mfma_f32_16x16x32_bf16 v[30:33], v[178:181], v[194:197], v[30:33]
	v_mfma_f32_16x16x32_bf16 v[22:25], v[168:171], v[202:205], v[22:25]
	v_mfma_f32_16x16x32_bf16 v[14:17], v[178:181], v[202:205], v[14:17]
	v_mfma_f32_16x16x32_bf16 v[6:9], v[168:171], v[210:213], v[6:9]
	v_mfma_f32_16x16x32_bf16 v[2:5], v[178:181], v[210:213], v[2:5]
	v_mfma_f32_16x16x32_bf16 v[54:57], v[172:175], v[190:193], v[54:57]
	v_mfma_f32_16x16x32_bf16 v[46:49], v[182:185], v[190:193], v[46:49]
	v_mfma_f32_16x16x32_bf16 v[38:41], v[172:175], v[198:201], v[38:41]
	v_mfma_f32_16x16x32_bf16 v[30:33], v[182:185], v[198:201], v[30:33]
	v_mfma_f32_16x16x32_bf16 v[22:25], v[172:175], v[206:209], v[22:25]
	v_mfma_f32_16x16x32_bf16 v[14:17], v[182:185], v[206:209], v[14:17]
	v_mfma_f32_16x16x32_bf16 v[6:9], v[172:175], v[214:217], v[6:9]
	v_mfma_f32_16x16x32_bf16 v[2:5], v[182:185], v[214:217], v[2:5]
	s_setprio 0
	s_barrier
	s_add_i32 s26, s26, 2
	s_add_u32 s12, s12, 0x100
	s_addc_u32 s13, s13, 0
	s_cmp_gt_u32 s26, 13
	s_cbranch_scc0 .LBB0_646
	s_cmpk_lt_u32 s16, 0x100
	s_mov_b32 s28, s33
	v_readlane_b32 s30, v253, 58
	s_cbranch_scc0 .LBB0_649
	s_barrier

.Lpk1098_peel:
	ds_read_b128 v[152:155], v148
	ds_read_b128 v[156:159], v148 offset:1024
	ds_read_b128 v[160:163], v148 offset:2048
	ds_read_b128 v[164:167], v148 offset:3072
	ds_read_b128 v[168:171], v149
	ds_read_b128 v[172:175], v149 offset:1024
	ds_read_b128 v[178:181], v149 offset:2048
	ds_read_b128 v[182:185], v149 offset:3072
	s_add_u32 s2, s30, 0xfffc0080
	s_addc_u32 s3, s31, -1
	s_cmp_eq_u32 s56, 12
	s_cselect_b32 s3, s15, s3
	s_cselect_b32 s2, s17, s2
	s_cselect_b32 s35, s52, s55
	s_cselect_b32 s34, s53, s54
	v_lshl_add_u64 v[144:145], s[30:31], 0, v[138:139]
	s_add_i32 m0, s40, 0xc000
	ds_read_b128 v[186:189], v150
	ds_read_b128 v[190:193], v150 offset:1024
	ds_read_b128 v[194:197], v150 offset:2048
	ds_read_b128 v[198:201], v150 offset:3072
	ds_read_b128 v[202:205], v150 offset:4096
	ds_read_b128 v[206:209], v150 offset:5120
	ds_read_b128 v[210:213], v150 offset:6144
	ds_read_b128 v[214:217], v150 offset:7168
	global_load_lds_dwordx4 v[144:145], off
	v_lshl_add_u64 v[144:145], s[30:31], 0, v[140:141]
	s_add_i32 m0, s40, 0xe000
	s_nop 0
	global_load_lds_dwordx4 v[144:145], off
	s_waitcnt vmcnt(8)
	s_waitcnt lgkmcnt(0)
	s_barrier
	s_setprio 1
	v_mfma_f32_16x16x32_bf16 v[126:129], v[152:155], v[186:189], 0
	v_mfma_f32_16x16x32_bf16 v[122:125], v[160:163], v[186:189], 0
	v_mfma_f32_16x16x32_bf16 v[114:117], v[152:155], v[194:197], 0
	v_mfma_f32_16x16x32_bf16 v[106:109], v[160:163], v[194:197], 0
	v_mfma_f32_16x16x32_bf16 v[98:101], v[152:155], v[202:205], 0
	v_mfma_f32_16x16x32_bf16 v[90:93], v[160:163], v[202:205], 0
	v_mfma_f32_16x16x32_bf16 v[82:85], v[152:155], v[210:213], 0
	v_mfma_f32_16x16x32_bf16 v[74:77], v[160:163], v[210:213], 0
	v_mfma_f32_16x16x32_bf16 v[126:129], v[156:159], v[190:193], v[126:129]
	v_mfma_f32_16x16x32_bf16 v[122:125], v[164:167], v[190:193], v[122:125]
	v_mfma_f32_16x16x32_bf16 v[114:117], v[156:159], v[198:201], v[114:117]
	v_mfma_f32_16x16x32_bf16 v[106:109], v[164:167], v[198:201], v[106:109]
	v_mfma_f32_16x16x32_bf16 v[98:101], v[156:159], v[206:209], v[98:101]
	v_mfma_f32_16x16x32_bf16 v[90:93], v[164:167], v[206:209], v[90:93]
	v_mfma_f32_16x16x32_bf16 v[82:85], v[156:159], v[214:217], v[82:85]
	v_mfma_f32_16x16x32_bf16 v[74:77], v[164:167], v[214:217], v[74:77]
	v_mfma_f32_16x16x32_bf16 v[118:121], v[168:171], v[186:189], 0
	v_mfma_f32_16x16x32_bf16 v[110:113], v[178:181], v[186:189], 0
	v_mfma_f32_16x16x32_bf16 v[102:105], v[168:171], v[194:197], 0
	v_mfma_f32_16x16x32_bf16 v[94:97], v[178:181], v[194:197], 0
	v_mfma_f32_16x16x32_bf16 v[86:89], v[168:171], v[202:205], 0
	v_mfma_f32_16x16x32_bf16 v[78:81], v[178:181], v[202:205], 0
	v_mfma_f32_16x16x32_bf16 v[70:73], v[168:171], v[210:213], 0
	v_mfma_f32_16x16x32_bf16 v[66:69], v[178:181], v[210:213], 0
	v_mfma_f32_16x16x32_bf16 v[118:121], v[172:175], v[190:193], v[118:121]
	v_mfma_f32_16x16x32_bf16 v[110:113], v[182:185], v[190:193], v[110:113]
	v_mfma_f32_16x16x32_bf16 v[102:105], v[172:175], v[198:201], v[102:105]
	v_mfma_f32_16x16x32_bf16 v[94:97], v[182:185], v[198:201], v[94:97]
	v_mfma_f32_16x16x32_bf16 v[86:89], v[172:175], v[206:209], v[86:89]
	v_mfma_f32_16x16x32_bf16 v[78:81], v[182:185], v[206:209], v[78:81]
	v_mfma_f32_16x16x32_bf16 v[70:73], v[172:175], v[214:217], v[70:73]
	v_mfma_f32_16x16x32_bf16 v[66:69], v[182:185], v[214:217], v[66:69]
	s_setprio 0
	s_barrier
	s_add_i32 s57, s47, s39
	v_lshl_add_u64 v[144:145], s[34:35], 0, v[132:133]
	s_mov_b32 m0, s57
	ds_read_b128 v[186:189], v150 offset:16384
	ds_read_b128 v[190:193], v150 offset:17408
	ds_read_b128 v[194:197], v150 offset:18432
	ds_read_b128 v[198:201], v150 offset:19456
	ds_read_b128 v[202:205], v150 offset:20480
	ds_read_b128 v[206:209], v150 offset:21504
	ds_read_b128 v[210:213], v150 offset:22528
	ds_read_b128 v[214:217], v150 offset:23552
	global_load_lds_dwordx4 v[144:145], off
	s_add_i32 m0, s57, 0x2000
	s_add_u32 s58, s34, 0x40000
	v_lshl_add_u64 v[218:219], s[34:35], 0, v[136:137]
	s_addc_u32 s59, s35, 0
	s_add_i32 s57, s48, s39
	global_load_lds_dwordx4 v[218:219], off
	v_lshl_add_u64 v[220:221], s[58:59], 0, v[132:133]
	s_mov_b32 m0, s57
	v_lshl_add_u64 v[222:223], s[2:3], 0, v[134:135]
	global_load_lds_dwordx4 v[220:221], off
	v_lshl_add_u64 v[220:221], s[58:59], 0, v[136:137]
	s_add_i32 m0, s57, 0x2000
	s_nop 0
	global_load_lds_dwordx4 v[220:221], off
	v_lshl_add_u64 v[220:221], s[2:3], 0, v[130:131]
	s_mov_b32 m0, s40
	s_nop 0
	global_load_lds_dwordx4 v[220:221], off
	s_mov_b32 m0, s29
	s_nop 0
	global_load_lds_dwordx4 v[222:223], off
	s_waitcnt vmcnt(8)
	s_waitcnt lgkmcnt(0)
	s_barrier
	s_setprio 1
	v_mfma_f32_16x16x32_bf16 v[62:65], v[152:155], v[186:189], 0
	v_mfma_f32_16x16x32_bf16 v[58:61], v[160:163], v[186:189], 0
	v_mfma_f32_16x16x32_bf16 v[50:53], v[152:155], v[194:197], 0
	v_mfma_f32_16x16x32_bf16 v[42:45], v[160:163], v[194:197], 0
	v_mfma_f32_16x16x32_bf16 v[34:37], v[152:155], v[202:205], 0
	v_mfma_f32_16x16x32_bf16 v[26:29], v[160:163], v[202:205], 0
	v_mfma_f32_16x16x32_bf16 v[18:21], v[152:155], v[210:213], 0
	v_mfma_f32_16x16x32_bf16 v[10:13], v[160:163], v[210:213], 0
	v_mfma_f32_16x16x32_bf16 v[62:65], v[156:159], v[190:193], v[62:65]
	v_mfma_f32_16x16x32_bf16 v[58:61], v[164:167], v[190:193], v[58:61]
	v_mfma_f32_16x16x32_bf16 v[50:53], v[156:159], v[198:201], v[50:53]
	v_mfma_f32_16x16x32_bf16 v[42:45], v[164:167], v[198:201], v[42:45]
	v_mfma_f32_16x16x32_bf16 v[34:37], v[156:159], v[206:209], v[34:37]
	v_mfma_f32_16x16x32_bf16 v[26:29], v[164:167], v[206:209], v[26:29]
	v_mfma_f32_16x16x32_bf16 v[18:21], v[156:159], v[214:217], v[18:21]
	v_mfma_f32_16x16x32_bf16 v[10:13], v[164:167], v[214:217], v[10:13]
	v_mfma_f32_16x16x32_bf16 v[54:57], v[168:171], v[186:189], 0
	v_mfma_f32_16x16x32_bf16 v[46:49], v[178:181], v[186:189], 0
	v_mfma_f32_16x16x32_bf16 v[38:41], v[168:171], v[194:197], 0
	v_mfma_f32_16x16x32_bf16 v[30:33], v[178:181], v[194:197], 0
	v_mfma_f32_16x16x32_bf16 v[22:25], v[168:171], v[202:205], 0
	v_mfma_f32_16x16x32_bf16 v[14:17], v[178:181], v[202:205], 0
	v_mfma_f32_16x16x32_bf16 v[6:9], v[168:171], v[210:213], 0
	v_mfma_f32_16x16x32_bf16 v[2:5], v[178:181], v[210:213], 0
	v_mfma_f32_16x16x32_bf16 v[54:57], v[172:175], v[190:193], v[54:57]
	v_mfma_f32_16x16x32_bf16 v[46:49], v[182:185], v[190:193], v[46:49]
	v_mfma_f32_16x16x32_bf16 v[38:41], v[172:175], v[198:201], v[38:41]
	v_mfma_f32_16x16x32_bf16 v[30:33], v[182:185], v[198:201], v[30:33]
	v_mfma_f32_16x16x32_bf16 v[22:25], v[172:175], v[206:209], v[22:25]
	v_mfma_f32_16x16x32_bf16 v[14:17], v[182:185], v[206:209], v[14:17]
	v_mfma_f32_16x16x32_bf16 v[6:9], v[172:175], v[214:217], v[6:9]
	v_mfma_f32_16x16x32_bf16 v[2:5], v[182:185], v[214:217], v[2:5]
	s_setprio 0
	s_barrier
	s_add_i32 s57, 0, 0x18000
	v_add_u32_e32 v151, s57, v146
	s_add_i32 s58, 0, 0x1c000
	ds_read_b128 v[152:155], v151
	ds_read_b128 v[156:159], v151 offset:1024
	ds_read_b128 v[160:163], v151 offset:2048
	ds_read_b128 v[164:167], v151 offset:3072
	v_add_u32_e32 v151, s58, v146
	ds_read_b128 v[168:171], v151
	ds_read_b128 v[172:175], v151 offset:1024
	ds_read_b128 v[178:181], v151 offset:2048
	ds_read_b128 v[182:185], v151 offset:3072
	s_add_u32 s2, s2, 0x40000
	s_addc_u32 s3, s3, 0
	s_mov_b32 m0, s41
	v_lshl_add_u64 v[224:225], s[2:3], 0, v[130:131]
	ds_read_b128 v[186:189], v150 offset:32768
	ds_read_b128 v[190:193], v150 offset:33792
	ds_read_b128 v[194:197], v150 offset:34816
	ds_read_b128 v[198:201], v150 offset:35840
	ds_read_b128 v[202:205], v150 offset:36864
	ds_read_b128 v[206:209], v150 offset:37888
	ds_read_b128 v[210:213], v150 offset:38912
	ds_read_b128 v[214:217], v150 offset:39936
	global_load_lds_dwordx4 v[224:225], off
	v_lshl_add_u64 v[224:225], s[2:3], 0, v[134:135]
	s_mov_b32 m0, s42
	s_nop 0
	global_load_lds_dwordx4 v[224:225], off
	s_waitcnt vmcnt(8)
	s_waitcnt lgkmcnt(0)
	s_barrier
	s_setprio 1
	v_mfma_f32_16x16x32_bf16 v[126:129], v[152:155], v[186:189], v[126:129]
	v_mfma_f32_16x16x32_bf16 v[122:125], v[160:163], v[186:189], v[122:125]
	v_mfma_f32_16x16x32_bf16 v[114:117], v[152:155], v[194:197], v[114:117]
	v_mfma_f32_16x16x32_bf16 v[106:109], v[160:163], v[194:197], v[106:109]
	v_mfma_f32_16x16x32_bf16 v[98:101], v[152:155], v[202:205], v[98:101]
	v_mfma_f32_16x16x32_bf16 v[90:93], v[160:163], v[202:205], v[90:93]
	v_mfma_f32_16x16x32_bf16 v[82:85], v[152:155], v[210:213], v[82:85]
	v_mfma_f32_16x16x32_bf16 v[74:77], v[160:163], v[210:213], v[74:77]
	v_mfma_f32_16x16x32_bf16 v[126:129], v[156:159], v[190:193], v[126:129]
	v_mfma_f32_16x16x32_bf16 v[122:125], v[164:167], v[190:193], v[122:125]
	v_mfma_f32_16x16x32_bf16 v[114:117], v[156:159], v[198:201], v[114:117]
	v_mfma_f32_16x16x32_bf16 v[106:109], v[164:167], v[198:201], v[106:109]
	v_mfma_f32_16x16x32_bf16 v[98:101], v[156:159], v[206:209], v[98:101]
	v_mfma_f32_16x16x32_bf16 v[90:93], v[164:167], v[206:209], v[90:93]
	v_mfma_f32_16x16x32_bf16 v[82:85], v[156:159], v[214:217], v[82:85]
	v_mfma_f32_16x16x32_bf16 v[74:77], v[164:167], v[214:217], v[74:77]
	v_mfma_f32_16x16x32_bf16 v[118:121], v[168:171], v[186:189], v[118:121]
	v_mfma_f32_16x16x32_bf16 v[110:113], v[178:181], v[186:189], v[110:113]
	v_mfma_f32_16x16x32_bf16 v[102:105], v[168:171], v[194:197], v[102:105]
	v_mfma_f32_16x16x32_bf16 v[94:97], v[178:181], v[194:197], v[94:97]
	v_mfma_f32_16x16x32_bf16 v[86:89], v[168:171], v[202:205], v[86:89]
	v_mfma_f32_16x16x32_bf16 v[78:81], v[178:181], v[202:205], v[78:81]
	v_mfma_f32_16x16x32_bf16 v[70:73], v[168:171], v[210:213], v[70:73]
	v_mfma_f32_16x16x32_bf16 v[66:69], v[178:181], v[210:213], v[66:69]
	v_mfma_f32_16x16x32_bf16 v[118:121], v[172:175], v[190:193], v[118:121]
	v_mfma_f32_16x16x32_bf16 v[110:113], v[182:185], v[190:193], v[110:113]
	v_mfma_f32_16x16x32_bf16 v[102:105], v[172:175], v[198:201], v[102:105]
	v_mfma_f32_16x16x32_bf16 v[94:97], v[182:185], v[198:201], v[94:97]
	v_mfma_f32_16x16x32_bf16 v[86:89], v[172:175], v[206:209], v[86:89]
	v_mfma_f32_16x16x32_bf16 v[78:81], v[182:185], v[206:209], v[78:81]
	v_mfma_f32_16x16x32_bf16 v[70:73], v[172:175], v[214:217], v[70:73]
	v_mfma_f32_16x16x32_bf16 v[66:69], v[182:185], v[214:217], v[66:69]
	s_setprio 0
	s_barrier
	s_add_i32 s2, s57, s39
	v_lshl_add_u64 v[144:145], v[144:145], 0, s[6:7]
	s_mov_b32 m0, s2
	ds_read_b128 v[186:189], v150 offset:49152
	ds_read_b128 v[190:193], v150 offset:50176
	ds_read_b128 v[194:197], v150 offset:51200
	ds_read_b128 v[198:201], v150 offset:52224
	ds_read_b128 v[202:205], v150 offset:53248
	ds_read_b128 v[206:209], v150 offset:54272
	ds_read_b128 v[210:213], v150 offset:55296
	ds_read_b128 v[214:217], v150 offset:56320
	global_load_lds_dwordx4 v[144:145], off
	s_add_i32 m0, s2, 0x2000
	s_add_u32 s2, s34, 0x40080
	v_lshl_add_u64 v[144:145], v[218:219], 0, s[6:7]
	s_addc_u32 s3, s35, 0
	s_add_i32 s34, s58, s39
	global_load_lds_dwordx4 v[144:145], off
	v_lshl_add_u64 v[144:145], s[2:3], 0, v[132:133]
	s_mov_b32 m0, s34
	s_nop 0
	global_load_lds_dwordx4 v[144:145], off
	v_lshl_add_u64 v[144:145], s[2:3], 0, v[136:137]
	s_add_i32 m0, s34, 0x2000
	s_nop 0
	global_load_lds_dwordx4 v[144:145], off
	v_lshl_add_u64 v[144:145], v[220:221], 0, s[6:7]
	s_mov_b32 m0, s44
	s_nop 0
	global_load_lds_dwordx4 v[144:145], off
	v_lshl_add_u64 v[144:145], v[222:223], 0, s[6:7]
	s_mov_b32 m0, s45
	s_nop 0
	global_load_lds_dwordx4 v[144:145], off
	s_waitcnt vmcnt(8)
	s_waitcnt lgkmcnt(0)
	s_barrier
	s_setprio 1
	v_mfma_f32_16x16x32_bf16 v[62:65], v[152:155], v[186:189], v[62:65]
	v_mfma_f32_16x16x32_bf16 v[58:61], v[160:163], v[186:189], v[58:61]
	v_mfma_f32_16x16x32_bf16 v[50:53], v[152:155], v[194:197], v[50:53]
	v_mfma_f32_16x16x32_bf16 v[42:45], v[160:163], v[194:197], v[42:45]
	v_mfma_f32_16x16x32_bf16 v[34:37], v[152:155], v[202:205], v[34:37]
	v_mfma_f32_16x16x32_bf16 v[26:29], v[160:163], v[202:205], v[26:29]
	v_mfma_f32_16x16x32_bf16 v[18:21], v[152:155], v[210:213], v[18:21]
	v_mfma_f32_16x16x32_bf16 v[10:13], v[160:163], v[210:213], v[10:13]
	v_mfma_f32_16x16x32_bf16 v[62:65], v[156:159], v[190:193], v[62:65]
	v_mfma_f32_16x16x32_bf16 v[58:61], v[164:167], v[190:193], v[58:61]
	v_mfma_f32_16x16x32_bf16 v[50:53], v[156:159], v[198:201], v[50:53]
	v_mfma_f32_16x16x32_bf16 v[42:45], v[164:167], v[198:201], v[42:45]
	v_mfma_f32_16x16x32_bf16 v[34:37], v[156:159], v[206:209], v[34:37]
	v_mfma_f32_16x16x32_bf16 v[26:29], v[164:167], v[206:209], v[26:29]
	v_mfma_f32_16x16x32_bf16 v[18:21], v[156:159], v[214:217], v[18:21]
	v_mfma_f32_16x16x32_bf16 v[10:13], v[164:167], v[214:217], v[10:13]
	v_mfma_f32_16x16x32_bf16 v[54:57], v[168:171], v[186:189], v[54:57]
	v_mfma_f32_16x16x32_bf16 v[46:49], v[178:181], v[186:189], v[46:49]
	v_mfma_f32_16x16x32_bf16 v[38:41], v[168:171], v[194:197], v[38:41]
	v_mfma_f32_16x16x32_bf16 v[30:33], v[178:181], v[194:197], v[30:33]
	v_mfma_f32_16x16x32_bf16 v[22:25], v[168:171], v[202:205], v[22:25]
	v_mfma_f32_16x16x32_bf16 v[14:17], v[178:181], v[202:205], v[14:17]
	v_mfma_f32_16x16x32_bf16 v[6:9], v[168:171], v[210:213], v[6:9]
	v_mfma_f32_16x16x32_bf16 v[2:5], v[178:181], v[210:213], v[2:5]
	v_mfma_f32_16x16x32_bf16 v[54:57], v[172:175], v[190:193], v[54:57]
	v_mfma_f32_16x16x32_bf16 v[46:49], v[182:185], v[190:193], v[46:49]
	v_mfma_f32_16x16x32_bf16 v[38:41], v[172:175], v[198:201], v[38:41]
	v_mfma_f32_16x16x32_bf16 v[30:33], v[182:185], v[198:201], v[30:33]
	v_mfma_f32_16x16x32_bf16 v[22:25], v[172:175], v[206:209], v[22:25]
	v_mfma_f32_16x16x32_bf16 v[14:17], v[182:185], v[206:209], v[14:17]
	v_mfma_f32_16x16x32_bf16 v[6:9], v[172:175], v[214:217], v[6:9]
	v_mfma_f32_16x16x32_bf16 v[2:5], v[182:185], v[214:217], v[2:5]
	s_setprio 0
	s_barrier
	s_add_i32 s56, s56, 2
	s_add_u32 s30, s30, 0x100
	s_addc_u32 s31, s31, 0
	s_add_u32 s54, s54, 0x100
	s_addc_u32 s55, s55, 0
	s_cmp_gt_u32 s56, 13
	s_cbranch_scc0 .LBB0_1098
	s_branch .Lpk1098_exit
.LBB0_1098:
	ds_read_b128 v[152:155], v148
	ds_read_b128 v[156:159], v148 offset:1024
	ds_read_b128 v[160:163], v148 offset:2048
	ds_read_b128 v[164:167], v148 offset:3072
	ds_read_b128 v[168:171], v149
	ds_read_b128 v[172:175], v149 offset:1024
	ds_read_b128 v[178:181], v149 offset:2048
	ds_read_b128 v[182:185], v149 offset:3072
	s_add_u32 s2, s30, 0xfffc0080
	s_addc_u32 s3, s31, -1
	s_cmp_eq_u32 s56, 12
	s_cselect_b32 s3, s15, s3
	s_cselect_b32 s2, s17, s2
	s_cselect_b32 s35, s52, s55
	s_cselect_b32 s34, s53, s54
	v_lshl_add_u64 v[144:145], s[30:31], 0, v[138:139]
	s_add_i32 m0, s40, 0xc000
	ds_read_b128 v[186:189], v150
	ds_read_b128 v[190:193], v150 offset:1024
	ds_read_b128 v[194:197], v150 offset:2048
	ds_read_b128 v[198:201], v150 offset:3072
	ds_read_b128 v[202:205], v150 offset:4096
	ds_read_b128 v[206:209], v150 offset:5120
	ds_read_b128 v[210:213], v150 offset:6144
	ds_read_b128 v[214:217], v150 offset:7168
	global_load_lds_dwordx4 v[144:145], off
	v_lshl_add_u64 v[144:145], s[30:31], 0, v[140:141]
	s_add_i32 m0, s40, 0xe000
	s_nop 0
	global_load_lds_dwordx4 v[144:145], off
	s_waitcnt vmcnt(8)
	s_waitcnt lgkmcnt(0)
	s_barrier
	s_setprio 1
	v_mfma_f32_16x16x32_bf16 v[126:129], v[152:155], v[186:189], v[126:129]
	v_mfma_f32_16x16x32_bf16 v[122:125], v[160:163], v[186:189], v[122:125]
	v_mfma_f32_16x16x32_bf16 v[114:117], v[152:155], v[194:197], v[114:117]
	v_mfma_f32_16x16x32_bf16 v[106:109], v[160:163], v[194:197], v[106:109]
	v_mfma_f32_16x16x32_bf16 v[98:101], v[152:155], v[202:205], v[98:101]
	v_mfma_f32_16x16x32_bf16 v[90:93], v[160:163], v[202:205], v[90:93]
	v_mfma_f32_16x16x32_bf16 v[82:85], v[152:155], v[210:213], v[82:85]
	v_mfma_f32_16x16x32_bf16 v[74:77], v[160:163], v[210:213], v[74:77]
	v_mfma_f32_16x16x32_bf16 v[126:129], v[156:159], v[190:193], v[126:129]
	v_mfma_f32_16x16x32_bf16 v[122:125], v[164:167], v[190:193], v[122:125]
	v_mfma_f32_16x16x32_bf16 v[114:117], v[156:159], v[198:201], v[114:117]
	v_mfma_f32_16x16x32_bf16 v[106:109], v[164:167], v[198:201], v[106:109]
	v_mfma_f32_16x16x32_bf16 v[98:101], v[156:159], v[206:209], v[98:101]
	v_mfma_f32_16x16x32_bf16 v[90:93], v[164:167], v[206:209], v[90:93]
	v_mfma_f32_16x16x32_bf16 v[82:85], v[156:159], v[214:217], v[82:85]
	v_mfma_f32_16x16x32_bf16 v[74:77], v[164:167], v[214:217], v[74:77]
	v_mfma_f32_16x16x32_bf16 v[118:121], v[168:171], v[186:189], v[118:121]
	v_mfma_f32_16x16x32_bf16 v[110:113], v[178:181], v[186:189], v[110:113]
	v_mfma_f32_16x16x32_bf16 v[102:105], v[168:171], v[194:197], v[102:105]
	v_mfma_f32_16x16x32_bf16 v[94:97], v[178:181], v[194:197], v[94:97]
	v_mfma_f32_16x16x32_bf16 v[86:89], v[168:171], v[202:205], v[86:89]
	v_mfma_f32_16x16x32_bf16 v[78:81], v[178:181], v[202:205], v[78:81]
	v_mfma_f32_16x16x32_bf16 v[70:73], v[168:171], v[210:213], v[70:73]
	v_mfma_f32_16x16x32_bf16 v[66:69], v[178:181], v[210:213], v[66:69]
	v_mfma_f32_16x16x32_bf16 v[118:121], v[172:175], v[190:193], v[118:121]
	v_mfma_f32_16x16x32_bf16 v[110:113], v[182:185], v[190:193], v[110:113]
	v_mfma_f32_16x16x32_bf16 v[102:105], v[172:175], v[198:201], v[102:105]
	v_mfma_f32_16x16x32_bf16 v[94:97], v[182:185], v[198:201], v[94:97]
	v_mfma_f32_16x16x32_bf16 v[86:89], v[172:175], v[206:209], v[86:89]
	v_mfma_f32_16x16x32_bf16 v[78:81], v[182:185], v[206:209], v[78:81]
	v_mfma_f32_16x16x32_bf16 v[70:73], v[172:175], v[214:217], v[70:73]
	v_mfma_f32_16x16x32_bf16 v[66:69], v[182:185], v[214:217], v[66:69]
	s_setprio 0
	s_barrier
	s_add_i32 s57, s47, s39
	v_lshl_add_u64 v[144:145], s[34:35], 0, v[132:133]
	s_mov_b32 m0, s57
	ds_read_b128 v[186:189], v150 offset:16384
	ds_read_b128 v[190:193], v150 offset:17408
	ds_read_b128 v[194:197], v150 offset:18432
	ds_read_b128 v[198:201], v150 offset:19456
	ds_read_b128 v[202:205], v150 offset:20480
	ds_read_b128 v[206:209], v150 offset:21504
	ds_read_b128 v[210:213], v150 offset:22528
	ds_read_b128 v[214:217], v150 offset:23552
	global_load_lds_dwordx4 v[144:145], off
	s_add_i32 m0, s57, 0x2000
	s_add_u32 s58, s34, 0x40000
	v_lshl_add_u64 v[218:219], s[34:35], 0, v[136:137]
	s_addc_u32 s59, s35, 0
	s_add_i32 s57, s48, s39
	global_load_lds_dwordx4 v[218:219], off
	v_lshl_add_u64 v[220:221], s[58:59], 0, v[132:133]
	s_mov_b32 m0, s57
	v_lshl_add_u64 v[222:223], s[2:3], 0, v[134:135]
	global_load_lds_dwordx4 v[220:221], off
	v_lshl_add_u64 v[220:221], s[58:59], 0, v[136:137]
	s_add_i32 m0, s57, 0x2000
	s_nop 0
	global_load_lds_dwordx4 v[220:221], off
	v_lshl_add_u64 v[220:221], s[2:3], 0, v[130:131]
	s_mov_b32 m0, s40
	s_nop 0
	global_load_lds_dwordx4 v[220:221], off
	s_mov_b32 m0, s29
	s_nop 0
	global_load_lds_dwordx4 v[222:223], off
	s_waitcnt vmcnt(8)
	s_waitcnt lgkmcnt(0)
	s_barrier
	s_setprio 1
	v_mfma_f32_16x16x32_bf16 v[62:65], v[152:155], v[186:189], v[62:65]
	v_mfma_f32_16x16x32_bf16 v[58:61], v[160:163], v[186:189], v[58:61]
	v_mfma_f32_16x16x32_bf16 v[50:53], v[152:155], v[194:197], v[50:53]
	v_mfma_f32_16x16x32_bf16 v[42:45], v[160:163], v[194:197], v[42:45]
	v_mfma_f32_16x16x32_bf16 v[34:37], v[152:155], v[202:205], v[34:37]
	v_mfma_f32_16x16x32_bf16 v[26:29], v[160:163], v[202:205], v[26:29]
	v_mfma_f32_16x16x32_bf16 v[18:21], v[152:155], v[210:213], v[18:21]
	v_mfma_f32_16x16x32_bf16 v[10:13], v[160:163], v[210:213], v[10:13]
	v_mfma_f32_16x16x32_bf16 v[62:65], v[156:159], v[190:193], v[62:65]
	v_mfma_f32_16x16x32_bf16 v[58:61], v[164:167], v[190:193], v[58:61]
	v_mfma_f32_16x16x32_bf16 v[50:53], v[156:159], v[198:201], v[50:53]
	v_mfma_f32_16x16x32_bf16 v[42:45], v[164:167], v[198:201], v[42:45]
	v_mfma_f32_16x16x32_bf16 v[34:37], v[156:159], v[206:209], v[34:37]
	v_mfma_f32_16x16x32_bf16 v[26:29], v[164:167], v[206:209], v[26:29]
	v_mfma_f32_16x16x32_bf16 v[18:21], v[156:159], v[214:217], v[18:21]
	v_mfma_f32_16x16x32_bf16 v[10:13], v[164:167], v[214:217], v[10:13]
	v_mfma_f32_16x16x32_bf16 v[54:57], v[168:171], v[186:189], v[54:57]
	v_mfma_f32_16x16x32_bf16 v[46:49], v[178:181], v[186:189], v[46:49]
	v_mfma_f32_16x16x32_bf16 v[38:41], v[168:171], v[194:197], v[38:41]
	v_mfma_f32_16x16x32_bf16 v[30:33], v[178:181], v[194:197], v[30:33]
	v_mfma_f32_16x16x32_bf16 v[22:25], v[168:171], v[202:205], v[22:25]
	v_mfma_f32_16x16x32_bf16 v[14:17], v[178:181], v[202:205], v[14:17]
	v_mfma_f32_16x16x32_bf16 v[6:9], v[168:171], v[210:213], v[6:9]
	v_mfma_f32_16x16x32_bf16 v[2:5], v[178:181], v[210:213], v[2:5]
	v_mfma_f32_16x16x32_bf16 v[54:57], v[172:175], v[190:193], v[54:57]
	v_mfma_f32_16x16x32_bf16 v[46:49], v[182:185], v[190:193], v[46:49]
	v_mfma_f32_16x16x32_bf16 v[38:41], v[172:175], v[198:201], v[38:41]
	v_mfma_f32_16x16x32_bf16 v[30:33], v[182:185], v[198:201], v[30:33]
	v_mfma_f32_16x16x32_bf16 v[22:25], v[172:175], v[206:209], v[22:25]
	v_mfma_f32_16x16x32_bf16 v[14:17], v[182:185], v[206:209], v[14:17]
	v_mfma_f32_16x16x32_bf16 v[6:9], v[172:175], v[214:217], v[6:9]
	v_mfma_f32_16x16x32_bf16 v[2:5], v[182:185], v[214:217], v[2:5]
	s_setprio 0
	s_barrier
	s_add_i32 s57, 0, 0x18000
	v_add_u32_e32 v151, s57, v146
	s_add_i32 s58, 0, 0x1c000
	ds_read_b128 v[152:155], v151
	ds_read_b128 v[156:159], v151 offset:1024
	ds_read_b128 v[160:163], v151 offset:2048
	ds_read_b128 v[164:167], v151 offset:3072
	v_add_u32_e32 v151, s58, v146
	ds_read_b128 v[168:171], v151
	ds_read_b128 v[172:175], v151 offset:1024
	ds_read_b128 v[178:181], v151 offset:2048
	ds_read_b128 v[182:185], v151 offset:3072
	s_add_u32 s2, s2, 0x40000
	s_addc_u32 s3, s3, 0
	s_mov_b32 m0, s41
	v_lshl_add_u64 v[224:225], s[2:3], 0, v[130:131]
	ds_read_b128 v[186:189], v150 offset:32768
	ds_read_b128 v[190:193], v150 offset:33792
	ds_read_b128 v[194:197], v150 offset:34816
	ds_read_b128 v[198:201], v150 offset:35840
	ds_read_b128 v[202:205], v150 offset:36864
	ds_read_b128 v[206:209], v150 offset:37888
	ds_read_b128 v[210:213], v150 offset:38912
	ds_read_b128 v[214:217], v150 offset:39936
	global_load_lds_dwordx4 v[224:225], off
	v_lshl_add_u64 v[224:225], s[2:3], 0, v[134:135]
	s_mov_b32 m0, s42
	s_nop 0
	global_load_lds_dwordx4 v[224:225], off
	s_waitcnt vmcnt(8)
	s_waitcnt lgkmcnt(0)
	s_barrier
	s_setprio 1
	v_mfma_f32_16x16x32_bf16 v[126:129], v[152:155], v[186:189], v[126:129]
	v_mfma_f32_16x16x32_bf16 v[122:125], v[160:163], v[186:189], v[122:125]
	v_mfma_f32_16x16x32_bf16 v[114:117], v[152:155], v[194:197], v[114:117]
	v_mfma_f32_16x16x32_bf16 v[106:109], v[160:163], v[194:197], v[106:109]
	v_mfma_f32_16x16x32_bf16 v[98:101], v[152:155], v[202:205], v[98:101]
	v_mfma_f32_16x16x32_bf16 v[90:93], v[160:163], v[202:205], v[90:93]
	v_mfma_f32_16x16x32_bf16 v[82:85], v[152:155], v[210:213], v[82:85]
	v_mfma_f32_16x16x32_bf16 v[74:77], v[160:163], v[210:213], v[74:77]
	v_mfma_f32_16x16x32_bf16 v[126:129], v[156:159], v[190:193], v[126:129]
	v_mfma_f32_16x16x32_bf16 v[122:125], v[164:167], v[190:193], v[122:125]
	v_mfma_f32_16x16x32_bf16 v[114:117], v[156:159], v[198:201], v[114:117]
	v_mfma_f32_16x16x32_bf16 v[106:109], v[164:167], v[198:201], v[106:109]
	v_mfma_f32_16x16x32_bf16 v[98:101], v[156:159], v[206:209], v[98:101]
	v_mfma_f32_16x16x32_bf16 v[90:93], v[164:167], v[206:209], v[90:93]
	v_mfma_f32_16x16x32_bf16 v[82:85], v[156:159], v[214:217], v[82:85]
	v_mfma_f32_16x16x32_bf16 v[74:77], v[164:167], v[214:217], v[74:77]
	v_mfma_f32_16x16x32_bf16 v[118:121], v[168:171], v[186:189], v[118:121]
	v_mfma_f32_16x16x32_bf16 v[110:113], v[178:181], v[186:189], v[110:113]
	v_mfma_f32_16x16x32_bf16 v[102:105], v[168:171], v[194:197], v[102:105]
	v_mfma_f32_16x16x32_bf16 v[94:97], v[178:181], v[194:197], v[94:97]
	v_mfma_f32_16x16x32_bf16 v[86:89], v[168:171], v[202:205], v[86:89]
	v_mfma_f32_16x16x32_bf16 v[78:81], v[178:181], v[202:205], v[78:81]
	v_mfma_f32_16x16x32_bf16 v[70:73], v[168:171], v[210:213], v[70:73]
	v_mfma_f32_16x16x32_bf16 v[66:69], v[178:181], v[210:213], v[66:69]
	v_mfma_f32_16x16x32_bf16 v[118:121], v[172:175], v[190:193], v[118:121]
	v_mfma_f32_16x16x32_bf16 v[110:113], v[182:185], v[190:193], v[110:113]
	v_mfma_f32_16x16x32_bf16 v[102:105], v[172:175], v[198:201], v[102:105]
	v_mfma_f32_16x16x32_bf16 v[94:97], v[182:185], v[198:201], v[94:97]
	v_mfma_f32_16x16x32_bf16 v[86:89], v[172:175], v[206:209], v[86:89]
	v_mfma_f32_16x16x32_bf16 v[78:81], v[182:185], v[206:209], v[78:81]
	v_mfma_f32_16x16x32_bf16 v[70:73], v[172:175], v[214:217], v[70:73]
	v_mfma_f32_16x16x32_bf16 v[66:69], v[182:185], v[214:217], v[66:69]
	s_setprio 0
	s_barrier
	s_add_i32 s2, s57, s39
	v_lshl_add_u64 v[144:145], v[144:145], 0, s[6:7]
	s_mov_b32 m0, s2
	ds_read_b128 v[186:189], v150 offset:49152
	ds_read_b128 v[190:193], v150 offset:50176
	ds_read_b128 v[194:197], v150 offset:51200
	ds_read_b128 v[198:201], v150 offset:52224
	ds_read_b128 v[202:205], v150 offset:53248
	ds_read_b128 v[206:209], v150 offset:54272
	ds_read_b128 v[210:213], v150 offset:55296
	ds_read_b128 v[214:217], v150 offset:56320
	global_load_lds_dwordx4 v[144:145], off
	s_add_i32 m0, s2, 0x2000
	s_add_u32 s2, s34, 0x40080
	v_lshl_add_u64 v[144:145], v[218:219], 0, s[6:7]
	s_addc_u32 s3, s35, 0
	s_add_i32 s34, s58, s39
	global_load_lds_dwordx4 v[144:145], off
	v_lshl_add_u64 v[144:145], s[2:3], 0, v[132:133]
	s_mov_b32 m0, s34
	s_nop 0
	global_load_lds_dwordx4 v[144:145], off
	v_lshl_add_u64 v[144:145], s[2:3], 0, v[136:137]
	s_add_i32 m0, s34, 0x2000
	s_nop 0
	global_load_lds_dwordx4 v[144:145], off
	v_lshl_add_u64 v[144:145], v[220:221], 0, s[6:7]
	s_mov_b32 m0, s44
	s_nop 0
	global_load_lds_dwordx4 v[144:145], off
	v_lshl_add_u64 v[144:145], v[222:223], 0, s[6:7]
	s_mov_b32 m0, s45
	s_nop 0
	global_load_lds_dwordx4 v[144:145], off
	s_waitcnt vmcnt(8)
	s_waitcnt lgkmcnt(0)
	s_barrier
	s_setprio 1
	v_mfma_f32_16x16x32_bf16 v[62:65], v[152:155], v[186:189], v[62:65]
	v_mfma_f32_16x16x32_bf16 v[58:61], v[160:163], v[186:189], v[58:61]
	v_mfma_f32_16x16x32_bf16 v[50:53], v[152:155], v[194:197], v[50:53]
	v_mfma_f32_16x16x32_bf16 v[42:45], v[160:163], v[194:197], v[42:45]
	v_mfma_f32_16x16x32_bf16 v[34:37], v[152:155], v[202:205], v[34:37]
	v_mfma_f32_16x16x32_bf16 v[26:29], v[160:163], v[202:205], v[26:29]
	v_mfma_f32_16x16x32_bf16 v[18:21], v[152:155], v[210:213], v[18:21]
	v_mfma_f32_16x16x32_bf16 v[10:13], v[160:163], v[210:213], v[10:13]
	v_mfma_f32_16x16x32_bf16 v[62:65], v[156:159], v[190:193], v[62:65]
	v_mfma_f32_16x16x32_bf16 v[58:61], v[164:167], v[190:193], v[58:61]
	v_mfma_f32_16x16x32_bf16 v[50:53], v[156:159], v[198:201], v[50:53]
	v_mfma_f32_16x16x32_bf16 v[42:45], v[164:167], v[198:201], v[42:45]
	v_mfma_f32_16x16x32_bf16 v[34:37], v[156:159], v[206:209], v[34:37]
	v_mfma_f32_16x16x32_bf16 v[26:29], v[164:167], v[206:209], v[26:29]
	v_mfma_f32_16x16x32_bf16 v[18:21], v[156:159], v[214:217], v[18:21]
	v_mfma_f32_16x16x32_bf16 v[10:13], v[164:167], v[214:217], v[10:13]
	v_mfma_f32_16x16x32_bf16 v[54:57], v[168:171], v[186:189], v[54:57]
	v_mfma_f32_16x16x32_bf16 v[46:49], v[178:181], v[186:189], v[46:49]
	v_mfma_f32_16x16x32_bf16 v[38:41], v[168:171], v[194:197], v[38:41]
	v_mfma_f32_16x16x32_bf16 v[30:33], v[178:181], v[194:197], v[30:33]
	v_mfma_f32_16x16x32_bf16 v[22:25], v[168:171], v[202:205], v[22:25]
	v_mfma_f32_16x16x32_bf16 v[14:17], v[178:181], v[202:205], v[14:17]
	v_mfma_f32_16x16x32_bf16 v[6:9], v[168:171], v[210:213], v[6:9]
	v_mfma_f32_16x16x32_bf16 v[2:5], v[178:181], v[210:213], v[2:5]
	v_mfma_f32_16x16x32_bf16 v[54:57], v[172:175], v[190:193], v[54:57]
	v_mfma_f32_16x16x32_bf16 v[46:49], v[182:185], v[190:193], v[46:49]
	v_mfma_f32_16x16x32_bf16 v[38:41], v[172:175], v[198:201], v[38:41]
	v_mfma_f32_16x16x32_bf16 v[30:33], v[182:185], v[198:201], v[30:33]
	v_mfma_f32_16x16x32_bf16 v[22:25], v[172:175], v[206:209], v[22:25]
	v_mfma_f32_16x16x32_bf16 v[14:17], v[182:185], v[206:209], v[14:17]
	v_mfma_f32_16x16x32_bf16 v[6:9], v[172:175], v[214:217], v[6:9]
	v_mfma_f32_16x16x32_bf16 v[2:5], v[182:185], v[214:217], v[2:5]
	s_setprio 0
	s_barrier
	s_add_i32 s56, s56, 2
	s_add_u32 s30, s30, 0x100
	s_addc_u32 s31, s31, 0
	s_add_u32 s54, s54, 0x100
	s_addc_u32 s55, s55, 0
	s_cmp_gt_u32 s56, 13
	s_cbranch_scc0 .LBB0_1098

.LBB0_1137:
	s_add_i32 s26, 0, 0x18000
	s_add_i32 s3, s26, s18
	s_mov_b64 s[24:25], 0x80
	v_lshl_add_u64 v[4:5], v[26:27], 0, s[24:25]
	s_mov_b32 m0, s3
	s_add_i32 s5, s3, 0x2000
	s_waitcnt vmcnt(2)
	s_barrier
	global_load_lds_dwordx4 v[4:5], off
	v_lshl_add_u64 v[6:7], v[28:29], 0, s[24:25]
	s_mov_b32 m0, s5
	s_add_i32 s4, s15, 0x8000
	global_load_lds_dwordx4 v[6:7], off
	v_lshl_add_u64 v[2:3], v[20:21], 0, s[24:25]
	s_mov_b32 m0, s4
	s_add_i32 s9, s15, 0xa000
	s_add_i32 s27, 0, 0x1c000
	global_load_lds_dwordx4 v[2:3], off
	v_lshl_add_u64 v[8:9], v[22:23], 0, s[24:25]
	s_mov_b32 m0, s9
	s_add_i32 s13, s27, s18
	global_load_lds_dwordx4 v[8:9], off
	v_lshl_add_u64 v[10:11], v[24:25], 0, s[24:25]
	s_mov_b32 m0, s13
	s_add_i32 s14, s13, 0x2000
	global_load_lds_dwordx4 v[10:11], off
	v_lshl_add_u64 v[12:13], v[18:19], 0, s[24:25]
	s_mov_b32 m0, s14
	v_and_b32_e32 v30, 15, v0
	global_load_lds_dwordx4 v[12:13], off
	v_lshlrev_b32_e32 v31, 1, v1
	v_lshlrev_b32_e32 v32, 2, v0
	v_lshl_or_b32 v130, s17, 6, v30
	v_lshl_or_b32 v30, v30, 6, v31
	s_lshl_b32 s2, s17, 13
	v_and_b32_e32 v32, 32, v32
	v_bitop3_b32 v62, v30, s2, v32 bitop3:0xde
	s_lshl_b32 s2, s19, 5
	s_and_b32 s2, s2, 0x60
	v_lshlrev_b32_e32 v30, 6, v0
	s_movk_i32 s17, 0x3c0
	v_and_or_b32 v30, v30, s17, v31
	s_lshl_b32 s17, s2, 7
	v_bitop3_b32 v63, s17, v30, v32 bitop3:0xf6
	s_add_i32 s29, 0, 0x10000
	s_add_i32 s28, 0, 0x14000
	v_add_u32_e32 v176, s29, v63
	s_waitcnt vmcnt(6)
	s_barrier
	v_add_u32_e32 v131, s28, v63
	ds_read_b128 v[30:33], v176
	ds_read_b128 v[34:37], v176 offset:1024
	ds_read_b128 v[38:41], v176 offset:2048
	ds_read_b128 v[42:45], v176 offset:3072
	ds_read_b128 v[46:49], v131
	ds_read_b128 v[50:53], v131 offset:1024
	ds_read_b128 v[54:57], v131 offset:2048
	ds_read_b128 v[58:61], v131 offset:3072
	s_add_i32 s20, s29, s18
	s_add_i32 s18, s28, s18
	s_add_i32 s22, s15, 0xc000
	s_add_i32 s21, s15, 0xe000
	s_add_i32 s19, s20, 0x2000
	s_add_i32 s17, s18, 0x2000
	s_cmpk_gt_u32 s23, 0xff
	v_add_u32_e32 v242, 0, v62
	v_add_u32_e32 v238, s27, v63
	v_add_u32_e32 v239, s26, v63
	s_mov_b32 m0, s22
	v_lshl_add_u64 v[94:95], v[14:15], 0, s[24:25]
	ds_read_b128 v[62:65], v242
	ds_read_b128 v[66:69], v242 offset:1024
	ds_read_b128 v[70:73], v242 offset:2048
	ds_read_b128 v[74:77], v242 offset:3072
	ds_read_b128 v[78:81], v242 offset:4096
	ds_read_b128 v[82:85], v242 offset:5120
	ds_read_b128 v[86:89], v242 offset:6144
	ds_read_b128 v[90:93], v242 offset:7168
	global_load_lds_dwordx4 v[94:95], off
	v_lshl_add_u64 v[94:95], v[16:17], 0, s[24:25]
	s_mov_b32 m0, s21
	s_nop 0
	global_load_lds_dwordx4 v[94:95], off
	s_waitcnt vmcnt(8)
	s_waitcnt lgkmcnt(0)
	s_barrier
	s_setprio 1
	v_mfma_f32_16x16x32_bf16 v[94:97], v[30:33], v[62:65], 0
	v_mfma_f32_16x16x32_bf16 v[98:101], v[38:41], v[62:65], 0
	v_mfma_f32_16x16x32_bf16 v[102:105], v[30:33], v[70:73], 0
	v_mfma_f32_16x16x32_bf16 v[106:109], v[38:41], v[70:73], 0
	v_mfma_f32_16x16x32_bf16 v[110:113], v[30:33], v[78:81], 0
	v_mfma_f32_16x16x32_bf16 v[114:117], v[38:41], v[78:81], 0
	v_mfma_f32_16x16x32_bf16 v[118:121], v[30:33], v[86:89], 0
	v_mfma_f32_16x16x32_bf16 v[122:125], v[38:41], v[86:89], 0
	v_mfma_f32_16x16x32_bf16 v[94:97], v[34:37], v[66:69], v[94:97]
	v_mfma_f32_16x16x32_bf16 v[98:101], v[42:45], v[66:69], v[98:101]
	v_mfma_f32_16x16x32_bf16 v[102:105], v[34:37], v[74:77], v[102:105]
	v_mfma_f32_16x16x32_bf16 v[106:109], v[42:45], v[74:77], v[106:109]
	v_mfma_f32_16x16x32_bf16 v[110:113], v[34:37], v[82:85], v[110:113]
	v_mfma_f32_16x16x32_bf16 v[114:117], v[42:45], v[82:85], v[114:117]
	v_mfma_f32_16x16x32_bf16 v[118:121], v[34:37], v[90:93], v[118:121]
	v_mfma_f32_16x16x32_bf16 v[122:125], v[42:45], v[90:93], v[122:125]
	v_mfma_f32_16x16x32_bf16 v[126:129], v[46:49], v[62:65], 0
	v_mfma_f32_16x16x32_bf16 v[62:65], v[54:57], v[62:65], 0
	v_mfma_f32_16x16x32_bf16 v[126:129], v[50:53], v[66:69], v[126:129]
	v_mfma_f32_16x16x32_bf16 v[62:65], v[58:61], v[66:69], v[62:65]
	v_mfma_f32_16x16x32_bf16 v[66:69], v[46:49], v[70:73], 0
	v_mfma_f32_16x16x32_bf16 v[70:73], v[54:57], v[70:73], 0
	v_mfma_f32_16x16x32_bf16 v[66:69], v[50:53], v[74:77], v[66:69]
	v_mfma_f32_16x16x32_bf16 v[70:73], v[58:61], v[74:77], v[70:73]
	v_mfma_f32_16x16x32_bf16 v[74:77], v[46:49], v[78:81], 0
	v_mfma_f32_16x16x32_bf16 v[78:81], v[54:57], v[78:81], 0
	v_mfma_f32_16x16x32_bf16 v[74:77], v[50:53], v[82:85], v[74:77]
	v_mfma_f32_16x16x32_bf16 v[78:81], v[58:61], v[82:85], v[78:81]
	v_mfma_f32_16x16x32_bf16 v[82:85], v[46:49], v[86:89], 0
	v_mfma_f32_16x16x32_bf16 v[86:89], v[54:57], v[86:89], 0
	v_mfma_f32_16x16x32_bf16 v[82:85], v[50:53], v[90:93], v[82:85]
	v_mfma_f32_16x16x32_bf16 v[86:89], v[58:61], v[90:93], v[86:89]
	s_setprio 0
	s_barrier
	s_mov_b64 s[24:25], 0x100
	s_mov_b32 m0, s20
	v_lshl_add_u64 v[160:161], v[26:27], 0, s[24:25]
	ds_read_b128 v[90:93], v242 offset:16384
	ds_read_b128 v[132:135], v242 offset:17408
	ds_read_b128 v[136:139], v242 offset:18432
	ds_read_b128 v[140:143], v242 offset:19456
	ds_read_b128 v[144:147], v242 offset:20480
	ds_read_b128 v[148:151], v242 offset:21504
	ds_read_b128 v[152:155], v242 offset:22528
	ds_read_b128 v[156:159], v242 offset:23552
	global_load_lds_dwordx4 v[160:161], off
	v_lshl_add_u64 v[160:161], v[28:29], 0, s[24:25]
	s_mov_b32 m0, s19
	s_nop 0
	global_load_lds_dwordx4 v[160:161], off
	v_lshl_add_u64 v[160:161], v[24:25], 0, s[24:25]
	s_mov_b32 m0, s18
	s_nop 0
	global_load_lds_dwordx4 v[160:161], off
	v_lshl_add_u64 v[160:161], v[18:19], 0, s[24:25]
	s_mov_b32 m0, s17
	s_nop 0
	global_load_lds_dwordx4 v[160:161], off
	v_lshl_add_u64 v[160:161], v[20:21], 0, s[24:25]
	s_mov_b32 m0, s15
	s_nop 0
	global_load_lds_dwordx4 v[160:161], off
	v_lshl_add_u64 v[160:161], v[22:23], 0, s[24:25]
	s_mov_b32 m0, s16
	s_nop 0
	global_load_lds_dwordx4 v[160:161], off
	s_waitcnt vmcnt(8)
	s_waitcnt lgkmcnt(0)
	s_barrier
	s_setprio 1
	v_mfma_f32_16x16x32_bf16 v[160:163], v[30:33], v[90:93], 0
	v_mfma_f32_16x16x32_bf16 v[168:171], v[30:33], v[136:139], 0
	v_mfma_f32_16x16x32_bf16 v[178:181], v[30:33], v[144:147], 0
	v_mfma_f32_16x16x32_bf16 v[30:33], v[30:33], v[152:155], 0
	v_mfma_f32_16x16x32_bf16 v[160:163], v[34:37], v[132:135], v[160:163]
	v_mfma_f32_16x16x32_bf16 v[168:171], v[34:37], v[140:143], v[168:171]
	v_mfma_f32_16x16x32_bf16 v[178:181], v[34:37], v[148:151], v[178:181]
	v_mfma_f32_16x16x32_bf16 v[30:33], v[34:37], v[156:159], v[30:33]
	v_mfma_f32_16x16x32_bf16 v[34:37], v[38:41], v[152:155], 0
	v_mfma_f32_16x16x32_bf16 v[164:167], v[38:41], v[90:93], 0
	v_mfma_f32_16x16x32_bf16 v[172:175], v[38:41], v[136:139], 0
	v_mfma_f32_16x16x32_bf16 v[182:185], v[38:41], v[144:147], 0
	v_mfma_f32_16x16x32_bf16 v[34:37], v[42:45], v[156:159], v[34:37]
	v_mfma_f32_16x16x32_bf16 v[164:167], v[42:45], v[132:135], v[164:167]
	v_mfma_f32_16x16x32_bf16 v[172:175], v[42:45], v[140:143], v[172:175]
	v_mfma_f32_16x16x32_bf16 v[182:185], v[42:45], v[148:151], v[182:185]
	v_mfma_f32_16x16x32_bf16 v[38:41], v[46:49], v[90:93], 0
	v_mfma_f32_16x16x32_bf16 v[42:45], v[54:57], v[90:93], 0
	v_mfma_f32_16x16x32_bf16 v[38:41], v[50:53], v[132:135], v[38:41]
	v_mfma_f32_16x16x32_bf16 v[42:45], v[58:61], v[132:135], v[42:45]
	v_mfma_f32_16x16x32_bf16 v[90:93], v[46:49], v[136:139], 0
	v_mfma_f32_16x16x32_bf16 v[132:135], v[54:57], v[136:139], 0
	v_mfma_f32_16x16x32_bf16 v[136:139], v[46:49], v[144:147], 0
	v_mfma_f32_16x16x32_bf16 v[46:49], v[46:49], v[152:155], 0
	v_mfma_f32_16x16x32_bf16 v[90:93], v[50:53], v[140:143], v[90:93]
	v_mfma_f32_16x16x32_bf16 v[136:139], v[50:53], v[148:151], v[136:139]
	v_mfma_f32_16x16x32_bf16 v[46:49], v[50:53], v[156:159], v[46:49]
	v_mfma_f32_16x16x32_bf16 v[50:53], v[54:57], v[152:155], 0
	v_mfma_f32_16x16x32_bf16 v[132:135], v[58:61], v[140:143], v[132:135]
	v_mfma_f32_16x16x32_bf16 v[140:143], v[54:57], v[144:147], 0
	v_mfma_f32_16x16x32_bf16 v[50:53], v[58:61], v[156:159], v[50:53]
	v_mfma_f32_16x16x32_bf16 v[140:143], v[58:61], v[148:151], v[140:143]
	s_setprio 0
	s_barrier
	ds_read_b128 v[54:57], v239
	ds_read_b128 v[58:61], v239 offset:1024
	ds_read_b128 v[144:147], v239 offset:2048
	ds_read_b128 v[148:151], v239 offset:3072
	ds_read_b128 v[152:155], v238
	ds_read_b128 v[156:159], v238 offset:1024
	ds_read_b128 v[186:189], v238 offset:2048
	ds_read_b128 v[190:193], v238 offset:3072
	s_mov_b32 m0, s11
	v_lshl_add_u64 v[226:227], v[14:15], 0, s[24:25]
	ds_read_b128 v[194:197], v242 offset:32768
	ds_read_b128 v[198:201], v242 offset:33792
	ds_read_b128 v[202:205], v242 offset:34816
	ds_read_b128 v[206:209], v242 offset:35840
	ds_read_b128 v[210:213], v242 offset:36864
	ds_read_b128 v[214:217], v242 offset:37888
	ds_read_b128 v[218:221], v242 offset:38912
	ds_read_b128 v[222:225], v242 offset:39936
	global_load_lds_dwordx4 v[226:227], off
	v_lshl_add_u64 v[226:227], v[16:17], 0, s[24:25]
	s_mov_b32 m0, s12
	s_nop 0
	global_load_lds_dwordx4 v[226:227], off
	s_waitcnt vmcnt(8)
	s_waitcnt lgkmcnt(0)
	s_barrier
	s_setprio 1
	v_mfma_f32_16x16x32_bf16 v[94:97], v[54:57], v[194:197], v[94:97]
	v_mfma_f32_16x16x32_bf16 v[98:101], v[144:147], v[194:197], v[98:101]
	v_mfma_f32_16x16x32_bf16 v[102:105], v[54:57], v[202:205], v[102:105]
	v_mfma_f32_16x16x32_bf16 v[106:109], v[144:147], v[202:205], v[106:109]
	v_mfma_f32_16x16x32_bf16 v[110:113], v[54:57], v[210:213], v[110:113]
	v_mfma_f32_16x16x32_bf16 v[114:117], v[144:147], v[210:213], v[114:117]
	v_mfma_f32_16x16x32_bf16 v[118:121], v[54:57], v[218:221], v[118:121]
	v_mfma_f32_16x16x32_bf16 v[122:125], v[144:147], v[218:221], v[122:125]
	v_mfma_f32_16x16x32_bf16 v[94:97], v[58:61], v[198:201], v[94:97]
	v_mfma_f32_16x16x32_bf16 v[98:101], v[148:151], v[198:201], v[98:101]
	v_mfma_f32_16x16x32_bf16 v[102:105], v[58:61], v[206:209], v[102:105]
	v_mfma_f32_16x16x32_bf16 v[106:109], v[148:151], v[206:209], v[106:109]
	v_mfma_f32_16x16x32_bf16 v[110:113], v[58:61], v[214:217], v[110:113]
	v_mfma_f32_16x16x32_bf16 v[114:117], v[148:151], v[214:217], v[114:117]
	v_mfma_f32_16x16x32_bf16 v[118:121], v[58:61], v[222:225], v[118:121]
	v_mfma_f32_16x16x32_bf16 v[122:125], v[148:151], v[222:225], v[122:125]
	v_mfma_f32_16x16x32_bf16 v[126:129], v[152:155], v[194:197], v[126:129]
	v_mfma_f32_16x16x32_bf16 v[62:65], v[186:189], v[194:197], v[62:65]
	v_mfma_f32_16x16x32_bf16 v[66:69], v[152:155], v[202:205], v[66:69]
	v_mfma_f32_16x16x32_bf16 v[70:73], v[186:189], v[202:205], v[70:73]
	v_mfma_f32_16x16x32_bf16 v[74:77], v[152:155], v[210:213], v[74:77]
	v_mfma_f32_16x16x32_bf16 v[78:81], v[186:189], v[210:213], v[78:81]
	v_mfma_f32_16x16x32_bf16 v[82:85], v[152:155], v[218:221], v[82:85]
	v_mfma_f32_16x16x32_bf16 v[86:89], v[186:189], v[218:221], v[86:89]
	v_mfma_f32_16x16x32_bf16 v[126:129], v[156:159], v[198:201], v[126:129]
	v_mfma_f32_16x16x32_bf16 v[62:65], v[190:193], v[198:201], v[62:65]
	v_mfma_f32_16x16x32_bf16 v[66:69], v[156:159], v[206:209], v[66:69]
	v_mfma_f32_16x16x32_bf16 v[70:73], v[190:193], v[206:209], v[70:73]
	v_mfma_f32_16x16x32_bf16 v[74:77], v[156:159], v[214:217], v[74:77]
	v_mfma_f32_16x16x32_bf16 v[78:81], v[190:193], v[214:217], v[78:81]
	v_mfma_f32_16x16x32_bf16 v[82:85], v[156:159], v[222:225], v[82:85]
	v_mfma_f32_16x16x32_bf16 v[86:89], v[190:193], v[222:225], v[86:89]
	s_setprio 0
	s_barrier
	s_mov_b64 s[24:25], 0x180
	s_mov_b32 m0, s3
	v_lshl_add_u64 v[226:227], v[26:27], 0, s[24:25]
	ds_read_b128 v[194:197], v242 offset:49152
	ds_read_b128 v[198:201], v242 offset:50176
	ds_read_b128 v[202:205], v242 offset:51200
	ds_read_b128 v[206:209], v242 offset:52224
	ds_read_b128 v[210:213], v242 offset:53248
	ds_read_b128 v[214:217], v242 offset:54272
	ds_read_b128 v[218:221], v242 offset:55296
	ds_read_b128 v[222:225], v242 offset:56320
	global_load_lds_dwordx4 v[226:227], off
	v_lshl_add_u64 v[226:227], v[28:29], 0, s[24:25]
	s_mov_b32 m0, s5
	s_nop 0
	global_load_lds_dwordx4 v[226:227], off
	v_lshl_add_u64 v[226:227], v[24:25], 0, s[24:25]
	s_mov_b32 m0, s13
	s_nop 0
	global_load_lds_dwordx4 v[226:227], off
	v_lshl_add_u64 v[226:227], v[18:19], 0, s[24:25]
	s_mov_b32 m0, s14
	s_nop 0
	global_load_lds_dwordx4 v[226:227], off
	v_lshl_add_u64 v[226:227], v[20:21], 0, s[24:25]
	s_mov_b32 m0, s4
	s_nop 0
	global_load_lds_dwordx4 v[226:227], off
	v_lshl_add_u64 v[226:227], v[22:23], 0, s[24:25]
	s_mov_b32 m0, s9
	s_nop 0
	global_load_lds_dwordx4 v[226:227], off
	s_waitcnt vmcnt(8)
	s_waitcnt lgkmcnt(0)
	s_barrier
	s_setprio 1
	v_mfma_f32_16x16x32_bf16 v[30:33], v[54:57], v[218:221], v[30:33]
	v_mfma_f32_16x16x32_bf16 v[34:37], v[144:147], v[218:221], v[34:37]
	v_mfma_f32_16x16x32_bf16 v[160:163], v[54:57], v[194:197], v[160:163]
	v_mfma_f32_16x16x32_bf16 v[164:167], v[144:147], v[194:197], v[164:167]
	v_mfma_f32_16x16x32_bf16 v[168:171], v[54:57], v[202:205], v[168:171]
	v_mfma_f32_16x16x32_bf16 v[172:175], v[144:147], v[202:205], v[172:175]
	v_mfma_f32_16x16x32_bf16 v[178:181], v[54:57], v[210:213], v[178:181]
	v_mfma_f32_16x16x32_bf16 v[182:185], v[144:147], v[210:213], v[182:185]
	v_mfma_f32_16x16x32_bf16 v[30:33], v[58:61], v[222:225], v[30:33]
	v_mfma_f32_16x16x32_bf16 v[34:37], v[148:151], v[222:225], v[34:37]
	v_mfma_f32_16x16x32_bf16 v[160:163], v[58:61], v[198:201], v[160:163]
	v_mfma_f32_16x16x32_bf16 v[164:167], v[148:151], v[198:201], v[164:167]
	v_mfma_f32_16x16x32_bf16 v[168:171], v[58:61], v[206:209], v[168:171]
	v_mfma_f32_16x16x32_bf16 v[172:175], v[148:151], v[206:209], v[172:175]
	v_mfma_f32_16x16x32_bf16 v[178:181], v[58:61], v[214:217], v[178:181]
	v_mfma_f32_16x16x32_bf16 v[182:185], v[148:151], v[214:217], v[182:185]
	v_mfma_f32_16x16x32_bf16 v[38:41], v[152:155], v[194:197], v[38:41]
	v_mfma_f32_16x16x32_bf16 v[42:45], v[186:189], v[194:197], v[42:45]
	v_mfma_f32_16x16x32_bf16 v[54:57], v[152:155], v[202:205], v[90:93]
	v_mfma_f32_16x16x32_bf16 v[58:61], v[186:189], v[202:205], v[132:135]
	v_mfma_f32_16x16x32_bf16 v[90:93], v[152:155], v[210:213], v[136:139]
	v_mfma_f32_16x16x32_bf16 v[46:49], v[152:155], v[218:221], v[46:49]
	v_mfma_f32_16x16x32_bf16 v[50:53], v[186:189], v[218:221], v[50:53]
	v_mfma_f32_16x16x32_bf16 v[38:41], v[156:159], v[198:201], v[38:41]
	v_mfma_f32_16x16x32_bf16 v[42:45], v[190:193], v[198:201], v[42:45]
	v_mfma_f32_16x16x32_bf16 v[54:57], v[156:159], v[206:209], v[54:57]
	v_mfma_f32_16x16x32_bf16 v[58:61], v[190:193], v[206:209], v[58:61]
	v_mfma_f32_16x16x32_bf16 v[90:93], v[156:159], v[214:217], v[90:93]
	v_mfma_f32_16x16x32_bf16 v[132:135], v[186:189], v[210:213], v[140:143]
	v_mfma_f32_16x16x32_bf16 v[46:49], v[156:159], v[222:225], v[46:49]
	v_mfma_f32_16x16x32_bf16 v[50:53], v[190:193], v[222:225], v[50:53]
	v_mfma_f32_16x16x32_bf16 v[132:135], v[190:193], v[214:217], v[132:135]
	s_setprio 0
	s_barrier
	ds_read_b128 v[136:139], v176
	ds_read_b128 v[140:143], v176 offset:1024
	ds_read_b128 v[144:147], v176 offset:2048
	ds_read_b128 v[148:151], v176 offset:3072
	ds_read_b128 v[152:155], v131
	ds_read_b128 v[156:159], v131 offset:1024
	ds_read_b128 v[186:189], v131 offset:2048
	ds_read_b128 v[190:193], v131 offset:3072
	s_mov_b32 m0, s22
	v_lshl_add_u64 v[226:227], v[14:15], 0, s[24:25]
	ds_read_b128 v[194:197], v242
	ds_read_b128 v[198:201], v242 offset:1024
	ds_read_b128 v[202:205], v242 offset:2048
	ds_read_b128 v[206:209], v242 offset:3072
	ds_read_b128 v[210:213], v242 offset:4096
	ds_read_b128 v[214:217], v242 offset:5120
	ds_read_b128 v[218:221], v242 offset:6144
	ds_read_b128 v[222:225], v242 offset:7168
	global_load_lds_dwordx4 v[226:227], off
	v_lshl_add_u64 v[226:227], v[16:17], 0, s[24:25]
	s_mov_b32 m0, s21
	s_nop 0
	global_load_lds_dwordx4 v[226:227], off
	s_waitcnt vmcnt(8)
	s_waitcnt lgkmcnt(0)
	s_barrier
	s_setprio 1
	v_mfma_f32_16x16x32_bf16 v[110:113], v[136:139], v[210:213], v[110:113]
	v_mfma_f32_16x16x32_bf16 v[226:229], v[140:143], v[214:217], v[110:113]
	v_mfma_f32_16x16x32_bf16 v[110:113], v[144:147], v[210:213], v[114:117]
	v_mfma_f32_16x16x32_bf16 v[94:97], v[136:139], v[194:197], v[94:97]
	v_mfma_f32_16x16x32_bf16 v[98:101], v[144:147], v[194:197], v[98:101]
	v_mfma_f32_16x16x32_bf16 v[102:105], v[136:139], v[202:205], v[102:105]
	v_mfma_f32_16x16x32_bf16 v[106:109], v[144:147], v[202:205], v[106:109]
	v_mfma_f32_16x16x32_bf16 v[114:117], v[148:151], v[214:217], v[110:113]
	v_mfma_f32_16x16x32_bf16 v[110:113], v[136:139], v[218:221], v[118:121]
	v_mfma_f32_16x16x32_bf16 v[94:97], v[140:143], v[198:201], v[94:97]
	v_mfma_f32_16x16x32_bf16 v[98:101], v[148:151], v[198:201], v[98:101]
	v_mfma_f32_16x16x32_bf16 v[102:105], v[140:143], v[206:209], v[102:105]
	v_mfma_f32_16x16x32_bf16 v[106:109], v[148:151], v[206:209], v[106:109]
	v_mfma_f32_16x16x32_bf16 v[118:121], v[140:143], v[222:225], v[110:113]
	v_mfma_f32_16x16x32_bf16 v[110:113], v[144:147], v[218:221], v[122:125]
	v_mfma_f32_16x16x32_bf16 v[230:233], v[148:151], v[222:225], v[110:113]
	v_mfma_f32_16x16x32_bf16 v[74:77], v[152:155], v[210:213], v[74:77]
	v_mfma_f32_16x16x32_bf16 v[110:113], v[152:155], v[194:197], v[126:129]
	v_mfma_f32_16x16x32_bf16 v[62:65], v[186:189], v[194:197], v[62:65]
	v_mfma_f32_16x16x32_bf16 v[194:197], v[156:159], v[214:217], v[74:77]
	v_mfma_f32_16x16x32_bf16 v[74:77], v[186:189], v[210:213], v[78:81]
	v_mfma_f32_16x16x32_bf16 v[234:237], v[156:159], v[198:201], v[110:113]
	v_mfma_f32_16x16x32_bf16 v[62:65], v[190:193], v[198:201], v[62:65]
	v_mfma_f32_16x16x32_bf16 v[66:69], v[152:155], v[202:205], v[66:69]
	v_mfma_f32_16x16x32_bf16 v[70:73], v[186:189], v[202:205], v[70:73]
	v_mfma_f32_16x16x32_bf16 v[198:201], v[190:193], v[214:217], v[74:77]
	v_mfma_f32_16x16x32_bf16 v[74:77], v[152:155], v[218:221], v[82:85]
	v_mfma_f32_16x16x32_bf16 v[66:69], v[156:159], v[206:209], v[66:69]
	v_mfma_f32_16x16x32_bf16 v[70:73], v[190:193], v[206:209], v[70:73]
	v_mfma_f32_16x16x32_bf16 v[202:205], v[156:159], v[222:225], v[74:77]
	v_mfma_f32_16x16x32_bf16 v[74:77], v[186:189], v[218:221], v[86:89]
	v_mfma_f32_16x16x32_bf16 v[206:209], v[190:193], v[222:225], v[74:77]
	s_setprio 0
	s_barrier
	s_mov_b32 m0, s20
	s_nop 3
	ds_read_b128 v[74:77], v242 offset:16384
	ds_read_b128 v[78:81], v242 offset:17408
	ds_read_b128 v[82:85], v242 offset:18432
	ds_read_b128 v[86:89], v242 offset:19456
	ds_read_b128 v[110:113], v242 offset:20480
	ds_read_b128 v[122:125], v242 offset:21504
	ds_read_b128 v[126:129], v242 offset:22528
	ds_read_b128 v[210:213], v242 offset:23552
	global_load_lds_dwordx4 v[26:27], off
	s_mov_b32 m0, s19
	s_nop 0
	global_load_lds_dwordx4 v[28:29], off
	s_mov_b32 m0, s18
	s_nop 0
	global_load_lds_dwordx4 v[24:25], off
	s_mov_b32 m0, s17
	s_nop 0
	global_load_lds_dwordx4 v[18:19], off
	s_mov_b32 m0, s15
	s_nop 0
	global_load_lds_dwordx4 v[20:21], off
	s_mov_b32 m0, s16
	s_nop 0
	global_load_lds_dwordx4 v[22:23], off
	s_waitcnt vmcnt(8)
	s_waitcnt lgkmcnt(0)
	s_barrier
	s_setprio 1
	v_mfma_f32_16x16x32_bf16 v[30:33], v[136:139], v[126:129], v[30:33]
	v_mfma_f32_16x16x32_bf16 v[18:21], v[136:139], v[74:77], v[160:163]
	v_mfma_f32_16x16x32_bf16 v[22:25], v[144:147], v[74:77], v[164:167]
	v_mfma_f32_16x16x32_bf16 v[26:29], v[136:139], v[82:85], v[168:171]
	v_mfma_f32_16x16x32_bf16 v[164:167], v[136:139], v[110:113], v[178:181]
	v_mfma_f32_16x16x32_bf16 v[136:139], v[140:143], v[210:213], v[30:33]
	v_mfma_f32_16x16x32_bf16 v[30:33], v[144:147], v[126:129], v[34:37]
	v_mfma_f32_16x16x32_bf16 v[18:21], v[140:143], v[78:81], v[18:21]
	v_mfma_f32_16x16x32_bf16 v[22:25], v[148:151], v[78:81], v[22:25]
	v_mfma_f32_16x16x32_bf16 v[26:29], v[140:143], v[86:89], v[26:29]
	v_mfma_f32_16x16x32_bf16 v[160:163], v[144:147], v[82:85], v[172:175]
	v_mfma_f32_16x16x32_bf16 v[168:171], v[144:147], v[110:113], v[182:185]
	v_mfma_f32_16x16x32_bf16 v[34:37], v[148:151], v[210:213], v[30:33]
	v_mfma_f32_16x16x32_bf16 v[160:163], v[148:151], v[86:89], v[160:163]
	v_mfma_f32_16x16x32_bf16 v[164:167], v[140:143], v[122:125], v[164:167]
	v_mfma_f32_16x16x32_bf16 v[168:171], v[148:151], v[122:125], v[168:171]
	v_mfma_f32_16x16x32_bf16 v[30:33], v[152:155], v[74:77], v[38:41]
	v_mfma_f32_16x16x32_bf16 v[38:41], v[156:159], v[78:81], v[30:33]
	v_mfma_f32_16x16x32_bf16 v[30:33], v[186:189], v[74:77], v[42:45]
	v_mfma_f32_16x16x32_bf16 v[140:143], v[190:193], v[78:81], v[30:33]
	v_mfma_f32_16x16x32_bf16 v[30:33], v[152:155], v[82:85], v[54:57]
	v_mfma_f32_16x16x32_bf16 v[144:147], v[156:159], v[86:89], v[30:33]
	v_mfma_f32_16x16x32_bf16 v[30:33], v[186:189], v[82:85], v[58:61]
	v_mfma_f32_16x16x32_bf16 v[148:151], v[190:193], v[86:89], v[30:33]
	v_mfma_f32_16x16x32_bf16 v[30:33], v[152:155], v[110:113], v[90:93]
	v_mfma_f32_16x16x32_bf16 v[172:175], v[156:159], v[122:125], v[30:33]
	v_mfma_f32_16x16x32_bf16 v[30:33], v[186:189], v[110:113], v[132:135]
	v_mfma_f32_16x16x32_bf16 v[132:135], v[190:193], v[122:125], v[30:33]
	v_mfma_f32_16x16x32_bf16 v[30:33], v[152:155], v[126:129], v[46:49]
	v_mfma_f32_16x16x32_bf16 v[152:155], v[156:159], v[210:213], v[30:33]
	v_mfma_f32_16x16x32_bf16 v[30:33], v[186:189], v[126:129], v[50:53]
	v_mfma_f32_16x16x32_bf16 v[156:159], v[190:193], v[210:213], v[30:33]
	s_setprio 0
	s_barrier
	ds_read_b128 v[50:53], v239
	ds_read_b128 v[54:57], v239 offset:1024
	ds_read_b128 v[178:181], v239 offset:2048
	ds_read_b128 v[182:185], v239 offset:3072
	ds_read_b128 v[186:189], v238
	ds_read_b128 v[190:193], v238 offset:1024
	ds_read_b128 v[210:213], v238 offset:2048
	ds_read_b128 v[214:217], v238 offset:3072
	s_mov_b32 m0, s11
	ds_read_b128 v[30:33], v242 offset:32768
	ds_read_b128 v[42:45], v242 offset:33792
	ds_read_b128 v[46:49], v242 offset:34816
	ds_read_b128 v[58:61], v242 offset:35840
	ds_read_b128 v[82:85], v242 offset:36864
	ds_read_b128 v[218:221], v242 offset:37888
	ds_read_b128 v[222:225], v242 offset:38912
	ds_read_b128 v[238:241], v242 offset:39936
	global_load_lds_dwordx4 v[14:15], off
	s_mov_b32 m0, s12
	s_nop 0
	global_load_lds_dwordx4 v[16:17], off
	s_waitcnt vmcnt(8)
	s_waitcnt lgkmcnt(0)
	s_barrier
	s_setprio 1
	v_mfma_f32_16x16x32_bf16 v[14:17], v[50:53], v[30:33], v[94:97]
	v_mfma_f32_16x16x32_bf16 v[126:129], v[54:57], v[42:45], v[14:17]
	v_mfma_f32_16x16x32_bf16 v[14:17], v[178:181], v[30:33], v[98:101]
	v_mfma_f32_16x16x32_bf16 v[122:125], v[182:185], v[42:45], v[14:17]
	v_mfma_f32_16x16x32_bf16 v[14:17], v[50:53], v[46:49], v[102:105]
	v_mfma_f32_16x16x32_bf16 v[110:113], v[54:57], v[58:61], v[14:17]
	v_mfma_f32_16x16x32_bf16 v[14:17], v[178:181], v[46:49], v[106:109]
	v_mfma_f32_16x16x32_bf16 v[106:109], v[182:185], v[58:61], v[14:17]
	v_mfma_f32_16x16x32_bf16 v[14:17], v[50:53], v[82:85], v[226:229]
	v_mfma_f32_16x16x32_bf16 v[94:97], v[54:57], v[218:221], v[14:17]
	v_mfma_f32_16x16x32_bf16 v[14:17], v[178:181], v[82:85], v[114:117]
	v_mfma_f32_16x16x32_bf16 v[90:93], v[182:185], v[218:221], v[14:17]
	v_mfma_f32_16x16x32_bf16 v[14:17], v[50:53], v[222:225], v[118:121]
	v_mfma_f32_16x16x32_bf16 v[78:81], v[54:57], v[238:241], v[14:17]
	v_mfma_f32_16x16x32_bf16 v[14:17], v[178:181], v[222:225], v[230:233]
	v_mfma_f32_16x16x32_bf16 v[74:77], v[182:185], v[238:241], v[14:17]
	v_mfma_f32_16x16x32_bf16 v[14:17], v[186:189], v[30:33], v[234:237]
	v_mfma_f32_16x16x32_bf16 v[118:121], v[190:193], v[42:45], v[14:17]
	v_mfma_f32_16x16x32_bf16 v[14:17], v[210:213], v[30:33], v[62:65]
	v_mfma_f32_16x16x32_bf16 v[114:117], v[214:217], v[42:45], v[14:17]
	v_mfma_f32_16x16x32_bf16 v[14:17], v[186:189], v[46:49], v[66:69]
	v_mfma_f32_16x16x32_bf16 v[102:105], v[190:193], v[58:61], v[14:17]
	v_mfma_f32_16x16x32_bf16 v[14:17], v[210:213], v[46:49], v[70:73]
	v_mfma_f32_16x16x32_bf16 v[98:101], v[214:217], v[58:61], v[14:17]
	v_mfma_f32_16x16x32_bf16 v[14:17], v[186:189], v[82:85], v[194:197]
	v_mfma_f32_16x16x32_bf16 v[86:89], v[190:193], v[218:221], v[14:17]
	v_mfma_f32_16x16x32_bf16 v[14:17], v[210:213], v[82:85], v[198:201]
	v_mfma_f32_16x16x32_bf16 v[82:85], v[214:217], v[218:221], v[14:17]
	v_mfma_f32_16x16x32_bf16 v[14:17], v[186:189], v[222:225], v[202:205]
	v_mfma_f32_16x16x32_bf16 v[66:69], v[190:193], v[238:241], v[14:17]
	v_mfma_f32_16x16x32_bf16 v[14:17], v[210:213], v[222:225], v[206:209]
	v_mfma_f32_16x16x32_bf16 v[58:61], v[214:217], v[238:241], v[14:17]
	s_setprio 0
	s_barrier
	s_mov_b32 m0, s3
	ds_read_b128 v[194:197], v242 offset:49152
	ds_read_b128 v[198:201], v242 offset:50176
	ds_read_b128 v[202:205], v242 offset:51200
	ds_read_b128 v[206:209], v242 offset:52224
	ds_read_b128 v[218:221], v242 offset:53248
	ds_read_b128 v[222:225], v242 offset:54272
	ds_read_b128 v[226:229], v242 offset:55296
	ds_read_b128 v[230:233], v242 offset:56320
	global_load_lds_dwordx4 v[4:5], off
	s_mov_b32 m0, s5
	s_nop 0
	global_load_lds_dwordx4 v[6:7], off
	s_mov_b32 m0, s13
	s_nop 0
	global_load_lds_dwordx4 v[10:11], off
	s_mov_b32 m0, s14
	s_nop 0
	global_load_lds_dwordx4 v[12:13], off
	s_mov_b32 m0, s4
	s_nop 0
	global_load_lds_dwordx4 v[2:3], off
	s_mov_b32 m0, s9
	s_nop 0
	global_load_lds_dwordx4 v[8:9], off
	s_waitcnt vmcnt(8)
	s_waitcnt lgkmcnt(0)
	s_barrier
	s_setprio 1
	v_mfma_f32_16x16x32_bf16 v[2:5], v[50:53], v[194:197], v[18:21]
	v_mfma_f32_16x16x32_bf16 v[70:73], v[54:57], v[198:201], v[2:5]
	v_mfma_f32_16x16x32_bf16 v[2:5], v[178:181], v[194:197], v[22:25]
	v_mfma_f32_16x16x32_bf16 v[62:65], v[182:185], v[198:201], v[2:5]
	v_mfma_f32_16x16x32_bf16 v[2:5], v[50:53], v[202:205], v[26:29]
	v_mfma_f32_16x16x32_bf16 v[46:49], v[54:57], v[206:209], v[2:5]
	v_mfma_f32_16x16x32_bf16 v[2:5], v[178:181], v[202:205], v[160:163]
	v_mfma_f32_16x16x32_bf16 v[42:45], v[182:185], v[206:209], v[2:5]
	v_mfma_f32_16x16x32_bf16 v[2:5], v[50:53], v[218:221], v[164:167]
	v_mfma_f32_16x16x32_bf16 v[30:33], v[54:57], v[222:225], v[2:5]
	v_mfma_f32_16x16x32_bf16 v[2:5], v[178:181], v[218:221], v[168:171]
	v_mfma_f32_16x16x32_bf16 v[26:29], v[182:185], v[222:225], v[2:5]
	v_mfma_f32_16x16x32_bf16 v[2:5], v[50:53], v[226:229], v[136:139]
	v_mfma_f32_16x16x32_bf16 v[14:17], v[54:57], v[230:233], v[2:5]
	v_mfma_f32_16x16x32_bf16 v[2:5], v[178:181], v[226:229], v[34:37]
	v_mfma_f32_16x16x32_bf16 v[10:13], v[182:185], v[230:233], v[2:5]
	v_mfma_f32_16x16x32_bf16 v[2:5], v[186:189], v[194:197], v[38:41]
	v_mfma_f32_16x16x32_bf16 v[54:57], v[190:193], v[198:201], v[2:5]
	v_mfma_f32_16x16x32_bf16 v[2:5], v[210:213], v[194:197], v[140:143]
	v_mfma_f32_16x16x32_bf16 v[50:53], v[214:217], v[198:201], v[2:5]
	v_mfma_f32_16x16x32_bf16 v[2:5], v[186:189], v[202:205], v[144:147]
	v_mfma_f32_16x16x32_bf16 v[38:41], v[190:193], v[206:209], v[2:5]
	v_mfma_f32_16x16x32_bf16 v[2:5], v[210:213], v[202:205], v[148:151]
	v_mfma_f32_16x16x32_bf16 v[34:37], v[214:217], v[206:209], v[2:5]
	v_mfma_f32_16x16x32_bf16 v[2:5], v[186:189], v[218:221], v[172:175]
	v_mfma_f32_16x16x32_bf16 v[22:25], v[190:193], v[222:225], v[2:5]
	v_mfma_f32_16x16x32_bf16 v[2:5], v[210:213], v[218:221], v[132:135]
	v_mfma_f32_16x16x32_bf16 v[18:21], v[214:217], v[222:225], v[2:5]
	v_mfma_f32_16x16x32_bf16 v[2:5], v[186:189], v[226:229], v[152:155]
	v_mfma_f32_16x16x32_bf16 v[6:9], v[190:193], v[230:233], v[2:5]
	v_mfma_f32_16x16x32_bf16 v[2:5], v[210:213], v[226:229], v[156:159]
	v_mfma_f32_16x16x32_bf16 v[2:5], v[214:217], v[230:233], v[2:5]
	s_setprio 0
	s_barrier
	s_cbranch_scc1 .LBB0_1139
	s_barrier

.Lpk1179_peel:
	ds_read_b128 v[144:147], v158
	ds_read_b128 v[164:167], v158 offset:1024
	ds_read_b128 v[168:171], v158 offset:2048
	ds_read_b128 v[172:175], v158 offset:3072
	ds_read_b128 v[178:181], v159
	ds_read_b128 v[182:185], v159 offset:1024
	ds_read_b128 v[186:189], v159 offset:2048
	ds_read_b128 v[190:193], v159 offset:3072
	s_add_u32 s2, s36, 0xfffc0080
	s_addc_u32 s3, s37, -1
	s_cmp_eq_u32 s61, 12
	s_cselect_b32 s3, s19, s3
	s_cselect_b32 s2, s21, s2
	s_cselect_b32 s39, s57, s60
	s_cselect_b32 s38, s58, s59
	v_lshl_add_u64 v[226:227], s[36:37], 0, v[138:139]
	s_add_i32 m0, s42, 0xc000
	ds_read_b128 v[194:197], v160
	ds_read_b128 v[198:201], v160 offset:1024
	ds_read_b128 v[202:205], v160 offset:2048
	ds_read_b128 v[206:209], v160 offset:3072
	ds_read_b128 v[210:213], v160 offset:4096
	ds_read_b128 v[214:217], v160 offset:5120
	ds_read_b128 v[218:221], v160 offset:6144
	ds_read_b128 v[222:225], v160 offset:7168
	global_load_lds_dwordx4 v[226:227], off
	v_lshl_add_u64 v[226:227], s[36:37], 0, v[140:141]
	s_add_i32 m0, s42, 0xe000
	s_nop 0
	global_load_lds_dwordx4 v[226:227], off
	s_waitcnt vmcnt(8)
	s_waitcnt lgkmcnt(0)
	s_barrier
	s_setprio 1
	v_mfma_f32_16x16x32_bf16 v[126:129], v[144:147], v[194:197], 0
	v_mfma_f32_16x16x32_bf16 v[122:125], v[168:171], v[194:197], 0
	v_mfma_f32_16x16x32_bf16 v[114:117], v[144:147], v[202:205], 0
	v_mfma_f32_16x16x32_bf16 v[106:109], v[168:171], v[202:205], 0
	v_mfma_f32_16x16x32_bf16 v[98:101], v[144:147], v[210:213], 0
	v_mfma_f32_16x16x32_bf16 v[90:93], v[168:171], v[210:213], 0
	v_mfma_f32_16x16x32_bf16 v[82:85], v[144:147], v[218:221], 0
	v_mfma_f32_16x16x32_bf16 v[74:77], v[168:171], v[218:221], 0
	v_mfma_f32_16x16x32_bf16 v[126:129], v[164:167], v[198:201], v[126:129]
	v_mfma_f32_16x16x32_bf16 v[122:125], v[172:175], v[198:201], v[122:125]
	v_mfma_f32_16x16x32_bf16 v[114:117], v[164:167], v[206:209], v[114:117]
	v_mfma_f32_16x16x32_bf16 v[106:109], v[172:175], v[206:209], v[106:109]
	v_mfma_f32_16x16x32_bf16 v[98:101], v[164:167], v[214:217], v[98:101]
	v_mfma_f32_16x16x32_bf16 v[90:93], v[172:175], v[214:217], v[90:93]
	v_mfma_f32_16x16x32_bf16 v[82:85], v[164:167], v[222:225], v[82:85]
	v_mfma_f32_16x16x32_bf16 v[74:77], v[172:175], v[222:225], v[74:77]
	v_mfma_f32_16x16x32_bf16 v[118:121], v[178:181], v[194:197], 0
	v_mfma_f32_16x16x32_bf16 v[110:113], v[186:189], v[194:197], 0
	v_mfma_f32_16x16x32_bf16 v[102:105], v[178:181], v[202:205], 0
	v_mfma_f32_16x16x32_bf16 v[94:97], v[186:189], v[202:205], 0
	v_mfma_f32_16x16x32_bf16 v[86:89], v[178:181], v[210:213], 0
	v_mfma_f32_16x16x32_bf16 v[78:81], v[186:189], v[210:213], 0
	v_mfma_f32_16x16x32_bf16 v[70:73], v[178:181], v[218:221], 0
	v_mfma_f32_16x16x32_bf16 v[66:69], v[186:189], v[218:221], 0
	v_mfma_f32_16x16x32_bf16 v[118:121], v[182:185], v[198:201], v[118:121]
	v_mfma_f32_16x16x32_bf16 v[110:113], v[190:193], v[198:201], v[110:113]
	v_mfma_f32_16x16x32_bf16 v[102:105], v[182:185], v[206:209], v[102:105]
	v_mfma_f32_16x16x32_bf16 v[94:97], v[190:193], v[206:209], v[94:97]
	v_mfma_f32_16x16x32_bf16 v[86:89], v[182:185], v[214:217], v[86:89]
	v_mfma_f32_16x16x32_bf16 v[78:81], v[190:193], v[214:217], v[78:81]
	v_mfma_f32_16x16x32_bf16 v[70:73], v[182:185], v[222:225], v[70:73]
	v_mfma_f32_16x16x32_bf16 v[66:69], v[190:193], v[222:225], v[66:69]
	s_setprio 0
	s_barrier
	s_add_i32 s62, s51, s41
	v_lshl_add_u64 v[226:227], s[38:39], 0, v[132:133]
	s_mov_b32 m0, s62
	ds_read_b128 v[194:197], v160 offset:16384
	ds_read_b128 v[198:201], v160 offset:17408
	ds_read_b128 v[202:205], v160 offset:18432
	ds_read_b128 v[206:209], v160 offset:19456
	ds_read_b128 v[210:213], v160 offset:20480
	ds_read_b128 v[214:217], v160 offset:21504
	ds_read_b128 v[218:221], v160 offset:22528
	ds_read_b128 v[222:225], v160 offset:23552
	global_load_lds_dwordx4 v[226:227], off
	s_add_i32 m0, s62, 0x2000
	s_add_u32 s62, s38, 0x40000
	v_lshl_add_u64 v[228:229], s[38:39], 0, v[136:137]
	s_addc_u32 s63, s39, 0
	s_add_i32 s64, s52, s41
	global_load_lds_dwordx4 v[228:229], off
	v_lshl_add_u64 v[230:231], s[62:63], 0, v[132:133]
	s_mov_b32 m0, s64
	v_lshl_add_u64 v[232:233], s[2:3], 0, v[134:135]
	global_load_lds_dwordx4 v[230:231], off
	v_lshl_add_u64 v[230:231], s[62:63], 0, v[136:137]
	s_add_i32 m0, s64, 0x2000
	s_nop 0
	global_load_lds_dwordx4 v[230:231], off
	v_lshl_add_u64 v[230:231], s[2:3], 0, v[130:131]
	s_mov_b32 m0, s42
	s_nop 0
	global_load_lds_dwordx4 v[230:231], off
	s_mov_b32 m0, s43
	s_nop 0
	global_load_lds_dwordx4 v[232:233], off
	s_waitcnt vmcnt(8)
	s_waitcnt lgkmcnt(0)
	s_barrier
	s_setprio 1
	v_mfma_f32_16x16x32_bf16 v[62:65], v[144:147], v[194:197], 0
	v_mfma_f32_16x16x32_bf16 v[58:61], v[168:171], v[194:197], 0
	v_mfma_f32_16x16x32_bf16 v[50:53], v[144:147], v[202:205], 0
	v_mfma_f32_16x16x32_bf16 v[42:45], v[168:171], v[202:205], 0
	v_mfma_f32_16x16x32_bf16 v[34:37], v[144:147], v[210:213], 0
	v_mfma_f32_16x16x32_bf16 v[26:29], v[168:171], v[210:213], 0
	v_mfma_f32_16x16x32_bf16 v[18:21], v[144:147], v[218:221], 0
	v_mfma_f32_16x16x32_bf16 v[10:13], v[168:171], v[218:221], 0
	v_mfma_f32_16x16x32_bf16 v[62:65], v[164:167], v[198:201], v[62:65]
	v_mfma_f32_16x16x32_bf16 v[58:61], v[172:175], v[198:201], v[58:61]
	v_mfma_f32_16x16x32_bf16 v[50:53], v[164:167], v[206:209], v[50:53]
	v_mfma_f32_16x16x32_bf16 v[42:45], v[172:175], v[206:209], v[42:45]
	v_mfma_f32_16x16x32_bf16 v[34:37], v[164:167], v[214:217], v[34:37]
	v_mfma_f32_16x16x32_bf16 v[26:29], v[172:175], v[214:217], v[26:29]
	v_mfma_f32_16x16x32_bf16 v[18:21], v[164:167], v[222:225], v[18:21]
	v_mfma_f32_16x16x32_bf16 v[10:13], v[172:175], v[222:225], v[10:13]
	v_mfma_f32_16x16x32_bf16 v[54:57], v[178:181], v[194:197], 0
	v_mfma_f32_16x16x32_bf16 v[46:49], v[186:189], v[194:197], 0
	v_mfma_f32_16x16x32_bf16 v[38:41], v[178:181], v[202:205], 0
	v_mfma_f32_16x16x32_bf16 v[30:33], v[186:189], v[202:205], 0
	v_mfma_f32_16x16x32_bf16 v[22:25], v[178:181], v[210:213], 0
	v_mfma_f32_16x16x32_bf16 v[14:17], v[186:189], v[210:213], 0
	v_mfma_f32_16x16x32_bf16 v[6:9], v[178:181], v[218:221], 0
	v_mfma_f32_16x16x32_bf16 v[2:5], v[186:189], v[218:221], 0
	v_mfma_f32_16x16x32_bf16 v[54:57], v[182:185], v[198:201], v[54:57]
	v_mfma_f32_16x16x32_bf16 v[46:49], v[190:193], v[198:201], v[46:49]
	v_mfma_f32_16x16x32_bf16 v[38:41], v[182:185], v[206:209], v[38:41]
	v_mfma_f32_16x16x32_bf16 v[30:33], v[190:193], v[206:209], v[30:33]
	v_mfma_f32_16x16x32_bf16 v[22:25], v[182:185], v[214:217], v[22:25]
	v_mfma_f32_16x16x32_bf16 v[14:17], v[190:193], v[214:217], v[14:17]
	v_mfma_f32_16x16x32_bf16 v[6:9], v[182:185], v[222:225], v[6:9]
	v_mfma_f32_16x16x32_bf16 v[2:5], v[190:193], v[222:225], v[2:5]
	s_setprio 0
	s_barrier
	s_add_i32 s62, 0, 0x18000
	v_add_u32_e32 v163, s62, v148
	s_add_i32 s63, 0, 0x1c000
	ds_read_b128 v[144:147], v163
	ds_read_b128 v[164:167], v163 offset:1024
	ds_read_b128 v[168:171], v163 offset:2048
	ds_read_b128 v[172:175], v163 offset:3072
	v_add_u32_e32 v163, s63, v148
	ds_read_b128 v[178:181], v163
	ds_read_b128 v[182:185], v163 offset:1024
	ds_read_b128 v[186:189], v163 offset:2048
	ds_read_b128 v[190:193], v163 offset:3072
	s_add_u32 s2, s2, 0x40000
	s_addc_u32 s3, s3, 0
	s_mov_b32 m0, s44
	v_lshl_add_u64 v[234:235], s[2:3], 0, v[130:131]
	ds_read_b128 v[194:197], v160 offset:32768
	ds_read_b128 v[198:201], v160 offset:33792
	ds_read_b128 v[202:205], v160 offset:34816
	ds_read_b128 v[206:209], v160 offset:35840
	ds_read_b128 v[210:213], v160 offset:36864
	ds_read_b128 v[214:217], v160 offset:37888
	ds_read_b128 v[218:221], v160 offset:38912
	ds_read_b128 v[222:225], v160 offset:39936
	global_load_lds_dwordx4 v[234:235], off
	v_lshl_add_u64 v[234:235], s[2:3], 0, v[134:135]
	s_mov_b32 m0, s45
	s_nop 0
	global_load_lds_dwordx4 v[234:235], off
	s_waitcnt vmcnt(8)
	s_waitcnt lgkmcnt(0)
	s_barrier
	s_setprio 1
	v_mfma_f32_16x16x32_bf16 v[126:129], v[144:147], v[194:197], v[126:129]
	v_mfma_f32_16x16x32_bf16 v[122:125], v[168:171], v[194:197], v[122:125]
	v_mfma_f32_16x16x32_bf16 v[114:117], v[144:147], v[202:205], v[114:117]
	v_mfma_f32_16x16x32_bf16 v[106:109], v[168:171], v[202:205], v[106:109]
	v_mfma_f32_16x16x32_bf16 v[98:101], v[144:147], v[210:213], v[98:101]
	v_mfma_f32_16x16x32_bf16 v[90:93], v[168:171], v[210:213], v[90:93]
	v_mfma_f32_16x16x32_bf16 v[82:85], v[144:147], v[218:221], v[82:85]
	v_mfma_f32_16x16x32_bf16 v[74:77], v[168:171], v[218:221], v[74:77]
	v_mfma_f32_16x16x32_bf16 v[126:129], v[164:167], v[198:201], v[126:129]
	v_mfma_f32_16x16x32_bf16 v[122:125], v[172:175], v[198:201], v[122:125]
	v_mfma_f32_16x16x32_bf16 v[114:117], v[164:167], v[206:209], v[114:117]
	v_mfma_f32_16x16x32_bf16 v[106:109], v[172:175], v[206:209], v[106:109]
	v_mfma_f32_16x16x32_bf16 v[98:101], v[164:167], v[214:217], v[98:101]
	v_mfma_f32_16x16x32_bf16 v[90:93], v[172:175], v[214:217], v[90:93]
	v_mfma_f32_16x16x32_bf16 v[82:85], v[164:167], v[222:225], v[82:85]
	v_mfma_f32_16x16x32_bf16 v[74:77], v[172:175], v[222:225], v[74:77]
	v_mfma_f32_16x16x32_bf16 v[118:121], v[178:181], v[194:197], v[118:121]
	v_mfma_f32_16x16x32_bf16 v[110:113], v[186:189], v[194:197], v[110:113]
	v_mfma_f32_16x16x32_bf16 v[102:105], v[178:181], v[202:205], v[102:105]
	v_mfma_f32_16x16x32_bf16 v[94:97], v[186:189], v[202:205], v[94:97]
	v_mfma_f32_16x16x32_bf16 v[86:89], v[178:181], v[210:213], v[86:89]
	v_mfma_f32_16x16x32_bf16 v[78:81], v[186:189], v[210:213], v[78:81]
	v_mfma_f32_16x16x32_bf16 v[70:73], v[178:181], v[218:221], v[70:73]
	v_mfma_f32_16x16x32_bf16 v[66:69], v[186:189], v[218:221], v[66:69]
	v_mfma_f32_16x16x32_bf16 v[118:121], v[182:185], v[198:201], v[118:121]
	v_mfma_f32_16x16x32_bf16 v[110:113], v[190:193], v[198:201], v[110:113]
	v_mfma_f32_16x16x32_bf16 v[102:105], v[182:185], v[206:209], v[102:105]
	v_mfma_f32_16x16x32_bf16 v[94:97], v[190:193], v[206:209], v[94:97]
	v_mfma_f32_16x16x32_bf16 v[86:89], v[182:185], v[214:217], v[86:89]
	v_mfma_f32_16x16x32_bf16 v[78:81], v[190:193], v[214:217], v[78:81]
	v_mfma_f32_16x16x32_bf16 v[70:73], v[182:185], v[222:225], v[70:73]
	v_mfma_f32_16x16x32_bf16 v[66:69], v[190:193], v[222:225], v[66:69]
	s_setprio 0
	s_barrier
	s_add_i32 s2, s62, s41
	v_lshl_add_u64 v[226:227], v[226:227], 0, s[10:11]
	s_mov_b32 m0, s2
	ds_read_b128 v[194:197], v160 offset:49152
	ds_read_b128 v[198:201], v160 offset:50176
	ds_read_b128 v[202:205], v160 offset:51200
	ds_read_b128 v[206:209], v160 offset:52224
	ds_read_b128 v[210:213], v160 offset:53248
	ds_read_b128 v[214:217], v160 offset:54272
	ds_read_b128 v[218:221], v160 offset:55296
	ds_read_b128 v[222:225], v160 offset:56320
	global_load_lds_dwordx4 v[226:227], off
	s_add_i32 m0, s2, 0x2000
	s_add_u32 s2, s38, 0x40080
	v_lshl_add_u64 v[226:227], v[228:229], 0, s[10:11]
	s_addc_u32 s3, s39, 0
	s_add_i32 s38, s63, s41
	global_load_lds_dwordx4 v[226:227], off
	v_lshl_add_u64 v[226:227], s[2:3], 0, v[132:133]
	s_mov_b32 m0, s38
	s_nop 0
	global_load_lds_dwordx4 v[226:227], off
	v_lshl_add_u64 v[226:227], s[2:3], 0, v[136:137]
	s_add_i32 m0, s38, 0x2000
	s_nop 0
	global_load_lds_dwordx4 v[226:227], off
	v_lshl_add_u64 v[226:227], v[230:231], 0, s[10:11]
	s_mov_b32 m0, s47
	s_nop 0
	global_load_lds_dwordx4 v[226:227], off
	v_lshl_add_u64 v[226:227], v[232:233], 0, s[10:11]
	s_mov_b32 m0, s48
	s_nop 0
	global_load_lds_dwordx4 v[226:227], off
	s_waitcnt vmcnt(8)
	s_waitcnt lgkmcnt(0)
	s_barrier
	s_setprio 1
	v_mfma_f32_16x16x32_bf16 v[62:65], v[144:147], v[194:197], v[62:65]
	v_mfma_f32_16x16x32_bf16 v[58:61], v[168:171], v[194:197], v[58:61]
	v_mfma_f32_16x16x32_bf16 v[50:53], v[144:147], v[202:205], v[50:53]
	v_mfma_f32_16x16x32_bf16 v[42:45], v[168:171], v[202:205], v[42:45]
	v_mfma_f32_16x16x32_bf16 v[34:37], v[144:147], v[210:213], v[34:37]
	v_mfma_f32_16x16x32_bf16 v[26:29], v[168:171], v[210:213], v[26:29]
	v_mfma_f32_16x16x32_bf16 v[18:21], v[144:147], v[218:221], v[18:21]
	v_mfma_f32_16x16x32_bf16 v[10:13], v[168:171], v[218:221], v[10:13]
	v_mfma_f32_16x16x32_bf16 v[62:65], v[164:167], v[198:201], v[62:65]
	v_mfma_f32_16x16x32_bf16 v[58:61], v[172:175], v[198:201], v[58:61]
	v_mfma_f32_16x16x32_bf16 v[50:53], v[164:167], v[206:209], v[50:53]
	v_mfma_f32_16x16x32_bf16 v[42:45], v[172:175], v[206:209], v[42:45]
	v_mfma_f32_16x16x32_bf16 v[34:37], v[164:167], v[214:217], v[34:37]
	v_mfma_f32_16x16x32_bf16 v[26:29], v[172:175], v[214:217], v[26:29]
	v_mfma_f32_16x16x32_bf16 v[18:21], v[164:167], v[222:225], v[18:21]
	v_mfma_f32_16x16x32_bf16 v[10:13], v[172:175], v[222:225], v[10:13]
	v_mfma_f32_16x16x32_bf16 v[54:57], v[178:181], v[194:197], v[54:57]
	v_mfma_f32_16x16x32_bf16 v[46:49], v[186:189], v[194:197], v[46:49]
	v_mfma_f32_16x16x32_bf16 v[38:41], v[178:181], v[202:205], v[38:41]
	v_mfma_f32_16x16x32_bf16 v[30:33], v[186:189], v[202:205], v[30:33]
	v_mfma_f32_16x16x32_bf16 v[22:25], v[178:181], v[210:213], v[22:25]
	v_mfma_f32_16x16x32_bf16 v[14:17], v[186:189], v[210:213], v[14:17]
	v_mfma_f32_16x16x32_bf16 v[6:9], v[178:181], v[218:221], v[6:9]
	v_mfma_f32_16x16x32_bf16 v[2:5], v[186:189], v[218:221], v[2:5]
	v_mfma_f32_16x16x32_bf16 v[54:57], v[182:185], v[198:201], v[54:57]
	v_mfma_f32_16x16x32_bf16 v[46:49], v[190:193], v[198:201], v[46:49]
	v_mfma_f32_16x16x32_bf16 v[38:41], v[182:185], v[206:209], v[38:41]
	v_mfma_f32_16x16x32_bf16 v[30:33], v[190:193], v[206:209], v[30:33]
	v_mfma_f32_16x16x32_bf16 v[22:25], v[182:185], v[214:217], v[22:25]
	v_mfma_f32_16x16x32_bf16 v[14:17], v[190:193], v[214:217], v[14:17]
	v_mfma_f32_16x16x32_bf16 v[6:9], v[182:185], v[222:225], v[6:9]
	v_mfma_f32_16x16x32_bf16 v[2:5], v[190:193], v[222:225], v[2:5]
	s_setprio 0
	s_barrier
	s_add_i32 s61, s61, 2
	s_add_u32 s36, s36, 0x100
	s_addc_u32 s37, s37, 0
	s_add_u32 s59, s59, 0x100
	s_addc_u32 s60, s60, 0
	s_cmp_gt_u32 s61, 13
	s_cbranch_scc0 .LBB0_1179
	s_branch .Lpk1179_exit
.LBB0_1179:
	ds_read_b128 v[144:147], v158
	ds_read_b128 v[164:167], v158 offset:1024
	ds_read_b128 v[168:171], v158 offset:2048
	ds_read_b128 v[172:175], v158 offset:3072
	ds_read_b128 v[178:181], v159
	ds_read_b128 v[182:185], v159 offset:1024
	ds_read_b128 v[186:189], v159 offset:2048
	ds_read_b128 v[190:193], v159 offset:3072
	s_add_u32 s2, s36, 0xfffc0080
	s_addc_u32 s3, s37, -1
	s_cmp_eq_u32 s61, 12
	s_cselect_b32 s3, s19, s3
	s_cselect_b32 s2, s21, s2
	s_cselect_b32 s39, s57, s60
	s_cselect_b32 s38, s58, s59
	v_lshl_add_u64 v[226:227], s[36:37], 0, v[138:139]
	s_add_i32 m0, s42, 0xc000
	ds_read_b128 v[194:197], v160
	ds_read_b128 v[198:201], v160 offset:1024
	ds_read_b128 v[202:205], v160 offset:2048
	ds_read_b128 v[206:209], v160 offset:3072
	ds_read_b128 v[210:213], v160 offset:4096
	ds_read_b128 v[214:217], v160 offset:5120
	ds_read_b128 v[218:221], v160 offset:6144
	ds_read_b128 v[222:225], v160 offset:7168
	global_load_lds_dwordx4 v[226:227], off
	v_lshl_add_u64 v[226:227], s[36:37], 0, v[140:141]
	s_add_i32 m0, s42, 0xe000
	s_nop 0
	global_load_lds_dwordx4 v[226:227], off
	s_waitcnt vmcnt(8)
	s_waitcnt lgkmcnt(0)
	s_barrier
	s_setprio 1
	v_mfma_f32_16x16x32_bf16 v[126:129], v[144:147], v[194:197], v[126:129]
	v_mfma_f32_16x16x32_bf16 v[122:125], v[168:171], v[194:197], v[122:125]
	v_mfma_f32_16x16x32_bf16 v[114:117], v[144:147], v[202:205], v[114:117]
	v_mfma_f32_16x16x32_bf16 v[106:109], v[168:171], v[202:205], v[106:109]
	v_mfma_f32_16x16x32_bf16 v[98:101], v[144:147], v[210:213], v[98:101]
	v_mfma_f32_16x16x32_bf16 v[90:93], v[168:171], v[210:213], v[90:93]
	v_mfma_f32_16x16x32_bf16 v[82:85], v[144:147], v[218:221], v[82:85]
	v_mfma_f32_16x16x32_bf16 v[74:77], v[168:171], v[218:221], v[74:77]
	v_mfma_f32_16x16x32_bf16 v[126:129], v[164:167], v[198:201], v[126:129]
	v_mfma_f32_16x16x32_bf16 v[122:125], v[172:175], v[198:201], v[122:125]
	v_mfma_f32_16x16x32_bf16 v[114:117], v[164:167], v[206:209], v[114:117]
	v_mfma_f32_16x16x32_bf16 v[106:109], v[172:175], v[206:209], v[106:109]
	v_mfma_f32_16x16x32_bf16 v[98:101], v[164:167], v[214:217], v[98:101]
	v_mfma_f32_16x16x32_bf16 v[90:93], v[172:175], v[214:217], v[90:93]
	v_mfma_f32_16x16x32_bf16 v[82:85], v[164:167], v[222:225], v[82:85]
	v_mfma_f32_16x16x32_bf16 v[74:77], v[172:175], v[222:225], v[74:77]
	v_mfma_f32_16x16x32_bf16 v[118:121], v[178:181], v[194:197], v[118:121]
	v_mfma_f32_16x16x32_bf16 v[110:113], v[186:189], v[194:197], v[110:113]
	v_mfma_f32_16x16x32_bf16 v[102:105], v[178:181], v[202:205], v[102:105]
	v_mfma_f32_16x16x32_bf16 v[94:97], v[186:189], v[202:205], v[94:97]
	v_mfma_f32_16x16x32_bf16 v[86:89], v[178:181], v[210:213], v[86:89]
	v_mfma_f32_16x16x32_bf16 v[78:81], v[186:189], v[210:213], v[78:81]
	v_mfma_f32_16x16x32_bf16 v[70:73], v[178:181], v[218:221], v[70:73]
	v_mfma_f32_16x16x32_bf16 v[66:69], v[186:189], v[218:221], v[66:69]
	v_mfma_f32_16x16x32_bf16 v[118:121], v[182:185], v[198:201], v[118:121]
	v_mfma_f32_16x16x32_bf16 v[110:113], v[190:193], v[198:201], v[110:113]
	v_mfma_f32_16x16x32_bf16 v[102:105], v[182:185], v[206:209], v[102:105]
	v_mfma_f32_16x16x32_bf16 v[94:97], v[190:193], v[206:209], v[94:97]
	v_mfma_f32_16x16x32_bf16 v[86:89], v[182:185], v[214:217], v[86:89]
	v_mfma_f32_16x16x32_bf16 v[78:81], v[190:193], v[214:217], v[78:81]
	v_mfma_f32_16x16x32_bf16 v[70:73], v[182:185], v[222:225], v[70:73]
	v_mfma_f32_16x16x32_bf16 v[66:69], v[190:193], v[222:225], v[66:69]
	s_setprio 0
	s_barrier
	s_add_i32 s62, s51, s41
	v_lshl_add_u64 v[226:227], s[38:39], 0, v[132:133]
	s_mov_b32 m0, s62
	ds_read_b128 v[194:197], v160 offset:16384
	ds_read_b128 v[198:201], v160 offset:17408
	ds_read_b128 v[202:205], v160 offset:18432
	ds_read_b128 v[206:209], v160 offset:19456
	ds_read_b128 v[210:213], v160 offset:20480
	ds_read_b128 v[214:217], v160 offset:21504
	ds_read_b128 v[218:221], v160 offset:22528
	ds_read_b128 v[222:225], v160 offset:23552
	global_load_lds_dwordx4 v[226:227], off
	s_add_i32 m0, s62, 0x2000
	s_add_u32 s62, s38, 0x40000
	v_lshl_add_u64 v[228:229], s[38:39], 0, v[136:137]
	s_addc_u32 s63, s39, 0
	s_add_i32 s64, s52, s41
	global_load_lds_dwordx4 v[228:229], off
	v_lshl_add_u64 v[230:231], s[62:63], 0, v[132:133]
	s_mov_b32 m0, s64
	v_lshl_add_u64 v[232:233], s[2:3], 0, v[134:135]
	global_load_lds_dwordx4 v[230:231], off
	v_lshl_add_u64 v[230:231], s[62:63], 0, v[136:137]
	s_add_i32 m0, s64, 0x2000
	s_nop 0
	global_load_lds_dwordx4 v[230:231], off
	v_lshl_add_u64 v[230:231], s[2:3], 0, v[130:131]
	s_mov_b32 m0, s42
	s_nop 0
	global_load_lds_dwordx4 v[230:231], off
	s_mov_b32 m0, s43
	s_nop 0
	global_load_lds_dwordx4 v[232:233], off
	s_waitcnt vmcnt(8)
	s_waitcnt lgkmcnt(0)
	s_barrier
	s_setprio 1
	v_mfma_f32_16x16x32_bf16 v[62:65], v[144:147], v[194:197], v[62:65]
	v_mfma_f32_16x16x32_bf16 v[58:61], v[168:171], v[194:197], v[58:61]
	v_mfma_f32_16x16x32_bf16 v[50:53], v[144:147], v[202:205], v[50:53]
	v_mfma_f32_16x16x32_bf16 v[42:45], v[168:171], v[202:205], v[42:45]
	v_mfma_f32_16x16x32_bf16 v[34:37], v[144:147], v[210:213], v[34:37]
	v_mfma_f32_16x16x32_bf16 v[26:29], v[168:171], v[210:213], v[26:29]
	v_mfma_f32_16x16x32_bf16 v[18:21], v[144:147], v[218:221], v[18:21]
	v_mfma_f32_16x16x32_bf16 v[10:13], v[168:171], v[218:221], v[10:13]
	v_mfma_f32_16x16x32_bf16 v[62:65], v[164:167], v[198:201], v[62:65]
	v_mfma_f32_16x16x32_bf16 v[58:61], v[172:175], v[198:201], v[58:61]
	v_mfma_f32_16x16x32_bf16 v[50:53], v[164:167], v[206:209], v[50:53]
	v_mfma_f32_16x16x32_bf16 v[42:45], v[172:175], v[206:209], v[42:45]
	v_mfma_f32_16x16x32_bf16 v[34:37], v[164:167], v[214:217], v[34:37]
	v_mfma_f32_16x16x32_bf16 v[26:29], v[172:175], v[214:217], v[26:29]
	v_mfma_f32_16x16x32_bf16 v[18:21], v[164:167], v[222:225], v[18:21]
	v_mfma_f32_16x16x32_bf16 v[10:13], v[172:175], v[222:225], v[10:13]
	v_mfma_f32_16x16x32_bf16 v[54:57], v[178:181], v[194:197], v[54:57]
	v_mfma_f32_16x16x32_bf16 v[46:49], v[186:189], v[194:197], v[46:49]
	v_mfma_f32_16x16x32_bf16 v[38:41], v[178:181], v[202:205], v[38:41]
	v_mfma_f32_16x16x32_bf16 v[30:33], v[186:189], v[202:205], v[30:33]
	v_mfma_f32_16x16x32_bf16 v[22:25], v[178:181], v[210:213], v[22:25]
	v_mfma_f32_16x16x32_bf16 v[14:17], v[186:189], v[210:213], v[14:17]
	v_mfma_f32_16x16x32_bf16 v[6:9], v[178:181], v[218:221], v[6:9]
	v_mfma_f32_16x16x32_bf16 v[2:5], v[186:189], v[218:221], v[2:5]
	v_mfma_f32_16x16x32_bf16 v[54:57], v[182:185], v[198:201], v[54:57]
	v_mfma_f32_16x16x32_bf16 v[46:49], v[190:193], v[198:201], v[46:49]
	v_mfma_f32_16x16x32_bf16 v[38:41], v[182:185], v[206:209], v[38:41]
	v_mfma_f32_16x16x32_bf16 v[30:33], v[190:193], v[206:209], v[30:33]
	v_mfma_f32_16x16x32_bf16 v[22:25], v[182:185], v[214:217], v[22:25]
	v_mfma_f32_16x16x32_bf16 v[14:17], v[190:193], v[214:217], v[14:17]
	v_mfma_f32_16x16x32_bf16 v[6:9], v[182:185], v[222:225], v[6:9]
	v_mfma_f32_16x16x32_bf16 v[2:5], v[190:193], v[222:225], v[2:5]
	s_setprio 0
	s_barrier
	s_add_i32 s62, 0, 0x18000
	v_add_u32_e32 v163, s62, v148
	s_add_i32 s63, 0, 0x1c000
	ds_read_b128 v[144:147], v163
	ds_read_b128 v[164:167], v163 offset:1024
	ds_read_b128 v[168:171], v163 offset:2048
	ds_read_b128 v[172:175], v163 offset:3072
	v_add_u32_e32 v163, s63, v148
	ds_read_b128 v[178:181], v163
	ds_read_b128 v[182:185], v163 offset:1024
	ds_read_b128 v[186:189], v163 offset:2048
	ds_read_b128 v[190:193], v163 offset:3072
	s_add_u32 s2, s2, 0x40000
	s_addc_u32 s3, s3, 0
	s_mov_b32 m0, s44
	v_lshl_add_u64 v[234:235], s[2:3], 0, v[130:131]
	ds_read_b128 v[194:197], v160 offset:32768
	ds_read_b128 v[198:201], v160 offset:33792
	ds_read_b128 v[202:205], v160 offset:34816
	ds_read_b128 v[206:209], v160 offset:35840
	ds_read_b128 v[210:213], v160 offset:36864
	ds_read_b128 v[214:217], v160 offset:37888
	ds_read_b128 v[218:221], v160 offset:38912
	ds_read_b128 v[222:225], v160 offset:39936
	global_load_lds_dwordx4 v[234:235], off
	v_lshl_add_u64 v[234:235], s[2:3], 0, v[134:135]
	s_mov_b32 m0, s45
	s_nop 0
	global_load_lds_dwordx4 v[234:235], off
	s_waitcnt vmcnt(8)
	s_waitcnt lgkmcnt(0)
	s_barrier
	s_setprio 1
	v_mfma_f32_16x16x32_bf16 v[126:129], v[144:147], v[194:197], v[126:129]
	v_mfma_f32_16x16x32_bf16 v[122:125], v[168:171], v[194:197], v[122:125]
	v_mfma_f32_16x16x32_bf16 v[114:117], v[144:147], v[202:205], v[114:117]
	v_mfma_f32_16x16x32_bf16 v[106:109], v[168:171], v[202:205], v[106:109]
	v_mfma_f32_16x16x32_bf16 v[98:101], v[144:147], v[210:213], v[98:101]
	v_mfma_f32_16x16x32_bf16 v[90:93], v[168:171], v[210:213], v[90:93]
	v_mfma_f32_16x16x32_bf16 v[82:85], v[144:147], v[218:221], v[82:85]
	v_mfma_f32_16x16x32_bf16 v[74:77], v[168:171], v[218:221], v[74:77]
	v_mfma_f32_16x16x32_bf16 v[126:129], v[164:167], v[198:201], v[126:129]
	v_mfma_f32_16x16x32_bf16 v[122:125], v[172:175], v[198:201], v[122:125]
	v_mfma_f32_16x16x32_bf16 v[114:117], v[164:167], v[206:209], v[114:117]
	v_mfma_f32_16x16x32_bf16 v[106:109], v[172:175], v[206:209], v[106:109]
	v_mfma_f32_16x16x32_bf16 v[98:101], v[164:167], v[214:217], v[98:101]
	v_mfma_f32_16x16x32_bf16 v[90:93], v[172:175], v[214:217], v[90:93]
	v_mfma_f32_16x16x32_bf16 v[82:85], v[164:167], v[222:225], v[82:85]
	v_mfma_f32_16x16x32_bf16 v[74:77], v[172:175], v[222:225], v[74:77]
	v_mfma_f32_16x16x32_bf16 v[118:121], v[178:181], v[194:197], v[118:121]
	v_mfma_f32_16x16x32_bf16 v[110:113], v[186:189], v[194:197], v[110:113]
	v_mfma_f32_16x16x32_bf16 v[102:105], v[178:181], v[202:205], v[102:105]
	v_mfma_f32_16x16x32_bf16 v[94:97], v[186:189], v[202:205], v[94:97]
	v_mfma_f32_16x16x32_bf16 v[86:89], v[178:181], v[210:213], v[86:89]
	v_mfma_f32_16x16x32_bf16 v[78:81], v[186:189], v[210:213], v[78:81]
	v_mfma_f32_16x16x32_bf16 v[70:73], v[178:181], v[218:221], v[70:73]
	v_mfma_f32_16x16x32_bf16 v[66:69], v[186:189], v[218:221], v[66:69]
	v_mfma_f32_16x16x32_bf16 v[118:121], v[182:185], v[198:201], v[118:121]
	v_mfma_f32_16x16x32_bf16 v[110:113], v[190:193], v[198:201], v[110:113]
	v_mfma_f32_16x16x32_bf16 v[102:105], v[182:185], v[206:209], v[102:105]
	v_mfma_f32_16x16x32_bf16 v[94:97], v[190:193], v[206:209], v[94:97]
	v_mfma_f32_16x16x32_bf16 v[86:89], v[182:185], v[214:217], v[86:89]
	v_mfma_f32_16x16x32_bf16 v[78:81], v[190:193], v[214:217], v[78:81]
	v_mfma_f32_16x16x32_bf16 v[70:73], v[182:185], v[222:225], v[70:73]
	v_mfma_f32_16x16x32_bf16 v[66:69], v[190:193], v[222:225], v[66:69]
	s_setprio 0
	s_barrier
	s_add_i32 s2, s62, s41
	v_lshl_add_u64 v[226:227], v[226:227], 0, s[10:11]
	s_mov_b32 m0, s2
	ds_read_b128 v[194:197], v160 offset:49152
	ds_read_b128 v[198:201], v160 offset:50176
	ds_read_b128 v[202:205], v160 offset:51200
	ds_read_b128 v[206:209], v160 offset:52224
	ds_read_b128 v[210:213], v160 offset:53248
	ds_read_b128 v[214:217], v160 offset:54272
	ds_read_b128 v[218:221], v160 offset:55296
	ds_read_b128 v[222:225], v160 offset:56320
	global_load_lds_dwordx4 v[226:227], off
	s_add_i32 m0, s2, 0x2000
	s_add_u32 s2, s38, 0x40080
	v_lshl_add_u64 v[226:227], v[228:229], 0, s[10:11]
	s_addc_u32 s3, s39, 0
	s_add_i32 s38, s63, s41
	global_load_lds_dwordx4 v[226:227], off
	v_lshl_add_u64 v[226:227], s[2:3], 0, v[132:133]
	s_mov_b32 m0, s38
	s_nop 0
	global_load_lds_dwordx4 v[226:227], off
	v_lshl_add_u64 v[226:227], s[2:3], 0, v[136:137]
	s_add_i32 m0, s38, 0x2000
	s_nop 0
	global_load_lds_dwordx4 v[226:227], off
	v_lshl_add_u64 v[226:227], v[230:231], 0, s[10:11]
	s_mov_b32 m0, s47
	s_nop 0
	global_load_lds_dwordx4 v[226:227], off
	v_lshl_add_u64 v[226:227], v[232:233], 0, s[10:11]
	s_mov_b32 m0, s48
	s_nop 0
	global_load_lds_dwordx4 v[226:227], off
	s_waitcnt vmcnt(8)
	s_waitcnt lgkmcnt(0)
	s_barrier
	s_setprio 1
	v_mfma_f32_16x16x32_bf16 v[62:65], v[144:147], v[194:197], v[62:65]
	v_mfma_f32_16x16x32_bf16 v[58:61], v[168:171], v[194:197], v[58:61]
	v_mfma_f32_16x16x32_bf16 v[50:53], v[144:147], v[202:205], v[50:53]
	v_mfma_f32_16x16x32_bf16 v[42:45], v[168:171], v[202:205], v[42:45]
	v_mfma_f32_16x16x32_bf16 v[34:37], v[144:147], v[210:213], v[34:37]
	v_mfma_f32_16x16x32_bf16 v[26:29], v[168:171], v[210:213], v[26:29]
	v_mfma_f32_16x16x32_bf16 v[18:21], v[144:147], v[218:221], v[18:21]
	v_mfma_f32_16x16x32_bf16 v[10:13], v[168:171], v[218:221], v[10:13]
	v_mfma_f32_16x16x32_bf16 v[62:65], v[164:167], v[198:201], v[62:65]
	v_mfma_f32_16x16x32_bf16 v[58:61], v[172:175], v[198:201], v[58:61]
	v_mfma_f32_16x16x32_bf16 v[50:53], v[164:167], v[206:209], v[50:53]
	v_mfma_f32_16x16x32_bf16 v[42:45], v[172:175], v[206:209], v[42:45]
	v_mfma_f32_16x16x32_bf16 v[34:37], v[164:167], v[214:217], v[34:37]
	v_mfma_f32_16x16x32_bf16 v[26:29], v[172:175], v[214:217], v[26:29]
	v_mfma_f32_16x16x32_bf16 v[18:21], v[164:167], v[222:225], v[18:21]
	v_mfma_f32_16x16x32_bf16 v[10:13], v[172:175], v[222:225], v[10:13]
	v_mfma_f32_16x16x32_bf16 v[54:57], v[178:181], v[194:197], v[54:57]
	v_mfma_f32_16x16x32_bf16 v[46:49], v[186:189], v[194:197], v[46:49]
	v_mfma_f32_16x16x32_bf16 v[38:41], v[178:181], v[202:205], v[38:41]
	v_mfma_f32_16x16x32_bf16 v[30:33], v[186:189], v[202:205], v[30:33]
	v_mfma_f32_16x16x32_bf16 v[22:25], v[178:181], v[210:213], v[22:25]
	v_mfma_f32_16x16x32_bf16 v[14:17], v[186:189], v[210:213], v[14:17]
	v_mfma_f32_16x16x32_bf16 v[6:9], v[178:181], v[218:221], v[6:9]
	v_mfma_f32_16x16x32_bf16 v[2:5], v[186:189], v[218:221], v[2:5]
	v_mfma_f32_16x16x32_bf16 v[54:57], v[182:185], v[198:201], v[54:57]
	v_mfma_f32_16x16x32_bf16 v[46:49], v[190:193], v[198:201], v[46:49]
	v_mfma_f32_16x16x32_bf16 v[38:41], v[182:185], v[206:209], v[38:41]
	v_mfma_f32_16x16x32_bf16 v[30:33], v[190:193], v[206:209], v[30:33]
	v_mfma_f32_16x16x32_bf16 v[22:25], v[182:185], v[214:217], v[22:25]
	v_mfma_f32_16x16x32_bf16 v[14:17], v[190:193], v[214:217], v[14:17]
	v_mfma_f32_16x16x32_bf16 v[6:9], v[182:185], v[222:225], v[6:9]
	v_mfma_f32_16x16x32_bf16 v[2:5], v[190:193], v[222:225], v[2:5]
	s_setprio 0
	s_barrier
	s_add_i32 s61, s61, 2
	s_add_u32 s36, s36, 0x100
	s_addc_u32 s37, s37, 0
	s_add_u32 s59, s59, 0x100
	s_addc_u32 s60, s60, 0
	s_cmp_gt_u32 s61, 13
	s_cbranch_scc0 .LBB0_1179

.Lpk1239_peel:
	ds_read_b128 v[152:155], v148
	ds_read_b128 v[156:159], v148 offset:1024
	ds_read_b128 v[160:163], v148 offset:2048
	ds_read_b128 v[164:167], v148 offset:3072
	ds_read_b128 v[168:171], v149
	ds_read_b128 v[172:175], v149 offset:1024
	ds_read_b128 v[178:181], v149 offset:2048
	ds_read_b128 v[182:185], v149 offset:3072
	s_add_u32 s2, s36, 0xfffc0080
	s_addc_u32 s3, s37, -1
	s_cmp_eq_u32 s62, 12
	s_cselect_b32 s3, s19, s3
	s_cselect_b32 s2, s21, s2
	s_cselect_b32 s39, s58, s61
	s_cselect_b32 s38, s59, s60
	v_lshl_add_u64 v[144:145], s[36:37], 0, v[138:139]
	s_add_i32 m0, s44, 0xc000
	ds_read_b128 v[186:189], v150
	ds_read_b128 v[190:193], v150 offset:1024
	ds_read_b128 v[194:197], v150 offset:2048
	ds_read_b128 v[198:201], v150 offset:3072
	ds_read_b128 v[202:205], v150 offset:4096
	ds_read_b128 v[206:209], v150 offset:5120
	ds_read_b128 v[210:213], v150 offset:6144
	ds_read_b128 v[214:217], v150 offset:7168
	global_load_lds_dwordx4 v[144:145], off
	v_lshl_add_u64 v[144:145], s[36:37], 0, v[140:141]
	s_add_i32 m0, s44, 0xe000
	s_nop 0
	global_load_lds_dwordx4 v[144:145], off
	s_waitcnt vmcnt(8)
	s_waitcnt lgkmcnt(0)
	s_barrier
	s_setprio 1
	v_mfma_f32_16x16x32_bf16 v[126:129], v[152:155], v[186:189], 0
	v_mfma_f32_16x16x32_bf16 v[122:125], v[160:163], v[186:189], 0
	v_mfma_f32_16x16x32_bf16 v[114:117], v[152:155], v[194:197], 0
	v_mfma_f32_16x16x32_bf16 v[106:109], v[160:163], v[194:197], 0
	v_mfma_f32_16x16x32_bf16 v[98:101], v[152:155], v[202:205], 0
	v_mfma_f32_16x16x32_bf16 v[90:93], v[160:163], v[202:205], 0
	v_mfma_f32_16x16x32_bf16 v[82:85], v[152:155], v[210:213], 0
	v_mfma_f32_16x16x32_bf16 v[74:77], v[160:163], v[210:213], 0
	v_mfma_f32_16x16x32_bf16 v[126:129], v[156:159], v[190:193], v[126:129]
	v_mfma_f32_16x16x32_bf16 v[122:125], v[164:167], v[190:193], v[122:125]
	v_mfma_f32_16x16x32_bf16 v[114:117], v[156:159], v[198:201], v[114:117]
	v_mfma_f32_16x16x32_bf16 v[106:109], v[164:167], v[198:201], v[106:109]
	v_mfma_f32_16x16x32_bf16 v[98:101], v[156:159], v[206:209], v[98:101]
	v_mfma_f32_16x16x32_bf16 v[90:93], v[164:167], v[206:209], v[90:93]
	v_mfma_f32_16x16x32_bf16 v[82:85], v[156:159], v[214:217], v[82:85]
	v_mfma_f32_16x16x32_bf16 v[74:77], v[164:167], v[214:217], v[74:77]
	v_mfma_f32_16x16x32_bf16 v[118:121], v[168:171], v[186:189], 0
	v_mfma_f32_16x16x32_bf16 v[110:113], v[178:181], v[186:189], 0
	v_mfma_f32_16x16x32_bf16 v[102:105], v[168:171], v[194:197], 0
	v_mfma_f32_16x16x32_bf16 v[94:97], v[178:181], v[194:197], 0
	v_mfma_f32_16x16x32_bf16 v[86:89], v[168:171], v[202:205], 0
	v_mfma_f32_16x16x32_bf16 v[78:81], v[178:181], v[202:205], 0
	v_mfma_f32_16x16x32_bf16 v[70:73], v[168:171], v[210:213], 0
	v_mfma_f32_16x16x32_bf16 v[66:69], v[178:181], v[210:213], 0
	v_mfma_f32_16x16x32_bf16 v[118:121], v[172:175], v[190:193], v[118:121]
	v_mfma_f32_16x16x32_bf16 v[110:113], v[182:185], v[190:193], v[110:113]
	v_mfma_f32_16x16x32_bf16 v[102:105], v[172:175], v[198:201], v[102:105]
	v_mfma_f32_16x16x32_bf16 v[94:97], v[182:185], v[198:201], v[94:97]
	v_mfma_f32_16x16x32_bf16 v[86:89], v[172:175], v[206:209], v[86:89]
	v_mfma_f32_16x16x32_bf16 v[78:81], v[182:185], v[206:209], v[78:81]
	v_mfma_f32_16x16x32_bf16 v[70:73], v[172:175], v[214:217], v[70:73]
	v_mfma_f32_16x16x32_bf16 v[66:69], v[182:185], v[214:217], v[66:69]
	s_setprio 0
	s_barrier
	s_add_i32 s63, s51, s43
	v_lshl_add_u64 v[144:145], s[38:39], 0, v[132:133]
	s_mov_b32 m0, s63
	ds_read_b128 v[186:189], v150 offset:16384
	ds_read_b128 v[190:193], v150 offset:17408
	ds_read_b128 v[194:197], v150 offset:18432
	ds_read_b128 v[198:201], v150 offset:19456
	ds_read_b128 v[202:205], v150 offset:20480
	ds_read_b128 v[206:209], v150 offset:21504
	ds_read_b128 v[210:213], v150 offset:22528
	ds_read_b128 v[214:217], v150 offset:23552
	global_load_lds_dwordx4 v[144:145], off
	s_add_i32 m0, s63, 0x2000
	s_add_u32 s64, s38, 0x40000
	v_lshl_add_u64 v[218:219], s[38:39], 0, v[136:137]
	s_addc_u32 s65, s39, 0
	s_add_i32 s63, s52, s43
	global_load_lds_dwordx4 v[218:219], off
	v_lshl_add_u64 v[220:221], s[64:65], 0, v[132:133]
	s_mov_b32 m0, s63
	v_lshl_add_u64 v[222:223], s[2:3], 0, v[134:135]
	global_load_lds_dwordx4 v[220:221], off
	v_lshl_add_u64 v[220:221], s[64:65], 0, v[136:137]
	s_add_i32 m0, s63, 0x2000
	s_nop 0
	global_load_lds_dwordx4 v[220:221], off
	v_lshl_add_u64 v[220:221], s[2:3], 0, v[130:131]
	s_mov_b32 m0, s44
	s_nop 0
	global_load_lds_dwordx4 v[220:221], off
	s_mov_b32 m0, s35
	s_nop 0
	global_load_lds_dwordx4 v[222:223], off
	s_waitcnt vmcnt(8)
	s_waitcnt lgkmcnt(0)
	s_barrier
	s_setprio 1
	v_mfma_f32_16x16x32_bf16 v[62:65], v[152:155], v[186:189], 0
	v_mfma_f32_16x16x32_bf16 v[58:61], v[160:163], v[186:189], 0
	v_mfma_f32_16x16x32_bf16 v[50:53], v[152:155], v[194:197], 0
	v_mfma_f32_16x16x32_bf16 v[42:45], v[160:163], v[194:197], 0
	v_mfma_f32_16x16x32_bf16 v[34:37], v[152:155], v[202:205], 0
	v_mfma_f32_16x16x32_bf16 v[26:29], v[160:163], v[202:205], 0
	v_mfma_f32_16x16x32_bf16 v[18:21], v[152:155], v[210:213], 0
	v_mfma_f32_16x16x32_bf16 v[10:13], v[160:163], v[210:213], 0
	v_mfma_f32_16x16x32_bf16 v[62:65], v[156:159], v[190:193], v[62:65]
	v_mfma_f32_16x16x32_bf16 v[58:61], v[164:167], v[190:193], v[58:61]
	v_mfma_f32_16x16x32_bf16 v[50:53], v[156:159], v[198:201], v[50:53]
	v_mfma_f32_16x16x32_bf16 v[42:45], v[164:167], v[198:201], v[42:45]
	v_mfma_f32_16x16x32_bf16 v[34:37], v[156:159], v[206:209], v[34:37]
	v_mfma_f32_16x16x32_bf16 v[26:29], v[164:167], v[206:209], v[26:29]
	v_mfma_f32_16x16x32_bf16 v[18:21], v[156:159], v[214:217], v[18:21]
	v_mfma_f32_16x16x32_bf16 v[10:13], v[164:167], v[214:217], v[10:13]
	v_mfma_f32_16x16x32_bf16 v[54:57], v[168:171], v[186:189], 0
	v_mfma_f32_16x16x32_bf16 v[46:49], v[178:181], v[186:189], 0
	v_mfma_f32_16x16x32_bf16 v[38:41], v[168:171], v[194:197], 0
	v_mfma_f32_16x16x32_bf16 v[30:33], v[178:181], v[194:197], 0
	v_mfma_f32_16x16x32_bf16 v[22:25], v[168:171], v[202:205], 0
	v_mfma_f32_16x16x32_bf16 v[14:17], v[178:181], v[202:205], 0
	v_mfma_f32_16x16x32_bf16 v[6:9], v[168:171], v[210:213], 0
	v_mfma_f32_16x16x32_bf16 v[2:5], v[178:181], v[210:213], 0
	v_mfma_f32_16x16x32_bf16 v[54:57], v[172:175], v[190:193], v[54:57]
	v_mfma_f32_16x16x32_bf16 v[46:49], v[182:185], v[190:193], v[46:49]
	v_mfma_f32_16x16x32_bf16 v[38:41], v[172:175], v[198:201], v[38:41]
	v_mfma_f32_16x16x32_bf16 v[30:33], v[182:185], v[198:201], v[30:33]
	v_mfma_f32_16x16x32_bf16 v[22:25], v[172:175], v[206:209], v[22:25]
	v_mfma_f32_16x16x32_bf16 v[14:17], v[182:185], v[206:209], v[14:17]
	v_mfma_f32_16x16x32_bf16 v[6:9], v[172:175], v[214:217], v[6:9]
	v_mfma_f32_16x16x32_bf16 v[2:5], v[182:185], v[214:217], v[2:5]
	s_setprio 0
	s_barrier
	s_add_i32 s63, 0, 0x18000
	v_add_u32_e32 v151, s63, v146
	s_add_i32 s64, 0, 0x1c000
	ds_read_b128 v[152:155], v151
	ds_read_b128 v[156:159], v151 offset:1024
	ds_read_b128 v[160:163], v151 offset:2048
	ds_read_b128 v[164:167], v151 offset:3072
	v_add_u32_e32 v151, s64, v146
	ds_read_b128 v[168:171], v151
	ds_read_b128 v[172:175], v151 offset:1024
	ds_read_b128 v[178:181], v151 offset:2048
	ds_read_b128 v[182:185], v151 offset:3072
	s_add_u32 s2, s2, 0x40000
	s_addc_u32 s3, s3, 0
	s_mov_b32 m0, s45
	v_lshl_add_u64 v[224:225], s[2:3], 0, v[130:131]
	ds_read_b128 v[186:189], v150 offset:32768
	ds_read_b128 v[190:193], v150 offset:33792
	ds_read_b128 v[194:197], v150 offset:34816
	ds_read_b128 v[198:201], v150 offset:35840
	ds_read_b128 v[202:205], v150 offset:36864
	ds_read_b128 v[206:209], v150 offset:37888
	ds_read_b128 v[210:213], v150 offset:38912
	ds_read_b128 v[214:217], v150 offset:39936
	global_load_lds_dwordx4 v[224:225], off
	v_lshl_add_u64 v[224:225], s[2:3], 0, v[134:135]
	s_mov_b32 m0, s46
	s_nop 0
	global_load_lds_dwordx4 v[224:225], off
	s_waitcnt vmcnt(8)
	s_waitcnt lgkmcnt(0)
	s_barrier
	s_setprio 1
	v_mfma_f32_16x16x32_bf16 v[126:129], v[152:155], v[186:189], v[126:129]
	v_mfma_f32_16x16x32_bf16 v[122:125], v[160:163], v[186:189], v[122:125]
	v_mfma_f32_16x16x32_bf16 v[114:117], v[152:155], v[194:197], v[114:117]
	v_mfma_f32_16x16x32_bf16 v[106:109], v[160:163], v[194:197], v[106:109]
	v_mfma_f32_16x16x32_bf16 v[98:101], v[152:155], v[202:205], v[98:101]
	v_mfma_f32_16x16x32_bf16 v[90:93], v[160:163], v[202:205], v[90:93]
	v_mfma_f32_16x16x32_bf16 v[82:85], v[152:155], v[210:213], v[82:85]
	v_mfma_f32_16x16x32_bf16 v[74:77], v[160:163], v[210:213], v[74:77]
	v_mfma_f32_16x16x32_bf16 v[126:129], v[156:159], v[190:193], v[126:129]
	v_mfma_f32_16x16x32_bf16 v[122:125], v[164:167], v[190:193], v[122:125]
	v_mfma_f32_16x16x32_bf16 v[114:117], v[156:159], v[198:201], v[114:117]
	v_mfma_f32_16x16x32_bf16 v[106:109], v[164:167], v[198:201], v[106:109]
	v_mfma_f32_16x16x32_bf16 v[98:101], v[156:159], v[206:209], v[98:101]
	v_mfma_f32_16x16x32_bf16 v[90:93], v[164:167], v[206:209], v[90:93]
	v_mfma_f32_16x16x32_bf16 v[82:85], v[156:159], v[214:217], v[82:85]
	v_mfma_f32_16x16x32_bf16 v[74:77], v[164:167], v[214:217], v[74:77]
	v_mfma_f32_16x16x32_bf16 v[118:121], v[168:171], v[186:189], v[118:121]
	v_mfma_f32_16x16x32_bf16 v[110:113], v[178:181], v[186:189], v[110:113]
	v_mfma_f32_16x16x32_bf16 v[102:105], v[168:171], v[194:197], v[102:105]
	v_mfma_f32_16x16x32_bf16 v[94:97], v[178:181], v[194:197], v[94:97]
	v_mfma_f32_16x16x32_bf16 v[86:89], v[168:171], v[202:205], v[86:89]
	v_mfma_f32_16x16x32_bf16 v[78:81], v[178:181], v[202:205], v[78:81]
	v_mfma_f32_16x16x32_bf16 v[70:73], v[168:171], v[210:213], v[70:73]
	v_mfma_f32_16x16x32_bf16 v[66:69], v[178:181], v[210:213], v[66:69]
	v_mfma_f32_16x16x32_bf16 v[118:121], v[172:175], v[190:193], v[118:121]
	v_mfma_f32_16x16x32_bf16 v[110:113], v[182:185], v[190:193], v[110:113]
	v_mfma_f32_16x16x32_bf16 v[102:105], v[172:175], v[198:201], v[102:105]
	v_mfma_f32_16x16x32_bf16 v[94:97], v[182:185], v[198:201], v[94:97]
	v_mfma_f32_16x16x32_bf16 v[86:89], v[172:175], v[206:209], v[86:89]
	v_mfma_f32_16x16x32_bf16 v[78:81], v[182:185], v[206:209], v[78:81]
	v_mfma_f32_16x16x32_bf16 v[70:73], v[172:175], v[214:217], v[70:73]
	v_mfma_f32_16x16x32_bf16 v[66:69], v[182:185], v[214:217], v[66:69]
	s_setprio 0
	s_barrier
	s_add_i32 s2, s63, s43
	v_lshl_add_u64 v[144:145], v[144:145], 0, s[8:9]
	s_mov_b32 m0, s2
	ds_read_b128 v[186:189], v150 offset:49152
	ds_read_b128 v[190:193], v150 offset:50176
	ds_read_b128 v[194:197], v150 offset:51200
	ds_read_b128 v[198:201], v150 offset:52224
	ds_read_b128 v[202:205], v150 offset:53248
	ds_read_b128 v[206:209], v150 offset:54272
	ds_read_b128 v[210:213], v150 offset:55296
	ds_read_b128 v[214:217], v150 offset:56320
	global_load_lds_dwordx4 v[144:145], off
	s_add_i32 m0, s2, 0x2000
	s_add_u32 s2, s38, 0x40080
	v_lshl_add_u64 v[144:145], v[218:219], 0, s[8:9]
	s_addc_u32 s3, s39, 0
	s_add_i32 s38, s64, s43
	global_load_lds_dwordx4 v[144:145], off
	v_lshl_add_u64 v[144:145], s[2:3], 0, v[132:133]
	s_mov_b32 m0, s38
	s_nop 0
	global_load_lds_dwordx4 v[144:145], off
	v_lshl_add_u64 v[144:145], s[2:3], 0, v[136:137]
	s_add_i32 m0, s38, 0x2000
	s_nop 0
	global_load_lds_dwordx4 v[144:145], off
	v_lshl_add_u64 v[144:145], v[220:221], 0, s[8:9]
	s_mov_b32 m0, s48
	s_nop 0
	global_load_lds_dwordx4 v[144:145], off
	v_lshl_add_u64 v[144:145], v[222:223], 0, s[8:9]
	s_mov_b32 m0, s49
	s_nop 0
	global_load_lds_dwordx4 v[144:145], off
	s_waitcnt vmcnt(8)
	s_waitcnt lgkmcnt(0)
	s_barrier
	s_setprio 1
	v_mfma_f32_16x16x32_bf16 v[62:65], v[152:155], v[186:189], v[62:65]
	v_mfma_f32_16x16x32_bf16 v[58:61], v[160:163], v[186:189], v[58:61]
	v_mfma_f32_16x16x32_bf16 v[50:53], v[152:155], v[194:197], v[50:53]
	v_mfma_f32_16x16x32_bf16 v[42:45], v[160:163], v[194:197], v[42:45]
	v_mfma_f32_16x16x32_bf16 v[34:37], v[152:155], v[202:205], v[34:37]
	v_mfma_f32_16x16x32_bf16 v[26:29], v[160:163], v[202:205], v[26:29]
	v_mfma_f32_16x16x32_bf16 v[18:21], v[152:155], v[210:213], v[18:21]
	v_mfma_f32_16x16x32_bf16 v[10:13], v[160:163], v[210:213], v[10:13]
	v_mfma_f32_16x16x32_bf16 v[62:65], v[156:159], v[190:193], v[62:65]
	v_mfma_f32_16x16x32_bf16 v[58:61], v[164:167], v[190:193], v[58:61]
	v_mfma_f32_16x16x32_bf16 v[50:53], v[156:159], v[198:201], v[50:53]
	v_mfma_f32_16x16x32_bf16 v[42:45], v[164:167], v[198:201], v[42:45]
	v_mfma_f32_16x16x32_bf16 v[34:37], v[156:159], v[206:209], v[34:37]
	v_mfma_f32_16x16x32_bf16 v[26:29], v[164:167], v[206:209], v[26:29]
	v_mfma_f32_16x16x32_bf16 v[18:21], v[156:159], v[214:217], v[18:21]
	v_mfma_f32_16x16x32_bf16 v[10:13], v[164:167], v[214:217], v[10:13]
	v_mfma_f32_16x16x32_bf16 v[54:57], v[168:171], v[186:189], v[54:57]
	v_mfma_f32_16x16x32_bf16 v[46:49], v[178:181], v[186:189], v[46:49]
	v_mfma_f32_16x16x32_bf16 v[38:41], v[168:171], v[194:197], v[38:41]
	v_mfma_f32_16x16x32_bf16 v[30:33], v[178:181], v[194:197], v[30:33]
	v_mfma_f32_16x16x32_bf16 v[22:25], v[168:171], v[202:205], v[22:25]
	v_mfma_f32_16x16x32_bf16 v[14:17], v[178:181], v[202:205], v[14:17]
	v_mfma_f32_16x16x32_bf16 v[6:9], v[168:171], v[210:213], v[6:9]
	v_mfma_f32_16x16x32_bf16 v[2:5], v[178:181], v[210:213], v[2:5]
	v_mfma_f32_16x16x32_bf16 v[54:57], v[172:175], v[190:193], v[54:57]
	v_mfma_f32_16x16x32_bf16 v[46:49], v[182:185], v[190:193], v[46:49]
	v_mfma_f32_16x16x32_bf16 v[38:41], v[172:175], v[198:201], v[38:41]
	v_mfma_f32_16x16x32_bf16 v[30:33], v[182:185], v[198:201], v[30:33]
	v_mfma_f32_16x16x32_bf16 v[22:25], v[172:175], v[206:209], v[22:25]
	v_mfma_f32_16x16x32_bf16 v[14:17], v[182:185], v[206:209], v[14:17]
	v_mfma_f32_16x16x32_bf16 v[6:9], v[172:175], v[214:217], v[6:9]
	v_mfma_f32_16x16x32_bf16 v[2:5], v[182:185], v[214:217], v[2:5]
	s_setprio 0
	s_barrier
	s_add_i32 s62, s62, 2
	s_add_u32 s36, s36, 0x100
	s_addc_u32 s37, s37, 0
	s_add_u32 s60, s60, 0x100
	s_addc_u32 s61, s61, 0
	s_cmp_gt_u32 s62, 13
	s_cbranch_scc0 .LBB0_1239
	s_branch .Lpk1239_exit
.LBB0_1239:
	ds_read_b128 v[152:155], v148
	ds_read_b128 v[156:159], v148 offset:1024
	ds_read_b128 v[160:163], v148 offset:2048
	ds_read_b128 v[164:167], v148 offset:3072
	ds_read_b128 v[168:171], v149
	ds_read_b128 v[172:175], v149 offset:1024
	ds_read_b128 v[178:181], v149 offset:2048
	ds_read_b128 v[182:185], v149 offset:3072
	s_add_u32 s2, s36, 0xfffc0080
	s_addc_u32 s3, s37, -1
	s_cmp_eq_u32 s62, 12
	s_cselect_b32 s3, s19, s3
	s_cselect_b32 s2, s21, s2
	s_cselect_b32 s39, s58, s61
	s_cselect_b32 s38, s59, s60
	v_lshl_add_u64 v[144:145], s[36:37], 0, v[138:139]
	s_add_i32 m0, s44, 0xc000
	ds_read_b128 v[186:189], v150
	ds_read_b128 v[190:193], v150 offset:1024
	ds_read_b128 v[194:197], v150 offset:2048
	ds_read_b128 v[198:201], v150 offset:3072
	ds_read_b128 v[202:205], v150 offset:4096
	ds_read_b128 v[206:209], v150 offset:5120
	ds_read_b128 v[210:213], v150 offset:6144
	ds_read_b128 v[214:217], v150 offset:7168
	global_load_lds_dwordx4 v[144:145], off
	v_lshl_add_u64 v[144:145], s[36:37], 0, v[140:141]
	s_add_i32 m0, s44, 0xe000
	s_nop 0
	global_load_lds_dwordx4 v[144:145], off
	s_waitcnt vmcnt(8)
	s_waitcnt lgkmcnt(0)
	s_barrier
	s_setprio 1
	v_mfma_f32_16x16x32_bf16 v[126:129], v[152:155], v[186:189], v[126:129]
	v_mfma_f32_16x16x32_bf16 v[122:125], v[160:163], v[186:189], v[122:125]
	v_mfma_f32_16x16x32_bf16 v[114:117], v[152:155], v[194:197], v[114:117]
	v_mfma_f32_16x16x32_bf16 v[106:109], v[160:163], v[194:197], v[106:109]
	v_mfma_f32_16x16x32_bf16 v[98:101], v[152:155], v[202:205], v[98:101]
	v_mfma_f32_16x16x32_bf16 v[90:93], v[160:163], v[202:205], v[90:93]
	v_mfma_f32_16x16x32_bf16 v[82:85], v[152:155], v[210:213], v[82:85]
	v_mfma_f32_16x16x32_bf16 v[74:77], v[160:163], v[210:213], v[74:77]
	v_mfma_f32_16x16x32_bf16 v[126:129], v[156:159], v[190:193], v[126:129]
	v_mfma_f32_16x16x32_bf16 v[122:125], v[164:167], v[190:193], v[122:125]
	v_mfma_f32_16x16x32_bf16 v[114:117], v[156:159], v[198:201], v[114:117]
	v_mfma_f32_16x16x32_bf16 v[106:109], v[164:167], v[198:201], v[106:109]
	v_mfma_f32_16x16x32_bf16 v[98:101], v[156:159], v[206:209], v[98:101]
	v_mfma_f32_16x16x32_bf16 v[90:93], v[164:167], v[206:209], v[90:93]
	v_mfma_f32_16x16x32_bf16 v[82:85], v[156:159], v[214:217], v[82:85]
	v_mfma_f32_16x16x32_bf16 v[74:77], v[164:167], v[214:217], v[74:77]
	v_mfma_f32_16x16x32_bf16 v[118:121], v[168:171], v[186:189], v[118:121]
	v_mfma_f32_16x16x32_bf16 v[110:113], v[178:181], v[186:189], v[110:113]
	v_mfma_f32_16x16x32_bf16 v[102:105], v[168:171], v[194:197], v[102:105]
	v_mfma_f32_16x16x32_bf16 v[94:97], v[178:181], v[194:197], v[94:97]
	v_mfma_f32_16x16x32_bf16 v[86:89], v[168:171], v[202:205], v[86:89]
	v_mfma_f32_16x16x32_bf16 v[78:81], v[178:181], v[202:205], v[78:81]
	v_mfma_f32_16x16x32_bf16 v[70:73], v[168:171], v[210:213], v[70:73]
	v_mfma_f32_16x16x32_bf16 v[66:69], v[178:181], v[210:213], v[66:69]
	v_mfma_f32_16x16x32_bf16 v[118:121], v[172:175], v[190:193], v[118:121]
	v_mfma_f32_16x16x32_bf16 v[110:113], v[182:185], v[190:193], v[110:113]
	v_mfma_f32_16x16x32_bf16 v[102:105], v[172:175], v[198:201], v[102:105]
	v_mfma_f32_16x16x32_bf16 v[94:97], v[182:185], v[198:201], v[94:97]
	v_mfma_f32_16x16x32_bf16 v[86:89], v[172:175], v[206:209], v[86:89]
	v_mfma_f32_16x16x32_bf16 v[78:81], v[182:185], v[206:209], v[78:81]
	v_mfma_f32_16x16x32_bf16 v[70:73], v[172:175], v[214:217], v[70:73]
	v_mfma_f32_16x16x32_bf16 v[66:69], v[182:185], v[214:217], v[66:69]
	s_setprio 0
	s_barrier
	s_add_i32 s63, s51, s43
	v_lshl_add_u64 v[144:145], s[38:39], 0, v[132:133]
	s_mov_b32 m0, s63
	ds_read_b128 v[186:189], v150 offset:16384
	ds_read_b128 v[190:193], v150 offset:17408
	ds_read_b128 v[194:197], v150 offset:18432
	ds_read_b128 v[198:201], v150 offset:19456
	ds_read_b128 v[202:205], v150 offset:20480
	ds_read_b128 v[206:209], v150 offset:21504
	ds_read_b128 v[210:213], v150 offset:22528
	ds_read_b128 v[214:217], v150 offset:23552
	global_load_lds_dwordx4 v[144:145], off
	s_add_i32 m0, s63, 0x2000
	s_add_u32 s64, s38, 0x40000
	v_lshl_add_u64 v[218:219], s[38:39], 0, v[136:137]
	s_addc_u32 s65, s39, 0
	s_add_i32 s63, s52, s43
	global_load_lds_dwordx4 v[218:219], off
	v_lshl_add_u64 v[220:221], s[64:65], 0, v[132:133]
	s_mov_b32 m0, s63
	v_lshl_add_u64 v[222:223], s[2:3], 0, v[134:135]
	global_load_lds_dwordx4 v[220:221], off
	v_lshl_add_u64 v[220:221], s[64:65], 0, v[136:137]
	s_add_i32 m0, s63, 0x2000
	s_nop 0
	global_load_lds_dwordx4 v[220:221], off
	v_lshl_add_u64 v[220:221], s[2:3], 0, v[130:131]
	s_mov_b32 m0, s44
	s_nop 0
	global_load_lds_dwordx4 v[220:221], off
	s_mov_b32 m0, s35
	s_nop 0
	global_load_lds_dwordx4 v[222:223], off
	s_waitcnt vmcnt(8)
	s_waitcnt lgkmcnt(0)
	s_barrier
	s_setprio 1
	v_mfma_f32_16x16x32_bf16 v[62:65], v[152:155], v[186:189], v[62:65]
	v_mfma_f32_16x16x32_bf16 v[58:61], v[160:163], v[186:189], v[58:61]
	v_mfma_f32_16x16x32_bf16 v[50:53], v[152:155], v[194:197], v[50:53]
	v_mfma_f32_16x16x32_bf16 v[42:45], v[160:163], v[194:197], v[42:45]
	v_mfma_f32_16x16x32_bf16 v[34:37], v[152:155], v[202:205], v[34:37]
	v_mfma_f32_16x16x32_bf16 v[26:29], v[160:163], v[202:205], v[26:29]
	v_mfma_f32_16x16x32_bf16 v[18:21], v[152:155], v[210:213], v[18:21]
	v_mfma_f32_16x16x32_bf16 v[10:13], v[160:163], v[210:213], v[10:13]
	v_mfma_f32_16x16x32_bf16 v[62:65], v[156:159], v[190:193], v[62:65]
	v_mfma_f32_16x16x32_bf16 v[58:61], v[164:167], v[190:193], v[58:61]
	v_mfma_f32_16x16x32_bf16 v[50:53], v[156:159], v[198:201], v[50:53]
	v_mfma_f32_16x16x32_bf16 v[42:45], v[164:167], v[198:201], v[42:45]
	v_mfma_f32_16x16x32_bf16 v[34:37], v[156:159], v[206:209], v[34:37]
	v_mfma_f32_16x16x32_bf16 v[26:29], v[164:167], v[206:209], v[26:29]
	v_mfma_f32_16x16x32_bf16 v[18:21], v[156:159], v[214:217], v[18:21]
	v_mfma_f32_16x16x32_bf16 v[10:13], v[164:167], v[214:217], v[10:13]
	v_mfma_f32_16x16x32_bf16 v[54:57], v[168:171], v[186:189], v[54:57]
	v_mfma_f32_16x16x32_bf16 v[46:49], v[178:181], v[186:189], v[46:49]
	v_mfma_f32_16x16x32_bf16 v[38:41], v[168:171], v[194:197], v[38:41]
	v_mfma_f32_16x16x32_bf16 v[30:33], v[178:181], v[194:197], v[30:33]
	v_mfma_f32_16x16x32_bf16 v[22:25], v[168:171], v[202:205], v[22:25]
	v_mfma_f32_16x16x32_bf16 v[14:17], v[178:181], v[202:205], v[14:17]
	v_mfma_f32_16x16x32_bf16 v[6:9], v[168:171], v[210:213], v[6:9]
	v_mfma_f32_16x16x32_bf16 v[2:5], v[178:181], v[210:213], v[2:5]
	v_mfma_f32_16x16x32_bf16 v[54:57], v[172:175], v[190:193], v[54:57]
	v_mfma_f32_16x16x32_bf16 v[46:49], v[182:185], v[190:193], v[46:49]
	v_mfma_f32_16x16x32_bf16 v[38:41], v[172:175], v[198:201], v[38:41]
	v_mfma_f32_16x16x32_bf16 v[30:33], v[182:185], v[198:201], v[30:33]
	v_mfma_f32_16x16x32_bf16 v[22:25], v[172:175], v[206:209], v[22:25]
	v_mfma_f32_16x16x32_bf16 v[14:17], v[182:185], v[206:209], v[14:17]
	v_mfma_f32_16x16x32_bf16 v[6:9], v[172:175], v[214:217], v[6:9]
	v_mfma_f32_16x16x32_bf16 v[2:5], v[182:185], v[214:217], v[2:5]
	s_setprio 0
	s_barrier
	s_add_i32 s63, 0, 0x18000
	v_add_u32_e32 v151, s63, v146
	s_add_i32 s64, 0, 0x1c000
	ds_read_b128 v[152:155], v151
	ds_read_b128 v[156:159], v151 offset:1024
	ds_read_b128 v[160:163], v151 offset:2048
	ds_read_b128 v[164:167], v151 offset:3072
	v_add_u32_e32 v151, s64, v146
	ds_read_b128 v[168:171], v151
	ds_read_b128 v[172:175], v151 offset:1024
	ds_read_b128 v[178:181], v151 offset:2048
	ds_read_b128 v[182:185], v151 offset:3072
	s_add_u32 s2, s2, 0x40000
	s_addc_u32 s3, s3, 0
	s_mov_b32 m0, s45
	v_lshl_add_u64 v[224:225], s[2:3], 0, v[130:131]
	ds_read_b128 v[186:189], v150 offset:32768
	ds_read_b128 v[190:193], v150 offset:33792
	ds_read_b128 v[194:197], v150 offset:34816
	ds_read_b128 v[198:201], v150 offset:35840
	ds_read_b128 v[202:205], v150 offset:36864
	ds_read_b128 v[206:209], v150 offset:37888
	ds_read_b128 v[210:213], v150 offset:38912
	ds_read_b128 v[214:217], v150 offset:39936
	global_load_lds_dwordx4 v[224:225], off
	v_lshl_add_u64 v[224:225], s[2:3], 0, v[134:135]
	s_mov_b32 m0, s46
	s_nop 0
	global_load_lds_dwordx4 v[224:225], off
	s_waitcnt vmcnt(8)
	s_waitcnt lgkmcnt(0)
	s_barrier
	s_setprio 1
	v_mfma_f32_16x16x32_bf16 v[126:129], v[152:155], v[186:189], v[126:129]
	v_mfma_f32_16x16x32_bf16 v[122:125], v[160:163], v[186:189], v[122:125]
	v_mfma_f32_16x16x32_bf16 v[114:117], v[152:155], v[194:197], v[114:117]
	v_mfma_f32_16x16x32_bf16 v[106:109], v[160:163], v[194:197], v[106:109]
	v_mfma_f32_16x16x32_bf16 v[98:101], v[152:155], v[202:205], v[98:101]
	v_mfma_f32_16x16x32_bf16 v[90:93], v[160:163], v[202:205], v[90:93]
	v_mfma_f32_16x16x32_bf16 v[82:85], v[152:155], v[210:213], v[82:85]
	v_mfma_f32_16x16x32_bf16 v[74:77], v[160:163], v[210:213], v[74:77]
	v_mfma_f32_16x16x32_bf16 v[126:129], v[156:159], v[190:193], v[126:129]
	v_mfma_f32_16x16x32_bf16 v[122:125], v[164:167], v[190:193], v[122:125]
	v_mfma_f32_16x16x32_bf16 v[114:117], v[156:159], v[198:201], v[114:117]
	v_mfma_f32_16x16x32_bf16 v[106:109], v[164:167], v[198:201], v[106:109]
	v_mfma_f32_16x16x32_bf16 v[98:101], v[156:159], v[206:209], v[98:101]
	v_mfma_f32_16x16x32_bf16 v[90:93], v[164:167], v[206:209], v[90:93]
	v_mfma_f32_16x16x32_bf16 v[82:85], v[156:159], v[214:217], v[82:85]
	v_mfma_f32_16x16x32_bf16 v[74:77], v[164:167], v[214:217], v[74:77]
	v_mfma_f32_16x16x32_bf16 v[118:121], v[168:171], v[186:189], v[118:121]
	v_mfma_f32_16x16x32_bf16 v[110:113], v[178:181], v[186:189], v[110:113]
	v_mfma_f32_16x16x32_bf16 v[102:105], v[168:171], v[194:197], v[102:105]
	v_mfma_f32_16x16x32_bf16 v[94:97], v[178:181], v[194:197], v[94:97]
	v_mfma_f32_16x16x32_bf16 v[86:89], v[168:171], v[202:205], v[86:89]
	v_mfma_f32_16x16x32_bf16 v[78:81], v[178:181], v[202:205], v[78:81]
	v_mfma_f32_16x16x32_bf16 v[70:73], v[168:171], v[210:213], v[70:73]
	v_mfma_f32_16x16x32_bf16 v[66:69], v[178:181], v[210:213], v[66:69]
	v_mfma_f32_16x16x32_bf16 v[118:121], v[172:175], v[190:193], v[118:121]
	v_mfma_f32_16x16x32_bf16 v[110:113], v[182:185], v[190:193], v[110:113]
	v_mfma_f32_16x16x32_bf16 v[102:105], v[172:175], v[198:201], v[102:105]
	v_mfma_f32_16x16x32_bf16 v[94:97], v[182:185], v[198:201], v[94:97]
	v_mfma_f32_16x16x32_bf16 v[86:89], v[172:175], v[206:209], v[86:89]
	v_mfma_f32_16x16x32_bf16 v[78:81], v[182:185], v[206:209], v[78:81]
	v_mfma_f32_16x16x32_bf16 v[70:73], v[172:175], v[214:217], v[70:73]
	v_mfma_f32_16x16x32_bf16 v[66:69], v[182:185], v[214:217], v[66:69]
	s_setprio 0
	s_barrier
	s_add_i32 s2, s63, s43
	v_lshl_add_u64 v[144:145], v[144:145], 0, s[8:9]
	s_mov_b32 m0, s2
	ds_read_b128 v[186:189], v150 offset:49152
	ds_read_b128 v[190:193], v150 offset:50176
	ds_read_b128 v[194:197], v150 offset:51200
	ds_read_b128 v[198:201], v150 offset:52224
	ds_read_b128 v[202:205], v150 offset:53248
	ds_read_b128 v[206:209], v150 offset:54272
	ds_read_b128 v[210:213], v150 offset:55296
	ds_read_b128 v[214:217], v150 offset:56320
	global_load_lds_dwordx4 v[144:145], off
	s_add_i32 m0, s2, 0x2000
	s_add_u32 s2, s38, 0x40080
	v_lshl_add_u64 v[144:145], v[218:219], 0, s[8:9]
	s_addc_u32 s3, s39, 0
	s_add_i32 s38, s64, s43
	global_load_lds_dwordx4 v[144:145], off
	v_lshl_add_u64 v[144:145], s[2:3], 0, v[132:133]
	s_mov_b32 m0, s38
	s_nop 0
	global_load_lds_dwordx4 v[144:145], off
	v_lshl_add_u64 v[144:145], s[2:3], 0, v[136:137]
	s_add_i32 m0, s38, 0x2000
	s_nop 0
	global_load_lds_dwordx4 v[144:145], off
	v_lshl_add_u64 v[144:145], v[220:221], 0, s[8:9]
	s_mov_b32 m0, s48
	s_nop 0
	global_load_lds_dwordx4 v[144:145], off
	v_lshl_add_u64 v[144:145], v[222:223], 0, s[8:9]
	s_mov_b32 m0, s49
	s_nop 0
	global_load_lds_dwordx4 v[144:145], off
	s_waitcnt vmcnt(8)
	s_waitcnt lgkmcnt(0)
	s_barrier
	s_setprio 1
	v_mfma_f32_16x16x32_bf16 v[62:65], v[152:155], v[186:189], v[62:65]
	v_mfma_f32_16x16x32_bf16 v[58:61], v[160:163], v[186:189], v[58:61]
	v_mfma_f32_16x16x32_bf16 v[50:53], v[152:155], v[194:197], v[50:53]
	v_mfma_f32_16x16x32_bf16 v[42:45], v[160:163], v[194:197], v[42:45]
	v_mfma_f32_16x16x32_bf16 v[34:37], v[152:155], v[202:205], v[34:37]
	v_mfma_f32_16x16x32_bf16 v[26:29], v[160:163], v[202:205], v[26:29]
	v_mfma_f32_16x16x32_bf16 v[18:21], v[152:155], v[210:213], v[18:21]
	v_mfma_f32_16x16x32_bf16 v[10:13], v[160:163], v[210:213], v[10:13]
	v_mfma_f32_16x16x32_bf16 v[62:65], v[156:159], v[190:193], v[62:65]
	v_mfma_f32_16x16x32_bf16 v[58:61], v[164:167], v[190:193], v[58:61]
	v_mfma_f32_16x16x32_bf16 v[50:53], v[156:159], v[198:201], v[50:53]
	v_mfma_f32_16x16x32_bf16 v[42:45], v[164:167], v[198:201], v[42:45]
	v_mfma_f32_16x16x32_bf16 v[34:37], v[156:159], v[206:209], v[34:37]
	v_mfma_f32_16x16x32_bf16 v[26:29], v[164:167], v[206:209], v[26:29]
	v_mfma_f32_16x16x32_bf16 v[18:21], v[156:159], v[214:217], v[18:21]
	v_mfma_f32_16x16x32_bf16 v[10:13], v[164:167], v[214:217], v[10:13]
	v_mfma_f32_16x16x32_bf16 v[54:57], v[168:171], v[186:189], v[54:57]
	v_mfma_f32_16x16x32_bf16 v[46:49], v[178:181], v[186:189], v[46:49]
	v_mfma_f32_16x16x32_bf16 v[38:41], v[168:171], v[194:197], v[38:41]
	v_mfma_f32_16x16x32_bf16 v[30:33], v[178:181], v[194:197], v[30:33]
	v_mfma_f32_16x16x32_bf16 v[22:25], v[168:171], v[202:205], v[22:25]
	v_mfma_f32_16x16x32_bf16 v[14:17], v[178:181], v[202:205], v[14:17]
	v_mfma_f32_16x16x32_bf16 v[6:9], v[168:171], v[210:213], v[6:9]
	v_mfma_f32_16x16x32_bf16 v[2:5], v[178:181], v[210:213], v[2:5]
	v_mfma_f32_16x16x32_bf16 v[54:57], v[172:175], v[190:193], v[54:57]
	v_mfma_f32_16x16x32_bf16 v[46:49], v[182:185], v[190:193], v[46:49]
	v_mfma_f32_16x16x32_bf16 v[38:41], v[172:175], v[198:201], v[38:41]
	v_mfma_f32_16x16x32_bf16 v[30:33], v[182:185], v[198:201], v[30:33]
	v_mfma_f32_16x16x32_bf16 v[22:25], v[172:175], v[206:209], v[22:25]
	v_mfma_f32_16x16x32_bf16 v[14:17], v[182:185], v[206:209], v[14:17]
	v_mfma_f32_16x16x32_bf16 v[6:9], v[172:175], v[214:217], v[6:9]
	v_mfma_f32_16x16x32_bf16 v[2:5], v[182:185], v[214:217], v[2:5]
	s_setprio 0
	s_barrier
	s_add_i32 s62, s62, 2
	s_add_u32 s36, s36, 0x100
	s_addc_u32 s37, s37, 0
	s_add_u32 s60, s60, 0x100
	s_addc_u32 s61, s61, 0
	s_cmp_gt_u32 s62, 13
	s_cbranch_scc0 .LBB0_1239

.Lpk1303_peel:
	ds_read_b128 v[166:169], v139
	ds_read_b128 v[170:173], v139 offset:1024
	ds_read_b128 v[178:181], v139 offset:2048
	ds_read_b128 v[182:185], v139 offset:3072
	ds_read_b128 v[186:189], v163
	ds_read_b128 v[190:193], v163 offset:1024
	ds_read_b128 v[194:197], v163 offset:2048
	ds_read_b128 v[198:201], v163 offset:3072
	s_add_u32 s2, s26, 0xfffc0080
	s_addc_u32 s3, s27, -1
	s_cmp_eq_u32 s55, 12
	s_cselect_b32 s3, s11, s3
	s_cselect_b32 s2, s13, s2
	s_cselect_b32 s29, s47, s54
	s_cselect_b32 s28, s52, s53
	v_lshl_add_u64 v[148:149], s[26:27], 0, v[142:143]
	s_add_i32 m0, s34, 0xc000
	ds_read_b128 v[202:205], v164
	ds_read_b128 v[206:209], v164 offset:1024
	ds_read_b128 v[210:213], v164 offset:2048
	ds_read_b128 v[214:217], v164 offset:3072
	ds_read_b128 v[218:221], v164 offset:4096
	ds_read_b128 v[222:225], v164 offset:5120
	ds_read_b128 v[226:229], v164 offset:6144
	ds_read_b128 v[230:233], v164 offset:7168
	global_load_lds_dwordx4 v[148:149], off
	v_lshl_add_u64 v[148:149], s[26:27], 0, v[144:145]
	s_add_i32 m0, s34, 0xe000
	s_nop 0
	global_load_lds_dwordx4 v[148:149], off
	s_waitcnt vmcnt(8)
	s_waitcnt lgkmcnt(0)
	s_barrier
	s_setprio 1
	v_mfma_f32_16x16x32_bf16 v[126:129], v[166:169], v[202:205], 0
	v_mfma_f32_16x16x32_bf16 v[122:125], v[178:181], v[202:205], 0
	v_mfma_f32_16x16x32_bf16 v[110:113], v[166:169], v[210:213], 0
	v_mfma_f32_16x16x32_bf16 v[106:109], v[178:181], v[210:213], 0
	v_mfma_f32_16x16x32_bf16 v[94:97], v[166:169], v[218:221], 0
	v_mfma_f32_16x16x32_bf16 v[90:93], v[178:181], v[218:221], 0
	v_mfma_f32_16x16x32_bf16 v[78:81], v[166:169], v[226:229], 0
	v_mfma_f32_16x16x32_bf16 v[74:77], v[178:181], v[226:229], 0
	v_mfma_f32_16x16x32_bf16 v[126:129], v[170:173], v[206:209], v[126:129]
	v_mfma_f32_16x16x32_bf16 v[122:125], v[182:185], v[206:209], v[122:125]
	v_mfma_f32_16x16x32_bf16 v[110:113], v[170:173], v[214:217], v[110:113]
	v_mfma_f32_16x16x32_bf16 v[106:109], v[182:185], v[214:217], v[106:109]
	v_mfma_f32_16x16x32_bf16 v[94:97], v[170:173], v[222:225], v[94:97]
	v_mfma_f32_16x16x32_bf16 v[90:93], v[182:185], v[222:225], v[90:93]
	v_mfma_f32_16x16x32_bf16 v[78:81], v[170:173], v[230:233], v[78:81]
	v_mfma_f32_16x16x32_bf16 v[74:77], v[182:185], v[230:233], v[74:77]
	v_mfma_f32_16x16x32_bf16 v[118:121], v[186:189], v[202:205], 0
	v_mfma_f32_16x16x32_bf16 v[114:117], v[194:197], v[202:205], 0
	v_mfma_f32_16x16x32_bf16 v[102:105], v[186:189], v[210:213], 0
	v_mfma_f32_16x16x32_bf16 v[98:101], v[194:197], v[210:213], 0
	v_mfma_f32_16x16x32_bf16 v[86:89], v[186:189], v[218:221], 0
	v_mfma_f32_16x16x32_bf16 v[82:85], v[194:197], v[218:221], 0
	v_mfma_f32_16x16x32_bf16 v[70:73], v[186:189], v[226:229], 0
	v_mfma_f32_16x16x32_bf16 v[66:69], v[194:197], v[226:229], 0
	v_mfma_f32_16x16x32_bf16 v[118:121], v[190:193], v[206:209], v[118:121]
	v_mfma_f32_16x16x32_bf16 v[114:117], v[198:201], v[206:209], v[114:117]
	v_mfma_f32_16x16x32_bf16 v[102:105], v[190:193], v[214:217], v[102:105]
	v_mfma_f32_16x16x32_bf16 v[98:101], v[198:201], v[214:217], v[98:101]
	v_mfma_f32_16x16x32_bf16 v[86:89], v[190:193], v[222:225], v[86:89]
	v_mfma_f32_16x16x32_bf16 v[82:85], v[198:201], v[222:225], v[82:85]
	v_mfma_f32_16x16x32_bf16 v[70:73], v[190:193], v[230:233], v[70:73]
	v_mfma_f32_16x16x32_bf16 v[66:69], v[198:201], v[230:233], v[66:69]
	s_setprio 0
	s_barrier
	s_add_i32 s56, s42, s30
	v_lshl_add_u64 v[148:149], s[28:29], 0, v[132:133]
	s_mov_b32 m0, s56
	ds_read_b128 v[202:205], v164 offset:16384
	ds_read_b128 v[206:209], v164 offset:17408
	ds_read_b128 v[210:213], v164 offset:18432
	ds_read_b128 v[214:217], v164 offset:19456
	ds_read_b128 v[218:221], v164 offset:20480
	ds_read_b128 v[222:225], v164 offset:21504
	ds_read_b128 v[226:229], v164 offset:22528
	ds_read_b128 v[230:233], v164 offset:23552
	global_load_lds_dwordx4 v[148:149], off
	s_add_i32 m0, s56, 0x2000
	s_add_u32 s56, s28, 0x40000
	v_lshl_add_u64 v[174:175], s[28:29], 0, v[136:137]
	s_addc_u32 s57, s29, 0
	s_add_i32 s58, s43, s30
	global_load_lds_dwordx4 v[174:175], off
	v_lshl_add_u64 v[234:235], s[56:57], 0, v[132:133]
	s_mov_b32 m0, s58
	v_lshl_add_u64 v[236:237], s[2:3], 0, v[134:135]
	global_load_lds_dwordx4 v[234:235], off
	v_lshl_add_u64 v[234:235], s[56:57], 0, v[136:137]
	s_add_i32 m0, s58, 0x2000
	s_nop 0
	global_load_lds_dwordx4 v[234:235], off
	v_lshl_add_u64 v[234:235], s[2:3], 0, v[130:131]
	s_mov_b32 m0, s34
	s_nop 0
	global_load_lds_dwordx4 v[234:235], off
	s_mov_b32 m0, s25
	s_nop 0
	global_load_lds_dwordx4 v[236:237], off
	s_waitcnt vmcnt(8)
	s_waitcnt lgkmcnt(0)
	s_barrier
	s_setprio 1
	v_mfma_f32_16x16x32_bf16 v[62:65], v[166:169], v[202:205], 0
	v_mfma_f32_16x16x32_bf16 v[58:61], v[178:181], v[202:205], 0
	v_mfma_f32_16x16x32_bf16 v[46:49], v[166:169], v[210:213], 0
	v_mfma_f32_16x16x32_bf16 v[42:45], v[178:181], v[210:213], 0
	v_mfma_f32_16x16x32_bf16 v[30:33], v[166:169], v[218:221], 0
	v_mfma_f32_16x16x32_bf16 v[26:29], v[178:181], v[218:221], 0
	v_mfma_f32_16x16x32_bf16 v[14:17], v[166:169], v[226:229], 0
	v_mfma_f32_16x16x32_bf16 v[10:13], v[178:181], v[226:229], 0
	v_mfma_f32_16x16x32_bf16 v[62:65], v[170:173], v[206:209], v[62:65]
	v_mfma_f32_16x16x32_bf16 v[58:61], v[182:185], v[206:209], v[58:61]
	v_mfma_f32_16x16x32_bf16 v[46:49], v[170:173], v[214:217], v[46:49]
	v_mfma_f32_16x16x32_bf16 v[42:45], v[182:185], v[214:217], v[42:45]
	v_mfma_f32_16x16x32_bf16 v[30:33], v[170:173], v[222:225], v[30:33]
	v_mfma_f32_16x16x32_bf16 v[26:29], v[182:185], v[222:225], v[26:29]
	v_mfma_f32_16x16x32_bf16 v[14:17], v[170:173], v[230:233], v[14:17]
	v_mfma_f32_16x16x32_bf16 v[10:13], v[182:185], v[230:233], v[10:13]
	v_mfma_f32_16x16x32_bf16 v[54:57], v[186:189], v[202:205], 0
	v_mfma_f32_16x16x32_bf16 v[50:53], v[194:197], v[202:205], 0
	v_mfma_f32_16x16x32_bf16 v[38:41], v[186:189], v[210:213], 0
	v_mfma_f32_16x16x32_bf16 v[34:37], v[194:197], v[210:213], 0
	v_mfma_f32_16x16x32_bf16 v[22:25], v[186:189], v[218:221], 0
	v_mfma_f32_16x16x32_bf16 v[18:21], v[194:197], v[218:221], 0
	v_mfma_f32_16x16x32_bf16 v[6:9], v[186:189], v[226:229], 0
	v_mfma_f32_16x16x32_bf16 v[2:5], v[194:197], v[226:229], 0
	v_mfma_f32_16x16x32_bf16 v[54:57], v[190:193], v[206:209], v[54:57]
	v_mfma_f32_16x16x32_bf16 v[50:53], v[198:201], v[206:209], v[50:53]
	v_mfma_f32_16x16x32_bf16 v[38:41], v[190:193], v[214:217], v[38:41]
	v_mfma_f32_16x16x32_bf16 v[34:37], v[198:201], v[214:217], v[34:37]
	v_mfma_f32_16x16x32_bf16 v[22:25], v[190:193], v[222:225], v[22:25]
	v_mfma_f32_16x16x32_bf16 v[18:21], v[198:201], v[222:225], v[18:21]
	v_mfma_f32_16x16x32_bf16 v[6:9], v[190:193], v[230:233], v[6:9]
	v_mfma_f32_16x16x32_bf16 v[2:5], v[198:201], v[230:233], v[2:5]
	s_setprio 0
	s_barrier
	s_add_i32 s56, 0, 0x18000
	v_add_u32_e32 v165, s56, v162
	s_add_i32 s57, 0, 0x1c000
	ds_read_b128 v[166:169], v165
	ds_read_b128 v[170:173], v165 offset:1024
	ds_read_b128 v[178:181], v165 offset:2048
	ds_read_b128 v[182:185], v165 offset:3072
	v_add_u32_e32 v165, s57, v162
	ds_read_b128 v[186:189], v165
	ds_read_b128 v[190:193], v165 offset:1024
	ds_read_b128 v[194:197], v165 offset:2048
	ds_read_b128 v[198:201], v165 offset:3072
	s_add_u32 s2, s2, 0x40000
	s_addc_u32 s3, s3, 0
	s_mov_b32 m0, s35
	v_lshl_add_u64 v[238:239], s[2:3], 0, v[130:131]
	ds_read_b128 v[202:205], v164 offset:32768
	ds_read_b128 v[206:209], v164 offset:33792
	ds_read_b128 v[210:213], v164 offset:34816
	ds_read_b128 v[214:217], v164 offset:35840
	ds_read_b128 v[218:221], v164 offset:36864
	ds_read_b128 v[222:225], v164 offset:37888
	ds_read_b128 v[226:229], v164 offset:38912
	ds_read_b128 v[230:233], v164 offset:39936
	global_load_lds_dwordx4 v[238:239], off
	v_lshl_add_u64 v[238:239], s[2:3], 0, v[134:135]
	s_mov_b32 m0, s36
	s_nop 0
	global_load_lds_dwordx4 v[238:239], off
	s_waitcnt vmcnt(8)
	s_waitcnt lgkmcnt(0)
	s_barrier
	s_setprio 1
	v_mfma_f32_16x16x32_bf16 v[126:129], v[166:169], v[202:205], v[126:129]
	v_mfma_f32_16x16x32_bf16 v[122:125], v[178:181], v[202:205], v[122:125]
	v_mfma_f32_16x16x32_bf16 v[110:113], v[166:169], v[210:213], v[110:113]
	v_mfma_f32_16x16x32_bf16 v[106:109], v[178:181], v[210:213], v[106:109]
	v_mfma_f32_16x16x32_bf16 v[94:97], v[166:169], v[218:221], v[94:97]
	v_mfma_f32_16x16x32_bf16 v[90:93], v[178:181], v[218:221], v[90:93]
	v_mfma_f32_16x16x32_bf16 v[78:81], v[166:169], v[226:229], v[78:81]
	v_mfma_f32_16x16x32_bf16 v[74:77], v[178:181], v[226:229], v[74:77]
	v_mfma_f32_16x16x32_bf16 v[126:129], v[170:173], v[206:209], v[126:129]
	v_mfma_f32_16x16x32_bf16 v[122:125], v[182:185], v[206:209], v[122:125]
	v_mfma_f32_16x16x32_bf16 v[110:113], v[170:173], v[214:217], v[110:113]
	v_mfma_f32_16x16x32_bf16 v[106:109], v[182:185], v[214:217], v[106:109]
	v_mfma_f32_16x16x32_bf16 v[94:97], v[170:173], v[222:225], v[94:97]
	v_mfma_f32_16x16x32_bf16 v[90:93], v[182:185], v[222:225], v[90:93]
	v_mfma_f32_16x16x32_bf16 v[78:81], v[170:173], v[230:233], v[78:81]
	v_mfma_f32_16x16x32_bf16 v[74:77], v[182:185], v[230:233], v[74:77]
	v_mfma_f32_16x16x32_bf16 v[118:121], v[186:189], v[202:205], v[118:121]
	v_mfma_f32_16x16x32_bf16 v[114:117], v[194:197], v[202:205], v[114:117]
	v_mfma_f32_16x16x32_bf16 v[102:105], v[186:189], v[210:213], v[102:105]
	v_mfma_f32_16x16x32_bf16 v[98:101], v[194:197], v[210:213], v[98:101]
	v_mfma_f32_16x16x32_bf16 v[86:89], v[186:189], v[218:221], v[86:89]
	v_mfma_f32_16x16x32_bf16 v[82:85], v[194:197], v[218:221], v[82:85]
	v_mfma_f32_16x16x32_bf16 v[70:73], v[186:189], v[226:229], v[70:73]
	v_mfma_f32_16x16x32_bf16 v[66:69], v[194:197], v[226:229], v[66:69]
	v_mfma_f32_16x16x32_bf16 v[118:121], v[190:193], v[206:209], v[118:121]
	v_mfma_f32_16x16x32_bf16 v[114:117], v[198:201], v[206:209], v[114:117]
	v_mfma_f32_16x16x32_bf16 v[102:105], v[190:193], v[214:217], v[102:105]
	v_mfma_f32_16x16x32_bf16 v[98:101], v[198:201], v[214:217], v[98:101]
	v_mfma_f32_16x16x32_bf16 v[86:89], v[190:193], v[222:225], v[86:89]
	v_mfma_f32_16x16x32_bf16 v[82:85], v[198:201], v[222:225], v[82:85]
	v_mfma_f32_16x16x32_bf16 v[70:73], v[190:193], v[230:233], v[70:73]
	v_mfma_f32_16x16x32_bf16 v[66:69], v[198:201], v[230:233], v[66:69]
	s_setprio 0
	s_barrier
	s_add_i32 s2, s56, s30
	v_lshl_add_u64 v[148:149], v[148:149], 0, s[6:7]
	s_mov_b32 m0, s2
	ds_read_b128 v[202:205], v164 offset:49152
	ds_read_b128 v[206:209], v164 offset:50176
	ds_read_b128 v[210:213], v164 offset:51200
	ds_read_b128 v[214:217], v164 offset:52224
	ds_read_b128 v[218:221], v164 offset:53248
	ds_read_b128 v[222:225], v164 offset:54272
	ds_read_b128 v[226:229], v164 offset:55296
	ds_read_b128 v[230:233], v164 offset:56320
	global_load_lds_dwordx4 v[148:149], off
	s_add_i32 m0, s2, 0x2000
	s_add_u32 s2, s28, 0x40080
	v_lshl_add_u64 v[148:149], v[174:175], 0, s[6:7]
	s_addc_u32 s3, s29, 0
	s_add_i32 s28, s57, s30
	global_load_lds_dwordx4 v[148:149], off
	v_lshl_add_u64 v[148:149], s[2:3], 0, v[132:133]
	s_mov_b32 m0, s28
	s_nop 0
	global_load_lds_dwordx4 v[148:149], off
	v_lshl_add_u64 v[148:149], s[2:3], 0, v[136:137]
	s_add_i32 m0, s28, 0x2000
	s_nop 0
	global_load_lds_dwordx4 v[148:149], off
	v_lshl_add_u64 v[148:149], v[234:235], 0, s[6:7]
	s_mov_b32 m0, s39
	s_nop 0
	global_load_lds_dwordx4 v[148:149], off
	v_lshl_add_u64 v[148:149], v[236:237], 0, s[6:7]
	s_mov_b32 m0, s40
	s_nop 0
	global_load_lds_dwordx4 v[148:149], off
	s_waitcnt vmcnt(8)
	s_waitcnt lgkmcnt(0)
	s_barrier
	s_setprio 1
	v_mfma_f32_16x16x32_bf16 v[62:65], v[166:169], v[202:205], v[62:65]
	v_mfma_f32_16x16x32_bf16 v[58:61], v[178:181], v[202:205], v[58:61]
	v_mfma_f32_16x16x32_bf16 v[46:49], v[166:169], v[210:213], v[46:49]
	v_mfma_f32_16x16x32_bf16 v[42:45], v[178:181], v[210:213], v[42:45]
	v_mfma_f32_16x16x32_bf16 v[30:33], v[166:169], v[218:221], v[30:33]
	v_mfma_f32_16x16x32_bf16 v[26:29], v[178:181], v[218:221], v[26:29]
	v_mfma_f32_16x16x32_bf16 v[14:17], v[166:169], v[226:229], v[14:17]
	v_mfma_f32_16x16x32_bf16 v[10:13], v[178:181], v[226:229], v[10:13]
	v_mfma_f32_16x16x32_bf16 v[62:65], v[170:173], v[206:209], v[62:65]
	v_mfma_f32_16x16x32_bf16 v[58:61], v[182:185], v[206:209], v[58:61]
	v_mfma_f32_16x16x32_bf16 v[46:49], v[170:173], v[214:217], v[46:49]
	v_mfma_f32_16x16x32_bf16 v[42:45], v[182:185], v[214:217], v[42:45]
	v_mfma_f32_16x16x32_bf16 v[30:33], v[170:173], v[222:225], v[30:33]
	v_mfma_f32_16x16x32_bf16 v[26:29], v[182:185], v[222:225], v[26:29]
	v_mfma_f32_16x16x32_bf16 v[14:17], v[170:173], v[230:233], v[14:17]
	v_mfma_f32_16x16x32_bf16 v[10:13], v[182:185], v[230:233], v[10:13]
	v_mfma_f32_16x16x32_bf16 v[54:57], v[186:189], v[202:205], v[54:57]
	v_mfma_f32_16x16x32_bf16 v[50:53], v[194:197], v[202:205], v[50:53]
	v_mfma_f32_16x16x32_bf16 v[38:41], v[186:189], v[210:213], v[38:41]
	v_mfma_f32_16x16x32_bf16 v[34:37], v[194:197], v[210:213], v[34:37]
	v_mfma_f32_16x16x32_bf16 v[22:25], v[186:189], v[218:221], v[22:25]
	v_mfma_f32_16x16x32_bf16 v[18:21], v[194:197], v[218:221], v[18:21]
	v_mfma_f32_16x16x32_bf16 v[6:9], v[186:189], v[226:229], v[6:9]
	v_mfma_f32_16x16x32_bf16 v[2:5], v[194:197], v[226:229], v[2:5]
	v_mfma_f32_16x16x32_bf16 v[54:57], v[190:193], v[206:209], v[54:57]
	v_mfma_f32_16x16x32_bf16 v[50:53], v[198:201], v[206:209], v[50:53]
	v_mfma_f32_16x16x32_bf16 v[38:41], v[190:193], v[214:217], v[38:41]
	v_mfma_f32_16x16x32_bf16 v[34:37], v[198:201], v[214:217], v[34:37]
	v_mfma_f32_16x16x32_bf16 v[22:25], v[190:193], v[222:225], v[22:25]
	v_mfma_f32_16x16x32_bf16 v[18:21], v[198:201], v[222:225], v[18:21]
	v_mfma_f32_16x16x32_bf16 v[6:9], v[190:193], v[230:233], v[6:9]
	v_mfma_f32_16x16x32_bf16 v[2:5], v[198:201], v[230:233], v[2:5]
	s_setprio 0
	s_barrier
	s_add_i32 s55, s55, 2
	s_add_u32 s26, s26, 0x100
	s_addc_u32 s27, s27, 0
	s_add_u32 s53, s53, 0x100
	s_addc_u32 s54, s54, 0
	s_cmp_gt_u32 s55, 13
	s_cbranch_scc0 .LBB0_1303
	s_branch .Lpk1303_exit
.LBB0_1303:
	ds_read_b128 v[166:169], v139
	ds_read_b128 v[170:173], v139 offset:1024
	ds_read_b128 v[178:181], v139 offset:2048
	ds_read_b128 v[182:185], v139 offset:3072
	ds_read_b128 v[186:189], v163
	ds_read_b128 v[190:193], v163 offset:1024
	ds_read_b128 v[194:197], v163 offset:2048
	ds_read_b128 v[198:201], v163 offset:3072
	s_add_u32 s2, s26, 0xfffc0080
	s_addc_u32 s3, s27, -1
	s_cmp_eq_u32 s55, 12
	s_cselect_b32 s3, s11, s3
	s_cselect_b32 s2, s13, s2
	s_cselect_b32 s29, s47, s54
	s_cselect_b32 s28, s52, s53
	v_lshl_add_u64 v[148:149], s[26:27], 0, v[142:143]
	s_add_i32 m0, s34, 0xc000
	ds_read_b128 v[202:205], v164
	ds_read_b128 v[206:209], v164 offset:1024
	ds_read_b128 v[210:213], v164 offset:2048
	ds_read_b128 v[214:217], v164 offset:3072
	ds_read_b128 v[218:221], v164 offset:4096
	ds_read_b128 v[222:225], v164 offset:5120
	ds_read_b128 v[226:229], v164 offset:6144
	ds_read_b128 v[230:233], v164 offset:7168
	global_load_lds_dwordx4 v[148:149], off
	v_lshl_add_u64 v[148:149], s[26:27], 0, v[144:145]
	s_add_i32 m0, s34, 0xe000
	s_nop 0
	global_load_lds_dwordx4 v[148:149], off
	s_waitcnt vmcnt(8)
	s_waitcnt lgkmcnt(0)
	s_barrier
	s_setprio 1
	v_mfma_f32_16x16x32_bf16 v[126:129], v[166:169], v[202:205], v[126:129]
	v_mfma_f32_16x16x32_bf16 v[122:125], v[178:181], v[202:205], v[122:125]
	v_mfma_f32_16x16x32_bf16 v[110:113], v[166:169], v[210:213], v[110:113]
	v_mfma_f32_16x16x32_bf16 v[106:109], v[178:181], v[210:213], v[106:109]
	v_mfma_f32_16x16x32_bf16 v[94:97], v[166:169], v[218:221], v[94:97]
	v_mfma_f32_16x16x32_bf16 v[90:93], v[178:181], v[218:221], v[90:93]
	v_mfma_f32_16x16x32_bf16 v[78:81], v[166:169], v[226:229], v[78:81]
	v_mfma_f32_16x16x32_bf16 v[74:77], v[178:181], v[226:229], v[74:77]
	v_mfma_f32_16x16x32_bf16 v[126:129], v[170:173], v[206:209], v[126:129]
	v_mfma_f32_16x16x32_bf16 v[122:125], v[182:185], v[206:209], v[122:125]
	v_mfma_f32_16x16x32_bf16 v[110:113], v[170:173], v[214:217], v[110:113]
	v_mfma_f32_16x16x32_bf16 v[106:109], v[182:185], v[214:217], v[106:109]
	v_mfma_f32_16x16x32_bf16 v[94:97], v[170:173], v[222:225], v[94:97]
	v_mfma_f32_16x16x32_bf16 v[90:93], v[182:185], v[222:225], v[90:93]
	v_mfma_f32_16x16x32_bf16 v[78:81], v[170:173], v[230:233], v[78:81]
	v_mfma_f32_16x16x32_bf16 v[74:77], v[182:185], v[230:233], v[74:77]
	v_mfma_f32_16x16x32_bf16 v[118:121], v[186:189], v[202:205], v[118:121]
	v_mfma_f32_16x16x32_bf16 v[114:117], v[194:197], v[202:205], v[114:117]
	v_mfma_f32_16x16x32_bf16 v[102:105], v[186:189], v[210:213], v[102:105]
	v_mfma_f32_16x16x32_bf16 v[98:101], v[194:197], v[210:213], v[98:101]
	v_mfma_f32_16x16x32_bf16 v[86:89], v[186:189], v[218:221], v[86:89]
	v_mfma_f32_16x16x32_bf16 v[82:85], v[194:197], v[218:221], v[82:85]
	v_mfma_f32_16x16x32_bf16 v[70:73], v[186:189], v[226:229], v[70:73]
	v_mfma_f32_16x16x32_bf16 v[66:69], v[194:197], v[226:229], v[66:69]
	v_mfma_f32_16x16x32_bf16 v[118:121], v[190:193], v[206:209], v[118:121]
	v_mfma_f32_16x16x32_bf16 v[114:117], v[198:201], v[206:209], v[114:117]
	v_mfma_f32_16x16x32_bf16 v[102:105], v[190:193], v[214:217], v[102:105]
	v_mfma_f32_16x16x32_bf16 v[98:101], v[198:201], v[214:217], v[98:101]
	v_mfma_f32_16x16x32_bf16 v[86:89], v[190:193], v[222:225], v[86:89]
	v_mfma_f32_16x16x32_bf16 v[82:85], v[198:201], v[222:225], v[82:85]
	v_mfma_f32_16x16x32_bf16 v[70:73], v[190:193], v[230:233], v[70:73]
	v_mfma_f32_16x16x32_bf16 v[66:69], v[198:201], v[230:233], v[66:69]
	s_setprio 0
	s_barrier
	s_add_i32 s56, s42, s30
	v_lshl_add_u64 v[148:149], s[28:29], 0, v[132:133]
	s_mov_b32 m0, s56
	ds_read_b128 v[202:205], v164 offset:16384
	ds_read_b128 v[206:209], v164 offset:17408
	ds_read_b128 v[210:213], v164 offset:18432
	ds_read_b128 v[214:217], v164 offset:19456
	ds_read_b128 v[218:221], v164 offset:20480
	ds_read_b128 v[222:225], v164 offset:21504
	ds_read_b128 v[226:229], v164 offset:22528
	ds_read_b128 v[230:233], v164 offset:23552
	global_load_lds_dwordx4 v[148:149], off
	s_add_i32 m0, s56, 0x2000
	s_add_u32 s56, s28, 0x40000
	v_lshl_add_u64 v[174:175], s[28:29], 0, v[136:137]
	s_addc_u32 s57, s29, 0
	s_add_i32 s58, s43, s30
	global_load_lds_dwordx4 v[174:175], off
	v_lshl_add_u64 v[234:235], s[56:57], 0, v[132:133]
	s_mov_b32 m0, s58
	v_lshl_add_u64 v[236:237], s[2:3], 0, v[134:135]
	global_load_lds_dwordx4 v[234:235], off
	v_lshl_add_u64 v[234:235], s[56:57], 0, v[136:137]
	s_add_i32 m0, s58, 0x2000
	s_nop 0
	global_load_lds_dwordx4 v[234:235], off
	v_lshl_add_u64 v[234:235], s[2:3], 0, v[130:131]
	s_mov_b32 m0, s34
	s_nop 0
	global_load_lds_dwordx4 v[234:235], off
	s_mov_b32 m0, s25
	s_nop 0
	global_load_lds_dwordx4 v[236:237], off
	s_waitcnt vmcnt(8)
	s_waitcnt lgkmcnt(0)
	s_barrier
	s_setprio 1
	v_mfma_f32_16x16x32_bf16 v[62:65], v[166:169], v[202:205], v[62:65]
	v_mfma_f32_16x16x32_bf16 v[58:61], v[178:181], v[202:205], v[58:61]
	v_mfma_f32_16x16x32_bf16 v[46:49], v[166:169], v[210:213], v[46:49]
	v_mfma_f32_16x16x32_bf16 v[42:45], v[178:181], v[210:213], v[42:45]
	v_mfma_f32_16x16x32_bf16 v[30:33], v[166:169], v[218:221], v[30:33]
	v_mfma_f32_16x16x32_bf16 v[26:29], v[178:181], v[218:221], v[26:29]
	v_mfma_f32_16x16x32_bf16 v[14:17], v[166:169], v[226:229], v[14:17]
	v_mfma_f32_16x16x32_bf16 v[10:13], v[178:181], v[226:229], v[10:13]
	v_mfma_f32_16x16x32_bf16 v[62:65], v[170:173], v[206:209], v[62:65]
	v_mfma_f32_16x16x32_bf16 v[58:61], v[182:185], v[206:209], v[58:61]
	v_mfma_f32_16x16x32_bf16 v[46:49], v[170:173], v[214:217], v[46:49]
	v_mfma_f32_16x16x32_bf16 v[42:45], v[182:185], v[214:217], v[42:45]
	v_mfma_f32_16x16x32_bf16 v[30:33], v[170:173], v[222:225], v[30:33]
	v_mfma_f32_16x16x32_bf16 v[26:29], v[182:185], v[222:225], v[26:29]
	v_mfma_f32_16x16x32_bf16 v[14:17], v[170:173], v[230:233], v[14:17]
	v_mfma_f32_16x16x32_bf16 v[10:13], v[182:185], v[230:233], v[10:13]
	v_mfma_f32_16x16x32_bf16 v[54:57], v[186:189], v[202:205], v[54:57]
	v_mfma_f32_16x16x32_bf16 v[50:53], v[194:197], v[202:205], v[50:53]
	v_mfma_f32_16x16x32_bf16 v[38:41], v[186:189], v[210:213], v[38:41]
	v_mfma_f32_16x16x32_bf16 v[34:37], v[194:197], v[210:213], v[34:37]
	v_mfma_f32_16x16x32_bf16 v[22:25], v[186:189], v[218:221], v[22:25]
	v_mfma_f32_16x16x32_bf16 v[18:21], v[194:197], v[218:221], v[18:21]
	v_mfma_f32_16x16x32_bf16 v[6:9], v[186:189], v[226:229], v[6:9]
	v_mfma_f32_16x16x32_bf16 v[2:5], v[194:197], v[226:229], v[2:5]
	v_mfma_f32_16x16x32_bf16 v[54:57], v[190:193], v[206:209], v[54:57]
	v_mfma_f32_16x16x32_bf16 v[50:53], v[198:201], v[206:209], v[50:53]
	v_mfma_f32_16x16x32_bf16 v[38:41], v[190:193], v[214:217], v[38:41]
	v_mfma_f32_16x16x32_bf16 v[34:37], v[198:201], v[214:217], v[34:37]
	v_mfma_f32_16x16x32_bf16 v[22:25], v[190:193], v[222:225], v[22:25]
	v_mfma_f32_16x16x32_bf16 v[18:21], v[198:201], v[222:225], v[18:21]
	v_mfma_f32_16x16x32_bf16 v[6:9], v[190:193], v[230:233], v[6:9]
	v_mfma_f32_16x16x32_bf16 v[2:5], v[198:201], v[230:233], v[2:5]
	s_setprio 0
	s_barrier
	s_add_i32 s56, 0, 0x18000
	v_add_u32_e32 v165, s56, v162
	s_add_i32 s57, 0, 0x1c000
	ds_read_b128 v[166:169], v165
	ds_read_b128 v[170:173], v165 offset:1024
	ds_read_b128 v[178:181], v165 offset:2048
	ds_read_b128 v[182:185], v165 offset:3072
	v_add_u32_e32 v165, s57, v162
	ds_read_b128 v[186:189], v165
	ds_read_b128 v[190:193], v165 offset:1024
	ds_read_b128 v[194:197], v165 offset:2048
	ds_read_b128 v[198:201], v165 offset:3072
	s_add_u32 s2, s2, 0x40000
	s_addc_u32 s3, s3, 0
	s_mov_b32 m0, s35
	v_lshl_add_u64 v[238:239], s[2:3], 0, v[130:131]
	ds_read_b128 v[202:205], v164 offset:32768
	ds_read_b128 v[206:209], v164 offset:33792
	ds_read_b128 v[210:213], v164 offset:34816
	ds_read_b128 v[214:217], v164 offset:35840
	ds_read_b128 v[218:221], v164 offset:36864
	ds_read_b128 v[222:225], v164 offset:37888
	ds_read_b128 v[226:229], v164 offset:38912
	ds_read_b128 v[230:233], v164 offset:39936
	global_load_lds_dwordx4 v[238:239], off
	v_lshl_add_u64 v[238:239], s[2:3], 0, v[134:135]
	s_mov_b32 m0, s36
	s_nop 0
	global_load_lds_dwordx4 v[238:239], off
	s_waitcnt vmcnt(8)
	s_waitcnt lgkmcnt(0)
	s_barrier
	s_setprio 1
	v_mfma_f32_16x16x32_bf16 v[126:129], v[166:169], v[202:205], v[126:129]
	v_mfma_f32_16x16x32_bf16 v[122:125], v[178:181], v[202:205], v[122:125]
	v_mfma_f32_16x16x32_bf16 v[110:113], v[166:169], v[210:213], v[110:113]
	v_mfma_f32_16x16x32_bf16 v[106:109], v[178:181], v[210:213], v[106:109]
	v_mfma_f32_16x16x32_bf16 v[94:97], v[166:169], v[218:221], v[94:97]
	v_mfma_f32_16x16x32_bf16 v[90:93], v[178:181], v[218:221], v[90:93]
	v_mfma_f32_16x16x32_bf16 v[78:81], v[166:169], v[226:229], v[78:81]
	v_mfma_f32_16x16x32_bf16 v[74:77], v[178:181], v[226:229], v[74:77]
	v_mfma_f32_16x16x32_bf16 v[126:129], v[170:173], v[206:209], v[126:129]
	v_mfma_f32_16x16x32_bf16 v[122:125], v[182:185], v[206:209], v[122:125]
	v_mfma_f32_16x16x32_bf16 v[110:113], v[170:173], v[214:217], v[110:113]
	v_mfma_f32_16x16x32_bf16 v[106:109], v[182:185], v[214:217], v[106:109]
	v_mfma_f32_16x16x32_bf16 v[94:97], v[170:173], v[222:225], v[94:97]
	v_mfma_f32_16x16x32_bf16 v[90:93], v[182:185], v[222:225], v[90:93]
	v_mfma_f32_16x16x32_bf16 v[78:81], v[170:173], v[230:233], v[78:81]
	v_mfma_f32_16x16x32_bf16 v[74:77], v[182:185], v[230:233], v[74:77]
	v_mfma_f32_16x16x32_bf16 v[118:121], v[186:189], v[202:205], v[118:121]
	v_mfma_f32_16x16x32_bf16 v[114:117], v[194:197], v[202:205], v[114:117]
	v_mfma_f32_16x16x32_bf16 v[102:105], v[186:189], v[210:213], v[102:105]
	v_mfma_f32_16x16x32_bf16 v[98:101], v[194:197], v[210:213], v[98:101]
	v_mfma_f32_16x16x32_bf16 v[86:89], v[186:189], v[218:221], v[86:89]
	v_mfma_f32_16x16x32_bf16 v[82:85], v[194:197], v[218:221], v[82:85]
	v_mfma_f32_16x16x32_bf16 v[70:73], v[186:189], v[226:229], v[70:73]
	v_mfma_f32_16x16x32_bf16 v[66:69], v[194:197], v[226:229], v[66:69]
	v_mfma_f32_16x16x32_bf16 v[118:121], v[190:193], v[206:209], v[118:121]
	v_mfma_f32_16x16x32_bf16 v[114:117], v[198:201], v[206:209], v[114:117]
	v_mfma_f32_16x16x32_bf16 v[102:105], v[190:193], v[214:217], v[102:105]
	v_mfma_f32_16x16x32_bf16 v[98:101], v[198:201], v[214:217], v[98:101]
	v_mfma_f32_16x16x32_bf16 v[86:89], v[190:193], v[222:225], v[86:89]
	v_mfma_f32_16x16x32_bf16 v[82:85], v[198:201], v[222:225], v[82:85]
	v_mfma_f32_16x16x32_bf16 v[70:73], v[190:193], v[230:233], v[70:73]
	v_mfma_f32_16x16x32_bf16 v[66:69], v[198:201], v[230:233], v[66:69]
	s_setprio 0
	s_barrier
	s_add_i32 s2, s56, s30
	v_lshl_add_u64 v[148:149], v[148:149], 0, s[6:7]
	s_mov_b32 m0, s2
	ds_read_b128 v[202:205], v164 offset:49152
	ds_read_b128 v[206:209], v164 offset:50176
	ds_read_b128 v[210:213], v164 offset:51200
	ds_read_b128 v[214:217], v164 offset:52224
	ds_read_b128 v[218:221], v164 offset:53248
	ds_read_b128 v[222:225], v164 offset:54272
	ds_read_b128 v[226:229], v164 offset:55296
	ds_read_b128 v[230:233], v164 offset:56320
	global_load_lds_dwordx4 v[148:149], off
	s_add_i32 m0, s2, 0x2000
	s_add_u32 s2, s28, 0x40080
	v_lshl_add_u64 v[148:149], v[174:175], 0, s[6:7]
	s_addc_u32 s3, s29, 0
	s_add_i32 s28, s57, s30
	global_load_lds_dwordx4 v[148:149], off
	v_lshl_add_u64 v[148:149], s[2:3], 0, v[132:133]
	s_mov_b32 m0, s28
	s_nop 0
	global_load_lds_dwordx4 v[148:149], off
	v_lshl_add_u64 v[148:149], s[2:3], 0, v[136:137]
	s_add_i32 m0, s28, 0x2000
	s_nop 0
	global_load_lds_dwordx4 v[148:149], off
	v_lshl_add_u64 v[148:149], v[234:235], 0, s[6:7]
	s_mov_b32 m0, s39
	s_nop 0
	global_load_lds_dwordx4 v[148:149], off
	v_lshl_add_u64 v[148:149], v[236:237], 0, s[6:7]
	s_mov_b32 m0, s40
	s_nop 0
	global_load_lds_dwordx4 v[148:149], off
	s_waitcnt vmcnt(8)
	s_waitcnt lgkmcnt(0)
	s_barrier
	s_setprio 1
	v_mfma_f32_16x16x32_bf16 v[62:65], v[166:169], v[202:205], v[62:65]
	v_mfma_f32_16x16x32_bf16 v[58:61], v[178:181], v[202:205], v[58:61]
	v_mfma_f32_16x16x32_bf16 v[46:49], v[166:169], v[210:213], v[46:49]
	v_mfma_f32_16x16x32_bf16 v[42:45], v[178:181], v[210:213], v[42:45]
	v_mfma_f32_16x16x32_bf16 v[30:33], v[166:169], v[218:221], v[30:33]
	v_mfma_f32_16x16x32_bf16 v[26:29], v[178:181], v[218:221], v[26:29]
	v_mfma_f32_16x16x32_bf16 v[14:17], v[166:169], v[226:229], v[14:17]
	v_mfma_f32_16x16x32_bf16 v[10:13], v[178:181], v[226:229], v[10:13]
	v_mfma_f32_16x16x32_bf16 v[62:65], v[170:173], v[206:209], v[62:65]
	v_mfma_f32_16x16x32_bf16 v[58:61], v[182:185], v[206:209], v[58:61]
	v_mfma_f32_16x16x32_bf16 v[46:49], v[170:173], v[214:217], v[46:49]
	v_mfma_f32_16x16x32_bf16 v[42:45], v[182:185], v[214:217], v[42:45]
	v_mfma_f32_16x16x32_bf16 v[30:33], v[170:173], v[222:225], v[30:33]
	v_mfma_f32_16x16x32_bf16 v[26:29], v[182:185], v[222:225], v[26:29]
	v_mfma_f32_16x16x32_bf16 v[14:17], v[170:173], v[230:233], v[14:17]
	v_mfma_f32_16x16x32_bf16 v[10:13], v[182:185], v[230:233], v[10:13]
	v_mfma_f32_16x16x32_bf16 v[54:57], v[186:189], v[202:205], v[54:57]
	v_mfma_f32_16x16x32_bf16 v[50:53], v[194:197], v[202:205], v[50:53]
	v_mfma_f32_16x16x32_bf16 v[38:41], v[186:189], v[210:213], v[38:41]
	v_mfma_f32_16x16x32_bf16 v[34:37], v[194:197], v[210:213], v[34:37]
	v_mfma_f32_16x16x32_bf16 v[22:25], v[186:189], v[218:221], v[22:25]
	v_mfma_f32_16x16x32_bf16 v[18:21], v[194:197], v[218:221], v[18:21]
	v_mfma_f32_16x16x32_bf16 v[6:9], v[186:189], v[226:229], v[6:9]
	v_mfma_f32_16x16x32_bf16 v[2:5], v[194:197], v[226:229], v[2:5]
	v_mfma_f32_16x16x32_bf16 v[54:57], v[190:193], v[206:209], v[54:57]
	v_mfma_f32_16x16x32_bf16 v[50:53], v[198:201], v[206:209], v[50:53]
	v_mfma_f32_16x16x32_bf16 v[38:41], v[190:193], v[214:217], v[38:41]
	v_mfma_f32_16x16x32_bf16 v[34:37], v[198:201], v[214:217], v[34:37]
	v_mfma_f32_16x16x32_bf16 v[22:25], v[190:193], v[222:225], v[22:25]
	v_mfma_f32_16x16x32_bf16 v[18:21], v[198:201], v[222:225], v[18:21]
	v_mfma_f32_16x16x32_bf16 v[6:9], v[190:193], v[230:233], v[6:9]
	v_mfma_f32_16x16x32_bf16 v[2:5], v[198:201], v[230:233], v[2:5]
	s_setprio 0
	s_barrier
	s_add_i32 s55, s55, 2
	s_add_u32 s26, s26, 0x100
	s_addc_u32 s27, s27, 0
	s_add_u32 s53, s53, 0x100
	s_addc_u32 s54, s54, 0
	s_cmp_gt_u32 s55, 13
	s_cbranch_scc0 .LBB0_1303

.LBB0_1386:
	ds_read_b128 v[160:163], v133
	ds_read_b128 v[164:167], v133 offset:1024
	ds_read_b128 v[168:171], v133 offset:2048
	ds_read_b128 v[172:175], v133 offset:3072
	ds_read_b128 v[178:181], v135
	ds_read_b128 v[182:185], v135 offset:1024
	ds_read_b128 v[186:189], v135 offset:2048
	ds_read_b128 v[190:193], v135 offset:3072
	s_cmp_lg_u32 s8, 0x160000
	s_cselect_b32 s13, s8, 0
	s_cselect_b32 s12, s9, 0
	s_add_u32 s2, s6, s13
	s_addc_u32 s3, s7, s12
	s_add_u32 s14, s0, s13
	s_addc_u32 s15, s1, s12
	s_add_u32 s12, s2, 0x8000
	s_addc_u32 s13, s3, 0
	v_lshl_add_u64 v[226:227], v[148:149], 0, s[8:9]
	s_mov_b32 m0, s27
	v_lshl_add_u64 v[226:227], v[226:227], 0, s[10:11]
	ds_read_b128 v[194:197], v137
	ds_read_b128 v[198:201], v137 offset:1024
	ds_read_b128 v[202:205], v137 offset:2048
	ds_read_b128 v[206:209], v137 offset:3072
	ds_read_b128 v[210:213], v137 offset:4096
	ds_read_b128 v[214:217], v137 offset:5120
	ds_read_b128 v[218:221], v137 offset:6144
	ds_read_b128 v[222:225], v137 offset:7168
	global_load_lds_dwordx4 v[226:227], off
	v_lshl_add_u64 v[226:227], v[150:151], 0, s[8:9]
	v_lshl_add_u64 v[226:227], v[226:227], 0, s[10:11]
	s_mov_b32 m0, s28
	s_nop 0
	global_load_lds_dwordx4 v[226:227], off
	s_waitcnt vmcnt(8)
	s_waitcnt lgkmcnt(0)
	s_barrier
	s_setprio 1
	v_mfma_f32_16x16x32_bf16 v[126:129], v[160:163], v[194:197], v[126:129]
	v_mfma_f32_16x16x32_bf16 v[122:125], v[168:171], v[194:197], v[122:125]
	v_mfma_f32_16x16x32_bf16 v[114:117], v[160:163], v[202:205], v[114:117]
	v_mfma_f32_16x16x32_bf16 v[106:109], v[168:171], v[202:205], v[106:109]
	v_mfma_f32_16x16x32_bf16 v[98:101], v[160:163], v[210:213], v[98:101]
	v_mfma_f32_16x16x32_bf16 v[90:93], v[168:171], v[210:213], v[90:93]
	v_mfma_f32_16x16x32_bf16 v[82:85], v[160:163], v[218:221], v[82:85]
	v_mfma_f32_16x16x32_bf16 v[74:77], v[168:171], v[218:221], v[74:77]
	v_mfma_f32_16x16x32_bf16 v[126:129], v[164:167], v[198:201], v[126:129]
	v_mfma_f32_16x16x32_bf16 v[122:125], v[172:175], v[198:201], v[122:125]
	v_mfma_f32_16x16x32_bf16 v[114:117], v[164:167], v[206:209], v[114:117]
	v_mfma_f32_16x16x32_bf16 v[106:109], v[172:175], v[206:209], v[106:109]
	v_mfma_f32_16x16x32_bf16 v[98:101], v[164:167], v[214:217], v[98:101]
	v_mfma_f32_16x16x32_bf16 v[90:93], v[172:175], v[214:217], v[90:93]
	v_mfma_f32_16x16x32_bf16 v[82:85], v[164:167], v[222:225], v[82:85]
	v_mfma_f32_16x16x32_bf16 v[74:77], v[172:175], v[222:225], v[74:77]
	v_mfma_f32_16x16x32_bf16 v[118:121], v[178:181], v[194:197], v[118:121]
	v_mfma_f32_16x16x32_bf16 v[110:113], v[186:189], v[194:197], v[110:113]
	v_mfma_f32_16x16x32_bf16 v[102:105], v[178:181], v[202:205], v[102:105]
	v_mfma_f32_16x16x32_bf16 v[94:97], v[186:189], v[202:205], v[94:97]
	v_mfma_f32_16x16x32_bf16 v[86:89], v[178:181], v[210:213], v[86:89]
	v_mfma_f32_16x16x32_bf16 v[78:81], v[186:189], v[210:213], v[78:81]
	v_mfma_f32_16x16x32_bf16 v[70:73], v[178:181], v[218:221], v[70:73]
	v_mfma_f32_16x16x32_bf16 v[66:69], v[186:189], v[218:221], v[66:69]
	v_mfma_f32_16x16x32_bf16 v[118:121], v[182:185], v[198:201], v[118:121]
	v_mfma_f32_16x16x32_bf16 v[110:113], v[190:193], v[198:201], v[110:113]
	v_mfma_f32_16x16x32_bf16 v[102:105], v[182:185], v[206:209], v[102:105]
	v_mfma_f32_16x16x32_bf16 v[94:97], v[190:193], v[206:209], v[94:97]
	v_mfma_f32_16x16x32_bf16 v[86:89], v[182:185], v[214:217], v[86:89]
	v_mfma_f32_16x16x32_bf16 v[78:81], v[190:193], v[214:217], v[78:81]
	v_mfma_f32_16x16x32_bf16 v[70:73], v[182:185], v[222:225], v[70:73]
	v_mfma_f32_16x16x32_bf16 v[66:69], v[190:193], v[222:225], v[66:69]
	s_setprio 0
	s_barrier
	s_mov_b32 m0, s29
	v_lshl_add_u64 v[226:227], s[14:15], 0, v[142:143]
	s_add_u32 s40, s14, 0x4000
	ds_read_b128 v[194:197], v137 offset:16384
	ds_read_b128 v[198:201], v137 offset:17408
	ds_read_b128 v[202:205], v137 offset:18432
	ds_read_b128 v[206:209], v137 offset:19456
	ds_read_b128 v[210:213], v137 offset:20480
	ds_read_b128 v[214:217], v137 offset:21504
	ds_read_b128 v[218:221], v137 offset:22528
	ds_read_b128 v[222:225], v137 offset:23552
	global_load_lds_dwordx4 v[226:227], off
	v_lshl_add_u64 v[226:227], s[14:15], 0, v[146:147]
	s_mov_b32 m0, s30
	s_addc_u32 s41, s15, 0
	global_load_lds_dwordx4 v[226:227], off
	v_lshl_add_u64 v[226:227], s[40:41], 0, v[142:143]
	s_mov_b32 m0, s31
	s_nop 0
	global_load_lds_dwordx4 v[226:227], off
	v_lshl_add_u64 v[226:227], s[40:41], 0, v[146:147]
	s_mov_b32 m0, s34
	s_nop 0
	global_load_lds_dwordx4 v[226:227], off
	v_lshl_add_u64 v[226:227], s[2:3], 0, v[140:141]
	s_mov_b32 m0, s19
	s_nop 0
	global_load_lds_dwordx4 v[226:227], off
	v_lshl_add_u64 v[226:227], s[2:3], 0, v[144:145]
	s_mov_b32 m0, s20
	s_nop 0
	global_load_lds_dwordx4 v[226:227], off
	s_waitcnt vmcnt(8)
	s_waitcnt lgkmcnt(0)
	s_barrier
	s_setprio 1
	v_mfma_f32_16x16x32_bf16 v[62:65], v[160:163], v[194:197], v[62:65]
	v_mfma_f32_16x16x32_bf16 v[58:61], v[168:171], v[194:197], v[58:61]
	v_mfma_f32_16x16x32_bf16 v[50:53], v[160:163], v[202:205], v[50:53]
	v_mfma_f32_16x16x32_bf16 v[42:45], v[168:171], v[202:205], v[42:45]
	v_mfma_f32_16x16x32_bf16 v[34:37], v[160:163], v[210:213], v[34:37]
	v_mfma_f32_16x16x32_bf16 v[26:29], v[168:171], v[210:213], v[26:29]
	v_mfma_f32_16x16x32_bf16 v[18:21], v[160:163], v[218:221], v[18:21]
	v_mfma_f32_16x16x32_bf16 v[10:13], v[168:171], v[218:221], v[10:13]
	v_mfma_f32_16x16x32_bf16 v[62:65], v[164:167], v[198:201], v[62:65]
	v_mfma_f32_16x16x32_bf16 v[58:61], v[172:175], v[198:201], v[58:61]
	v_mfma_f32_16x16x32_bf16 v[50:53], v[164:167], v[206:209], v[50:53]
	v_mfma_f32_16x16x32_bf16 v[42:45], v[172:175], v[206:209], v[42:45]
	v_mfma_f32_16x16x32_bf16 v[34:37], v[164:167], v[214:217], v[34:37]
	v_mfma_f32_16x16x32_bf16 v[26:29], v[172:175], v[214:217], v[26:29]
	v_mfma_f32_16x16x32_bf16 v[18:21], v[164:167], v[222:225], v[18:21]
	v_mfma_f32_16x16x32_bf16 v[10:13], v[172:175], v[222:225], v[10:13]
	v_mfma_f32_16x16x32_bf16 v[54:57], v[178:181], v[194:197], v[54:57]
	v_mfma_f32_16x16x32_bf16 v[46:49], v[186:189], v[194:197], v[46:49]
	v_mfma_f32_16x16x32_bf16 v[38:41], v[178:181], v[202:205], v[38:41]
	v_mfma_f32_16x16x32_bf16 v[30:33], v[186:189], v[202:205], v[30:33]
	v_mfma_f32_16x16x32_bf16 v[22:25], v[178:181], v[210:213], v[22:25]
	v_mfma_f32_16x16x32_bf16 v[14:17], v[186:189], v[210:213], v[14:17]
	v_mfma_f32_16x16x32_bf16 v[6:9], v[178:181], v[218:221], v[6:9]
	v_mfma_f32_16x16x32_bf16 v[2:5], v[186:189], v[218:221], v[2:5]
	v_mfma_f32_16x16x32_bf16 v[54:57], v[182:185], v[198:201], v[54:57]
	v_mfma_f32_16x16x32_bf16 v[46:49], v[190:193], v[198:201], v[46:49]
	v_mfma_f32_16x16x32_bf16 v[38:41], v[182:185], v[206:209], v[38:41]
	v_mfma_f32_16x16x32_bf16 v[30:33], v[190:193], v[206:209], v[30:33]
	v_mfma_f32_16x16x32_bf16 v[22:25], v[182:185], v[214:217], v[22:25]
	v_mfma_f32_16x16x32_bf16 v[14:17], v[190:193], v[214:217], v[14:17]
	v_mfma_f32_16x16x32_bf16 v[6:9], v[182:185], v[222:225], v[6:9]
	v_mfma_f32_16x16x32_bf16 v[2:5], v[190:193], v[222:225], v[2:5]
	s_setprio 0
	s_barrier
	ds_read_b128 v[160:163], v139
	ds_read_b128 v[164:167], v139 offset:1024
	ds_read_b128 v[168:171], v139 offset:2048
	ds_read_b128 v[172:175], v139 offset:3072
	ds_read_b128 v[178:181], v158
	ds_read_b128 v[182:185], v158 offset:1024
	ds_read_b128 v[186:189], v158 offset:2048
	ds_read_b128 v[190:193], v158 offset:3072
	s_add_u32 s2, s2, 0x4000
	s_addc_u32 s3, s3, 0
	s_mov_b32 m0, s21
	v_lshl_add_u64 v[226:227], s[2:3], 0, v[140:141]
	ds_read_b128 v[194:197], v137 offset:32768
	ds_read_b128 v[198:201], v137 offset:33792
	ds_read_b128 v[202:205], v137 offset:34816
	ds_read_b128 v[206:209], v137 offset:35840
	ds_read_b128 v[210:213], v137 offset:36864
	ds_read_b128 v[214:217], v137 offset:37888
	ds_read_b128 v[218:221], v137 offset:38912
	ds_read_b128 v[222:225], v137 offset:39936
	global_load_lds_dwordx4 v[226:227], off
	v_lshl_add_u64 v[226:227], s[2:3], 0, v[144:145]
	s_mov_b32 m0, s22
	s_nop 0
	global_load_lds_dwordx4 v[226:227], off
	s_waitcnt vmcnt(8)
	s_waitcnt lgkmcnt(0)
	s_barrier
	s_setprio 1
	v_mfma_f32_16x16x32_bf16 v[126:129], v[160:163], v[194:197], v[126:129]
	v_mfma_f32_16x16x32_bf16 v[122:125], v[168:171], v[194:197], v[122:125]
	v_mfma_f32_16x16x32_bf16 v[114:117], v[160:163], v[202:205], v[114:117]
	v_mfma_f32_16x16x32_bf16 v[106:109], v[168:171], v[202:205], v[106:109]
	v_mfma_f32_16x16x32_bf16 v[98:101], v[160:163], v[210:213], v[98:101]
	v_mfma_f32_16x16x32_bf16 v[90:93], v[168:171], v[210:213], v[90:93]
	v_mfma_f32_16x16x32_bf16 v[82:85], v[160:163], v[218:221], v[82:85]
	v_mfma_f32_16x16x32_bf16 v[74:77], v[168:171], v[218:221], v[74:77]
	v_mfma_f32_16x16x32_bf16 v[126:129], v[164:167], v[198:201], v[126:129]
	v_mfma_f32_16x16x32_bf16 v[122:125], v[172:175], v[198:201], v[122:125]
	v_mfma_f32_16x16x32_bf16 v[114:117], v[164:167], v[206:209], v[114:117]
	v_mfma_f32_16x16x32_bf16 v[106:109], v[172:175], v[206:209], v[106:109]
	v_mfma_f32_16x16x32_bf16 v[98:101], v[164:167], v[214:217], v[98:101]
	v_mfma_f32_16x16x32_bf16 v[90:93], v[172:175], v[214:217], v[90:93]
	v_mfma_f32_16x16x32_bf16 v[82:85], v[164:167], v[222:225], v[82:85]
	v_mfma_f32_16x16x32_bf16 v[74:77], v[172:175], v[222:225], v[74:77]
	v_mfma_f32_16x16x32_bf16 v[118:121], v[178:181], v[194:197], v[118:121]
	v_mfma_f32_16x16x32_bf16 v[110:113], v[186:189], v[194:197], v[110:113]
	v_mfma_f32_16x16x32_bf16 v[102:105], v[178:181], v[202:205], v[102:105]
	v_mfma_f32_16x16x32_bf16 v[94:97], v[186:189], v[202:205], v[94:97]
	v_mfma_f32_16x16x32_bf16 v[86:89], v[178:181], v[210:213], v[86:89]
	v_mfma_f32_16x16x32_bf16 v[78:81], v[186:189], v[210:213], v[78:81]
	v_mfma_f32_16x16x32_bf16 v[70:73], v[178:181], v[218:221], v[70:73]
	v_mfma_f32_16x16x32_bf16 v[66:69], v[186:189], v[218:221], v[66:69]
	v_mfma_f32_16x16x32_bf16 v[118:121], v[182:185], v[198:201], v[118:121]
	v_mfma_f32_16x16x32_bf16 v[110:113], v[190:193], v[198:201], v[110:113]
	v_mfma_f32_16x16x32_bf16 v[102:105], v[182:185], v[206:209], v[102:105]
	v_mfma_f32_16x16x32_bf16 v[94:97], v[190:193], v[206:209], v[94:97]
	v_mfma_f32_16x16x32_bf16 v[86:89], v[182:185], v[214:217], v[86:89]
	v_mfma_f32_16x16x32_bf16 v[78:81], v[190:193], v[214:217], v[78:81]
	v_mfma_f32_16x16x32_bf16 v[70:73], v[182:185], v[222:225], v[70:73]
	v_mfma_f32_16x16x32_bf16 v[66:69], v[190:193], v[222:225], v[66:69]
	s_setprio 0
	s_barrier
	s_add_u32 s2, s14, 0x8000
	s_addc_u32 s3, s15, 0
	s_mov_b32 m0, s35
	v_lshl_add_u64 v[226:227], s[2:3], 0, v[142:143]
	ds_read_b128 v[194:197], v137 offset:49152
	ds_read_b128 v[198:201], v137 offset:50176
	ds_read_b128 v[202:205], v137 offset:51200
	ds_read_b128 v[206:209], v137 offset:52224
	ds_read_b128 v[210:213], v137 offset:53248
	ds_read_b128 v[214:217], v137 offset:54272
	ds_read_b128 v[218:221], v137 offset:55296
	ds_read_b128 v[222:225], v137 offset:56320
	global_load_lds_dwordx4 v[226:227], off
	v_lshl_add_u64 v[226:227], s[2:3], 0, v[146:147]
	s_add_u32 s2, s14, 0xc000
	s_mov_b32 m0, s36
	s_addc_u32 s3, s15, 0
	global_load_lds_dwordx4 v[226:227], off
	v_lshl_add_u64 v[226:227], s[2:3], 0, v[142:143]
	s_mov_b32 m0, s37
	s_nop 0
	global_load_lds_dwordx4 v[226:227], off
	v_lshl_add_u64 v[226:227], s[2:3], 0, v[146:147]
	s_mov_b32 m0, s38
	s_nop 0
	global_load_lds_dwordx4 v[226:227], off
	v_lshl_add_u64 v[226:227], s[12:13], 0, v[140:141]
	s_mov_b32 m0, s24
	s_nop 0
	global_load_lds_dwordx4 v[226:227], off
	v_lshl_add_u64 v[226:227], s[12:13], 0, v[144:145]
	s_mov_b32 m0, s25
	s_nop 0
	global_load_lds_dwordx4 v[226:227], off
	s_waitcnt vmcnt(8)
	s_waitcnt lgkmcnt(0)
	s_barrier
	s_setprio 1
	v_mfma_f32_16x16x32_bf16 v[62:65], v[160:163], v[194:197], v[62:65]
	v_mfma_f32_16x16x32_bf16 v[58:61], v[168:171], v[194:197], v[58:61]
	v_mfma_f32_16x16x32_bf16 v[50:53], v[160:163], v[202:205], v[50:53]
	v_mfma_f32_16x16x32_bf16 v[42:45], v[168:171], v[202:205], v[42:45]
	v_mfma_f32_16x16x32_bf16 v[34:37], v[160:163], v[210:213], v[34:37]
	v_mfma_f32_16x16x32_bf16 v[26:29], v[168:171], v[210:213], v[26:29]
	v_mfma_f32_16x16x32_bf16 v[18:21], v[160:163], v[218:221], v[18:21]
	v_mfma_f32_16x16x32_bf16 v[10:13], v[168:171], v[218:221], v[10:13]
	v_mfma_f32_16x16x32_bf16 v[62:65], v[164:167], v[198:201], v[62:65]
	v_mfma_f32_16x16x32_bf16 v[58:61], v[172:175], v[198:201], v[58:61]
	v_mfma_f32_16x16x32_bf16 v[50:53], v[164:167], v[206:209], v[50:53]
	v_mfma_f32_16x16x32_bf16 v[42:45], v[172:175], v[206:209], v[42:45]
	v_mfma_f32_16x16x32_bf16 v[34:37], v[164:167], v[214:217], v[34:37]
	v_mfma_f32_16x16x32_bf16 v[26:29], v[172:175], v[214:217], v[26:29]
	v_mfma_f32_16x16x32_bf16 v[18:21], v[164:167], v[222:225], v[18:21]
	v_mfma_f32_16x16x32_bf16 v[10:13], v[172:175], v[222:225], v[10:13]
	v_mfma_f32_16x16x32_bf16 v[54:57], v[178:181], v[194:197], v[54:57]
	v_mfma_f32_16x16x32_bf16 v[46:49], v[186:189], v[194:197], v[46:49]
	v_mfma_f32_16x16x32_bf16 v[38:41], v[178:181], v[202:205], v[38:41]
	v_mfma_f32_16x16x32_bf16 v[30:33], v[186:189], v[202:205], v[30:33]
	v_mfma_f32_16x16x32_bf16 v[22:25], v[178:181], v[210:213], v[22:25]
	v_mfma_f32_16x16x32_bf16 v[14:17], v[186:189], v[210:213], v[14:17]
	v_mfma_f32_16x16x32_bf16 v[6:9], v[178:181], v[218:221], v[6:9]
	v_mfma_f32_16x16x32_bf16 v[2:5], v[186:189], v[218:221], v[2:5]
	v_mfma_f32_16x16x32_bf16 v[54:57], v[182:185], v[198:201], v[54:57]
	v_mfma_f32_16x16x32_bf16 v[46:49], v[190:193], v[198:201], v[46:49]
	v_mfma_f32_16x16x32_bf16 v[38:41], v[182:185], v[206:209], v[38:41]
	v_mfma_f32_16x16x32_bf16 v[30:33], v[190:193], v[206:209], v[30:33]
	v_mfma_f32_16x16x32_bf16 v[22:25], v[182:185], v[214:217], v[22:25]
	v_mfma_f32_16x16x32_bf16 v[14:17], v[190:193], v[214:217], v[14:17]
	v_mfma_f32_16x16x32_bf16 v[6:9], v[182:185], v[222:225], v[6:9]
	v_mfma_f32_16x16x32_bf16 v[2:5], v[190:193], v[222:225], v[2:5]
	s_setprio 0
	s_barrier
	s_add_i32 s26, s26, 2
	s_add_u32 s8, s8, 0x10000
	s_addc_u32 s9, s9, 0
	s_cmp_gt_u32 s26, 41
	s_cbranch_scc0 .LBB0_1386
	s_cmpk_lt_u32 s16, 0x100
	s_cbranch_scc0 .LBB0_1389
	s_barrier

.Lpk1400_peel:
	ds_read_b128 v[152:155], v1
	ds_read_b128 v[156:159], v1 offset:1024
	ds_read_b128 v[160:163], v1 offset:2048
	ds_read_b128 v[164:167], v1 offset:3072
	ds_read_b128 v[168:171], v149
	ds_read_b128 v[172:175], v149 offset:1024
	ds_read_b128 v[178:181], v149 offset:2048
	ds_read_b128 v[182:185], v149 offset:3072
	s_add_u32 s2, s28, 0xfffc0080
	s_addc_u32 s3, s29, -1
	s_cmp_eq_u32 s55, 12
	s_cselect_b32 s3, s11, s3
	s_cselect_b32 s2, s13, s2
	s_cselect_b32 s31, s47, s54
	s_cselect_b32 s30, s52, s53
	v_lshl_add_u64 v[146:147], s[28:29], 0, v[140:141]
	s_add_i32 m0, s25, 0xc000
	ds_read_b128 v[186:189], v150
	ds_read_b128 v[190:193], v150 offset:1024
	ds_read_b128 v[194:197], v150 offset:2048
	ds_read_b128 v[198:201], v150 offset:3072
	ds_read_b128 v[202:205], v150 offset:4096
	ds_read_b128 v[206:209], v150 offset:5120
	ds_read_b128 v[210:213], v150 offset:6144
	ds_read_b128 v[214:217], v150 offset:7168
	global_load_lds_dwordx4 v[146:147], off
	v_lshl_add_u64 v[146:147], s[28:29], 0, v[142:143]
	s_add_i32 m0, s25, 0xe000
	s_nop 0
	global_load_lds_dwordx4 v[146:147], off
	s_waitcnt vmcnt(8)
	s_waitcnt lgkmcnt(0)
	s_barrier
	s_setprio 1
	v_mfma_f32_16x16x32_bf16 v[126:129], v[152:155], v[186:189], 0
	v_mfma_f32_16x16x32_bf16 v[122:125], v[160:163], v[186:189], 0
	v_mfma_f32_16x16x32_bf16 v[110:113], v[152:155], v[194:197], 0
	v_mfma_f32_16x16x32_bf16 v[106:109], v[160:163], v[194:197], 0
	v_mfma_f32_16x16x32_bf16 v[94:97], v[152:155], v[202:205], 0
	v_mfma_f32_16x16x32_bf16 v[90:93], v[160:163], v[202:205], 0
	v_mfma_f32_16x16x32_bf16 v[78:81], v[152:155], v[210:213], 0
	v_mfma_f32_16x16x32_bf16 v[74:77], v[160:163], v[210:213], 0
	v_mfma_f32_16x16x32_bf16 v[126:129], v[156:159], v[190:193], v[126:129]
	v_mfma_f32_16x16x32_bf16 v[122:125], v[164:167], v[190:193], v[122:125]
	v_mfma_f32_16x16x32_bf16 v[110:113], v[156:159], v[198:201], v[110:113]
	v_mfma_f32_16x16x32_bf16 v[106:109], v[164:167], v[198:201], v[106:109]
	v_mfma_f32_16x16x32_bf16 v[94:97], v[156:159], v[206:209], v[94:97]
	v_mfma_f32_16x16x32_bf16 v[90:93], v[164:167], v[206:209], v[90:93]
	v_mfma_f32_16x16x32_bf16 v[78:81], v[156:159], v[214:217], v[78:81]
	v_mfma_f32_16x16x32_bf16 v[74:77], v[164:167], v[214:217], v[74:77]
	v_mfma_f32_16x16x32_bf16 v[118:121], v[168:171], v[186:189], 0
	v_mfma_f32_16x16x32_bf16 v[114:117], v[178:181], v[186:189], 0
	v_mfma_f32_16x16x32_bf16 v[102:105], v[168:171], v[194:197], 0
	v_mfma_f32_16x16x32_bf16 v[98:101], v[178:181], v[194:197], 0
	v_mfma_f32_16x16x32_bf16 v[86:89], v[168:171], v[202:205], 0
	v_mfma_f32_16x16x32_bf16 v[82:85], v[178:181], v[202:205], 0
	v_mfma_f32_16x16x32_bf16 v[70:73], v[168:171], v[210:213], 0
	v_mfma_f32_16x16x32_bf16 v[66:69], v[178:181], v[210:213], 0
	v_mfma_f32_16x16x32_bf16 v[118:121], v[172:175], v[190:193], v[118:121]
	v_mfma_f32_16x16x32_bf16 v[114:117], v[182:185], v[190:193], v[114:117]
	v_mfma_f32_16x16x32_bf16 v[102:105], v[172:175], v[198:201], v[102:105]
	v_mfma_f32_16x16x32_bf16 v[98:101], v[182:185], v[198:201], v[98:101]
	v_mfma_f32_16x16x32_bf16 v[86:89], v[172:175], v[206:209], v[86:89]
	v_mfma_f32_16x16x32_bf16 v[82:85], v[182:185], v[206:209], v[82:85]
	v_mfma_f32_16x16x32_bf16 v[70:73], v[172:175], v[214:217], v[70:73]
	v_mfma_f32_16x16x32_bf16 v[66:69], v[182:185], v[214:217], v[66:69]
	s_setprio 0
	s_barrier
	s_add_i32 s56, s43, s34
	v_lshl_add_u64 v[146:147], s[30:31], 0, v[132:133]
	s_mov_b32 m0, s56
	ds_read_b128 v[186:189], v150 offset:16384
	ds_read_b128 v[190:193], v150 offset:17408
	ds_read_b128 v[194:197], v150 offset:18432
	ds_read_b128 v[198:201], v150 offset:19456
	ds_read_b128 v[202:205], v150 offset:20480
	ds_read_b128 v[206:209], v150 offset:21504
	ds_read_b128 v[210:213], v150 offset:22528
	ds_read_b128 v[214:217], v150 offset:23552
	global_load_lds_dwordx4 v[146:147], off
	s_add_i32 m0, s56, 0x2000
	s_add_u32 s56, s30, 0x40000
	v_lshl_add_u64 v[218:219], s[30:31], 0, v[136:137]
	s_addc_u32 s57, s31, 0
	s_add_i32 s58, s44, s34
	global_load_lds_dwordx4 v[218:219], off
	v_lshl_add_u64 v[220:221], s[56:57], 0, v[132:133]
	s_mov_b32 m0, s58
	v_lshl_add_u64 v[222:223], s[2:3], 0, v[134:135]
	global_load_lds_dwordx4 v[220:221], off
	v_lshl_add_u64 v[220:221], s[56:57], 0, v[136:137]
	s_add_i32 m0, s58, 0x2000
	s_nop 0
	global_load_lds_dwordx4 v[220:221], off
	v_lshl_add_u64 v[220:221], s[2:3], 0, v[130:131]
	s_mov_b32 m0, s25
	s_nop 0
	global_load_lds_dwordx4 v[220:221], off
	s_mov_b32 m0, s27
	s_nop 0
	global_load_lds_dwordx4 v[222:223], off
	s_waitcnt vmcnt(8)
	s_waitcnt lgkmcnt(0)
	s_barrier
	s_setprio 1
	v_mfma_f32_16x16x32_bf16 v[62:65], v[152:155], v[186:189], 0
	v_mfma_f32_16x16x32_bf16 v[58:61], v[160:163], v[186:189], 0
	v_mfma_f32_16x16x32_bf16 v[46:49], v[152:155], v[194:197], 0
	v_mfma_f32_16x16x32_bf16 v[42:45], v[160:163], v[194:197], 0
	v_mfma_f32_16x16x32_bf16 v[30:33], v[152:155], v[202:205], 0
	v_mfma_f32_16x16x32_bf16 v[26:29], v[160:163], v[202:205], 0
	v_mfma_f32_16x16x32_bf16 v[14:17], v[152:155], v[210:213], 0
	v_mfma_f32_16x16x32_bf16 v[10:13], v[160:163], v[210:213], 0
	v_mfma_f32_16x16x32_bf16 v[62:65], v[156:159], v[190:193], v[62:65]
	v_mfma_f32_16x16x32_bf16 v[58:61], v[164:167], v[190:193], v[58:61]
	v_mfma_f32_16x16x32_bf16 v[46:49], v[156:159], v[198:201], v[46:49]
	v_mfma_f32_16x16x32_bf16 v[42:45], v[164:167], v[198:201], v[42:45]
	v_mfma_f32_16x16x32_bf16 v[30:33], v[156:159], v[206:209], v[30:33]
	v_mfma_f32_16x16x32_bf16 v[26:29], v[164:167], v[206:209], v[26:29]
	v_mfma_f32_16x16x32_bf16 v[14:17], v[156:159], v[214:217], v[14:17]
	v_mfma_f32_16x16x32_bf16 v[10:13], v[164:167], v[214:217], v[10:13]
	v_mfma_f32_16x16x32_bf16 v[54:57], v[168:171], v[186:189], 0
	v_mfma_f32_16x16x32_bf16 v[50:53], v[178:181], v[186:189], 0
	v_mfma_f32_16x16x32_bf16 v[38:41], v[168:171], v[194:197], 0
	v_mfma_f32_16x16x32_bf16 v[34:37], v[178:181], v[194:197], 0
	v_mfma_f32_16x16x32_bf16 v[22:25], v[168:171], v[202:205], 0
	v_mfma_f32_16x16x32_bf16 v[18:21], v[178:181], v[202:205], 0
	v_mfma_f32_16x16x32_bf16 v[6:9], v[168:171], v[210:213], 0
	v_mfma_f32_16x16x32_bf16 v[2:5], v[178:181], v[210:213], 0
	v_mfma_f32_16x16x32_bf16 v[54:57], v[172:175], v[190:193], v[54:57]
	v_mfma_f32_16x16x32_bf16 v[50:53], v[182:185], v[190:193], v[50:53]
	v_mfma_f32_16x16x32_bf16 v[38:41], v[172:175], v[198:201], v[38:41]
	v_mfma_f32_16x16x32_bf16 v[34:37], v[182:185], v[198:201], v[34:37]
	v_mfma_f32_16x16x32_bf16 v[22:25], v[172:175], v[206:209], v[22:25]
	v_mfma_f32_16x16x32_bf16 v[18:21], v[182:185], v[206:209], v[18:21]
	v_mfma_f32_16x16x32_bf16 v[6:9], v[172:175], v[214:217], v[6:9]
	v_mfma_f32_16x16x32_bf16 v[2:5], v[182:185], v[214:217], v[2:5]
	s_setprio 0
	s_barrier
	s_add_i32 s56, 0, 0x18000
	v_add_u32_e32 v151, s56, v148
	s_add_i32 s57, 0, 0x1c000
	ds_read_b128 v[152:155], v151
	ds_read_b128 v[156:159], v151 offset:1024
	ds_read_b128 v[160:163], v151 offset:2048
	ds_read_b128 v[164:167], v151 offset:3072
	v_add_u32_e32 v151, s57, v148
	ds_read_b128 v[168:171], v151
	ds_read_b128 v[172:175], v151 offset:1024
	ds_read_b128 v[178:181], v151 offset:2048
	ds_read_b128 v[182:185], v151 offset:3072
	s_add_u32 s2, s2, 0x40000
	s_addc_u32 s3, s3, 0
	s_mov_b32 m0, s36
	v_lshl_add_u64 v[224:225], s[2:3], 0, v[130:131]
	ds_read_b128 v[186:189], v150 offset:32768
	ds_read_b128 v[190:193], v150 offset:33792
	ds_read_b128 v[194:197], v150 offset:34816
	ds_read_b128 v[198:201], v150 offset:35840
	ds_read_b128 v[202:205], v150 offset:36864
	ds_read_b128 v[206:209], v150 offset:37888
	ds_read_b128 v[210:213], v150 offset:38912
	ds_read_b128 v[214:217], v150 offset:39936
	global_load_lds_dwordx4 v[224:225], off
	v_lshl_add_u64 v[224:225], s[2:3], 0, v[134:135]
	s_mov_b32 m0, s37
	s_nop 0
	global_load_lds_dwordx4 v[224:225], off
	s_waitcnt vmcnt(8)
	s_waitcnt lgkmcnt(0)
	s_barrier
	s_setprio 1
	v_mfma_f32_16x16x32_bf16 v[126:129], v[152:155], v[186:189], v[126:129]
	v_mfma_f32_16x16x32_bf16 v[122:125], v[160:163], v[186:189], v[122:125]
	v_mfma_f32_16x16x32_bf16 v[110:113], v[152:155], v[194:197], v[110:113]
	v_mfma_f32_16x16x32_bf16 v[106:109], v[160:163], v[194:197], v[106:109]
	v_mfma_f32_16x16x32_bf16 v[94:97], v[152:155], v[202:205], v[94:97]
	v_mfma_f32_16x16x32_bf16 v[90:93], v[160:163], v[202:205], v[90:93]
	v_mfma_f32_16x16x32_bf16 v[78:81], v[152:155], v[210:213], v[78:81]
	v_mfma_f32_16x16x32_bf16 v[74:77], v[160:163], v[210:213], v[74:77]
	v_mfma_f32_16x16x32_bf16 v[126:129], v[156:159], v[190:193], v[126:129]
	v_mfma_f32_16x16x32_bf16 v[122:125], v[164:167], v[190:193], v[122:125]
	v_mfma_f32_16x16x32_bf16 v[110:113], v[156:159], v[198:201], v[110:113]
	v_mfma_f32_16x16x32_bf16 v[106:109], v[164:167], v[198:201], v[106:109]
	v_mfma_f32_16x16x32_bf16 v[94:97], v[156:159], v[206:209], v[94:97]
	v_mfma_f32_16x16x32_bf16 v[90:93], v[164:167], v[206:209], v[90:93]
	v_mfma_f32_16x16x32_bf16 v[78:81], v[156:159], v[214:217], v[78:81]
	v_mfma_f32_16x16x32_bf16 v[74:77], v[164:167], v[214:217], v[74:77]
	v_mfma_f32_16x16x32_bf16 v[118:121], v[168:171], v[186:189], v[118:121]
	v_mfma_f32_16x16x32_bf16 v[114:117], v[178:181], v[186:189], v[114:117]
	v_mfma_f32_16x16x32_bf16 v[102:105], v[168:171], v[194:197], v[102:105]
	v_mfma_f32_16x16x32_bf16 v[98:101], v[178:181], v[194:197], v[98:101]
	v_mfma_f32_16x16x32_bf16 v[86:89], v[168:171], v[202:205], v[86:89]
	v_mfma_f32_16x16x32_bf16 v[82:85], v[178:181], v[202:205], v[82:85]
	v_mfma_f32_16x16x32_bf16 v[70:73], v[168:171], v[210:213], v[70:73]
	v_mfma_f32_16x16x32_bf16 v[66:69], v[178:181], v[210:213], v[66:69]
	v_mfma_f32_16x16x32_bf16 v[118:121], v[172:175], v[190:193], v[118:121]
	v_mfma_f32_16x16x32_bf16 v[114:117], v[182:185], v[190:193], v[114:117]
	v_mfma_f32_16x16x32_bf16 v[102:105], v[172:175], v[198:201], v[102:105]
	v_mfma_f32_16x16x32_bf16 v[98:101], v[182:185], v[198:201], v[98:101]
	v_mfma_f32_16x16x32_bf16 v[86:89], v[172:175], v[206:209], v[86:89]
	v_mfma_f32_16x16x32_bf16 v[82:85], v[182:185], v[206:209], v[82:85]
	v_mfma_f32_16x16x32_bf16 v[70:73], v[172:175], v[214:217], v[70:73]
	v_mfma_f32_16x16x32_bf16 v[66:69], v[182:185], v[214:217], v[66:69]
	s_setprio 0
	s_barrier
	s_add_i32 s2, s56, s34
	v_lshl_add_u64 v[146:147], v[146:147], 0, s[6:7]
	s_mov_b32 m0, s2
	ds_read_b128 v[186:189], v150 offset:49152
	ds_read_b128 v[190:193], v150 offset:50176
	ds_read_b128 v[194:197], v150 offset:51200
	ds_read_b128 v[198:201], v150 offset:52224
	ds_read_b128 v[202:205], v150 offset:53248
	ds_read_b128 v[206:209], v150 offset:54272
	ds_read_b128 v[210:213], v150 offset:55296
	ds_read_b128 v[214:217], v150 offset:56320
	global_load_lds_dwordx4 v[146:147], off
	s_add_i32 m0, s2, 0x2000
	s_add_u32 s2, s30, 0x40080
	v_lshl_add_u64 v[146:147], v[218:219], 0, s[6:7]
	s_addc_u32 s3, s31, 0
	s_add_i32 s30, s57, s34
	global_load_lds_dwordx4 v[146:147], off
	v_lshl_add_u64 v[146:147], s[2:3], 0, v[132:133]
	s_mov_b32 m0, s30
	s_nop 0
	global_load_lds_dwordx4 v[146:147], off
	v_lshl_add_u64 v[146:147], s[2:3], 0, v[136:137]
	s_add_i32 m0, s30, 0x2000
	s_nop 0
	global_load_lds_dwordx4 v[146:147], off
	v_lshl_add_u64 v[146:147], v[220:221], 0, s[6:7]
	s_mov_b32 m0, s40
	s_nop 0
	global_load_lds_dwordx4 v[146:147], off
	v_lshl_add_u64 v[146:147], v[222:223], 0, s[6:7]
	s_mov_b32 m0, s41
	s_nop 0
	global_load_lds_dwordx4 v[146:147], off
	s_waitcnt vmcnt(8)
	s_waitcnt lgkmcnt(0)
	s_barrier
	s_setprio 1
	v_mfma_f32_16x16x32_bf16 v[62:65], v[152:155], v[186:189], v[62:65]
	v_mfma_f32_16x16x32_bf16 v[58:61], v[160:163], v[186:189], v[58:61]
	v_mfma_f32_16x16x32_bf16 v[46:49], v[152:155], v[194:197], v[46:49]
	v_mfma_f32_16x16x32_bf16 v[42:45], v[160:163], v[194:197], v[42:45]
	v_mfma_f32_16x16x32_bf16 v[30:33], v[152:155], v[202:205], v[30:33]
	v_mfma_f32_16x16x32_bf16 v[26:29], v[160:163], v[202:205], v[26:29]
	v_mfma_f32_16x16x32_bf16 v[14:17], v[152:155], v[210:213], v[14:17]
	v_mfma_f32_16x16x32_bf16 v[10:13], v[160:163], v[210:213], v[10:13]
	v_mfma_f32_16x16x32_bf16 v[62:65], v[156:159], v[190:193], v[62:65]
	v_mfma_f32_16x16x32_bf16 v[58:61], v[164:167], v[190:193], v[58:61]
	v_mfma_f32_16x16x32_bf16 v[46:49], v[156:159], v[198:201], v[46:49]
	v_mfma_f32_16x16x32_bf16 v[42:45], v[164:167], v[198:201], v[42:45]
	v_mfma_f32_16x16x32_bf16 v[30:33], v[156:159], v[206:209], v[30:33]
	v_mfma_f32_16x16x32_bf16 v[26:29], v[164:167], v[206:209], v[26:29]
	v_mfma_f32_16x16x32_bf16 v[14:17], v[156:159], v[214:217], v[14:17]
	v_mfma_f32_16x16x32_bf16 v[10:13], v[164:167], v[214:217], v[10:13]
	v_mfma_f32_16x16x32_bf16 v[54:57], v[168:171], v[186:189], v[54:57]
	v_mfma_f32_16x16x32_bf16 v[50:53], v[178:181], v[186:189], v[50:53]
	v_mfma_f32_16x16x32_bf16 v[38:41], v[168:171], v[194:197], v[38:41]
	v_mfma_f32_16x16x32_bf16 v[34:37], v[178:181], v[194:197], v[34:37]
	v_mfma_f32_16x16x32_bf16 v[22:25], v[168:171], v[202:205], v[22:25]
	v_mfma_f32_16x16x32_bf16 v[18:21], v[178:181], v[202:205], v[18:21]
	v_mfma_f32_16x16x32_bf16 v[6:9], v[168:171], v[210:213], v[6:9]
	v_mfma_f32_16x16x32_bf16 v[2:5], v[178:181], v[210:213], v[2:5]
	v_mfma_f32_16x16x32_bf16 v[54:57], v[172:175], v[190:193], v[54:57]
	v_mfma_f32_16x16x32_bf16 v[50:53], v[182:185], v[190:193], v[50:53]
	v_mfma_f32_16x16x32_bf16 v[38:41], v[172:175], v[198:201], v[38:41]
	v_mfma_f32_16x16x32_bf16 v[34:37], v[182:185], v[198:201], v[34:37]
	v_mfma_f32_16x16x32_bf16 v[22:25], v[172:175], v[206:209], v[22:25]
	v_mfma_f32_16x16x32_bf16 v[18:21], v[182:185], v[206:209], v[18:21]
	v_mfma_f32_16x16x32_bf16 v[6:9], v[172:175], v[214:217], v[6:9]
	v_mfma_f32_16x16x32_bf16 v[2:5], v[182:185], v[214:217], v[2:5]
	s_setprio 0
	s_barrier
	s_add_i32 s55, s55, 2
	s_add_u32 s28, s28, 0x100
	s_addc_u32 s29, s29, 0
	s_add_u32 s53, s53, 0x100
	s_addc_u32 s54, s54, 0
	s_cmp_gt_u32 s55, 13
	s_cbranch_scc0 .LBB0_1400
	s_branch .Lpk1400_exit
.LBB0_1400:
	ds_read_b128 v[152:155], v1
	ds_read_b128 v[156:159], v1 offset:1024
	ds_read_b128 v[160:163], v1 offset:2048
	ds_read_b128 v[164:167], v1 offset:3072
	ds_read_b128 v[168:171], v149
	ds_read_b128 v[172:175], v149 offset:1024
	ds_read_b128 v[178:181], v149 offset:2048
	ds_read_b128 v[182:185], v149 offset:3072
	s_add_u32 s2, s28, 0xfffc0080
	s_addc_u32 s3, s29, -1
	s_cmp_eq_u32 s55, 12
	s_cselect_b32 s3, s11, s3
	s_cselect_b32 s2, s13, s2
	s_cselect_b32 s31, s47, s54
	s_cselect_b32 s30, s52, s53
	v_lshl_add_u64 v[146:147], s[28:29], 0, v[140:141]
	s_add_i32 m0, s25, 0xc000
	ds_read_b128 v[186:189], v150
	ds_read_b128 v[190:193], v150 offset:1024
	ds_read_b128 v[194:197], v150 offset:2048
	ds_read_b128 v[198:201], v150 offset:3072
	ds_read_b128 v[202:205], v150 offset:4096
	ds_read_b128 v[206:209], v150 offset:5120
	ds_read_b128 v[210:213], v150 offset:6144
	ds_read_b128 v[214:217], v150 offset:7168
	global_load_lds_dwordx4 v[146:147], off
	v_lshl_add_u64 v[146:147], s[28:29], 0, v[142:143]
	s_add_i32 m0, s25, 0xe000
	s_nop 0
	global_load_lds_dwordx4 v[146:147], off
	s_waitcnt vmcnt(8)
	s_waitcnt lgkmcnt(0)
	s_barrier
	s_setprio 1
	v_mfma_f32_16x16x32_bf16 v[126:129], v[152:155], v[186:189], v[126:129]
	v_mfma_f32_16x16x32_bf16 v[122:125], v[160:163], v[186:189], v[122:125]
	v_mfma_f32_16x16x32_bf16 v[110:113], v[152:155], v[194:197], v[110:113]
	v_mfma_f32_16x16x32_bf16 v[106:109], v[160:163], v[194:197], v[106:109]
	v_mfma_f32_16x16x32_bf16 v[94:97], v[152:155], v[202:205], v[94:97]
	v_mfma_f32_16x16x32_bf16 v[90:93], v[160:163], v[202:205], v[90:93]
	v_mfma_f32_16x16x32_bf16 v[78:81], v[152:155], v[210:213], v[78:81]
	v_mfma_f32_16x16x32_bf16 v[74:77], v[160:163], v[210:213], v[74:77]
	v_mfma_f32_16x16x32_bf16 v[126:129], v[156:159], v[190:193], v[126:129]
	v_mfma_f32_16x16x32_bf16 v[122:125], v[164:167], v[190:193], v[122:125]
	v_mfma_f32_16x16x32_bf16 v[110:113], v[156:159], v[198:201], v[110:113]
	v_mfma_f32_16x16x32_bf16 v[106:109], v[164:167], v[198:201], v[106:109]
	v_mfma_f32_16x16x32_bf16 v[94:97], v[156:159], v[206:209], v[94:97]
	v_mfma_f32_16x16x32_bf16 v[90:93], v[164:167], v[206:209], v[90:93]
	v_mfma_f32_16x16x32_bf16 v[78:81], v[156:159], v[214:217], v[78:81]
	v_mfma_f32_16x16x32_bf16 v[74:77], v[164:167], v[214:217], v[74:77]
	v_mfma_f32_16x16x32_bf16 v[118:121], v[168:171], v[186:189], v[118:121]
	v_mfma_f32_16x16x32_bf16 v[114:117], v[178:181], v[186:189], v[114:117]
	v_mfma_f32_16x16x32_bf16 v[102:105], v[168:171], v[194:197], v[102:105]
	v_mfma_f32_16x16x32_bf16 v[98:101], v[178:181], v[194:197], v[98:101]
	v_mfma_f32_16x16x32_bf16 v[86:89], v[168:171], v[202:205], v[86:89]
	v_mfma_f32_16x16x32_bf16 v[82:85], v[178:181], v[202:205], v[82:85]
	v_mfma_f32_16x16x32_bf16 v[70:73], v[168:171], v[210:213], v[70:73]
	v_mfma_f32_16x16x32_bf16 v[66:69], v[178:181], v[210:213], v[66:69]
	v_mfma_f32_16x16x32_bf16 v[118:121], v[172:175], v[190:193], v[118:121]
	v_mfma_f32_16x16x32_bf16 v[114:117], v[182:185], v[190:193], v[114:117]
	v_mfma_f32_16x16x32_bf16 v[102:105], v[172:175], v[198:201], v[102:105]
	v_mfma_f32_16x16x32_bf16 v[98:101], v[182:185], v[198:201], v[98:101]
	v_mfma_f32_16x16x32_bf16 v[86:89], v[172:175], v[206:209], v[86:89]
	v_mfma_f32_16x16x32_bf16 v[82:85], v[182:185], v[206:209], v[82:85]
	v_mfma_f32_16x16x32_bf16 v[70:73], v[172:175], v[214:217], v[70:73]
	v_mfma_f32_16x16x32_bf16 v[66:69], v[182:185], v[214:217], v[66:69]
	s_setprio 0
	s_barrier
	s_add_i32 s56, s43, s34
	v_lshl_add_u64 v[146:147], s[30:31], 0, v[132:133]
	s_mov_b32 m0, s56
	ds_read_b128 v[186:189], v150 offset:16384
	ds_read_b128 v[190:193], v150 offset:17408
	ds_read_b128 v[194:197], v150 offset:18432
	ds_read_b128 v[198:201], v150 offset:19456
	ds_read_b128 v[202:205], v150 offset:20480
	ds_read_b128 v[206:209], v150 offset:21504
	ds_read_b128 v[210:213], v150 offset:22528
	ds_read_b128 v[214:217], v150 offset:23552
	global_load_lds_dwordx4 v[146:147], off
	s_add_i32 m0, s56, 0x2000
	s_add_u32 s56, s30, 0x40000
	v_lshl_add_u64 v[218:219], s[30:31], 0, v[136:137]
	s_addc_u32 s57, s31, 0
	s_add_i32 s58, s44, s34
	global_load_lds_dwordx4 v[218:219], off
	v_lshl_add_u64 v[220:221], s[56:57], 0, v[132:133]
	s_mov_b32 m0, s58
	v_lshl_add_u64 v[222:223], s[2:3], 0, v[134:135]
	global_load_lds_dwordx4 v[220:221], off
	v_lshl_add_u64 v[220:221], s[56:57], 0, v[136:137]
	s_add_i32 m0, s58, 0x2000
	s_nop 0
	global_load_lds_dwordx4 v[220:221], off
	v_lshl_add_u64 v[220:221], s[2:3], 0, v[130:131]
	s_mov_b32 m0, s25
	s_nop 0
	global_load_lds_dwordx4 v[220:221], off
	s_mov_b32 m0, s27
	s_nop 0
	global_load_lds_dwordx4 v[222:223], off
	s_waitcnt vmcnt(8)
	s_waitcnt lgkmcnt(0)
	s_barrier
	s_setprio 1
	v_mfma_f32_16x16x32_bf16 v[62:65], v[152:155], v[186:189], v[62:65]
	v_mfma_f32_16x16x32_bf16 v[58:61], v[160:163], v[186:189], v[58:61]
	v_mfma_f32_16x16x32_bf16 v[46:49], v[152:155], v[194:197], v[46:49]
	v_mfma_f32_16x16x32_bf16 v[42:45], v[160:163], v[194:197], v[42:45]
	v_mfma_f32_16x16x32_bf16 v[30:33], v[152:155], v[202:205], v[30:33]
	v_mfma_f32_16x16x32_bf16 v[26:29], v[160:163], v[202:205], v[26:29]
	v_mfma_f32_16x16x32_bf16 v[14:17], v[152:155], v[210:213], v[14:17]
	v_mfma_f32_16x16x32_bf16 v[10:13], v[160:163], v[210:213], v[10:13]
	v_mfma_f32_16x16x32_bf16 v[62:65], v[156:159], v[190:193], v[62:65]
	v_mfma_f32_16x16x32_bf16 v[58:61], v[164:167], v[190:193], v[58:61]
	v_mfma_f32_16x16x32_bf16 v[46:49], v[156:159], v[198:201], v[46:49]
	v_mfma_f32_16x16x32_bf16 v[42:45], v[164:167], v[198:201], v[42:45]
	v_mfma_f32_16x16x32_bf16 v[30:33], v[156:159], v[206:209], v[30:33]
	v_mfma_f32_16x16x32_bf16 v[26:29], v[164:167], v[206:209], v[26:29]
	v_mfma_f32_16x16x32_bf16 v[14:17], v[156:159], v[214:217], v[14:17]
	v_mfma_f32_16x16x32_bf16 v[10:13], v[164:167], v[214:217], v[10:13]
	v_mfma_f32_16x16x32_bf16 v[54:57], v[168:171], v[186:189], v[54:57]
	v_mfma_f32_16x16x32_bf16 v[50:53], v[178:181], v[186:189], v[50:53]
	v_mfma_f32_16x16x32_bf16 v[38:41], v[168:171], v[194:197], v[38:41]
	v_mfma_f32_16x16x32_bf16 v[34:37], v[178:181], v[194:197], v[34:37]
	v_mfma_f32_16x16x32_bf16 v[22:25], v[168:171], v[202:205], v[22:25]
	v_mfma_f32_16x16x32_bf16 v[18:21], v[178:181], v[202:205], v[18:21]
	v_mfma_f32_16x16x32_bf16 v[6:9], v[168:171], v[210:213], v[6:9]
	v_mfma_f32_16x16x32_bf16 v[2:5], v[178:181], v[210:213], v[2:5]
	v_mfma_f32_16x16x32_bf16 v[54:57], v[172:175], v[190:193], v[54:57]
	v_mfma_f32_16x16x32_bf16 v[50:53], v[182:185], v[190:193], v[50:53]
	v_mfma_f32_16x16x32_bf16 v[38:41], v[172:175], v[198:201], v[38:41]
	v_mfma_f32_16x16x32_bf16 v[34:37], v[182:185], v[198:201], v[34:37]
	v_mfma_f32_16x16x32_bf16 v[22:25], v[172:175], v[206:209], v[22:25]
	v_mfma_f32_16x16x32_bf16 v[18:21], v[182:185], v[206:209], v[18:21]
	v_mfma_f32_16x16x32_bf16 v[6:9], v[172:175], v[214:217], v[6:9]
	v_mfma_f32_16x16x32_bf16 v[2:5], v[182:185], v[214:217], v[2:5]
	s_setprio 0
	s_barrier
	s_add_i32 s56, 0, 0x18000
	v_add_u32_e32 v151, s56, v148
	s_add_i32 s57, 0, 0x1c000
	ds_read_b128 v[152:155], v151
	ds_read_b128 v[156:159], v151 offset:1024
	ds_read_b128 v[160:163], v151 offset:2048
	ds_read_b128 v[164:167], v151 offset:3072
	v_add_u32_e32 v151, s57, v148
	ds_read_b128 v[168:171], v151
	ds_read_b128 v[172:175], v151 offset:1024
	ds_read_b128 v[178:181], v151 offset:2048
	ds_read_b128 v[182:185], v151 offset:3072
	s_add_u32 s2, s2, 0x40000
	s_addc_u32 s3, s3, 0
	s_mov_b32 m0, s36
	v_lshl_add_u64 v[224:225], s[2:3], 0, v[130:131]
	ds_read_b128 v[186:189], v150 offset:32768
	ds_read_b128 v[190:193], v150 offset:33792
	ds_read_b128 v[194:197], v150 offset:34816
	ds_read_b128 v[198:201], v150 offset:35840
	ds_read_b128 v[202:205], v150 offset:36864
	ds_read_b128 v[206:209], v150 offset:37888
	ds_read_b128 v[210:213], v150 offset:38912
	ds_read_b128 v[214:217], v150 offset:39936
	global_load_lds_dwordx4 v[224:225], off
	v_lshl_add_u64 v[224:225], s[2:3], 0, v[134:135]
	s_mov_b32 m0, s37
	s_nop 0
	global_load_lds_dwordx4 v[224:225], off
	s_waitcnt vmcnt(8)
	s_waitcnt lgkmcnt(0)
	s_barrier
	s_setprio 1
	v_mfma_f32_16x16x32_bf16 v[126:129], v[152:155], v[186:189], v[126:129]
	v_mfma_f32_16x16x32_bf16 v[122:125], v[160:163], v[186:189], v[122:125]
	v_mfma_f32_16x16x32_bf16 v[110:113], v[152:155], v[194:197], v[110:113]
	v_mfma_f32_16x16x32_bf16 v[106:109], v[160:163], v[194:197], v[106:109]
	v_mfma_f32_16x16x32_bf16 v[94:97], v[152:155], v[202:205], v[94:97]
	v_mfma_f32_16x16x32_bf16 v[90:93], v[160:163], v[202:205], v[90:93]
	v_mfma_f32_16x16x32_bf16 v[78:81], v[152:155], v[210:213], v[78:81]
	v_mfma_f32_16x16x32_bf16 v[74:77], v[160:163], v[210:213], v[74:77]
	v_mfma_f32_16x16x32_bf16 v[126:129], v[156:159], v[190:193], v[126:129]
	v_mfma_f32_16x16x32_bf16 v[122:125], v[164:167], v[190:193], v[122:125]
	v_mfma_f32_16x16x32_bf16 v[110:113], v[156:159], v[198:201], v[110:113]
	v_mfma_f32_16x16x32_bf16 v[106:109], v[164:167], v[198:201], v[106:109]
	v_mfma_f32_16x16x32_bf16 v[94:97], v[156:159], v[206:209], v[94:97]
	v_mfma_f32_16x16x32_bf16 v[90:93], v[164:167], v[206:209], v[90:93]
	v_mfma_f32_16x16x32_bf16 v[78:81], v[156:159], v[214:217], v[78:81]
	v_mfma_f32_16x16x32_bf16 v[74:77], v[164:167], v[214:217], v[74:77]
	v_mfma_f32_16x16x32_bf16 v[118:121], v[168:171], v[186:189], v[118:121]
	v_mfma_f32_16x16x32_bf16 v[114:117], v[178:181], v[186:189], v[114:117]
	v_mfma_f32_16x16x32_bf16 v[102:105], v[168:171], v[194:197], v[102:105]
	v_mfma_f32_16x16x32_bf16 v[98:101], v[178:181], v[194:197], v[98:101]
	v_mfma_f32_16x16x32_bf16 v[86:89], v[168:171], v[202:205], v[86:89]
	v_mfma_f32_16x16x32_bf16 v[82:85], v[178:181], v[202:205], v[82:85]
	v_mfma_f32_16x16x32_bf16 v[70:73], v[168:171], v[210:213], v[70:73]
	v_mfma_f32_16x16x32_bf16 v[66:69], v[178:181], v[210:213], v[66:69]
	v_mfma_f32_16x16x32_bf16 v[118:121], v[172:175], v[190:193], v[118:121]
	v_mfma_f32_16x16x32_bf16 v[114:117], v[182:185], v[190:193], v[114:117]
	v_mfma_f32_16x16x32_bf16 v[102:105], v[172:175], v[198:201], v[102:105]
	v_mfma_f32_16x16x32_bf16 v[98:101], v[182:185], v[198:201], v[98:101]
	v_mfma_f32_16x16x32_bf16 v[86:89], v[172:175], v[206:209], v[86:89]
	v_mfma_f32_16x16x32_bf16 v[82:85], v[182:185], v[206:209], v[82:85]
	v_mfma_f32_16x16x32_bf16 v[70:73], v[172:175], v[214:217], v[70:73]
	v_mfma_f32_16x16x32_bf16 v[66:69], v[182:185], v[214:217], v[66:69]
	s_setprio 0
	s_barrier
	s_add_i32 s2, s56, s34
	v_lshl_add_u64 v[146:147], v[146:147], 0, s[6:7]
	s_mov_b32 m0, s2
	ds_read_b128 v[186:189], v150 offset:49152
	ds_read_b128 v[190:193], v150 offset:50176
	ds_read_b128 v[194:197], v150 offset:51200
	ds_read_b128 v[198:201], v150 offset:52224
	ds_read_b128 v[202:205], v150 offset:53248
	ds_read_b128 v[206:209], v150 offset:54272
	ds_read_b128 v[210:213], v150 offset:55296
	ds_read_b128 v[214:217], v150 offset:56320
	global_load_lds_dwordx4 v[146:147], off
	s_add_i32 m0, s2, 0x2000
	s_add_u32 s2, s30, 0x40080
	v_lshl_add_u64 v[146:147], v[218:219], 0, s[6:7]
	s_addc_u32 s3, s31, 0
	s_add_i32 s30, s57, s34
	global_load_lds_dwordx4 v[146:147], off
	v_lshl_add_u64 v[146:147], s[2:3], 0, v[132:133]
	s_mov_b32 m0, s30
	s_nop 0
	global_load_lds_dwordx4 v[146:147], off
	v_lshl_add_u64 v[146:147], s[2:3], 0, v[136:137]
	s_add_i32 m0, s30, 0x2000
	s_nop 0
	global_load_lds_dwordx4 v[146:147], off
	v_lshl_add_u64 v[146:147], v[220:221], 0, s[6:7]
	s_mov_b32 m0, s40
	s_nop 0
	global_load_lds_dwordx4 v[146:147], off
	v_lshl_add_u64 v[146:147], v[222:223], 0, s[6:7]
	s_mov_b32 m0, s41
	s_nop 0
	global_load_lds_dwordx4 v[146:147], off
	s_waitcnt vmcnt(8)
	s_waitcnt lgkmcnt(0)
	s_barrier
	s_setprio 1
	v_mfma_f32_16x16x32_bf16 v[62:65], v[152:155], v[186:189], v[62:65]
	v_mfma_f32_16x16x32_bf16 v[58:61], v[160:163], v[186:189], v[58:61]
	v_mfma_f32_16x16x32_bf16 v[46:49], v[152:155], v[194:197], v[46:49]
	v_mfma_f32_16x16x32_bf16 v[42:45], v[160:163], v[194:197], v[42:45]
	v_mfma_f32_16x16x32_bf16 v[30:33], v[152:155], v[202:205], v[30:33]
	v_mfma_f32_16x16x32_bf16 v[26:29], v[160:163], v[202:205], v[26:29]
	v_mfma_f32_16x16x32_bf16 v[14:17], v[152:155], v[210:213], v[14:17]
	v_mfma_f32_16x16x32_bf16 v[10:13], v[160:163], v[210:213], v[10:13]
	v_mfma_f32_16x16x32_bf16 v[62:65], v[156:159], v[190:193], v[62:65]
	v_mfma_f32_16x16x32_bf16 v[58:61], v[164:167], v[190:193], v[58:61]
	v_mfma_f32_16x16x32_bf16 v[46:49], v[156:159], v[198:201], v[46:49]
	v_mfma_f32_16x16x32_bf16 v[42:45], v[164:167], v[198:201], v[42:45]
	v_mfma_f32_16x16x32_bf16 v[30:33], v[156:159], v[206:209], v[30:33]
	v_mfma_f32_16x16x32_bf16 v[26:29], v[164:167], v[206:209], v[26:29]
	v_mfma_f32_16x16x32_bf16 v[14:17], v[156:159], v[214:217], v[14:17]
	v_mfma_f32_16x16x32_bf16 v[10:13], v[164:167], v[214:217], v[10:13]
	v_mfma_f32_16x16x32_bf16 v[54:57], v[168:171], v[186:189], v[54:57]
	v_mfma_f32_16x16x32_bf16 v[50:53], v[178:181], v[186:189], v[50:53]
	v_mfma_f32_16x16x32_bf16 v[38:41], v[168:171], v[194:197], v[38:41]
	v_mfma_f32_16x16x32_bf16 v[34:37], v[178:181], v[194:197], v[34:37]
	v_mfma_f32_16x16x32_bf16 v[22:25], v[168:171], v[202:205], v[22:25]
	v_mfma_f32_16x16x32_bf16 v[18:21], v[178:181], v[202:205], v[18:21]
	v_mfma_f32_16x16x32_bf16 v[6:9], v[168:171], v[210:213], v[6:9]
	v_mfma_f32_16x16x32_bf16 v[2:5], v[178:181], v[210:213], v[2:5]
	v_mfma_f32_16x16x32_bf16 v[54:57], v[172:175], v[190:193], v[54:57]
	v_mfma_f32_16x16x32_bf16 v[50:53], v[182:185], v[190:193], v[50:53]
	v_mfma_f32_16x16x32_bf16 v[38:41], v[172:175], v[198:201], v[38:41]
	v_mfma_f32_16x16x32_bf16 v[34:37], v[182:185], v[198:201], v[34:37]
	v_mfma_f32_16x16x32_bf16 v[22:25], v[172:175], v[206:209], v[22:25]
	v_mfma_f32_16x16x32_bf16 v[18:21], v[182:185], v[206:209], v[18:21]
	v_mfma_f32_16x16x32_bf16 v[6:9], v[172:175], v[214:217], v[6:9]
	v_mfma_f32_16x16x32_bf16 v[2:5], v[182:185], v[214:217], v[2:5]
	s_setprio 0
	s_barrier
	s_add_i32 s55, s55, 2
	s_add_u32 s28, s28, 0x100
	s_addc_u32 s29, s29, 0
	s_add_u32 s53, s53, 0x100
	s_addc_u32 s54, s54, 0
	s_cmp_gt_u32 s55, 13
	s_cbranch_scc0 .LBB0_1400

.Lpk1444_peel:
	ds_read_b128 v[152:155], v148
	ds_read_b128 v[156:159], v148 offset:1024
	ds_read_b128 v[160:163], v148 offset:2048
	ds_read_b128 v[164:167], v148 offset:3072
	ds_read_b128 v[168:171], v149
	ds_read_b128 v[172:175], v149 offset:1024
	ds_read_b128 v[178:181], v149 offset:2048
	ds_read_b128 v[182:185], v149 offset:3072
	s_add_u32 s2, s26, 0x4000
	s_addc_u32 s3, s27, 0
	s_cmp_eq_u32 s62, 40
	s_cselect_b32 s2, s57, s2
	s_cselect_b32 s3, s56, s3
	s_cselect_b32 s31, s58, s61
	s_cselect_b32 s30, s59, s60
	s_add_u32 s28, s2, 0x8000
	s_addc_u32 s29, s3, 0
	v_lshl_add_u64 v[144:145], s[26:27], 0, v[138:139]
	s_add_i32 m0, s39, 0xc000
	ds_read_b128 v[186:189], v150
	ds_read_b128 v[190:193], v150 offset:1024
	ds_read_b128 v[194:197], v150 offset:2048
	ds_read_b128 v[198:201], v150 offset:3072
	ds_read_b128 v[202:205], v150 offset:4096
	ds_read_b128 v[206:209], v150 offset:5120
	ds_read_b128 v[210:213], v150 offset:6144
	ds_read_b128 v[214:217], v150 offset:7168
	global_load_lds_dwordx4 v[144:145], off
	v_lshl_add_u64 v[144:145], s[26:27], 0, v[140:141]
	s_add_i32 m0, s39, 0xe000
	s_nop 0
	global_load_lds_dwordx4 v[144:145], off
	s_waitcnt vmcnt(8)
	s_waitcnt lgkmcnt(0)
	s_barrier
	s_setprio 1
	v_mfma_f32_16x16x32_bf16 v[126:129], v[152:155], v[186:189], 0
	v_mfma_f32_16x16x32_bf16 v[122:125], v[160:163], v[186:189], 0
	v_mfma_f32_16x16x32_bf16 v[114:117], v[152:155], v[194:197], 0
	v_mfma_f32_16x16x32_bf16 v[106:109], v[160:163], v[194:197], 0
	v_mfma_f32_16x16x32_bf16 v[98:101], v[152:155], v[202:205], 0
	v_mfma_f32_16x16x32_bf16 v[90:93], v[160:163], v[202:205], 0
	v_mfma_f32_16x16x32_bf16 v[82:85], v[152:155], v[210:213], 0
	v_mfma_f32_16x16x32_bf16 v[74:77], v[160:163], v[210:213], 0
	v_mfma_f32_16x16x32_bf16 v[126:129], v[156:159], v[190:193], v[126:129]
	v_mfma_f32_16x16x32_bf16 v[122:125], v[164:167], v[190:193], v[122:125]
	v_mfma_f32_16x16x32_bf16 v[114:117], v[156:159], v[198:201], v[114:117]
	v_mfma_f32_16x16x32_bf16 v[106:109], v[164:167], v[198:201], v[106:109]
	v_mfma_f32_16x16x32_bf16 v[98:101], v[156:159], v[206:209], v[98:101]
	v_mfma_f32_16x16x32_bf16 v[90:93], v[164:167], v[206:209], v[90:93]
	v_mfma_f32_16x16x32_bf16 v[82:85], v[156:159], v[214:217], v[82:85]
	v_mfma_f32_16x16x32_bf16 v[74:77], v[164:167], v[214:217], v[74:77]
	v_mfma_f32_16x16x32_bf16 v[118:121], v[168:171], v[186:189], 0
	v_mfma_f32_16x16x32_bf16 v[110:113], v[178:181], v[186:189], 0
	v_mfma_f32_16x16x32_bf16 v[102:105], v[168:171], v[194:197], 0
	v_mfma_f32_16x16x32_bf16 v[94:97], v[178:181], v[194:197], 0
	v_mfma_f32_16x16x32_bf16 v[86:89], v[168:171], v[202:205], 0
	v_mfma_f32_16x16x32_bf16 v[78:81], v[178:181], v[202:205], 0
	v_mfma_f32_16x16x32_bf16 v[70:73], v[168:171], v[210:213], 0
	v_mfma_f32_16x16x32_bf16 v[66:69], v[178:181], v[210:213], 0
	v_mfma_f32_16x16x32_bf16 v[118:121], v[172:175], v[190:193], v[118:121]
	v_mfma_f32_16x16x32_bf16 v[110:113], v[182:185], v[190:193], v[110:113]
	v_mfma_f32_16x16x32_bf16 v[102:105], v[172:175], v[198:201], v[102:105]
	v_mfma_f32_16x16x32_bf16 v[94:97], v[182:185], v[198:201], v[94:97]
	v_mfma_f32_16x16x32_bf16 v[86:89], v[172:175], v[206:209], v[86:89]
	v_mfma_f32_16x16x32_bf16 v[78:81], v[182:185], v[206:209], v[78:81]
	v_mfma_f32_16x16x32_bf16 v[70:73], v[172:175], v[214:217], v[70:73]
	v_mfma_f32_16x16x32_bf16 v[66:69], v[182:185], v[214:217], v[66:69]
	s_setprio 0
	s_barrier
	s_add_i32 s63, s46, s38
	v_lshl_add_u64 v[144:145], s[30:31], 0, v[132:133]
	s_mov_b32 m0, s63
	ds_read_b128 v[186:189], v150 offset:16384
	ds_read_b128 v[190:193], v150 offset:17408
	ds_read_b128 v[194:197], v150 offset:18432
	ds_read_b128 v[198:201], v150 offset:19456
	ds_read_b128 v[202:205], v150 offset:20480
	ds_read_b128 v[206:209], v150 offset:21504
	ds_read_b128 v[210:213], v150 offset:22528
	ds_read_b128 v[214:217], v150 offset:23552
	global_load_lds_dwordx4 v[144:145], off
	s_add_i32 m0, s63, 0x2000
	s_add_u32 s64, s30, 0x4000
	v_lshl_add_u64 v[144:145], s[30:31], 0, v[136:137]
	s_addc_u32 s65, s31, 0
	s_add_i32 s63, s47, s38
	global_load_lds_dwordx4 v[144:145], off
	v_lshl_add_u64 v[144:145], s[64:65], 0, v[132:133]
	s_mov_b32 m0, s63
	s_nop 0
	global_load_lds_dwordx4 v[144:145], off
	v_lshl_add_u64 v[144:145], s[64:65], 0, v[136:137]
	s_add_i32 m0, s63, 0x2000
	s_nop 0
	global_load_lds_dwordx4 v[144:145], off
	v_lshl_add_u64 v[144:145], s[2:3], 0, v[130:131]
	s_mov_b32 m0, s39
	s_nop 0
	global_load_lds_dwordx4 v[144:145], off
	v_lshl_add_u64 v[144:145], s[2:3], 0, v[134:135]
	s_mov_b32 m0, s40
	s_nop 0
	global_load_lds_dwordx4 v[144:145], off
	s_waitcnt vmcnt(8)
	s_waitcnt lgkmcnt(0)
	s_barrier
	s_setprio 1
	v_mfma_f32_16x16x32_bf16 v[62:65], v[152:155], v[186:189], 0
	v_mfma_f32_16x16x32_bf16 v[58:61], v[160:163], v[186:189], 0
	v_mfma_f32_16x16x32_bf16 v[50:53], v[152:155], v[194:197], 0
	v_mfma_f32_16x16x32_bf16 v[42:45], v[160:163], v[194:197], 0
	v_mfma_f32_16x16x32_bf16 v[34:37], v[152:155], v[202:205], 0
	v_mfma_f32_16x16x32_bf16 v[26:29], v[160:163], v[202:205], 0
	v_mfma_f32_16x16x32_bf16 v[18:21], v[152:155], v[210:213], 0
	v_mfma_f32_16x16x32_bf16 v[10:13], v[160:163], v[210:213], 0
	v_mfma_f32_16x16x32_bf16 v[62:65], v[156:159], v[190:193], v[62:65]
	v_mfma_f32_16x16x32_bf16 v[58:61], v[164:167], v[190:193], v[58:61]
	v_mfma_f32_16x16x32_bf16 v[50:53], v[156:159], v[198:201], v[50:53]
	v_mfma_f32_16x16x32_bf16 v[42:45], v[164:167], v[198:201], v[42:45]
	v_mfma_f32_16x16x32_bf16 v[34:37], v[156:159], v[206:209], v[34:37]
	v_mfma_f32_16x16x32_bf16 v[26:29], v[164:167], v[206:209], v[26:29]
	v_mfma_f32_16x16x32_bf16 v[18:21], v[156:159], v[214:217], v[18:21]
	v_mfma_f32_16x16x32_bf16 v[10:13], v[164:167], v[214:217], v[10:13]
	v_mfma_f32_16x16x32_bf16 v[54:57], v[168:171], v[186:189], 0
	v_mfma_f32_16x16x32_bf16 v[46:49], v[178:181], v[186:189], 0
	v_mfma_f32_16x16x32_bf16 v[38:41], v[168:171], v[194:197], 0
	v_mfma_f32_16x16x32_bf16 v[30:33], v[178:181], v[194:197], 0
	v_mfma_f32_16x16x32_bf16 v[22:25], v[168:171], v[202:205], 0
	v_mfma_f32_16x16x32_bf16 v[14:17], v[178:181], v[202:205], 0
	v_mfma_f32_16x16x32_bf16 v[6:9], v[168:171], v[210:213], 0
	v_mfma_f32_16x16x32_bf16 v[2:5], v[178:181], v[210:213], 0
	v_mfma_f32_16x16x32_bf16 v[54:57], v[172:175], v[190:193], v[54:57]
	v_mfma_f32_16x16x32_bf16 v[46:49], v[182:185], v[190:193], v[46:49]
	v_mfma_f32_16x16x32_bf16 v[38:41], v[172:175], v[198:201], v[38:41]
	v_mfma_f32_16x16x32_bf16 v[30:33], v[182:185], v[198:201], v[30:33]
	v_mfma_f32_16x16x32_bf16 v[22:25], v[172:175], v[206:209], v[22:25]
	v_mfma_f32_16x16x32_bf16 v[14:17], v[182:185], v[206:209], v[14:17]
	v_mfma_f32_16x16x32_bf16 v[6:9], v[172:175], v[214:217], v[6:9]
	v_mfma_f32_16x16x32_bf16 v[2:5], v[182:185], v[214:217], v[2:5]
	s_setprio 0
	s_barrier
	s_add_i32 s63, 0, 0x18000
	v_add_u32_e32 v144, s63, v146
	s_add_i32 s64, 0, 0x1c000
	ds_read_b128 v[152:155], v144
	ds_read_b128 v[156:159], v144 offset:1024
	ds_read_b128 v[160:163], v144 offset:2048
	ds_read_b128 v[164:167], v144 offset:3072
	v_add_u32_e32 v144, s64, v146
	ds_read_b128 v[168:171], v144
	ds_read_b128 v[172:175], v144 offset:1024
	ds_read_b128 v[178:181], v144 offset:2048
	ds_read_b128 v[182:185], v144 offset:3072
	s_add_u32 s2, s2, 0x4000
	s_addc_u32 s3, s3, 0
	s_mov_b32 m0, s41
	v_lshl_add_u64 v[144:145], s[2:3], 0, v[130:131]
	ds_read_b128 v[186:189], v150 offset:32768
	ds_read_b128 v[190:193], v150 offset:33792
	ds_read_b128 v[194:197], v150 offset:34816
	ds_read_b128 v[198:201], v150 offset:35840
	ds_read_b128 v[202:205], v150 offset:36864
	ds_read_b128 v[206:209], v150 offset:37888
	ds_read_b128 v[210:213], v150 offset:38912
	ds_read_b128 v[214:217], v150 offset:39936
	global_load_lds_dwordx4 v[144:145], off
	v_lshl_add_u64 v[144:145], s[2:3], 0, v[134:135]
	s_mov_b32 m0, s42
	s_nop 0
	global_load_lds_dwordx4 v[144:145], off
	s_waitcnt vmcnt(8)
	s_waitcnt lgkmcnt(0)
	s_barrier
	s_setprio 1
	v_mfma_f32_16x16x32_bf16 v[126:129], v[152:155], v[186:189], v[126:129]
	v_mfma_f32_16x16x32_bf16 v[122:125], v[160:163], v[186:189], v[122:125]
	v_mfma_f32_16x16x32_bf16 v[114:117], v[152:155], v[194:197], v[114:117]
	v_mfma_f32_16x16x32_bf16 v[106:109], v[160:163], v[194:197], v[106:109]
	v_mfma_f32_16x16x32_bf16 v[98:101], v[152:155], v[202:205], v[98:101]
	v_mfma_f32_16x16x32_bf16 v[90:93], v[160:163], v[202:205], v[90:93]
	v_mfma_f32_16x16x32_bf16 v[82:85], v[152:155], v[210:213], v[82:85]
	v_mfma_f32_16x16x32_bf16 v[74:77], v[160:163], v[210:213], v[74:77]
	v_mfma_f32_16x16x32_bf16 v[126:129], v[156:159], v[190:193], v[126:129]
	v_mfma_f32_16x16x32_bf16 v[122:125], v[164:167], v[190:193], v[122:125]
	v_mfma_f32_16x16x32_bf16 v[114:117], v[156:159], v[198:201], v[114:117]
	v_mfma_f32_16x16x32_bf16 v[106:109], v[164:167], v[198:201], v[106:109]
	v_mfma_f32_16x16x32_bf16 v[98:101], v[156:159], v[206:209], v[98:101]
	v_mfma_f32_16x16x32_bf16 v[90:93], v[164:167], v[206:209], v[90:93]
	v_mfma_f32_16x16x32_bf16 v[82:85], v[156:159], v[214:217], v[82:85]
	v_mfma_f32_16x16x32_bf16 v[74:77], v[164:167], v[214:217], v[74:77]
	v_mfma_f32_16x16x32_bf16 v[118:121], v[168:171], v[186:189], v[118:121]
	v_mfma_f32_16x16x32_bf16 v[110:113], v[178:181], v[186:189], v[110:113]
	v_mfma_f32_16x16x32_bf16 v[102:105], v[168:171], v[194:197], v[102:105]
	v_mfma_f32_16x16x32_bf16 v[94:97], v[178:181], v[194:197], v[94:97]
	v_mfma_f32_16x16x32_bf16 v[86:89], v[168:171], v[202:205], v[86:89]
	v_mfma_f32_16x16x32_bf16 v[78:81], v[178:181], v[202:205], v[78:81]
	v_mfma_f32_16x16x32_bf16 v[70:73], v[168:171], v[210:213], v[70:73]
	v_mfma_f32_16x16x32_bf16 v[66:69], v[178:181], v[210:213], v[66:69]
	v_mfma_f32_16x16x32_bf16 v[118:121], v[172:175], v[190:193], v[118:121]
	v_mfma_f32_16x16x32_bf16 v[110:113], v[182:185], v[190:193], v[110:113]
	v_mfma_f32_16x16x32_bf16 v[102:105], v[172:175], v[198:201], v[102:105]
	v_mfma_f32_16x16x32_bf16 v[94:97], v[182:185], v[198:201], v[94:97]
	v_mfma_f32_16x16x32_bf16 v[86:89], v[172:175], v[206:209], v[86:89]
	v_mfma_f32_16x16x32_bf16 v[78:81], v[182:185], v[206:209], v[78:81]
	v_mfma_f32_16x16x32_bf16 v[70:73], v[172:175], v[214:217], v[70:73]
	v_mfma_f32_16x16x32_bf16 v[66:69], v[182:185], v[214:217], v[66:69]
	s_setprio 0
	s_barrier
	s_add_u32 s2, s30, 0x8000
	s_addc_u32 s3, s31, 0
	s_add_i32 s63, s63, s38
	v_lshl_add_u64 v[144:145], s[2:3], 0, v[132:133]
	s_mov_b32 m0, s63
	ds_read_b128 v[186:189], v150 offset:49152
	ds_read_b128 v[190:193], v150 offset:50176
	ds_read_b128 v[194:197], v150 offset:51200
	ds_read_b128 v[198:201], v150 offset:52224
	ds_read_b128 v[202:205], v150 offset:53248
	ds_read_b128 v[206:209], v150 offset:54272
	ds_read_b128 v[210:213], v150 offset:55296
	ds_read_b128 v[214:217], v150 offset:56320
	global_load_lds_dwordx4 v[144:145], off
	s_add_i32 m0, s63, 0x2000
	v_lshl_add_u64 v[144:145], s[2:3], 0, v[136:137]
	s_add_u32 s2, s30, 0xc000
	s_addc_u32 s3, s31, 0
	s_add_i32 s30, s64, s38
	global_load_lds_dwordx4 v[144:145], off
	v_lshl_add_u64 v[144:145], s[2:3], 0, v[132:133]
	s_mov_b32 m0, s30
	s_nop 0
	global_load_lds_dwordx4 v[144:145], off
	v_lshl_add_u64 v[144:145], s[2:3], 0, v[136:137]
	s_add_i32 m0, s30, 0x2000
	s_nop 0
	global_load_lds_dwordx4 v[144:145], off
	v_lshl_add_u64 v[144:145], s[28:29], 0, v[130:131]
	s_mov_b32 m0, s44
	s_nop 0
	global_load_lds_dwordx4 v[144:145], off
	v_lshl_add_u64 v[144:145], s[28:29], 0, v[134:135]
	s_mov_b32 m0, s45
	s_nop 0
	global_load_lds_dwordx4 v[144:145], off
	s_waitcnt vmcnt(8)
	s_waitcnt lgkmcnt(0)
	s_barrier
	s_setprio 1
	v_mfma_f32_16x16x32_bf16 v[62:65], v[152:155], v[186:189], v[62:65]
	v_mfma_f32_16x16x32_bf16 v[58:61], v[160:163], v[186:189], v[58:61]
	v_mfma_f32_16x16x32_bf16 v[50:53], v[152:155], v[194:197], v[50:53]
	v_mfma_f32_16x16x32_bf16 v[42:45], v[160:163], v[194:197], v[42:45]
	v_mfma_f32_16x16x32_bf16 v[34:37], v[152:155], v[202:205], v[34:37]
	v_mfma_f32_16x16x32_bf16 v[26:29], v[160:163], v[202:205], v[26:29]
	v_mfma_f32_16x16x32_bf16 v[18:21], v[152:155], v[210:213], v[18:21]
	v_mfma_f32_16x16x32_bf16 v[10:13], v[160:163], v[210:213], v[10:13]
	v_mfma_f32_16x16x32_bf16 v[62:65], v[156:159], v[190:193], v[62:65]
	v_mfma_f32_16x16x32_bf16 v[58:61], v[164:167], v[190:193], v[58:61]
	v_mfma_f32_16x16x32_bf16 v[50:53], v[156:159], v[198:201], v[50:53]
	v_mfma_f32_16x16x32_bf16 v[42:45], v[164:167], v[198:201], v[42:45]
	v_mfma_f32_16x16x32_bf16 v[34:37], v[156:159], v[206:209], v[34:37]
	v_mfma_f32_16x16x32_bf16 v[26:29], v[164:167], v[206:209], v[26:29]
	v_mfma_f32_16x16x32_bf16 v[18:21], v[156:159], v[214:217], v[18:21]
	v_mfma_f32_16x16x32_bf16 v[10:13], v[164:167], v[214:217], v[10:13]
	v_mfma_f32_16x16x32_bf16 v[54:57], v[168:171], v[186:189], v[54:57]
	v_mfma_f32_16x16x32_bf16 v[46:49], v[178:181], v[186:189], v[46:49]
	v_mfma_f32_16x16x32_bf16 v[38:41], v[168:171], v[194:197], v[38:41]
	v_mfma_f32_16x16x32_bf16 v[30:33], v[178:181], v[194:197], v[30:33]
	v_mfma_f32_16x16x32_bf16 v[22:25], v[168:171], v[202:205], v[22:25]
	v_mfma_f32_16x16x32_bf16 v[14:17], v[178:181], v[202:205], v[14:17]
	v_mfma_f32_16x16x32_bf16 v[6:9], v[168:171], v[210:213], v[6:9]
	v_mfma_f32_16x16x32_bf16 v[2:5], v[178:181], v[210:213], v[2:5]
	v_mfma_f32_16x16x32_bf16 v[54:57], v[172:175], v[190:193], v[54:57]
	v_mfma_f32_16x16x32_bf16 v[46:49], v[182:185], v[190:193], v[46:49]
	v_mfma_f32_16x16x32_bf16 v[38:41], v[172:175], v[198:201], v[38:41]
	v_mfma_f32_16x16x32_bf16 v[30:33], v[182:185], v[198:201], v[30:33]
	v_mfma_f32_16x16x32_bf16 v[22:25], v[172:175], v[206:209], v[22:25]
	v_mfma_f32_16x16x32_bf16 v[14:17], v[182:185], v[206:209], v[14:17]
	v_mfma_f32_16x16x32_bf16 v[6:9], v[172:175], v[214:217], v[6:9]
	v_mfma_f32_16x16x32_bf16 v[2:5], v[182:185], v[214:217], v[2:5]
	s_setprio 0
	s_barrier
	s_add_i32 s62, s62, 2
	s_add_u32 s26, s26, 0x10000
	s_addc_u32 s27, s27, 0
	s_add_u32 s60, s60, 0x10000
	s_addc_u32 s61, s61, 0
	s_cmp_gt_u32 s62, 41
	s_cbranch_scc0 .LBB0_1444
	s_branch .Lpk1444_exit
.LBB0_1444:
	ds_read_b128 v[152:155], v148
	ds_read_b128 v[156:159], v148 offset:1024
	ds_read_b128 v[160:163], v148 offset:2048
	ds_read_b128 v[164:167], v148 offset:3072
	ds_read_b128 v[168:171], v149
	ds_read_b128 v[172:175], v149 offset:1024
	ds_read_b128 v[178:181], v149 offset:2048
	ds_read_b128 v[182:185], v149 offset:3072
	s_add_u32 s2, s26, 0x4000
	s_addc_u32 s3, s27, 0
	s_cmp_eq_u32 s62, 40
	s_cselect_b32 s2, s57, s2
	s_cselect_b32 s3, s56, s3
	s_cselect_b32 s31, s58, s61
	s_cselect_b32 s30, s59, s60
	s_add_u32 s28, s2, 0x8000
	s_addc_u32 s29, s3, 0
	v_lshl_add_u64 v[144:145], s[26:27], 0, v[138:139]
	s_add_i32 m0, s39, 0xc000
	ds_read_b128 v[186:189], v150
	ds_read_b128 v[190:193], v150 offset:1024
	ds_read_b128 v[194:197], v150 offset:2048
	ds_read_b128 v[198:201], v150 offset:3072
	ds_read_b128 v[202:205], v150 offset:4096
	ds_read_b128 v[206:209], v150 offset:5120
	ds_read_b128 v[210:213], v150 offset:6144
	ds_read_b128 v[214:217], v150 offset:7168
	global_load_lds_dwordx4 v[144:145], off
	v_lshl_add_u64 v[144:145], s[26:27], 0, v[140:141]
	s_add_i32 m0, s39, 0xe000
	s_nop 0
	global_load_lds_dwordx4 v[144:145], off
	s_waitcnt vmcnt(8)
	s_waitcnt lgkmcnt(0)
	s_barrier
	s_setprio 1
	v_mfma_f32_16x16x32_bf16 v[126:129], v[152:155], v[186:189], v[126:129]
	v_mfma_f32_16x16x32_bf16 v[122:125], v[160:163], v[186:189], v[122:125]
	v_mfma_f32_16x16x32_bf16 v[114:117], v[152:155], v[194:197], v[114:117]
	v_mfma_f32_16x16x32_bf16 v[106:109], v[160:163], v[194:197], v[106:109]
	v_mfma_f32_16x16x32_bf16 v[98:101], v[152:155], v[202:205], v[98:101]
	v_mfma_f32_16x16x32_bf16 v[90:93], v[160:163], v[202:205], v[90:93]
	v_mfma_f32_16x16x32_bf16 v[82:85], v[152:155], v[210:213], v[82:85]
	v_mfma_f32_16x16x32_bf16 v[74:77], v[160:163], v[210:213], v[74:77]
	v_mfma_f32_16x16x32_bf16 v[126:129], v[156:159], v[190:193], v[126:129]
	v_mfma_f32_16x16x32_bf16 v[122:125], v[164:167], v[190:193], v[122:125]
	v_mfma_f32_16x16x32_bf16 v[114:117], v[156:159], v[198:201], v[114:117]
	v_mfma_f32_16x16x32_bf16 v[106:109], v[164:167], v[198:201], v[106:109]
	v_mfma_f32_16x16x32_bf16 v[98:101], v[156:159], v[206:209], v[98:101]
	v_mfma_f32_16x16x32_bf16 v[90:93], v[164:167], v[206:209], v[90:93]
	v_mfma_f32_16x16x32_bf16 v[82:85], v[156:159], v[214:217], v[82:85]
	v_mfma_f32_16x16x32_bf16 v[74:77], v[164:167], v[214:217], v[74:77]
	v_mfma_f32_16x16x32_bf16 v[118:121], v[168:171], v[186:189], v[118:121]
	v_mfma_f32_16x16x32_bf16 v[110:113], v[178:181], v[186:189], v[110:113]
	v_mfma_f32_16x16x32_bf16 v[102:105], v[168:171], v[194:197], v[102:105]
	v_mfma_f32_16x16x32_bf16 v[94:97], v[178:181], v[194:197], v[94:97]
	v_mfma_f32_16x16x32_bf16 v[86:89], v[168:171], v[202:205], v[86:89]
	v_mfma_f32_16x16x32_bf16 v[78:81], v[178:181], v[202:205], v[78:81]
	v_mfma_f32_16x16x32_bf16 v[70:73], v[168:171], v[210:213], v[70:73]
	v_mfma_f32_16x16x32_bf16 v[66:69], v[178:181], v[210:213], v[66:69]
	v_mfma_f32_16x16x32_bf16 v[118:121], v[172:175], v[190:193], v[118:121]
	v_mfma_f32_16x16x32_bf16 v[110:113], v[182:185], v[190:193], v[110:113]
	v_mfma_f32_16x16x32_bf16 v[102:105], v[172:175], v[198:201], v[102:105]
	v_mfma_f32_16x16x32_bf16 v[94:97], v[182:185], v[198:201], v[94:97]
	v_mfma_f32_16x16x32_bf16 v[86:89], v[172:175], v[206:209], v[86:89]
	v_mfma_f32_16x16x32_bf16 v[78:81], v[182:185], v[206:209], v[78:81]
	v_mfma_f32_16x16x32_bf16 v[70:73], v[172:175], v[214:217], v[70:73]
	v_mfma_f32_16x16x32_bf16 v[66:69], v[182:185], v[214:217], v[66:69]
	s_setprio 0
	s_barrier
	s_add_i32 s63, s46, s38
	v_lshl_add_u64 v[144:145], s[30:31], 0, v[132:133]
	s_mov_b32 m0, s63
	ds_read_b128 v[186:189], v150 offset:16384
	ds_read_b128 v[190:193], v150 offset:17408
	ds_read_b128 v[194:197], v150 offset:18432
	ds_read_b128 v[198:201], v150 offset:19456
	ds_read_b128 v[202:205], v150 offset:20480
	ds_read_b128 v[206:209], v150 offset:21504
	ds_read_b128 v[210:213], v150 offset:22528
	ds_read_b128 v[214:217], v150 offset:23552
	global_load_lds_dwordx4 v[144:145], off
	s_add_i32 m0, s63, 0x2000
	s_add_u32 s64, s30, 0x4000
	v_lshl_add_u64 v[144:145], s[30:31], 0, v[136:137]
	s_addc_u32 s65, s31, 0
	s_add_i32 s63, s47, s38
	global_load_lds_dwordx4 v[144:145], off
	v_lshl_add_u64 v[144:145], s[64:65], 0, v[132:133]
	s_mov_b32 m0, s63
	s_nop 0
	global_load_lds_dwordx4 v[144:145], off
	v_lshl_add_u64 v[144:145], s[64:65], 0, v[136:137]
	s_add_i32 m0, s63, 0x2000
	s_nop 0
	global_load_lds_dwordx4 v[144:145], off
	v_lshl_add_u64 v[144:145], s[2:3], 0, v[130:131]
	s_mov_b32 m0, s39
	s_nop 0
	global_load_lds_dwordx4 v[144:145], off
	v_lshl_add_u64 v[144:145], s[2:3], 0, v[134:135]
	s_mov_b32 m0, s40
	s_nop 0
	global_load_lds_dwordx4 v[144:145], off
	s_waitcnt vmcnt(8)
	s_waitcnt lgkmcnt(0)
	s_barrier
	s_setprio 1
	v_mfma_f32_16x16x32_bf16 v[62:65], v[152:155], v[186:189], v[62:65]
	v_mfma_f32_16x16x32_bf16 v[58:61], v[160:163], v[186:189], v[58:61]
	v_mfma_f32_16x16x32_bf16 v[50:53], v[152:155], v[194:197], v[50:53]
	v_mfma_f32_16x16x32_bf16 v[42:45], v[160:163], v[194:197], v[42:45]
	v_mfma_f32_16x16x32_bf16 v[34:37], v[152:155], v[202:205], v[34:37]
	v_mfma_f32_16x16x32_bf16 v[26:29], v[160:163], v[202:205], v[26:29]
	v_mfma_f32_16x16x32_bf16 v[18:21], v[152:155], v[210:213], v[18:21]
	v_mfma_f32_16x16x32_bf16 v[10:13], v[160:163], v[210:213], v[10:13]
	v_mfma_f32_16x16x32_bf16 v[62:65], v[156:159], v[190:193], v[62:65]
	v_mfma_f32_16x16x32_bf16 v[58:61], v[164:167], v[190:193], v[58:61]
	v_mfma_f32_16x16x32_bf16 v[50:53], v[156:159], v[198:201], v[50:53]
	v_mfma_f32_16x16x32_bf16 v[42:45], v[164:167], v[198:201], v[42:45]
	v_mfma_f32_16x16x32_bf16 v[34:37], v[156:159], v[206:209], v[34:37]
	v_mfma_f32_16x16x32_bf16 v[26:29], v[164:167], v[206:209], v[26:29]
	v_mfma_f32_16x16x32_bf16 v[18:21], v[156:159], v[214:217], v[18:21]
	v_mfma_f32_16x16x32_bf16 v[10:13], v[164:167], v[214:217], v[10:13]
	v_mfma_f32_16x16x32_bf16 v[54:57], v[168:171], v[186:189], v[54:57]
	v_mfma_f32_16x16x32_bf16 v[46:49], v[178:181], v[186:189], v[46:49]
	v_mfma_f32_16x16x32_bf16 v[38:41], v[168:171], v[194:197], v[38:41]
	v_mfma_f32_16x16x32_bf16 v[30:33], v[178:181], v[194:197], v[30:33]
	v_mfma_f32_16x16x32_bf16 v[22:25], v[168:171], v[202:205], v[22:25]
	v_mfma_f32_16x16x32_bf16 v[14:17], v[178:181], v[202:205], v[14:17]
	v_mfma_f32_16x16x32_bf16 v[6:9], v[168:171], v[210:213], v[6:9]
	v_mfma_f32_16x16x32_bf16 v[2:5], v[178:181], v[210:213], v[2:5]
	v_mfma_f32_16x16x32_bf16 v[54:57], v[172:175], v[190:193], v[54:57]
	v_mfma_f32_16x16x32_bf16 v[46:49], v[182:185], v[190:193], v[46:49]
	v_mfma_f32_16x16x32_bf16 v[38:41], v[172:175], v[198:201], v[38:41]
	v_mfma_f32_16x16x32_bf16 v[30:33], v[182:185], v[198:201], v[30:33]
	v_mfma_f32_16x16x32_bf16 v[22:25], v[172:175], v[206:209], v[22:25]
	v_mfma_f32_16x16x32_bf16 v[14:17], v[182:185], v[206:209], v[14:17]
	v_mfma_f32_16x16x32_bf16 v[6:9], v[172:175], v[214:217], v[6:9]
	v_mfma_f32_16x16x32_bf16 v[2:5], v[182:185], v[214:217], v[2:5]
	s_setprio 0
	s_barrier
	s_add_i32 s63, 0, 0x18000
	v_add_u32_e32 v144, s63, v146
	s_add_i32 s64, 0, 0x1c000
	ds_read_b128 v[152:155], v144
	ds_read_b128 v[156:159], v144 offset:1024
	ds_read_b128 v[160:163], v144 offset:2048
	ds_read_b128 v[164:167], v144 offset:3072
	v_add_u32_e32 v144, s64, v146
	ds_read_b128 v[168:171], v144
	ds_read_b128 v[172:175], v144 offset:1024
	ds_read_b128 v[178:181], v144 offset:2048
	ds_read_b128 v[182:185], v144 offset:3072
	s_add_u32 s2, s2, 0x4000
	s_addc_u32 s3, s3, 0
	s_mov_b32 m0, s41
	v_lshl_add_u64 v[144:145], s[2:3], 0, v[130:131]
	ds_read_b128 v[186:189], v150 offset:32768
	ds_read_b128 v[190:193], v150 offset:33792
	ds_read_b128 v[194:197], v150 offset:34816
	ds_read_b128 v[198:201], v150 offset:35840
	ds_read_b128 v[202:205], v150 offset:36864
	ds_read_b128 v[206:209], v150 offset:37888
	ds_read_b128 v[210:213], v150 offset:38912
	ds_read_b128 v[214:217], v150 offset:39936
	global_load_lds_dwordx4 v[144:145], off
	v_lshl_add_u64 v[144:145], s[2:3], 0, v[134:135]
	s_mov_b32 m0, s42
	s_nop 0
	global_load_lds_dwordx4 v[144:145], off
	s_waitcnt vmcnt(8)
	s_waitcnt lgkmcnt(0)
	s_barrier
	s_setprio 1
	v_mfma_f32_16x16x32_bf16 v[126:129], v[152:155], v[186:189], v[126:129]
	v_mfma_f32_16x16x32_bf16 v[122:125], v[160:163], v[186:189], v[122:125]
	v_mfma_f32_16x16x32_bf16 v[114:117], v[152:155], v[194:197], v[114:117]
	v_mfma_f32_16x16x32_bf16 v[106:109], v[160:163], v[194:197], v[106:109]
	v_mfma_f32_16x16x32_bf16 v[98:101], v[152:155], v[202:205], v[98:101]
	v_mfma_f32_16x16x32_bf16 v[90:93], v[160:163], v[202:205], v[90:93]
	v_mfma_f32_16x16x32_bf16 v[82:85], v[152:155], v[210:213], v[82:85]
	v_mfma_f32_16x16x32_bf16 v[74:77], v[160:163], v[210:213], v[74:77]
	v_mfma_f32_16x16x32_bf16 v[126:129], v[156:159], v[190:193], v[126:129]
	v_mfma_f32_16x16x32_bf16 v[122:125], v[164:167], v[190:193], v[122:125]
	v_mfma_f32_16x16x32_bf16 v[114:117], v[156:159], v[198:201], v[114:117]
	v_mfma_f32_16x16x32_bf16 v[106:109], v[164:167], v[198:201], v[106:109]
	v_mfma_f32_16x16x32_bf16 v[98:101], v[156:159], v[206:209], v[98:101]
	v_mfma_f32_16x16x32_bf16 v[90:93], v[164:167], v[206:209], v[90:93]
	v_mfma_f32_16x16x32_bf16 v[82:85], v[156:159], v[214:217], v[82:85]
	v_mfma_f32_16x16x32_bf16 v[74:77], v[164:167], v[214:217], v[74:77]
	v_mfma_f32_16x16x32_bf16 v[118:121], v[168:171], v[186:189], v[118:121]
	v_mfma_f32_16x16x32_bf16 v[110:113], v[178:181], v[186:189], v[110:113]
	v_mfma_f32_16x16x32_bf16 v[102:105], v[168:171], v[194:197], v[102:105]
	v_mfma_f32_16x16x32_bf16 v[94:97], v[178:181], v[194:197], v[94:97]
	v_mfma_f32_16x16x32_bf16 v[86:89], v[168:171], v[202:205], v[86:89]
	v_mfma_f32_16x16x32_bf16 v[78:81], v[178:181], v[202:205], v[78:81]
	v_mfma_f32_16x16x32_bf16 v[70:73], v[168:171], v[210:213], v[70:73]
	v_mfma_f32_16x16x32_bf16 v[66:69], v[178:181], v[210:213], v[66:69]
	v_mfma_f32_16x16x32_bf16 v[118:121], v[172:175], v[190:193], v[118:121]
	v_mfma_f32_16x16x32_bf16 v[110:113], v[182:185], v[190:193], v[110:113]
	v_mfma_f32_16x16x32_bf16 v[102:105], v[172:175], v[198:201], v[102:105]
	v_mfma_f32_16x16x32_bf16 v[94:97], v[182:185], v[198:201], v[94:97]
	v_mfma_f32_16x16x32_bf16 v[86:89], v[172:175], v[206:209], v[86:89]
	v_mfma_f32_16x16x32_bf16 v[78:81], v[182:185], v[206:209], v[78:81]
	v_mfma_f32_16x16x32_bf16 v[70:73], v[172:175], v[214:217], v[70:73]
	v_mfma_f32_16x16x32_bf16 v[66:69], v[182:185], v[214:217], v[66:69]
	s_setprio 0
	s_barrier
	s_add_u32 s2, s30, 0x8000
	s_addc_u32 s3, s31, 0
	s_add_i32 s63, s63, s38
	v_lshl_add_u64 v[144:145], s[2:3], 0, v[132:133]
	s_mov_b32 m0, s63
	ds_read_b128 v[186:189], v150 offset:49152
	ds_read_b128 v[190:193], v150 offset:50176
	ds_read_b128 v[194:197], v150 offset:51200
	ds_read_b128 v[198:201], v150 offset:52224
	ds_read_b128 v[202:205], v150 offset:53248
	ds_read_b128 v[206:209], v150 offset:54272
	ds_read_b128 v[210:213], v150 offset:55296
	ds_read_b128 v[214:217], v150 offset:56320
	global_load_lds_dwordx4 v[144:145], off
	s_add_i32 m0, s63, 0x2000
	v_lshl_add_u64 v[144:145], s[2:3], 0, v[136:137]
	s_add_u32 s2, s30, 0xc000
	s_addc_u32 s3, s31, 0
	s_add_i32 s30, s64, s38
	global_load_lds_dwordx4 v[144:145], off
	v_lshl_add_u64 v[144:145], s[2:3], 0, v[132:133]
	s_mov_b32 m0, s30
	s_nop 0
	global_load_lds_dwordx4 v[144:145], off
	v_lshl_add_u64 v[144:145], s[2:3], 0, v[136:137]
	s_add_i32 m0, s30, 0x2000
	s_nop 0
	global_load_lds_dwordx4 v[144:145], off
	v_lshl_add_u64 v[144:145], s[28:29], 0, v[130:131]
	s_mov_b32 m0, s44
	s_nop 0
	global_load_lds_dwordx4 v[144:145], off
	v_lshl_add_u64 v[144:145], s[28:29], 0, v[134:135]
	s_mov_b32 m0, s45
	s_nop 0
	global_load_lds_dwordx4 v[144:145], off
	s_waitcnt vmcnt(8)
	s_waitcnt lgkmcnt(0)
	s_barrier
	s_setprio 1
	v_mfma_f32_16x16x32_bf16 v[62:65], v[152:155], v[186:189], v[62:65]
	v_mfma_f32_16x16x32_bf16 v[58:61], v[160:163], v[186:189], v[58:61]
	v_mfma_f32_16x16x32_bf16 v[50:53], v[152:155], v[194:197], v[50:53]
	v_mfma_f32_16x16x32_bf16 v[42:45], v[160:163], v[194:197], v[42:45]
	v_mfma_f32_16x16x32_bf16 v[34:37], v[152:155], v[202:205], v[34:37]
	v_mfma_f32_16x16x32_bf16 v[26:29], v[160:163], v[202:205], v[26:29]
	v_mfma_f32_16x16x32_bf16 v[18:21], v[152:155], v[210:213], v[18:21]
	v_mfma_f32_16x16x32_bf16 v[10:13], v[160:163], v[210:213], v[10:13]
	v_mfma_f32_16x16x32_bf16 v[62:65], v[156:159], v[190:193], v[62:65]
	v_mfma_f32_16x16x32_bf16 v[58:61], v[164:167], v[190:193], v[58:61]
	v_mfma_f32_16x16x32_bf16 v[50:53], v[156:159], v[198:201], v[50:53]
	v_mfma_f32_16x16x32_bf16 v[42:45], v[164:167], v[198:201], v[42:45]
	v_mfma_f32_16x16x32_bf16 v[34:37], v[156:159], v[206:209], v[34:37]
	v_mfma_f32_16x16x32_bf16 v[26:29], v[164:167], v[206:209], v[26:29]
	v_mfma_f32_16x16x32_bf16 v[18:21], v[156:159], v[214:217], v[18:21]
	v_mfma_f32_16x16x32_bf16 v[10:13], v[164:167], v[214:217], v[10:13]
	v_mfma_f32_16x16x32_bf16 v[54:57], v[168:171], v[186:189], v[54:57]
	v_mfma_f32_16x16x32_bf16 v[46:49], v[178:181], v[186:189], v[46:49]
	v_mfma_f32_16x16x32_bf16 v[38:41], v[168:171], v[194:197], v[38:41]
	v_mfma_f32_16x16x32_bf16 v[30:33], v[178:181], v[194:197], v[30:33]
	v_mfma_f32_16x16x32_bf16 v[22:25], v[168:171], v[202:205], v[22:25]
	v_mfma_f32_16x16x32_bf16 v[14:17], v[178:181], v[202:205], v[14:17]
	v_mfma_f32_16x16x32_bf16 v[6:9], v[168:171], v[210:213], v[6:9]
	v_mfma_f32_16x16x32_bf16 v[2:5], v[178:181], v[210:213], v[2:5]
	v_mfma_f32_16x16x32_bf16 v[54:57], v[172:175], v[190:193], v[54:57]
	v_mfma_f32_16x16x32_bf16 v[46:49], v[182:185], v[190:193], v[46:49]
	v_mfma_f32_16x16x32_bf16 v[38:41], v[172:175], v[198:201], v[38:41]
	v_mfma_f32_16x16x32_bf16 v[30:33], v[182:185], v[198:201], v[30:33]
	v_mfma_f32_16x16x32_bf16 v[22:25], v[172:175], v[206:209], v[22:25]
	v_mfma_f32_16x16x32_bf16 v[14:17], v[182:185], v[206:209], v[14:17]
	v_mfma_f32_16x16x32_bf16 v[6:9], v[172:175], v[214:217], v[6:9]
	v_mfma_f32_16x16x32_bf16 v[2:5], v[182:185], v[214:217], v[2:5]
	s_setprio 0
	s_barrier
	s_add_i32 s62, s62, 2
	s_add_u32 s26, s26, 0x10000
	s_addc_u32 s27, s27, 0
	s_add_u32 s60, s60, 0x10000
	s_addc_u32 s61, s61, 0
	s_cmp_gt_u32 s62, 41
	s_cbranch_scc0 .LBB0_1444
